# GEMM load segments: all ds_reads issued first, scalar/address/DMA work after (64 segments); on top of v022
# speedup vs baseline: 1.0600x; 1.0054x over previous
.LBB0_183:
	s_ashr_i32 s13, s12, 31
	s_lshl_b64 s[24:25], s[12:13], 19
	s_add_u32 s24, s80, s24
	s_addc_u32 s25, s81, s25
	s_and_b64 s[30:31], s[4:5], exec
	s_cselect_b32 s13, s25, s45
	s_cselect_b32 s66, s24, s44
	s_ashr_i32 s11, s10, 31
	s_lshl_b64 s[30:31], s[10:11], 19
	s_add_u32 s30, s52, s30
	s_addc_u32 s31, s53, s31
	s_and_b64 s[48:49], s[4:5], exec
	s_cselect_b32 s11, s31, s47
	s_cselect_b32 s67, s30, s46
	s_add_u32 s44, s44, 0x40080
	s_addc_u32 s45, s45, 0
	s_add_u32 s68, s46, 0x100
	s_addc_u32 s69, s47, 0
	s_mov_b32 s70, -2
	ds_read_b128 v[140:143], v147
	ds_read_b128 v[150:153], v147 offset:1024
	ds_read_b128 v[154:157], v147 offset:2048
	ds_read_b128 v[158:161], v147 offset:3072
	ds_read_b128 v[162:165], v148
	ds_read_b128 v[166:169], v148 offset:1024
	ds_read_b128 v[170:173], v148 offset:2048
	ds_read_b128 v[174:177], v148 offset:3072
	s_add_u32 s18, s44, 0xfffc0080
	s_addc_u32 s19, s45, -1
	s_cmp_eq_u32 s70, 12
	s_cselect_b32 s49, s13, s19
	s_cselect_b32 s48, s66, s18
	s_cselect_b32 s47, s11, s69
	s_cselect_b32 s46, s67, s68
	v_lshl_add_u64 v[178:179], s[44:45], 0, v[132:133]
	s_add_i32 m0, s37, 0xc000
	ds_read_b128 v[184:187], v149
	ds_read_b128 v[188:191], v149 offset:1024
	ds_read_b128 v[192:195], v149 offset:2048
	ds_read_b128 v[196:199], v149 offset:3072
	ds_read_b128 v[200:203], v149 offset:4096
	ds_read_b128 v[204:207], v149 offset:5120
	ds_read_b128 v[208:211], v149 offset:6144
	ds_read_b128 v[212:215], v149 offset:7168
	global_load_lds_dwordx4 v[178:179], off
	v_lshl_add_u64 v[178:179], s[44:45], 0, v[134:135]
	s_add_i32 m0, s37, 0xe000
	s_nop 0
	global_load_lds_dwordx4 v[178:179], off
	s_waitcnt vmcnt(8)
	s_waitcnt lgkmcnt(0)
	s_barrier
	s_setprio 1
	s_waitcnt lgkmcnt(0)
	v_mfma_f32_16x16x32_bf16 v[124:127], v[140:143], v[184:187], 0
	v_mfma_f32_16x16x32_bf16 v[124:127], v[150:153], v[188:191], v[124:127]
	v_mfma_f32_16x16x32_bf16 v[120:123], v[154:157], v[184:187], 0
	v_mfma_f32_16x16x32_bf16 v[120:123], v[158:161], v[188:191], v[120:123]
	v_mfma_f32_16x16x32_bf16 v[108:111], v[140:143], v[192:195], 0
	v_mfma_f32_16x16x32_bf16 v[108:111], v[150:153], v[196:199], v[108:111]
	v_mfma_f32_16x16x32_bf16 v[104:107], v[154:157], v[192:195], 0
	v_mfma_f32_16x16x32_bf16 v[104:107], v[158:161], v[196:199], v[104:107]
	v_mfma_f32_16x16x32_bf16 v[92:95], v[140:143], v[200:203], 0
	v_mfma_f32_16x16x32_bf16 v[92:95], v[150:153], v[204:207], v[92:95]
	v_mfma_f32_16x16x32_bf16 v[88:91], v[154:157], v[200:203], 0
	v_mfma_f32_16x16x32_bf16 v[88:91], v[158:161], v[204:207], v[88:91]
	v_mfma_f32_16x16x32_bf16 v[76:79], v[140:143], v[208:211], 0
	v_mfma_f32_16x16x32_bf16 v[76:79], v[150:153], v[212:215], v[76:79]
	v_mfma_f32_16x16x32_bf16 v[72:75], v[154:157], v[208:211], 0
	v_mfma_f32_16x16x32_bf16 v[72:75], v[158:161], v[212:215], v[72:75]
	v_mfma_f32_16x16x32_bf16 v[116:119], v[162:165], v[184:187], 0
	v_mfma_f32_16x16x32_bf16 v[116:119], v[166:169], v[188:191], v[116:119]
	v_mfma_f32_16x16x32_bf16 v[112:115], v[170:173], v[184:187], 0
	v_mfma_f32_16x16x32_bf16 v[112:115], v[174:177], v[188:191], v[112:115]
	v_mfma_f32_16x16x32_bf16 v[100:103], v[162:165], v[192:195], 0
	v_mfma_f32_16x16x32_bf16 v[100:103], v[166:169], v[196:199], v[100:103]
	v_mfma_f32_16x16x32_bf16 v[96:99], v[170:173], v[192:195], 0
	v_mfma_f32_16x16x32_bf16 v[96:99], v[174:177], v[196:199], v[96:99]
	v_mfma_f32_16x16x32_bf16 v[84:87], v[162:165], v[200:203], 0
	v_mfma_f32_16x16x32_bf16 v[84:87], v[166:169], v[204:207], v[84:87]
	v_mfma_f32_16x16x32_bf16 v[80:83], v[170:173], v[200:203], 0
	v_mfma_f32_16x16x32_bf16 v[80:83], v[174:177], v[204:207], v[80:83]
	v_mfma_f32_16x16x32_bf16 v[68:71], v[162:165], v[208:211], 0
	v_mfma_f32_16x16x32_bf16 v[68:71], v[166:169], v[212:215], v[68:71]
	v_mfma_f32_16x16x32_bf16 v[64:67], v[170:173], v[208:211], 0
	v_mfma_f32_16x16x32_bf16 v[64:67], v[174:177], v[212:215], v[64:67]
	s_setprio 0
	s_barrier
	ds_read_b128 v[184:187], v149 offset:16384
	ds_read_b128 v[188:191], v149 offset:17408
	ds_read_b128 v[192:195], v149 offset:18432
	ds_read_b128 v[196:199], v149 offset:19456
	ds_read_b128 v[200:203], v149 offset:20480
	ds_read_b128 v[204:207], v149 offset:21504
	ds_read_b128 v[208:211], v149 offset:22528
	ds_read_b128 v[212:215], v149 offset:23552
	s_add_i32 s18, s62, s54
	v_lshl_add_u64 v[178:179], s[46:47], 0, v[130:131]
	s_mov_b32 m0, s18
	s_nop 0
	global_load_lds_dwordx4 v[178:179], off
	s_add_i32 m0, s18, 0x2000
	s_add_u32 s72, s46, 0x40000
	v_lshl_add_u64 v[216:217], s[46:47], 0, v[128:129]
	s_addc_u32 s73, s47, 0
	s_add_i32 s18, s63, s54
	global_load_lds_dwordx4 v[216:217], off
	v_lshl_add_u64 v[218:219], s[72:73], 0, v[130:131]
	s_mov_b32 m0, s18
	v_lshl_add_u64 v[220:221], s[48:49], 0, v[128:129]
	global_load_lds_dwordx4 v[218:219], off
	v_lshl_add_u64 v[218:219], s[72:73], 0, v[128:129]
	s_add_i32 m0, s18, 0x2000
	s_nop 0
	global_load_lds_dwordx4 v[218:219], off
	v_lshl_add_u64 v[218:219], s[48:49], 0, v[130:131]
	s_mov_b32 m0, s37
	s_nop 0
	global_load_lds_dwordx4 v[218:219], off
	s_mov_b32 m0, s56
	s_nop 0
	global_load_lds_dwordx4 v[220:221], off
	s_waitcnt vmcnt(8)
	s_waitcnt lgkmcnt(0)
	s_barrier
	s_setprio 1
	s_waitcnt lgkmcnt(0)
	v_mfma_f32_16x16x32_bf16 v[60:63], v[140:143], v[184:187], 0
	v_mfma_f32_16x16x32_bf16 v[60:63], v[150:153], v[188:191], v[60:63]
	v_mfma_f32_16x16x32_bf16 v[56:59], v[154:157], v[184:187], 0
	v_mfma_f32_16x16x32_bf16 v[56:59], v[158:161], v[188:191], v[56:59]
	v_mfma_f32_16x16x32_bf16 v[44:47], v[140:143], v[192:195], 0
	v_mfma_f32_16x16x32_bf16 v[44:47], v[150:153], v[196:199], v[44:47]
	v_mfma_f32_16x16x32_bf16 v[40:43], v[154:157], v[192:195], 0
	v_mfma_f32_16x16x32_bf16 v[40:43], v[158:161], v[196:199], v[40:43]
	v_mfma_f32_16x16x32_bf16 v[28:31], v[140:143], v[200:203], 0
	v_mfma_f32_16x16x32_bf16 v[28:31], v[150:153], v[204:207], v[28:31]
	v_mfma_f32_16x16x32_bf16 v[24:27], v[154:157], v[200:203], 0
	v_mfma_f32_16x16x32_bf16 v[24:27], v[158:161], v[204:207], v[24:27]
	v_mfma_f32_16x16x32_bf16 v[12:15], v[140:143], v[208:211], 0
	v_mfma_f32_16x16x32_bf16 v[12:15], v[150:153], v[212:215], v[12:15]
	v_mfma_f32_16x16x32_bf16 v[8:11], v[154:157], v[208:211], 0
	v_mfma_f32_16x16x32_bf16 v[8:11], v[158:161], v[212:215], v[8:11]
	v_mfma_f32_16x16x32_bf16 v[52:55], v[162:165], v[184:187], 0
	v_mfma_f32_16x16x32_bf16 v[52:55], v[166:169], v[188:191], v[52:55]
	v_mfma_f32_16x16x32_bf16 v[48:51], v[170:173], v[184:187], 0
	v_mfma_f32_16x16x32_bf16 v[48:51], v[174:177], v[188:191], v[48:51]
	v_mfma_f32_16x16x32_bf16 v[36:39], v[162:165], v[192:195], 0
	v_mfma_f32_16x16x32_bf16 v[36:39], v[166:169], v[196:199], v[36:39]
	v_mfma_f32_16x16x32_bf16 v[32:35], v[170:173], v[192:195], 0
	v_mfma_f32_16x16x32_bf16 v[32:35], v[174:177], v[196:199], v[32:35]
	v_mfma_f32_16x16x32_bf16 v[20:23], v[162:165], v[200:203], 0
	v_mfma_f32_16x16x32_bf16 v[20:23], v[166:169], v[204:207], v[20:23]
	v_mfma_f32_16x16x32_bf16 v[16:19], v[170:173], v[200:203], 0
	v_mfma_f32_16x16x32_bf16 v[16:19], v[174:177], v[204:207], v[16:19]
	v_mfma_f32_16x16x32_bf16 v[4:7], v[162:165], v[208:211], 0
	v_mfma_f32_16x16x32_bf16 v[4:7], v[166:169], v[212:215], v[4:7]
	v_mfma_f32_16x16x32_bf16 v[0:3], v[170:173], v[208:211], 0
	v_mfma_f32_16x16x32_bf16 v[0:3], v[174:177], v[212:215], v[0:3]
	s_setprio 0
	s_barrier
	s_branch .Lmid_gemm0
.LBB0_184:
	ds_read_b128 v[140:143], v147
	ds_read_b128 v[150:153], v147 offset:1024
	ds_read_b128 v[154:157], v147 offset:2048
	ds_read_b128 v[158:161], v147 offset:3072
	ds_read_b128 v[162:165], v148
	ds_read_b128 v[166:169], v148 offset:1024
	ds_read_b128 v[170:173], v148 offset:2048
	ds_read_b128 v[174:177], v148 offset:3072
	ds_read_b128 v[184:187], v149
	ds_read_b128 v[188:191], v149 offset:1024
	ds_read_b128 v[192:195], v149 offset:2048
	ds_read_b128 v[196:199], v149 offset:3072
	ds_read_b128 v[200:203], v149 offset:4096
	ds_read_b128 v[204:207], v149 offset:5120
	ds_read_b128 v[208:211], v149 offset:6144
	ds_read_b128 v[212:215], v149 offset:7168
	s_add_u32 s18, s44, 0xfffc0080
	s_addc_u32 s19, s45, -1
	s_cmp_eq_u32 s70, 12
	s_cselect_b32 s49, s13, s19
	s_cselect_b32 s48, s66, s18
	s_cselect_b32 s47, s11, s69
	s_cselect_b32 s46, s67, s68
	v_lshl_add_u64 v[178:179], s[44:45], 0, v[132:133]
	s_add_i32 m0, s37, 0xc000
	s_nop 0
	global_load_lds_dwordx4 v[178:179], off
	v_lshl_add_u64 v[178:179], s[44:45], 0, v[134:135]
	s_add_i32 m0, s37, 0xe000
	s_nop 0
	global_load_lds_dwordx4 v[178:179], off
	s_waitcnt vmcnt(8)
	s_waitcnt lgkmcnt(0)
	s_barrier
	s_setprio 1
	s_waitcnt lgkmcnt(0)
	v_mfma_f32_16x16x32_bf16 v[124:127], v[140:143], v[184:187], v[124:127]
	v_mfma_f32_16x16x32_bf16 v[124:127], v[150:153], v[188:191], v[124:127]
	v_mfma_f32_16x16x32_bf16 v[120:123], v[154:157], v[184:187], v[120:123]
	v_mfma_f32_16x16x32_bf16 v[120:123], v[158:161], v[188:191], v[120:123]
	v_mfma_f32_16x16x32_bf16 v[108:111], v[140:143], v[192:195], v[108:111]
	v_mfma_f32_16x16x32_bf16 v[108:111], v[150:153], v[196:199], v[108:111]
	v_mfma_f32_16x16x32_bf16 v[104:107], v[154:157], v[192:195], v[104:107]
	v_mfma_f32_16x16x32_bf16 v[104:107], v[158:161], v[196:199], v[104:107]
	v_mfma_f32_16x16x32_bf16 v[92:95], v[140:143], v[200:203], v[92:95]
	v_mfma_f32_16x16x32_bf16 v[92:95], v[150:153], v[204:207], v[92:95]
	v_mfma_f32_16x16x32_bf16 v[88:91], v[154:157], v[200:203], v[88:91]
	v_mfma_f32_16x16x32_bf16 v[88:91], v[158:161], v[204:207], v[88:91]
	v_mfma_f32_16x16x32_bf16 v[76:79], v[140:143], v[208:211], v[76:79]
	v_mfma_f32_16x16x32_bf16 v[76:79], v[150:153], v[212:215], v[76:79]
	v_mfma_f32_16x16x32_bf16 v[72:75], v[154:157], v[208:211], v[72:75]
	v_mfma_f32_16x16x32_bf16 v[72:75], v[158:161], v[212:215], v[72:75]
	v_mfma_f32_16x16x32_bf16 v[116:119], v[162:165], v[184:187], v[116:119]
	v_mfma_f32_16x16x32_bf16 v[116:119], v[166:169], v[188:191], v[116:119]
	v_mfma_f32_16x16x32_bf16 v[112:115], v[170:173], v[184:187], v[112:115]
	v_mfma_f32_16x16x32_bf16 v[112:115], v[174:177], v[188:191], v[112:115]
	v_mfma_f32_16x16x32_bf16 v[100:103], v[162:165], v[192:195], v[100:103]
	v_mfma_f32_16x16x32_bf16 v[100:103], v[166:169], v[196:199], v[100:103]
	v_mfma_f32_16x16x32_bf16 v[96:99], v[170:173], v[192:195], v[96:99]
	v_mfma_f32_16x16x32_bf16 v[96:99], v[174:177], v[196:199], v[96:99]
	v_mfma_f32_16x16x32_bf16 v[84:87], v[162:165], v[200:203], v[84:87]
	v_mfma_f32_16x16x32_bf16 v[84:87], v[166:169], v[204:207], v[84:87]
	v_mfma_f32_16x16x32_bf16 v[80:83], v[170:173], v[200:203], v[80:83]
	v_mfma_f32_16x16x32_bf16 v[80:83], v[174:177], v[204:207], v[80:83]
	v_mfma_f32_16x16x32_bf16 v[68:71], v[162:165], v[208:211], v[68:71]
	v_mfma_f32_16x16x32_bf16 v[68:71], v[166:169], v[212:215], v[68:71]
	v_mfma_f32_16x16x32_bf16 v[64:67], v[170:173], v[208:211], v[64:67]
	v_mfma_f32_16x16x32_bf16 v[64:67], v[174:177], v[212:215], v[64:67]
	s_setprio 0
	s_barrier
	ds_read_b128 v[184:187], v149 offset:16384
	ds_read_b128 v[188:191], v149 offset:17408
	ds_read_b128 v[192:195], v149 offset:18432
	ds_read_b128 v[196:199], v149 offset:19456
	ds_read_b128 v[200:203], v149 offset:20480
	ds_read_b128 v[204:207], v149 offset:21504
	ds_read_b128 v[208:211], v149 offset:22528
	ds_read_b128 v[212:215], v149 offset:23552
	s_add_i32 s18, s62, s54
	v_lshl_add_u64 v[178:179], s[46:47], 0, v[130:131]
	s_mov_b32 m0, s18
	s_nop 0
	global_load_lds_dwordx4 v[178:179], off
	s_add_i32 m0, s18, 0x2000
	s_add_u32 s72, s46, 0x40000
	v_lshl_add_u64 v[216:217], s[46:47], 0, v[128:129]
	s_addc_u32 s73, s47, 0
	s_add_i32 s18, s63, s54
	global_load_lds_dwordx4 v[216:217], off
	v_lshl_add_u64 v[218:219], s[72:73], 0, v[130:131]
	s_mov_b32 m0, s18
	v_lshl_add_u64 v[220:221], s[48:49], 0, v[128:129]
	global_load_lds_dwordx4 v[218:219], off
	v_lshl_add_u64 v[218:219], s[72:73], 0, v[128:129]
	s_add_i32 m0, s18, 0x2000
	s_nop 0
	global_load_lds_dwordx4 v[218:219], off
	v_lshl_add_u64 v[218:219], s[48:49], 0, v[130:131]
	s_mov_b32 m0, s37
	s_nop 0
	global_load_lds_dwordx4 v[218:219], off
	s_mov_b32 m0, s56
	s_nop 0
	global_load_lds_dwordx4 v[220:221], off
	s_waitcnt vmcnt(8)
	s_waitcnt lgkmcnt(0)
	s_barrier
	s_setprio 1
	s_waitcnt lgkmcnt(0)
	v_mfma_f32_16x16x32_bf16 v[60:63], v[140:143], v[184:187], v[60:63]
	v_mfma_f32_16x16x32_bf16 v[60:63], v[150:153], v[188:191], v[60:63]
	v_mfma_f32_16x16x32_bf16 v[56:59], v[154:157], v[184:187], v[56:59]
	v_mfma_f32_16x16x32_bf16 v[56:59], v[158:161], v[188:191], v[56:59]
	v_mfma_f32_16x16x32_bf16 v[44:47], v[140:143], v[192:195], v[44:47]
	v_mfma_f32_16x16x32_bf16 v[44:47], v[150:153], v[196:199], v[44:47]
	v_mfma_f32_16x16x32_bf16 v[40:43], v[154:157], v[192:195], v[40:43]
	v_mfma_f32_16x16x32_bf16 v[40:43], v[158:161], v[196:199], v[40:43]
	v_mfma_f32_16x16x32_bf16 v[28:31], v[140:143], v[200:203], v[28:31]
	v_mfma_f32_16x16x32_bf16 v[28:31], v[150:153], v[204:207], v[28:31]
	v_mfma_f32_16x16x32_bf16 v[24:27], v[154:157], v[200:203], v[24:27]
	v_mfma_f32_16x16x32_bf16 v[24:27], v[158:161], v[204:207], v[24:27]
	v_mfma_f32_16x16x32_bf16 v[12:15], v[140:143], v[208:211], v[12:15]
	v_mfma_f32_16x16x32_bf16 v[12:15], v[150:153], v[212:215], v[12:15]
	v_mfma_f32_16x16x32_bf16 v[8:11], v[154:157], v[208:211], v[8:11]
	v_mfma_f32_16x16x32_bf16 v[8:11], v[158:161], v[212:215], v[8:11]
	v_mfma_f32_16x16x32_bf16 v[52:55], v[162:165], v[184:187], v[52:55]
	v_mfma_f32_16x16x32_bf16 v[52:55], v[166:169], v[188:191], v[52:55]
	v_mfma_f32_16x16x32_bf16 v[48:51], v[170:173], v[184:187], v[48:51]
	v_mfma_f32_16x16x32_bf16 v[48:51], v[174:177], v[188:191], v[48:51]
	v_mfma_f32_16x16x32_bf16 v[36:39], v[162:165], v[192:195], v[36:39]
	v_mfma_f32_16x16x32_bf16 v[36:39], v[166:169], v[196:199], v[36:39]
	v_mfma_f32_16x16x32_bf16 v[32:35], v[170:173], v[192:195], v[32:35]
	v_mfma_f32_16x16x32_bf16 v[32:35], v[174:177], v[196:199], v[32:35]
	v_mfma_f32_16x16x32_bf16 v[20:23], v[162:165], v[200:203], v[20:23]
	v_mfma_f32_16x16x32_bf16 v[20:23], v[166:169], v[204:207], v[20:23]
	v_mfma_f32_16x16x32_bf16 v[16:19], v[170:173], v[200:203], v[16:19]
	v_mfma_f32_16x16x32_bf16 v[16:19], v[174:177], v[204:207], v[16:19]
	v_mfma_f32_16x16x32_bf16 v[4:7], v[162:165], v[208:211], v[4:7]
	v_mfma_f32_16x16x32_bf16 v[4:7], v[166:169], v[212:215], v[4:7]
	v_mfma_f32_16x16x32_bf16 v[0:3], v[170:173], v[208:211], v[0:3]
	v_mfma_f32_16x16x32_bf16 v[0:3], v[174:177], v[212:215], v[0:3]
	s_setprio 0
	s_barrier
.Lmid_gemm0:
	s_add_i32 s18, 0, 0x18000
	s_add_i32 s19, 0, 0x1c000
	v_add_u32_e32 v158, s18, v145
	v_add_u32_e32 v174, s19, v145
	ds_read_b128 v[140:143], v158
	ds_read_b128 v[150:153], v158 offset:1024
	ds_read_b128 v[154:157], v158 offset:2048
	ds_read_b128 v[158:161], v158 offset:3072
	ds_read_b128 v[162:165], v174
	ds_read_b128 v[166:169], v174 offset:1024
	ds_read_b128 v[170:173], v174 offset:2048
	ds_read_b128 v[174:177], v174 offset:3072
	ds_read_b128 v[184:187], v149 offset:32768
	ds_read_b128 v[188:191], v149 offset:33792
	ds_read_b128 v[192:195], v149 offset:34816
	ds_read_b128 v[196:199], v149 offset:35840
	ds_read_b128 v[200:203], v149 offset:36864
	ds_read_b128 v[204:207], v149 offset:37888
	ds_read_b128 v[208:211], v149 offset:38912
	ds_read_b128 v[212:215], v149 offset:39936
	s_add_u32 s48, s48, 0x40000
	s_addc_u32 s49, s49, 0
	s_mov_b32 m0, s57
	v_lshl_add_u64 v[222:223], s[48:49], 0, v[130:131]
	global_load_lds_dwordx4 v[222:223], off
	v_lshl_add_u64 v[222:223], s[48:49], 0, v[128:129]
	s_mov_b32 m0, s58
	s_nop 0
	global_load_lds_dwordx4 v[222:223], off
	s_waitcnt vmcnt(8)
	s_waitcnt lgkmcnt(0)
	s_barrier
	s_setprio 1
	s_waitcnt lgkmcnt(0)
	v_mfma_f32_16x16x32_bf16 v[124:127], v[140:143], v[184:187], v[124:127]
	v_mfma_f32_16x16x32_bf16 v[124:127], v[150:153], v[188:191], v[124:127]
	v_mfma_f32_16x16x32_bf16 v[120:123], v[154:157], v[184:187], v[120:123]
	v_mfma_f32_16x16x32_bf16 v[120:123], v[158:161], v[188:191], v[120:123]
	v_mfma_f32_16x16x32_bf16 v[108:111], v[140:143], v[192:195], v[108:111]
	v_mfma_f32_16x16x32_bf16 v[108:111], v[150:153], v[196:199], v[108:111]
	v_mfma_f32_16x16x32_bf16 v[104:107], v[154:157], v[192:195], v[104:107]
	v_mfma_f32_16x16x32_bf16 v[104:107], v[158:161], v[196:199], v[104:107]
	v_mfma_f32_16x16x32_bf16 v[92:95], v[140:143], v[200:203], v[92:95]
	v_mfma_f32_16x16x32_bf16 v[92:95], v[150:153], v[204:207], v[92:95]
	v_mfma_f32_16x16x32_bf16 v[88:91], v[154:157], v[200:203], v[88:91]
	v_mfma_f32_16x16x32_bf16 v[88:91], v[158:161], v[204:207], v[88:91]
	v_mfma_f32_16x16x32_bf16 v[76:79], v[140:143], v[208:211], v[76:79]
	v_mfma_f32_16x16x32_bf16 v[76:79], v[150:153], v[212:215], v[76:79]
	v_mfma_f32_16x16x32_bf16 v[72:75], v[154:157], v[208:211], v[72:75]
	v_mfma_f32_16x16x32_bf16 v[72:75], v[158:161], v[212:215], v[72:75]
	v_mfma_f32_16x16x32_bf16 v[116:119], v[162:165], v[184:187], v[116:119]
	v_mfma_f32_16x16x32_bf16 v[116:119], v[166:169], v[188:191], v[116:119]
	v_mfma_f32_16x16x32_bf16 v[112:115], v[170:173], v[184:187], v[112:115]
	v_mfma_f32_16x16x32_bf16 v[112:115], v[174:177], v[188:191], v[112:115]
	v_mfma_f32_16x16x32_bf16 v[100:103], v[162:165], v[192:195], v[100:103]
	v_mfma_f32_16x16x32_bf16 v[100:103], v[166:169], v[196:199], v[100:103]
	v_mfma_f32_16x16x32_bf16 v[96:99], v[170:173], v[192:195], v[96:99]
	v_mfma_f32_16x16x32_bf16 v[96:99], v[174:177], v[196:199], v[96:99]
	v_mfma_f32_16x16x32_bf16 v[84:87], v[162:165], v[200:203], v[84:87]
	v_mfma_f32_16x16x32_bf16 v[84:87], v[166:169], v[204:207], v[84:87]
	v_mfma_f32_16x16x32_bf16 v[80:83], v[170:173], v[200:203], v[80:83]
	v_mfma_f32_16x16x32_bf16 v[80:83], v[174:177], v[204:207], v[80:83]
	v_mfma_f32_16x16x32_bf16 v[68:71], v[162:165], v[208:211], v[68:71]
	v_mfma_f32_16x16x32_bf16 v[68:71], v[166:169], v[212:215], v[68:71]
	v_mfma_f32_16x16x32_bf16 v[64:67], v[170:173], v[208:211], v[64:67]
	v_mfma_f32_16x16x32_bf16 v[64:67], v[174:177], v[212:215], v[64:67]
	s_setprio 0
	s_barrier
	ds_read_b128 v[184:187], v149 offset:49152
	ds_read_b128 v[188:191], v149 offset:50176
	ds_read_b128 v[192:195], v149 offset:51200
	ds_read_b128 v[196:199], v149 offset:52224
	ds_read_b128 v[200:203], v149 offset:53248
	ds_read_b128 v[204:207], v149 offset:54272
	ds_read_b128 v[208:211], v149 offset:55296
	ds_read_b128 v[212:215], v149 offset:56320
	s_add_i32 s18, s18, s54
	v_lshl_add_u64 v[178:179], v[178:179], 0, s[6:7]
	s_mov_b32 m0, s18
	s_nop 0
	global_load_lds_dwordx4 v[178:179], off
	s_add_i32 m0, s18, 0x2000
	s_add_u32 s46, s46, 0x40080
	v_lshl_add_u64 v[178:179], v[216:217], 0, s[6:7]
	s_addc_u32 s47, s47, 0
	s_add_i32 s18, s19, s54
	global_load_lds_dwordx4 v[178:179], off
	v_lshl_add_u64 v[178:179], s[46:47], 0, v[130:131]
	s_mov_b32 m0, s18
	s_nop 0
	global_load_lds_dwordx4 v[178:179], off
	v_lshl_add_u64 v[178:179], s[46:47], 0, v[128:129]
	s_add_i32 m0, s18, 0x2000
	s_nop 0
	global_load_lds_dwordx4 v[178:179], off
	v_lshl_add_u64 v[178:179], v[218:219], 0, s[6:7]
	s_mov_b32 m0, s60
	s_nop 0
	global_load_lds_dwordx4 v[178:179], off
	v_lshl_add_u64 v[178:179], v[220:221], 0, s[6:7]
	s_mov_b32 m0, s61
	s_nop 0
	global_load_lds_dwordx4 v[178:179], off
	s_waitcnt vmcnt(8)
	s_waitcnt lgkmcnt(0)
	s_barrier
	s_setprio 1
	s_waitcnt lgkmcnt(0)
	v_mfma_f32_16x16x32_bf16 v[60:63], v[140:143], v[184:187], v[60:63]
	v_mfma_f32_16x16x32_bf16 v[60:63], v[150:153], v[188:191], v[60:63]
	v_mfma_f32_16x16x32_bf16 v[56:59], v[154:157], v[184:187], v[56:59]
	v_mfma_f32_16x16x32_bf16 v[56:59], v[158:161], v[188:191], v[56:59]
	v_mfma_f32_16x16x32_bf16 v[44:47], v[140:143], v[192:195], v[44:47]
	v_mfma_f32_16x16x32_bf16 v[44:47], v[150:153], v[196:199], v[44:47]
	v_mfma_f32_16x16x32_bf16 v[40:43], v[154:157], v[192:195], v[40:43]
	v_mfma_f32_16x16x32_bf16 v[40:43], v[158:161], v[196:199], v[40:43]
	v_mfma_f32_16x16x32_bf16 v[28:31], v[140:143], v[200:203], v[28:31]
	v_mfma_f32_16x16x32_bf16 v[28:31], v[150:153], v[204:207], v[28:31]
	v_mfma_f32_16x16x32_bf16 v[24:27], v[154:157], v[200:203], v[24:27]
	v_mfma_f32_16x16x32_bf16 v[24:27], v[158:161], v[204:207], v[24:27]
	v_mfma_f32_16x16x32_bf16 v[12:15], v[140:143], v[208:211], v[12:15]
	v_mfma_f32_16x16x32_bf16 v[12:15], v[150:153], v[212:215], v[12:15]
	v_mfma_f32_16x16x32_bf16 v[8:11], v[154:157], v[208:211], v[8:11]
	v_mfma_f32_16x16x32_bf16 v[8:11], v[158:161], v[212:215], v[8:11]
	v_mfma_f32_16x16x32_bf16 v[52:55], v[162:165], v[184:187], v[52:55]
	v_mfma_f32_16x16x32_bf16 v[52:55], v[166:169], v[188:191], v[52:55]
	v_mfma_f32_16x16x32_bf16 v[48:51], v[170:173], v[184:187], v[48:51]
	v_mfma_f32_16x16x32_bf16 v[48:51], v[174:177], v[188:191], v[48:51]
	v_mfma_f32_16x16x32_bf16 v[36:39], v[162:165], v[192:195], v[36:39]
	v_mfma_f32_16x16x32_bf16 v[36:39], v[166:169], v[196:199], v[36:39]
	v_mfma_f32_16x16x32_bf16 v[32:35], v[170:173], v[192:195], v[32:35]
	v_mfma_f32_16x16x32_bf16 v[32:35], v[174:177], v[196:199], v[32:35]
	v_mfma_f32_16x16x32_bf16 v[20:23], v[162:165], v[200:203], v[20:23]
	v_mfma_f32_16x16x32_bf16 v[20:23], v[166:169], v[204:207], v[20:23]
	v_mfma_f32_16x16x32_bf16 v[16:19], v[170:173], v[200:203], v[16:19]
	v_mfma_f32_16x16x32_bf16 v[16:19], v[174:177], v[204:207], v[16:19]
	v_mfma_f32_16x16x32_bf16 v[4:7], v[162:165], v[208:211], v[4:7]
	v_mfma_f32_16x16x32_bf16 v[4:7], v[166:169], v[212:215], v[4:7]
	v_mfma_f32_16x16x32_bf16 v[0:3], v[170:173], v[208:211], v[0:3]
	v_mfma_f32_16x16x32_bf16 v[0:3], v[174:177], v[212:215], v[0:3]
	s_setprio 0
	s_barrier
	s_add_i32 s70, s70, 2
	s_add_u32 s44, s44, 0x100
	s_addc_u32 s45, s45, 0
	s_add_u32 s68, s68, 0x100
	s_addc_u32 s69, s69, 0
	s_cmp_gt_u32 s70, 13
	s_cbranch_scc0 .LBB0_184
	s_and_b64 vcc, exec, s[8:9]
	s_cbranch_vccz .LBB0_187
	s_barrier

.LBB0_263:
	s_add_u32 s84, s54, 0x100
	s_addc_u32 s85, s55, 0
	s_mov_b32 s86, -2
	ds_read_b128 v[152:155], v149
	ds_read_b128 v[156:159], v149 offset:1024
	ds_read_b128 v[160:163], v149 offset:2048
	ds_read_b128 v[164:167], v149 offset:3072
	ds_read_b128 v[168:171], v150
	ds_read_b128 v[172:175], v150 offset:1024
	ds_read_b128 v[176:179], v150 offset:2048
	ds_read_b128 v[184:187], v150 offset:3072
	s_add_u32 s54, s52, 0x100
	s_addc_u32 s55, s53, 0
	s_cmp_eq_u32 s86, 40
	s_cselect_b32 s59, s7, s55
	s_cselect_b32 s58, s6, s54
	s_cselect_b32 s57, s49, s85
	s_cselect_b32 s56, s48, s84
	v_lshl_add_u64 v[144:145], s[52:53], 0, v[136:137]
	s_add_i32 m0, s63, 0xc000
	ds_read_b128 v[188:191], v151
	ds_read_b128 v[192:195], v151 offset:1024
	ds_read_b128 v[196:199], v151 offset:2048
	ds_read_b128 v[200:203], v151 offset:3072
	ds_read_b128 v[204:207], v151 offset:4096
	ds_read_b128 v[208:211], v151 offset:5120
	ds_read_b128 v[212:215], v151 offset:6144
	ds_read_b128 v[216:219], v151 offset:7168
	global_load_lds_dwordx4 v[144:145], off
	v_lshl_add_u64 v[144:145], s[52:53], 0, v[138:139]
	s_add_i32 m0, s63, 0xe000
	s_nop 0
	global_load_lds_dwordx4 v[144:145], off
	s_waitcnt vmcnt(8)
	s_waitcnt lgkmcnt(0)
	s_barrier
	s_setprio 1
	s_waitcnt lgkmcnt(0)
	v_mfma_f32_16x16x32_bf16 v[124:127], v[152:155], v[188:191], 0
	v_mfma_f32_16x16x32_bf16 v[124:127], v[156:159], v[192:195], v[124:127]
	v_mfma_f32_16x16x32_bf16 v[120:123], v[160:163], v[188:191], 0
	v_mfma_f32_16x16x32_bf16 v[120:123], v[164:167], v[192:195], v[120:123]
	v_mfma_f32_16x16x32_bf16 v[116:119], v[152:155], v[196:199], 0
	v_mfma_f32_16x16x32_bf16 v[116:119], v[156:159], v[200:203], v[116:119]
	v_mfma_f32_16x16x32_bf16 v[108:111], v[160:163], v[196:199], 0
	v_mfma_f32_16x16x32_bf16 v[108:111], v[164:167], v[200:203], v[108:111]
	v_mfma_f32_16x16x32_bf16 v[100:103], v[152:155], v[204:207], 0
	v_mfma_f32_16x16x32_bf16 v[100:103], v[156:159], v[208:211], v[100:103]
	v_mfma_f32_16x16x32_bf16 v[92:95], v[160:163], v[204:207], 0
	v_mfma_f32_16x16x32_bf16 v[92:95], v[164:167], v[208:211], v[92:95]
	v_mfma_f32_16x16x32_bf16 v[84:87], v[152:155], v[212:215], 0
	v_mfma_f32_16x16x32_bf16 v[84:87], v[156:159], v[216:219], v[84:87]
	v_mfma_f32_16x16x32_bf16 v[76:79], v[160:163], v[212:215], 0
	v_mfma_f32_16x16x32_bf16 v[76:79], v[164:167], v[216:219], v[76:79]
	v_mfma_f32_16x16x32_bf16 v[112:115], v[168:171], v[188:191], 0
	v_mfma_f32_16x16x32_bf16 v[112:115], v[172:175], v[192:195], v[112:115]
	v_mfma_f32_16x16x32_bf16 v[104:107], v[176:179], v[188:191], 0
	v_mfma_f32_16x16x32_bf16 v[104:107], v[184:187], v[192:195], v[104:107]
	v_mfma_f32_16x16x32_bf16 v[96:99], v[168:171], v[196:199], 0
	v_mfma_f32_16x16x32_bf16 v[96:99], v[172:175], v[200:203], v[96:99]
	v_mfma_f32_16x16x32_bf16 v[88:91], v[176:179], v[196:199], 0
	v_mfma_f32_16x16x32_bf16 v[88:91], v[184:187], v[200:203], v[88:91]
	v_mfma_f32_16x16x32_bf16 v[80:83], v[168:171], v[204:207], 0
	v_mfma_f32_16x16x32_bf16 v[80:83], v[172:175], v[208:211], v[80:83]
	v_mfma_f32_16x16x32_bf16 v[72:75], v[176:179], v[204:207], 0
	v_mfma_f32_16x16x32_bf16 v[72:75], v[184:187], v[208:211], v[72:75]
	v_mfma_f32_16x16x32_bf16 v[68:71], v[168:171], v[212:215], 0
	v_mfma_f32_16x16x32_bf16 v[68:71], v[172:175], v[216:219], v[68:71]
	v_mfma_f32_16x16x32_bf16 v[64:67], v[176:179], v[212:215], 0
	v_mfma_f32_16x16x32_bf16 v[64:67], v[184:187], v[216:219], v[64:67]
	s_setprio 0
	s_barrier
	ds_read_b128 v[188:191], v151 offset:16384
	ds_read_b128 v[192:195], v151 offset:17408
	ds_read_b128 v[196:199], v151 offset:18432
	ds_read_b128 v[200:203], v151 offset:19456
	ds_read_b128 v[204:207], v151 offset:20480
	ds_read_b128 v[208:211], v151 offset:21504
	ds_read_b128 v[212:215], v151 offset:22528
	ds_read_b128 v[216:219], v151 offset:23552
	s_add_i32 s18, s70, s62
	v_lshl_add_u64 v[144:145], s[56:57], 0, v[130:131]
	s_mov_b32 m0, s18
	s_nop 0
	global_load_lds_dwordx4 v[144:145], off
	s_add_i32 m0, s18, 0x2000
	s_add_u32 s52, s56, 0xb0000
	v_lshl_add_u64 v[220:221], s[56:57], 0, v[134:135]
	s_addc_u32 s53, s57, 0
	s_add_i32 s18, s71, s62
	global_load_lds_dwordx4 v[220:221], off
	v_lshl_add_u64 v[222:223], s[52:53], 0, v[130:131]
	s_mov_b32 m0, s18
	v_lshl_add_u64 v[224:225], s[58:59], 0, v[132:133]
	global_load_lds_dwordx4 v[222:223], off
	v_lshl_add_u64 v[222:223], s[52:53], 0, v[134:135]
	s_add_i32 m0, s18, 0x2000
	s_nop 0
	global_load_lds_dwordx4 v[222:223], off
	v_lshl_add_u64 v[222:223], s[58:59], 0, v[128:129]
	s_mov_b32 m0, s63
	s_nop 0
	global_load_lds_dwordx4 v[222:223], off
	s_mov_b32 m0, s64
	s_nop 0
	global_load_lds_dwordx4 v[224:225], off
	s_waitcnt vmcnt(8)
	s_waitcnt lgkmcnt(0)
	s_barrier
	s_setprio 1
	s_waitcnt lgkmcnt(0)
	v_mfma_f32_16x16x32_bf16 v[60:63], v[152:155], v[188:191], 0
	v_mfma_f32_16x16x32_bf16 v[60:63], v[156:159], v[192:195], v[60:63]
	v_mfma_f32_16x16x32_bf16 v[56:59], v[160:163], v[188:191], 0
	v_mfma_f32_16x16x32_bf16 v[56:59], v[164:167], v[192:195], v[56:59]
	v_mfma_f32_16x16x32_bf16 v[52:55], v[152:155], v[196:199], 0
	v_mfma_f32_16x16x32_bf16 v[52:55], v[156:159], v[200:203], v[52:55]
	v_mfma_f32_16x16x32_bf16 v[44:47], v[160:163], v[196:199], 0
	v_mfma_f32_16x16x32_bf16 v[44:47], v[164:167], v[200:203], v[44:47]
	v_mfma_f32_16x16x32_bf16 v[36:39], v[152:155], v[204:207], 0
	v_mfma_f32_16x16x32_bf16 v[36:39], v[156:159], v[208:211], v[36:39]
	v_mfma_f32_16x16x32_bf16 v[28:31], v[160:163], v[204:207], 0
	v_mfma_f32_16x16x32_bf16 v[28:31], v[164:167], v[208:211], v[28:31]
	v_mfma_f32_16x16x32_bf16 v[20:23], v[152:155], v[212:215], 0
	v_mfma_f32_16x16x32_bf16 v[20:23], v[156:159], v[216:219], v[20:23]
	v_mfma_f32_16x16x32_bf16 v[12:15], v[160:163], v[212:215], 0
	v_mfma_f32_16x16x32_bf16 v[12:15], v[164:167], v[216:219], v[12:15]
	v_mfma_f32_16x16x32_bf16 v[48:51], v[168:171], v[188:191], 0
	v_mfma_f32_16x16x32_bf16 v[48:51], v[172:175], v[192:195], v[48:51]
	v_mfma_f32_16x16x32_bf16 v[40:43], v[176:179], v[188:191], 0
	v_mfma_f32_16x16x32_bf16 v[40:43], v[184:187], v[192:195], v[40:43]
	v_mfma_f32_16x16x32_bf16 v[32:35], v[168:171], v[196:199], 0
	v_mfma_f32_16x16x32_bf16 v[32:35], v[172:175], v[200:203], v[32:35]
	v_mfma_f32_16x16x32_bf16 v[24:27], v[176:179], v[196:199], 0
	v_mfma_f32_16x16x32_bf16 v[24:27], v[184:187], v[200:203], v[24:27]
	v_mfma_f32_16x16x32_bf16 v[16:19], v[168:171], v[204:207], 0
	v_mfma_f32_16x16x32_bf16 v[16:19], v[172:175], v[208:211], v[16:19]
	v_mfma_f32_16x16x32_bf16 v[8:11], v[176:179], v[204:207], 0
	v_mfma_f32_16x16x32_bf16 v[8:11], v[184:187], v[208:211], v[8:11]
	v_mfma_f32_16x16x32_bf16 v[4:7], v[168:171], v[212:215], 0
	v_mfma_f32_16x16x32_bf16 v[4:7], v[172:175], v[216:219], v[4:7]
	v_mfma_f32_16x16x32_bf16 v[0:3], v[176:179], v[212:215], 0
	v_mfma_f32_16x16x32_bf16 v[0:3], v[184:187], v[216:219], v[0:3]
	s_setprio 0
	s_barrier
	s_branch .Lmid_gemm1
.LBB0_264:
	ds_read_b128 v[152:155], v149
	ds_read_b128 v[156:159], v149 offset:1024
	ds_read_b128 v[160:163], v149 offset:2048
	ds_read_b128 v[164:167], v149 offset:3072
	ds_read_b128 v[168:171], v150
	ds_read_b128 v[172:175], v150 offset:1024
	ds_read_b128 v[176:179], v150 offset:2048
	ds_read_b128 v[184:187], v150 offset:3072
	ds_read_b128 v[188:191], v151
	ds_read_b128 v[192:195], v151 offset:1024
	ds_read_b128 v[196:199], v151 offset:2048
	ds_read_b128 v[200:203], v151 offset:3072
	ds_read_b128 v[204:207], v151 offset:4096
	ds_read_b128 v[208:211], v151 offset:5120
	ds_read_b128 v[212:215], v151 offset:6144
	ds_read_b128 v[216:219], v151 offset:7168
	s_add_u32 s54, s52, 0x100
	s_addc_u32 s55, s53, 0
	s_cmp_eq_u32 s86, 40
	s_cselect_b32 s59, s7, s55
	s_cselect_b32 s58, s6, s54
	s_cselect_b32 s57, s49, s85
	s_cselect_b32 s56, s48, s84
	v_lshl_add_u64 v[144:145], s[52:53], 0, v[136:137]
	s_add_i32 m0, s63, 0xc000
	s_nop 0
	global_load_lds_dwordx4 v[144:145], off
	v_lshl_add_u64 v[144:145], s[52:53], 0, v[138:139]
	s_add_i32 m0, s63, 0xe000
	s_nop 0
	global_load_lds_dwordx4 v[144:145], off
	s_waitcnt vmcnt(8)
	s_waitcnt lgkmcnt(0)
	s_barrier
	s_setprio 1
	s_waitcnt lgkmcnt(0)
	v_mfma_f32_16x16x32_bf16 v[124:127], v[152:155], v[188:191], v[124:127]
	v_mfma_f32_16x16x32_bf16 v[124:127], v[156:159], v[192:195], v[124:127]
	v_mfma_f32_16x16x32_bf16 v[120:123], v[160:163], v[188:191], v[120:123]
	v_mfma_f32_16x16x32_bf16 v[120:123], v[164:167], v[192:195], v[120:123]
	v_mfma_f32_16x16x32_bf16 v[116:119], v[152:155], v[196:199], v[116:119]
	v_mfma_f32_16x16x32_bf16 v[116:119], v[156:159], v[200:203], v[116:119]
	v_mfma_f32_16x16x32_bf16 v[108:111], v[160:163], v[196:199], v[108:111]
	v_mfma_f32_16x16x32_bf16 v[108:111], v[164:167], v[200:203], v[108:111]
	v_mfma_f32_16x16x32_bf16 v[100:103], v[152:155], v[204:207], v[100:103]
	v_mfma_f32_16x16x32_bf16 v[100:103], v[156:159], v[208:211], v[100:103]
	v_mfma_f32_16x16x32_bf16 v[92:95], v[160:163], v[204:207], v[92:95]
	v_mfma_f32_16x16x32_bf16 v[92:95], v[164:167], v[208:211], v[92:95]
	v_mfma_f32_16x16x32_bf16 v[84:87], v[152:155], v[212:215], v[84:87]
	v_mfma_f32_16x16x32_bf16 v[84:87], v[156:159], v[216:219], v[84:87]
	v_mfma_f32_16x16x32_bf16 v[76:79], v[160:163], v[212:215], v[76:79]
	v_mfma_f32_16x16x32_bf16 v[76:79], v[164:167], v[216:219], v[76:79]
	v_mfma_f32_16x16x32_bf16 v[112:115], v[168:171], v[188:191], v[112:115]
	v_mfma_f32_16x16x32_bf16 v[112:115], v[172:175], v[192:195], v[112:115]
	v_mfma_f32_16x16x32_bf16 v[104:107], v[176:179], v[188:191], v[104:107]
	v_mfma_f32_16x16x32_bf16 v[104:107], v[184:187], v[192:195], v[104:107]
	v_mfma_f32_16x16x32_bf16 v[96:99], v[168:171], v[196:199], v[96:99]
	v_mfma_f32_16x16x32_bf16 v[96:99], v[172:175], v[200:203], v[96:99]
	v_mfma_f32_16x16x32_bf16 v[88:91], v[176:179], v[196:199], v[88:91]
	v_mfma_f32_16x16x32_bf16 v[88:91], v[184:187], v[200:203], v[88:91]
	v_mfma_f32_16x16x32_bf16 v[80:83], v[168:171], v[204:207], v[80:83]
	v_mfma_f32_16x16x32_bf16 v[80:83], v[172:175], v[208:211], v[80:83]
	v_mfma_f32_16x16x32_bf16 v[72:75], v[176:179], v[204:207], v[72:75]
	v_mfma_f32_16x16x32_bf16 v[72:75], v[184:187], v[208:211], v[72:75]
	v_mfma_f32_16x16x32_bf16 v[68:71], v[168:171], v[212:215], v[68:71]
	v_mfma_f32_16x16x32_bf16 v[68:71], v[172:175], v[216:219], v[68:71]
	v_mfma_f32_16x16x32_bf16 v[64:67], v[176:179], v[212:215], v[64:67]
	v_mfma_f32_16x16x32_bf16 v[64:67], v[184:187], v[216:219], v[64:67]
	s_setprio 0
	s_barrier
	ds_read_b128 v[188:191], v151 offset:16384
	ds_read_b128 v[192:195], v151 offset:17408
	ds_read_b128 v[196:199], v151 offset:18432
	ds_read_b128 v[200:203], v151 offset:19456
	ds_read_b128 v[204:207], v151 offset:20480
	ds_read_b128 v[208:211], v151 offset:21504
	ds_read_b128 v[212:215], v151 offset:22528
	ds_read_b128 v[216:219], v151 offset:23552
	s_add_i32 s18, s70, s62
	v_lshl_add_u64 v[144:145], s[56:57], 0, v[130:131]
	s_mov_b32 m0, s18
	s_nop 0
	global_load_lds_dwordx4 v[144:145], off
	s_add_i32 m0, s18, 0x2000
	s_add_u32 s52, s56, 0xb0000
	v_lshl_add_u64 v[220:221], s[56:57], 0, v[134:135]
	s_addc_u32 s53, s57, 0
	s_add_i32 s18, s71, s62
	global_load_lds_dwordx4 v[220:221], off
	v_lshl_add_u64 v[222:223], s[52:53], 0, v[130:131]
	s_mov_b32 m0, s18
	v_lshl_add_u64 v[224:225], s[58:59], 0, v[132:133]
	global_load_lds_dwordx4 v[222:223], off
	v_lshl_add_u64 v[222:223], s[52:53], 0, v[134:135]
	s_add_i32 m0, s18, 0x2000
	s_nop 0
	global_load_lds_dwordx4 v[222:223], off
	v_lshl_add_u64 v[222:223], s[58:59], 0, v[128:129]
	s_mov_b32 m0, s63
	s_nop 0
	global_load_lds_dwordx4 v[222:223], off
	s_mov_b32 m0, s64
	s_nop 0
	global_load_lds_dwordx4 v[224:225], off
	s_waitcnt vmcnt(8)
	s_waitcnt lgkmcnt(0)
	s_barrier
	s_setprio 1
	s_waitcnt lgkmcnt(0)
	v_mfma_f32_16x16x32_bf16 v[60:63], v[152:155], v[188:191], v[60:63]
	v_mfma_f32_16x16x32_bf16 v[60:63], v[156:159], v[192:195], v[60:63]
	v_mfma_f32_16x16x32_bf16 v[56:59], v[160:163], v[188:191], v[56:59]
	v_mfma_f32_16x16x32_bf16 v[56:59], v[164:167], v[192:195], v[56:59]
	v_mfma_f32_16x16x32_bf16 v[52:55], v[152:155], v[196:199], v[52:55]
	v_mfma_f32_16x16x32_bf16 v[52:55], v[156:159], v[200:203], v[52:55]
	v_mfma_f32_16x16x32_bf16 v[44:47], v[160:163], v[196:199], v[44:47]
	v_mfma_f32_16x16x32_bf16 v[44:47], v[164:167], v[200:203], v[44:47]
	v_mfma_f32_16x16x32_bf16 v[36:39], v[152:155], v[204:207], v[36:39]
	v_mfma_f32_16x16x32_bf16 v[36:39], v[156:159], v[208:211], v[36:39]
	v_mfma_f32_16x16x32_bf16 v[28:31], v[160:163], v[204:207], v[28:31]
	v_mfma_f32_16x16x32_bf16 v[28:31], v[164:167], v[208:211], v[28:31]
	v_mfma_f32_16x16x32_bf16 v[20:23], v[152:155], v[212:215], v[20:23]
	v_mfma_f32_16x16x32_bf16 v[20:23], v[156:159], v[216:219], v[20:23]
	v_mfma_f32_16x16x32_bf16 v[12:15], v[160:163], v[212:215], v[12:15]
	v_mfma_f32_16x16x32_bf16 v[12:15], v[164:167], v[216:219], v[12:15]
	v_mfma_f32_16x16x32_bf16 v[48:51], v[168:171], v[188:191], v[48:51]
	v_mfma_f32_16x16x32_bf16 v[48:51], v[172:175], v[192:195], v[48:51]
	v_mfma_f32_16x16x32_bf16 v[40:43], v[176:179], v[188:191], v[40:43]
	v_mfma_f32_16x16x32_bf16 v[40:43], v[184:187], v[192:195], v[40:43]
	v_mfma_f32_16x16x32_bf16 v[32:35], v[168:171], v[196:199], v[32:35]
	v_mfma_f32_16x16x32_bf16 v[32:35], v[172:175], v[200:203], v[32:35]
	v_mfma_f32_16x16x32_bf16 v[24:27], v[176:179], v[196:199], v[24:27]
	v_mfma_f32_16x16x32_bf16 v[24:27], v[184:187], v[200:203], v[24:27]
	v_mfma_f32_16x16x32_bf16 v[16:19], v[168:171], v[204:207], v[16:19]
	v_mfma_f32_16x16x32_bf16 v[16:19], v[172:175], v[208:211], v[16:19]
	v_mfma_f32_16x16x32_bf16 v[8:11], v[176:179], v[204:207], v[8:11]
	v_mfma_f32_16x16x32_bf16 v[8:11], v[184:187], v[208:211], v[8:11]
	v_mfma_f32_16x16x32_bf16 v[4:7], v[168:171], v[212:215], v[4:7]
	v_mfma_f32_16x16x32_bf16 v[4:7], v[172:175], v[216:219], v[4:7]
	v_mfma_f32_16x16x32_bf16 v[0:3], v[176:179], v[212:215], v[0:3]
	v_mfma_f32_16x16x32_bf16 v[0:3], v[184:187], v[216:219], v[0:3]
	s_setprio 0
	s_barrier
.Lmid_gemm1:
	s_add_i32 s18, 0, 0x18000
	s_add_i32 s19, 0, 0x1c000
	v_add_u32_e32 v164, s18, v147
	v_add_u32_e32 v181, s19, v147
	ds_read_b128 v[152:155], v164
	ds_read_b128 v[156:159], v164 offset:1024
	ds_read_b128 v[160:163], v164 offset:2048
	ds_read_b128 v[164:167], v164 offset:3072
	ds_read_b128 v[168:171], v181
	ds_read_b128 v[172:175], v181 offset:1024
	ds_read_b128 v[176:179], v181 offset:2048
	ds_read_b128 v[184:187], v181 offset:3072
	ds_read_b128 v[188:191], v151 offset:32768
	ds_read_b128 v[192:195], v151 offset:33792
	ds_read_b128 v[196:199], v151 offset:34816
	ds_read_b128 v[200:203], v151 offset:35840
	ds_read_b128 v[204:207], v151 offset:36864
	ds_read_b128 v[208:211], v151 offset:37888
	ds_read_b128 v[212:215], v151 offset:38912
	ds_read_b128 v[216:219], v151 offset:39936
	s_add_u32 s52, s58, 0xb0000
	s_addc_u32 s53, s59, 0
	s_mov_b32 m0, s65
	v_lshl_add_u64 v[226:227], s[52:53], 0, v[128:129]
	global_load_lds_dwordx4 v[226:227], off
	v_lshl_add_u64 v[226:227], s[52:53], 0, v[132:133]
	s_mov_b32 m0, s66
	s_nop 0
	global_load_lds_dwordx4 v[226:227], off
	s_waitcnt vmcnt(8)
	s_waitcnt lgkmcnt(0)
	s_barrier
	s_setprio 1
	s_waitcnt lgkmcnt(0)
	v_mfma_f32_16x16x32_bf16 v[124:127], v[152:155], v[188:191], v[124:127]
	v_mfma_f32_16x16x32_bf16 v[124:127], v[156:159], v[192:195], v[124:127]
	v_mfma_f32_16x16x32_bf16 v[120:123], v[160:163], v[188:191], v[120:123]
	v_mfma_f32_16x16x32_bf16 v[120:123], v[164:167], v[192:195], v[120:123]
	v_mfma_f32_16x16x32_bf16 v[116:119], v[152:155], v[196:199], v[116:119]
	v_mfma_f32_16x16x32_bf16 v[116:119], v[156:159], v[200:203], v[116:119]
	v_mfma_f32_16x16x32_bf16 v[108:111], v[160:163], v[196:199], v[108:111]
	v_mfma_f32_16x16x32_bf16 v[108:111], v[164:167], v[200:203], v[108:111]
	v_mfma_f32_16x16x32_bf16 v[100:103], v[152:155], v[204:207], v[100:103]
	v_mfma_f32_16x16x32_bf16 v[100:103], v[156:159], v[208:211], v[100:103]
	v_mfma_f32_16x16x32_bf16 v[92:95], v[160:163], v[204:207], v[92:95]
	v_mfma_f32_16x16x32_bf16 v[92:95], v[164:167], v[208:211], v[92:95]
	v_mfma_f32_16x16x32_bf16 v[84:87], v[152:155], v[212:215], v[84:87]
	v_mfma_f32_16x16x32_bf16 v[84:87], v[156:159], v[216:219], v[84:87]
	v_mfma_f32_16x16x32_bf16 v[76:79], v[160:163], v[212:215], v[76:79]
	v_mfma_f32_16x16x32_bf16 v[76:79], v[164:167], v[216:219], v[76:79]
	v_mfma_f32_16x16x32_bf16 v[112:115], v[168:171], v[188:191], v[112:115]
	v_mfma_f32_16x16x32_bf16 v[112:115], v[172:175], v[192:195], v[112:115]
	v_mfma_f32_16x16x32_bf16 v[104:107], v[176:179], v[188:191], v[104:107]
	v_mfma_f32_16x16x32_bf16 v[104:107], v[184:187], v[192:195], v[104:107]
	v_mfma_f32_16x16x32_bf16 v[96:99], v[168:171], v[196:199], v[96:99]
	v_mfma_f32_16x16x32_bf16 v[96:99], v[172:175], v[200:203], v[96:99]
	v_mfma_f32_16x16x32_bf16 v[88:91], v[176:179], v[196:199], v[88:91]
	v_mfma_f32_16x16x32_bf16 v[88:91], v[184:187], v[200:203], v[88:91]
	v_mfma_f32_16x16x32_bf16 v[80:83], v[168:171], v[204:207], v[80:83]
	v_mfma_f32_16x16x32_bf16 v[80:83], v[172:175], v[208:211], v[80:83]
	v_mfma_f32_16x16x32_bf16 v[72:75], v[176:179], v[204:207], v[72:75]
	v_mfma_f32_16x16x32_bf16 v[72:75], v[184:187], v[208:211], v[72:75]
	v_mfma_f32_16x16x32_bf16 v[68:71], v[168:171], v[212:215], v[68:71]
	v_mfma_f32_16x16x32_bf16 v[68:71], v[172:175], v[216:219], v[68:71]
	v_mfma_f32_16x16x32_bf16 v[64:67], v[176:179], v[212:215], v[64:67]
	v_mfma_f32_16x16x32_bf16 v[64:67], v[184:187], v[216:219], v[64:67]
	s_setprio 0
	s_barrier
	ds_read_b128 v[188:191], v151 offset:49152
	ds_read_b128 v[192:195], v151 offset:50176
	ds_read_b128 v[196:199], v151 offset:51200
	ds_read_b128 v[200:203], v151 offset:52224
	ds_read_b128 v[204:207], v151 offset:53248
	ds_read_b128 v[208:211], v151 offset:54272
	ds_read_b128 v[212:215], v151 offset:55296
	ds_read_b128 v[216:219], v151 offset:56320
	s_add_i32 s18, s18, s62
	v_lshl_add_u64 v[144:145], v[144:145], 0, s[8:9]
	s_mov_b32 m0, s18
	s_nop 0
	global_load_lds_dwordx4 v[144:145], off
	s_add_i32 m0, s18, 0x2000
	s_add_u32 s52, s56, 0xb0080
	v_lshl_add_u64 v[144:145], v[220:221], 0, s[8:9]
	s_addc_u32 s53, s57, 0
	s_add_i32 s18, s19, s62
	global_load_lds_dwordx4 v[144:145], off
	v_lshl_add_u64 v[144:145], s[52:53], 0, v[130:131]
	s_mov_b32 m0, s18
	s_nop 0
	global_load_lds_dwordx4 v[144:145], off
	v_lshl_add_u64 v[144:145], s[52:53], 0, v[134:135]
	s_add_i32 m0, s18, 0x2000
	s_nop 0
	global_load_lds_dwordx4 v[144:145], off
	v_lshl_add_u64 v[144:145], v[222:223], 0, s[8:9]
	s_mov_b32 m0, s68
	s_nop 0
	global_load_lds_dwordx4 v[144:145], off
	v_lshl_add_u64 v[144:145], v[224:225], 0, s[8:9]
	s_mov_b32 m0, s69
	s_nop 0
	global_load_lds_dwordx4 v[144:145], off
	s_waitcnt vmcnt(8)
	s_waitcnt lgkmcnt(0)
	s_barrier
	s_setprio 1
	s_waitcnt lgkmcnt(0)
	v_mfma_f32_16x16x32_bf16 v[60:63], v[152:155], v[188:191], v[60:63]
	v_mfma_f32_16x16x32_bf16 v[60:63], v[156:159], v[192:195], v[60:63]
	v_mfma_f32_16x16x32_bf16 v[56:59], v[160:163], v[188:191], v[56:59]
	v_mfma_f32_16x16x32_bf16 v[56:59], v[164:167], v[192:195], v[56:59]
	v_mfma_f32_16x16x32_bf16 v[52:55], v[152:155], v[196:199], v[52:55]
	v_mfma_f32_16x16x32_bf16 v[52:55], v[156:159], v[200:203], v[52:55]
	v_mfma_f32_16x16x32_bf16 v[44:47], v[160:163], v[196:199], v[44:47]
	v_mfma_f32_16x16x32_bf16 v[44:47], v[164:167], v[200:203], v[44:47]
	v_mfma_f32_16x16x32_bf16 v[36:39], v[152:155], v[204:207], v[36:39]
	v_mfma_f32_16x16x32_bf16 v[36:39], v[156:159], v[208:211], v[36:39]
	v_mfma_f32_16x16x32_bf16 v[28:31], v[160:163], v[204:207], v[28:31]
	v_mfma_f32_16x16x32_bf16 v[28:31], v[164:167], v[208:211], v[28:31]
	v_mfma_f32_16x16x32_bf16 v[20:23], v[152:155], v[212:215], v[20:23]
	v_mfma_f32_16x16x32_bf16 v[20:23], v[156:159], v[216:219], v[20:23]
	v_mfma_f32_16x16x32_bf16 v[12:15], v[160:163], v[212:215], v[12:15]
	v_mfma_f32_16x16x32_bf16 v[12:15], v[164:167], v[216:219], v[12:15]
	v_mfma_f32_16x16x32_bf16 v[48:51], v[168:171], v[188:191], v[48:51]
	v_mfma_f32_16x16x32_bf16 v[48:51], v[172:175], v[192:195], v[48:51]
	v_mfma_f32_16x16x32_bf16 v[40:43], v[176:179], v[188:191], v[40:43]
	v_mfma_f32_16x16x32_bf16 v[40:43], v[184:187], v[192:195], v[40:43]
	v_mfma_f32_16x16x32_bf16 v[32:35], v[168:171], v[196:199], v[32:35]
	v_mfma_f32_16x16x32_bf16 v[32:35], v[172:175], v[200:203], v[32:35]
	v_mfma_f32_16x16x32_bf16 v[24:27], v[176:179], v[196:199], v[24:27]
	v_mfma_f32_16x16x32_bf16 v[24:27], v[184:187], v[200:203], v[24:27]
	v_mfma_f32_16x16x32_bf16 v[16:19], v[168:171], v[204:207], v[16:19]
	v_mfma_f32_16x16x32_bf16 v[16:19], v[172:175], v[208:211], v[16:19]
	v_mfma_f32_16x16x32_bf16 v[8:11], v[176:179], v[204:207], v[8:11]
	v_mfma_f32_16x16x32_bf16 v[8:11], v[184:187], v[208:211], v[8:11]
	v_mfma_f32_16x16x32_bf16 v[4:7], v[168:171], v[212:215], v[4:7]
	v_mfma_f32_16x16x32_bf16 v[4:7], v[172:175], v[216:219], v[4:7]
	v_mfma_f32_16x16x32_bf16 v[0:3], v[176:179], v[212:215], v[0:3]
	v_mfma_f32_16x16x32_bf16 v[0:3], v[184:187], v[216:219], v[0:3]
	s_setprio 0
	s_barrier
	s_add_i32 s86, s86, 2
	s_add_u32 s84, s84, 0x100
	s_addc_u32 s85, s85, 0
	s_cmp_gt_u32 s86, 41
	s_mov_b64 s[52:53], s[54:55]
	s_cbranch_scc0 .LBB0_264
	s_and_b64 vcc, exec, s[10:11]
	s_cbranch_vccz .LBB0_267
	s_barrier

.LBB0_386:
	s_ashr_i32 s49, s48, 31
	s_lshl_b64 s[52:53], s[48:49], 19
	s_add_u32 s52, s80, s52
	s_addc_u32 s53, s81, s53
	s_and_b64 s[54:55], s[4:5], exec
	s_cselect_b32 s49, s53, s59
	s_cselect_b32 s82, s52, s58
	s_ashr_i32 s47, s46, 31
	s_lshl_b64 s[54:55], s[46:47], 19
	s_add_u32 s54, s64, s54
	s_addc_u32 s55, s65, s55
	s_and_b64 s[62:63], s[4:5], exec
	s_cselect_b32 s47, s55, s61
	s_cselect_b32 s83, s54, s60
	s_add_u32 s58, s58, 0x40080
	s_addc_u32 s59, s59, 0
	s_add_u32 s84, s60, 0x100
	s_addc_u32 s85, s61, 0
	s_mov_b32 s86, -2
	ds_read_b128 v[152:155], v148
	ds_read_b128 v[156:159], v148 offset:1024
	ds_read_b128 v[160:163], v148 offset:2048
	ds_read_b128 v[164:167], v148 offset:3072
	ds_read_b128 v[168:171], v149
	ds_read_b128 v[172:175], v149 offset:1024
	ds_read_b128 v[176:179], v149 offset:2048
	ds_read_b128 v[184:187], v149 offset:3072
	s_add_u32 s18, s58, 0xfffc0080
	s_addc_u32 s19, s59, -1
	s_cmp_eq_u32 s86, 12
	s_cselect_b32 s63, s49, s19
	s_cselect_b32 s62, s82, s18
	s_cselect_b32 s61, s47, s85
	s_cselect_b32 s60, s83, s84
	v_lshl_add_u64 v[220:221], s[58:59], 0, v[138:139]
	s_add_i32 m0, s68, 0xc000
	ds_read_b128 v[188:191], v150
	ds_read_b128 v[192:195], v150 offset:1024
	ds_read_b128 v[196:199], v150 offset:2048
	ds_read_b128 v[200:203], v150 offset:3072
	ds_read_b128 v[204:207], v150 offset:4096
	ds_read_b128 v[208:211], v150 offset:5120
	ds_read_b128 v[212:215], v150 offset:6144
	ds_read_b128 v[216:219], v150 offset:7168
	global_load_lds_dwordx4 v[220:221], off
	v_lshl_add_u64 v[220:221], s[58:59], 0, v[140:141]
	s_add_i32 m0, s68, 0xe000
	s_nop 0
	global_load_lds_dwordx4 v[220:221], off
	s_waitcnt vmcnt(8)
	s_waitcnt lgkmcnt(0)
	s_barrier
	s_setprio 1
	s_waitcnt lgkmcnt(0)
	v_mfma_f32_16x16x32_bf16 v[124:127], v[152:155], v[188:191], 0
	v_mfma_f32_16x16x32_bf16 v[124:127], v[156:159], v[192:195], v[124:127]
	v_mfma_f32_16x16x32_bf16 v[120:123], v[160:163], v[188:191], 0
	v_mfma_f32_16x16x32_bf16 v[120:123], v[164:167], v[192:195], v[120:123]
	v_mfma_f32_16x16x32_bf16 v[116:119], v[152:155], v[196:199], 0
	v_mfma_f32_16x16x32_bf16 v[116:119], v[156:159], v[200:203], v[116:119]
	v_mfma_f32_16x16x32_bf16 v[112:115], v[160:163], v[196:199], 0
	v_mfma_f32_16x16x32_bf16 v[112:115], v[164:167], v[200:203], v[112:115]
	v_mfma_f32_16x16x32_bf16 v[108:111], v[152:155], v[204:207], 0
	v_mfma_f32_16x16x32_bf16 v[108:111], v[156:159], v[208:211], v[108:111]
	v_mfma_f32_16x16x32_bf16 v[104:107], v[160:163], v[204:207], 0
	v_mfma_f32_16x16x32_bf16 v[104:107], v[164:167], v[208:211], v[104:107]
	v_mfma_f32_16x16x32_bf16 v[100:103], v[152:155], v[212:215], 0
	v_mfma_f32_16x16x32_bf16 v[100:103], v[156:159], v[216:219], v[100:103]
	v_mfma_f32_16x16x32_bf16 v[96:99], v[160:163], v[212:215], 0
	v_mfma_f32_16x16x32_bf16 v[96:99], v[164:167], v[216:219], v[96:99]
	v_mfma_f32_16x16x32_bf16 v[68:71], v[168:171], v[188:191], 0
	v_mfma_f32_16x16x32_bf16 v[68:71], v[172:175], v[192:195], v[68:71]
	v_mfma_f32_16x16x32_bf16 v[64:67], v[176:179], v[188:191], 0
	v_mfma_f32_16x16x32_bf16 v[64:67], v[184:187], v[192:195], v[64:67]
	v_mfma_f32_16x16x32_bf16 v[52:55], v[168:171], v[196:199], 0
	v_mfma_f32_16x16x32_bf16 v[52:55], v[172:175], v[200:203], v[52:55]
	v_mfma_f32_16x16x32_bf16 v[48:51], v[176:179], v[196:199], 0
	v_mfma_f32_16x16x32_bf16 v[48:51], v[184:187], v[200:203], v[48:51]
	v_mfma_f32_16x16x32_bf16 v[44:47], v[168:171], v[204:207], 0
	v_mfma_f32_16x16x32_bf16 v[44:47], v[172:175], v[208:211], v[44:47]
	v_mfma_f32_16x16x32_bf16 v[40:43], v[176:179], v[204:207], 0
	v_mfma_f32_16x16x32_bf16 v[40:43], v[184:187], v[208:211], v[40:43]
	v_mfma_f32_16x16x32_bf16 v[36:39], v[168:171], v[212:215], 0
	v_mfma_f32_16x16x32_bf16 v[36:39], v[172:175], v[216:219], v[36:39]
	v_mfma_f32_16x16x32_bf16 v[32:35], v[176:179], v[212:215], 0
	v_mfma_f32_16x16x32_bf16 v[32:35], v[184:187], v[216:219], v[32:35]
	s_setprio 0
	s_barrier
	ds_read_b128 v[188:191], v150 offset:16384
	ds_read_b128 v[192:195], v150 offset:17408
	ds_read_b128 v[196:199], v150 offset:18432
	ds_read_b128 v[200:203], v150 offset:19456
	ds_read_b128 v[204:207], v150 offset:20480
	ds_read_b128 v[208:211], v150 offset:21504
	ds_read_b128 v[212:215], v150 offset:22528
	ds_read_b128 v[216:219], v150 offset:23552
	s_add_i32 s18, s76, s66
	v_lshl_add_u64 v[220:221], s[60:61], 0, v[132:133]
	s_mov_b32 m0, s18
	s_nop 0
	global_load_lds_dwordx4 v[220:221], off
	s_add_i32 m0, s18, 0x2000
	s_add_u32 s88, s60, 0x40000
	v_lshl_add_u64 v[222:223], s[60:61], 0, v[128:129]
	s_addc_u32 s89, s61, 0
	s_add_i32 s18, s77, s66
	global_load_lds_dwordx4 v[222:223], off
	v_lshl_add_u64 v[224:225], s[88:89], 0, v[132:133]
	s_mov_b32 m0, s18
	v_lshl_add_u64 v[226:227], s[62:63], 0, v[130:131]
	global_load_lds_dwordx4 v[224:225], off
	v_lshl_add_u64 v[224:225], s[88:89], 0, v[128:129]
	s_add_i32 m0, s18, 0x2000
	s_nop 0
	global_load_lds_dwordx4 v[224:225], off
	v_lshl_add_u64 v[224:225], s[62:63], 0, v[134:135]
	s_mov_b32 m0, s68
	s_nop 0
	global_load_lds_dwordx4 v[224:225], off
	s_mov_b32 m0, s69
	s_nop 0
	global_load_lds_dwordx4 v[226:227], off
	s_waitcnt vmcnt(8)
	s_waitcnt lgkmcnt(0)
	s_barrier
	s_setprio 1
	s_waitcnt lgkmcnt(0)
	v_mfma_f32_16x16x32_bf16 v[92:95], v[152:155], v[188:191], 0
	v_mfma_f32_16x16x32_bf16 v[92:95], v[156:159], v[192:195], v[92:95]
	v_mfma_f32_16x16x32_bf16 v[88:91], v[160:163], v[188:191], 0
	v_mfma_f32_16x16x32_bf16 v[88:91], v[164:167], v[192:195], v[88:91]
	v_mfma_f32_16x16x32_bf16 v[84:87], v[152:155], v[196:199], 0
	v_mfma_f32_16x16x32_bf16 v[84:87], v[156:159], v[200:203], v[84:87]
	v_mfma_f32_16x16x32_bf16 v[80:83], v[160:163], v[196:199], 0
	v_mfma_f32_16x16x32_bf16 v[80:83], v[164:167], v[200:203], v[80:83]
	v_mfma_f32_16x16x32_bf16 v[76:79], v[152:155], v[204:207], 0
	v_mfma_f32_16x16x32_bf16 v[76:79], v[156:159], v[208:211], v[76:79]
	v_mfma_f32_16x16x32_bf16 v[72:75], v[160:163], v[204:207], 0
	v_mfma_f32_16x16x32_bf16 v[72:75], v[164:167], v[208:211], v[72:75]
	v_mfma_f32_16x16x32_bf16 v[60:63], v[152:155], v[212:215], 0
	v_mfma_f32_16x16x32_bf16 v[60:63], v[156:159], v[216:219], v[60:63]
	v_mfma_f32_16x16x32_bf16 v[56:59], v[160:163], v[212:215], 0
	v_mfma_f32_16x16x32_bf16 v[56:59], v[164:167], v[216:219], v[56:59]
	v_mfma_f32_16x16x32_bf16 v[28:31], v[168:171], v[188:191], 0
	v_mfma_f32_16x16x32_bf16 v[28:31], v[172:175], v[192:195], v[28:31]
	v_mfma_f32_16x16x32_bf16 v[24:27], v[176:179], v[188:191], 0
	v_mfma_f32_16x16x32_bf16 v[24:27], v[184:187], v[192:195], v[24:27]
	v_mfma_f32_16x16x32_bf16 v[20:23], v[168:171], v[196:199], 0
	v_mfma_f32_16x16x32_bf16 v[20:23], v[172:175], v[200:203], v[20:23]
	v_mfma_f32_16x16x32_bf16 v[16:19], v[176:179], v[196:199], 0
	v_mfma_f32_16x16x32_bf16 v[16:19], v[184:187], v[200:203], v[16:19]
	v_mfma_f32_16x16x32_bf16 v[12:15], v[168:171], v[204:207], 0
	v_mfma_f32_16x16x32_bf16 v[12:15], v[172:175], v[208:211], v[12:15]
	v_mfma_f32_16x16x32_bf16 v[8:11], v[176:179], v[204:207], 0
	v_mfma_f32_16x16x32_bf16 v[8:11], v[184:187], v[208:211], v[8:11]
	v_mfma_f32_16x16x32_bf16 v[4:7], v[168:171], v[212:215], 0
	v_mfma_f32_16x16x32_bf16 v[4:7], v[172:175], v[216:219], v[4:7]
	v_mfma_f32_16x16x32_bf16 v[0:3], v[176:179], v[212:215], 0
	v_mfma_f32_16x16x32_bf16 v[0:3], v[184:187], v[216:219], v[0:3]
	s_setprio 0
	s_barrier
	s_branch .Lmid_gemm2
.LBB0_387:
	ds_read_b128 v[152:155], v148
	ds_read_b128 v[156:159], v148 offset:1024
	ds_read_b128 v[160:163], v148 offset:2048
	ds_read_b128 v[164:167], v148 offset:3072
	ds_read_b128 v[168:171], v149
	ds_read_b128 v[172:175], v149 offset:1024
	ds_read_b128 v[176:179], v149 offset:2048
	ds_read_b128 v[184:187], v149 offset:3072
	ds_read_b128 v[188:191], v150
	ds_read_b128 v[192:195], v150 offset:1024
	ds_read_b128 v[196:199], v150 offset:2048
	ds_read_b128 v[200:203], v150 offset:3072
	ds_read_b128 v[204:207], v150 offset:4096
	ds_read_b128 v[208:211], v150 offset:5120
	ds_read_b128 v[212:215], v150 offset:6144
	ds_read_b128 v[216:219], v150 offset:7168
	s_add_u32 s18, s58, 0xfffc0080
	s_addc_u32 s19, s59, -1
	s_cmp_eq_u32 s86, 12
	s_cselect_b32 s63, s49, s19
	s_cselect_b32 s62, s82, s18
	s_cselect_b32 s61, s47, s85
	s_cselect_b32 s60, s83, s84
	v_lshl_add_u64 v[220:221], s[58:59], 0, v[138:139]
	s_add_i32 m0, s68, 0xc000
	s_nop 0
	global_load_lds_dwordx4 v[220:221], off
	v_lshl_add_u64 v[220:221], s[58:59], 0, v[140:141]
	s_add_i32 m0, s68, 0xe000
	s_nop 0
	global_load_lds_dwordx4 v[220:221], off
	s_waitcnt vmcnt(8)
	s_waitcnt lgkmcnt(0)
	s_barrier
	s_setprio 1
	s_waitcnt lgkmcnt(0)
	v_mfma_f32_16x16x32_bf16 v[124:127], v[152:155], v[188:191], v[124:127]
	v_mfma_f32_16x16x32_bf16 v[124:127], v[156:159], v[192:195], v[124:127]
	v_mfma_f32_16x16x32_bf16 v[120:123], v[160:163], v[188:191], v[120:123]
	v_mfma_f32_16x16x32_bf16 v[120:123], v[164:167], v[192:195], v[120:123]
	v_mfma_f32_16x16x32_bf16 v[116:119], v[152:155], v[196:199], v[116:119]
	v_mfma_f32_16x16x32_bf16 v[116:119], v[156:159], v[200:203], v[116:119]
	v_mfma_f32_16x16x32_bf16 v[112:115], v[160:163], v[196:199], v[112:115]
	v_mfma_f32_16x16x32_bf16 v[112:115], v[164:167], v[200:203], v[112:115]
	v_mfma_f32_16x16x32_bf16 v[108:111], v[152:155], v[204:207], v[108:111]
	v_mfma_f32_16x16x32_bf16 v[108:111], v[156:159], v[208:211], v[108:111]
	v_mfma_f32_16x16x32_bf16 v[104:107], v[160:163], v[204:207], v[104:107]
	v_mfma_f32_16x16x32_bf16 v[104:107], v[164:167], v[208:211], v[104:107]
	v_mfma_f32_16x16x32_bf16 v[100:103], v[152:155], v[212:215], v[100:103]
	v_mfma_f32_16x16x32_bf16 v[100:103], v[156:159], v[216:219], v[100:103]
	v_mfma_f32_16x16x32_bf16 v[96:99], v[160:163], v[212:215], v[96:99]
	v_mfma_f32_16x16x32_bf16 v[96:99], v[164:167], v[216:219], v[96:99]
	v_mfma_f32_16x16x32_bf16 v[68:71], v[168:171], v[188:191], v[68:71]
	v_mfma_f32_16x16x32_bf16 v[68:71], v[172:175], v[192:195], v[68:71]
	v_mfma_f32_16x16x32_bf16 v[64:67], v[176:179], v[188:191], v[64:67]
	v_mfma_f32_16x16x32_bf16 v[64:67], v[184:187], v[192:195], v[64:67]
	v_mfma_f32_16x16x32_bf16 v[52:55], v[168:171], v[196:199], v[52:55]
	v_mfma_f32_16x16x32_bf16 v[52:55], v[172:175], v[200:203], v[52:55]
	v_mfma_f32_16x16x32_bf16 v[48:51], v[176:179], v[196:199], v[48:51]
	v_mfma_f32_16x16x32_bf16 v[48:51], v[184:187], v[200:203], v[48:51]
	v_mfma_f32_16x16x32_bf16 v[44:47], v[168:171], v[204:207], v[44:47]
	v_mfma_f32_16x16x32_bf16 v[44:47], v[172:175], v[208:211], v[44:47]
	v_mfma_f32_16x16x32_bf16 v[40:43], v[176:179], v[204:207], v[40:43]
	v_mfma_f32_16x16x32_bf16 v[40:43], v[184:187], v[208:211], v[40:43]
	v_mfma_f32_16x16x32_bf16 v[36:39], v[168:171], v[212:215], v[36:39]
	v_mfma_f32_16x16x32_bf16 v[36:39], v[172:175], v[216:219], v[36:39]
	v_mfma_f32_16x16x32_bf16 v[32:35], v[176:179], v[212:215], v[32:35]
	v_mfma_f32_16x16x32_bf16 v[32:35], v[184:187], v[216:219], v[32:35]
	s_setprio 0
	s_barrier
	ds_read_b128 v[188:191], v150 offset:16384
	ds_read_b128 v[192:195], v150 offset:17408
	ds_read_b128 v[196:199], v150 offset:18432
	ds_read_b128 v[200:203], v150 offset:19456
	ds_read_b128 v[204:207], v150 offset:20480
	ds_read_b128 v[208:211], v150 offset:21504
	ds_read_b128 v[212:215], v150 offset:22528
	ds_read_b128 v[216:219], v150 offset:23552
	s_add_i32 s18, s76, s66
	v_lshl_add_u64 v[220:221], s[60:61], 0, v[132:133]
	s_mov_b32 m0, s18
	s_nop 0
	global_load_lds_dwordx4 v[220:221], off
	s_add_i32 m0, s18, 0x2000
	s_add_u32 s88, s60, 0x40000
	v_lshl_add_u64 v[222:223], s[60:61], 0, v[128:129]
	s_addc_u32 s89, s61, 0
	s_add_i32 s18, s77, s66
	global_load_lds_dwordx4 v[222:223], off
	v_lshl_add_u64 v[224:225], s[88:89], 0, v[132:133]
	s_mov_b32 m0, s18
	v_lshl_add_u64 v[226:227], s[62:63], 0, v[130:131]
	global_load_lds_dwordx4 v[224:225], off
	v_lshl_add_u64 v[224:225], s[88:89], 0, v[128:129]
	s_add_i32 m0, s18, 0x2000
	s_nop 0
	global_load_lds_dwordx4 v[224:225], off
	v_lshl_add_u64 v[224:225], s[62:63], 0, v[134:135]
	s_mov_b32 m0, s68
	s_nop 0
	global_load_lds_dwordx4 v[224:225], off
	s_mov_b32 m0, s69
	s_nop 0
	global_load_lds_dwordx4 v[226:227], off
	s_waitcnt vmcnt(8)
	s_waitcnt lgkmcnt(0)
	s_barrier
	s_setprio 1
	s_waitcnt lgkmcnt(0)
	v_mfma_f32_16x16x32_bf16 v[92:95], v[152:155], v[188:191], v[92:95]
	v_mfma_f32_16x16x32_bf16 v[92:95], v[156:159], v[192:195], v[92:95]
	v_mfma_f32_16x16x32_bf16 v[88:91], v[160:163], v[188:191], v[88:91]
	v_mfma_f32_16x16x32_bf16 v[88:91], v[164:167], v[192:195], v[88:91]
	v_mfma_f32_16x16x32_bf16 v[84:87], v[152:155], v[196:199], v[84:87]
	v_mfma_f32_16x16x32_bf16 v[84:87], v[156:159], v[200:203], v[84:87]
	v_mfma_f32_16x16x32_bf16 v[80:83], v[160:163], v[196:199], v[80:83]
	v_mfma_f32_16x16x32_bf16 v[80:83], v[164:167], v[200:203], v[80:83]
	v_mfma_f32_16x16x32_bf16 v[76:79], v[152:155], v[204:207], v[76:79]
	v_mfma_f32_16x16x32_bf16 v[76:79], v[156:159], v[208:211], v[76:79]
	v_mfma_f32_16x16x32_bf16 v[72:75], v[160:163], v[204:207], v[72:75]
	v_mfma_f32_16x16x32_bf16 v[72:75], v[164:167], v[208:211], v[72:75]
	v_mfma_f32_16x16x32_bf16 v[60:63], v[152:155], v[212:215], v[60:63]
	v_mfma_f32_16x16x32_bf16 v[60:63], v[156:159], v[216:219], v[60:63]
	v_mfma_f32_16x16x32_bf16 v[56:59], v[160:163], v[212:215], v[56:59]
	v_mfma_f32_16x16x32_bf16 v[56:59], v[164:167], v[216:219], v[56:59]
	v_mfma_f32_16x16x32_bf16 v[28:31], v[168:171], v[188:191], v[28:31]
	v_mfma_f32_16x16x32_bf16 v[28:31], v[172:175], v[192:195], v[28:31]
	v_mfma_f32_16x16x32_bf16 v[24:27], v[176:179], v[188:191], v[24:27]
	v_mfma_f32_16x16x32_bf16 v[24:27], v[184:187], v[192:195], v[24:27]
	v_mfma_f32_16x16x32_bf16 v[20:23], v[168:171], v[196:199], v[20:23]
	v_mfma_f32_16x16x32_bf16 v[20:23], v[172:175], v[200:203], v[20:23]
	v_mfma_f32_16x16x32_bf16 v[16:19], v[176:179], v[196:199], v[16:19]
	v_mfma_f32_16x16x32_bf16 v[16:19], v[184:187], v[200:203], v[16:19]
	v_mfma_f32_16x16x32_bf16 v[12:15], v[168:171], v[204:207], v[12:15]
	v_mfma_f32_16x16x32_bf16 v[12:15], v[172:175], v[208:211], v[12:15]
	v_mfma_f32_16x16x32_bf16 v[8:11], v[176:179], v[204:207], v[8:11]
	v_mfma_f32_16x16x32_bf16 v[8:11], v[184:187], v[208:211], v[8:11]
	v_mfma_f32_16x16x32_bf16 v[4:7], v[168:171], v[212:215], v[4:7]
	v_mfma_f32_16x16x32_bf16 v[4:7], v[172:175], v[216:219], v[4:7]
	v_mfma_f32_16x16x32_bf16 v[0:3], v[176:179], v[212:215], v[0:3]
	v_mfma_f32_16x16x32_bf16 v[0:3], v[184:187], v[216:219], v[0:3]
	s_setprio 0
	s_barrier
.Lmid_gemm2:
	s_add_i32 s18, 0, 0x18000
	s_add_i32 s19, 0, 0x1c000
	v_add_u32_e32 v164, s18, v147
	v_add_u32_e32 v181, s19, v147
	ds_read_b128 v[152:155], v164
	ds_read_b128 v[156:159], v164 offset:1024
	ds_read_b128 v[160:163], v164 offset:2048
	ds_read_b128 v[164:167], v164 offset:3072
	ds_read_b128 v[168:171], v181
	ds_read_b128 v[172:175], v181 offset:1024
	ds_read_b128 v[176:179], v181 offset:2048
	ds_read_b128 v[184:187], v181 offset:3072
	ds_read_b128 v[188:191], v150 offset:32768
	ds_read_b128 v[192:195], v150 offset:33792
	ds_read_b128 v[196:199], v150 offset:34816
	ds_read_b128 v[200:203], v150 offset:35840
	ds_read_b128 v[204:207], v150 offset:36864
	ds_read_b128 v[208:211], v150 offset:37888
	ds_read_b128 v[212:215], v150 offset:38912
	ds_read_b128 v[216:219], v150 offset:39936
	s_add_u32 s62, s62, 0x40000
	s_addc_u32 s63, s63, 0
	s_mov_b32 m0, s70
	v_lshl_add_u64 v[228:229], s[62:63], 0, v[134:135]
	global_load_lds_dwordx4 v[228:229], off
	v_lshl_add_u64 v[228:229], s[62:63], 0, v[130:131]
	s_mov_b32 m0, s71
	s_nop 0
	global_load_lds_dwordx4 v[228:229], off
	s_waitcnt vmcnt(8)
	s_waitcnt lgkmcnt(0)
	s_barrier
	s_setprio 1
	s_waitcnt lgkmcnt(0)
	v_mfma_f32_16x16x32_bf16 v[124:127], v[152:155], v[188:191], v[124:127]
	v_mfma_f32_16x16x32_bf16 v[124:127], v[156:159], v[192:195], v[124:127]
	v_mfma_f32_16x16x32_bf16 v[120:123], v[160:163], v[188:191], v[120:123]
	v_mfma_f32_16x16x32_bf16 v[120:123], v[164:167], v[192:195], v[120:123]
	v_mfma_f32_16x16x32_bf16 v[116:119], v[152:155], v[196:199], v[116:119]
	v_mfma_f32_16x16x32_bf16 v[116:119], v[156:159], v[200:203], v[116:119]
	v_mfma_f32_16x16x32_bf16 v[112:115], v[160:163], v[196:199], v[112:115]
	v_mfma_f32_16x16x32_bf16 v[112:115], v[164:167], v[200:203], v[112:115]
	v_mfma_f32_16x16x32_bf16 v[108:111], v[152:155], v[204:207], v[108:111]
	v_mfma_f32_16x16x32_bf16 v[108:111], v[156:159], v[208:211], v[108:111]
	v_mfma_f32_16x16x32_bf16 v[104:107], v[160:163], v[204:207], v[104:107]
	v_mfma_f32_16x16x32_bf16 v[104:107], v[164:167], v[208:211], v[104:107]
	v_mfma_f32_16x16x32_bf16 v[100:103], v[152:155], v[212:215], v[100:103]
	v_mfma_f32_16x16x32_bf16 v[100:103], v[156:159], v[216:219], v[100:103]
	v_mfma_f32_16x16x32_bf16 v[96:99], v[160:163], v[212:215], v[96:99]
	v_mfma_f32_16x16x32_bf16 v[96:99], v[164:167], v[216:219], v[96:99]
	v_mfma_f32_16x16x32_bf16 v[68:71], v[168:171], v[188:191], v[68:71]
	v_mfma_f32_16x16x32_bf16 v[68:71], v[172:175], v[192:195], v[68:71]
	v_mfma_f32_16x16x32_bf16 v[64:67], v[176:179], v[188:191], v[64:67]
	v_mfma_f32_16x16x32_bf16 v[64:67], v[184:187], v[192:195], v[64:67]
	v_mfma_f32_16x16x32_bf16 v[52:55], v[168:171], v[196:199], v[52:55]
	v_mfma_f32_16x16x32_bf16 v[52:55], v[172:175], v[200:203], v[52:55]
	v_mfma_f32_16x16x32_bf16 v[48:51], v[176:179], v[196:199], v[48:51]
	v_mfma_f32_16x16x32_bf16 v[48:51], v[184:187], v[200:203], v[48:51]
	v_mfma_f32_16x16x32_bf16 v[44:47], v[168:171], v[204:207], v[44:47]
	v_mfma_f32_16x16x32_bf16 v[44:47], v[172:175], v[208:211], v[44:47]
	v_mfma_f32_16x16x32_bf16 v[40:43], v[176:179], v[204:207], v[40:43]
	v_mfma_f32_16x16x32_bf16 v[40:43], v[184:187], v[208:211], v[40:43]
	v_mfma_f32_16x16x32_bf16 v[36:39], v[168:171], v[212:215], v[36:39]
	v_mfma_f32_16x16x32_bf16 v[36:39], v[172:175], v[216:219], v[36:39]
	v_mfma_f32_16x16x32_bf16 v[32:35], v[176:179], v[212:215], v[32:35]
	v_mfma_f32_16x16x32_bf16 v[32:35], v[184:187], v[216:219], v[32:35]
	s_setprio 0
	s_barrier
	ds_read_b128 v[188:191], v150 offset:49152
	ds_read_b128 v[192:195], v150 offset:50176
	ds_read_b128 v[196:199], v150 offset:51200
	ds_read_b128 v[200:203], v150 offset:52224
	ds_read_b128 v[204:207], v150 offset:53248
	ds_read_b128 v[208:211], v150 offset:54272
	ds_read_b128 v[212:215], v150 offset:55296
	ds_read_b128 v[216:219], v150 offset:56320
	s_add_i32 s18, s18, s66
	v_lshl_add_u64 v[220:221], v[220:221], 0, s[6:7]
	s_mov_b32 m0, s18
	s_nop 0
	global_load_lds_dwordx4 v[220:221], off
	s_add_i32 m0, s18, 0x2000
	s_add_u32 s60, s60, 0x40080
	v_lshl_add_u64 v[220:221], v[222:223], 0, s[6:7]
	s_addc_u32 s61, s61, 0
	s_add_i32 s18, s19, s66
	global_load_lds_dwordx4 v[220:221], off
	v_lshl_add_u64 v[220:221], s[60:61], 0, v[132:133]
	s_mov_b32 m0, s18
	s_nop 0
	global_load_lds_dwordx4 v[220:221], off
	v_lshl_add_u64 v[220:221], s[60:61], 0, v[128:129]
	s_add_i32 m0, s18, 0x2000
	s_nop 0
	global_load_lds_dwordx4 v[220:221], off
	v_lshl_add_u64 v[220:221], v[224:225], 0, s[6:7]
	s_mov_b32 m0, s74
	s_nop 0
	global_load_lds_dwordx4 v[220:221], off
	v_lshl_add_u64 v[220:221], v[226:227], 0, s[6:7]
	s_mov_b32 m0, s75
	s_nop 0
	global_load_lds_dwordx4 v[220:221], off
	s_waitcnt vmcnt(8)
	s_waitcnt lgkmcnt(0)
	s_barrier
	s_setprio 1
	s_waitcnt lgkmcnt(0)
	v_mfma_f32_16x16x32_bf16 v[92:95], v[152:155], v[188:191], v[92:95]
	v_mfma_f32_16x16x32_bf16 v[92:95], v[156:159], v[192:195], v[92:95]
	v_mfma_f32_16x16x32_bf16 v[88:91], v[160:163], v[188:191], v[88:91]
	v_mfma_f32_16x16x32_bf16 v[88:91], v[164:167], v[192:195], v[88:91]
	v_mfma_f32_16x16x32_bf16 v[84:87], v[152:155], v[196:199], v[84:87]
	v_mfma_f32_16x16x32_bf16 v[84:87], v[156:159], v[200:203], v[84:87]
	v_mfma_f32_16x16x32_bf16 v[80:83], v[160:163], v[196:199], v[80:83]
	v_mfma_f32_16x16x32_bf16 v[80:83], v[164:167], v[200:203], v[80:83]
	v_mfma_f32_16x16x32_bf16 v[76:79], v[152:155], v[204:207], v[76:79]
	v_mfma_f32_16x16x32_bf16 v[76:79], v[156:159], v[208:211], v[76:79]
	v_mfma_f32_16x16x32_bf16 v[72:75], v[160:163], v[204:207], v[72:75]
	v_mfma_f32_16x16x32_bf16 v[72:75], v[164:167], v[208:211], v[72:75]
	v_mfma_f32_16x16x32_bf16 v[60:63], v[152:155], v[212:215], v[60:63]
	v_mfma_f32_16x16x32_bf16 v[60:63], v[156:159], v[216:219], v[60:63]
	v_mfma_f32_16x16x32_bf16 v[56:59], v[160:163], v[212:215], v[56:59]
	v_mfma_f32_16x16x32_bf16 v[56:59], v[164:167], v[216:219], v[56:59]
	v_mfma_f32_16x16x32_bf16 v[28:31], v[168:171], v[188:191], v[28:31]
	v_mfma_f32_16x16x32_bf16 v[28:31], v[172:175], v[192:195], v[28:31]
	v_mfma_f32_16x16x32_bf16 v[24:27], v[176:179], v[188:191], v[24:27]
	v_mfma_f32_16x16x32_bf16 v[24:27], v[184:187], v[192:195], v[24:27]
	v_mfma_f32_16x16x32_bf16 v[20:23], v[168:171], v[196:199], v[20:23]
	v_mfma_f32_16x16x32_bf16 v[20:23], v[172:175], v[200:203], v[20:23]
	v_mfma_f32_16x16x32_bf16 v[16:19], v[176:179], v[196:199], v[16:19]
	v_mfma_f32_16x16x32_bf16 v[16:19], v[184:187], v[200:203], v[16:19]
	v_mfma_f32_16x16x32_bf16 v[12:15], v[168:171], v[204:207], v[12:15]
	v_mfma_f32_16x16x32_bf16 v[12:15], v[172:175], v[208:211], v[12:15]
	v_mfma_f32_16x16x32_bf16 v[8:11], v[176:179], v[204:207], v[8:11]
	v_mfma_f32_16x16x32_bf16 v[8:11], v[184:187], v[208:211], v[8:11]
	v_mfma_f32_16x16x32_bf16 v[4:7], v[168:171], v[212:215], v[4:7]
	v_mfma_f32_16x16x32_bf16 v[4:7], v[172:175], v[216:219], v[4:7]
	v_mfma_f32_16x16x32_bf16 v[0:3], v[176:179], v[212:215], v[0:3]
	v_mfma_f32_16x16x32_bf16 v[0:3], v[184:187], v[216:219], v[0:3]
	s_setprio 0
	s_barrier
	s_add_i32 s86, s86, 2
	s_add_u32 s58, s58, 0x100
	s_addc_u32 s59, s59, 0
	s_add_u32 s84, s84, 0x100
	s_addc_u32 s85, s85, 0
	s_cmp_gt_u32 s86, 13
	s_cbranch_scc0 .LBB0_387
	s_and_b64 vcc, exec, s[8:9]
	s_cbranch_vccz .LBB0_390
	s_barrier

.LBB0_600:
	s_ashr_i32 s49, s48, 31
	s_lshl_b64 s[18:19], s[48:49], 19
	s_add_u32 s52, s38, s18
	s_addc_u32 s53, s39, s19
	s_and_b64 s[18:19], s[4:5], exec
	s_cselect_b32 s49, s53, s59
	s_cselect_b32 s84, s52, s58
	s_ashr_i32 s47, s46, 31
	s_lshl_b64 s[18:19], s[46:47], 19
	s_add_u32 s54, s64, s18
	s_addc_u32 s55, s65, s19
	s_and_b64 s[18:19], s[4:5], exec
	s_cselect_b32 s47, s55, s61
	s_cselect_b32 s85, s54, s60
	s_add_u32 s58, s58, 0x40080
	s_addc_u32 s59, s59, 0
	s_add_u32 s86, s60, 0x100
	s_addc_u32 s87, s61, 0
	s_mov_b32 s88, -2
	ds_read_b128 v[152:155], v149
	ds_read_b128 v[156:159], v149 offset:1024
	ds_read_b128 v[160:163], v149 offset:2048
	ds_read_b128 v[164:167], v149 offset:3072
	ds_read_b128 v[168:171], v150
	ds_read_b128 v[172:175], v150 offset:1024
	ds_read_b128 v[176:179], v150 offset:2048
	ds_read_b128 v[184:187], v150 offset:3072
	s_add_u32 s18, s58, 0xfffc0080
	s_addc_u32 s19, s59, -1
	s_cmp_eq_u32 s88, 12
	s_cselect_b32 s63, s49, s19
	s_cselect_b32 s62, s84, s18
	s_cselect_b32 s61, s47, s87
	s_cselect_b32 s60, s85, s86
	v_lshl_add_u64 v[144:145], s[58:59], 0, v[136:137]
	s_add_i32 m0, s57, 0xc000
	ds_read_b128 v[188:191], v151
	ds_read_b128 v[192:195], v151 offset:1024
	ds_read_b128 v[196:199], v151 offset:2048
	ds_read_b128 v[200:203], v151 offset:3072
	ds_read_b128 v[204:207], v151 offset:4096
	ds_read_b128 v[208:211], v151 offset:5120
	ds_read_b128 v[212:215], v151 offset:6144
	ds_read_b128 v[216:219], v151 offset:7168
	global_load_lds_dwordx4 v[144:145], off
	v_lshl_add_u64 v[144:145], s[58:59], 0, v[138:139]
	s_add_i32 m0, s57, 0xe000
	s_nop 0
	global_load_lds_dwordx4 v[144:145], off
	s_waitcnt vmcnt(8)
	s_waitcnt lgkmcnt(0)
	s_barrier
	s_setprio 1
	s_waitcnt lgkmcnt(0)
	v_mfma_f32_16x16x32_bf16 v[124:127], v[152:155], v[188:191], 0
	v_mfma_f32_16x16x32_bf16 v[124:127], v[156:159], v[192:195], v[124:127]
	v_mfma_f32_16x16x32_bf16 v[120:123], v[160:163], v[188:191], 0
	v_mfma_f32_16x16x32_bf16 v[120:123], v[164:167], v[192:195], v[120:123]
	v_mfma_f32_16x16x32_bf16 v[116:119], v[152:155], v[196:199], 0
	v_mfma_f32_16x16x32_bf16 v[116:119], v[156:159], v[200:203], v[116:119]
	v_mfma_f32_16x16x32_bf16 v[108:111], v[160:163], v[196:199], 0
	v_mfma_f32_16x16x32_bf16 v[108:111], v[164:167], v[200:203], v[108:111]
	v_mfma_f32_16x16x32_bf16 v[100:103], v[152:155], v[204:207], 0
	v_mfma_f32_16x16x32_bf16 v[100:103], v[156:159], v[208:211], v[100:103]
	v_mfma_f32_16x16x32_bf16 v[92:95], v[160:163], v[204:207], 0
	v_mfma_f32_16x16x32_bf16 v[92:95], v[164:167], v[208:211], v[92:95]
	v_mfma_f32_16x16x32_bf16 v[84:87], v[152:155], v[212:215], 0
	v_mfma_f32_16x16x32_bf16 v[84:87], v[156:159], v[216:219], v[84:87]
	v_mfma_f32_16x16x32_bf16 v[76:79], v[160:163], v[212:215], 0
	v_mfma_f32_16x16x32_bf16 v[76:79], v[164:167], v[216:219], v[76:79]
	v_mfma_f32_16x16x32_bf16 v[112:115], v[168:171], v[188:191], 0
	v_mfma_f32_16x16x32_bf16 v[112:115], v[172:175], v[192:195], v[112:115]
	v_mfma_f32_16x16x32_bf16 v[104:107], v[176:179], v[188:191], 0
	v_mfma_f32_16x16x32_bf16 v[104:107], v[184:187], v[192:195], v[104:107]
	v_mfma_f32_16x16x32_bf16 v[96:99], v[168:171], v[196:199], 0
	v_mfma_f32_16x16x32_bf16 v[96:99], v[172:175], v[200:203], v[96:99]
	v_mfma_f32_16x16x32_bf16 v[88:91], v[176:179], v[196:199], 0
	v_mfma_f32_16x16x32_bf16 v[88:91], v[184:187], v[200:203], v[88:91]
	v_mfma_f32_16x16x32_bf16 v[80:83], v[168:171], v[204:207], 0
	v_mfma_f32_16x16x32_bf16 v[80:83], v[172:175], v[208:211], v[80:83]
	v_mfma_f32_16x16x32_bf16 v[72:75], v[176:179], v[204:207], 0
	v_mfma_f32_16x16x32_bf16 v[72:75], v[184:187], v[208:211], v[72:75]
	v_mfma_f32_16x16x32_bf16 v[68:71], v[168:171], v[212:215], 0
	v_mfma_f32_16x16x32_bf16 v[68:71], v[172:175], v[216:219], v[68:71]
	v_mfma_f32_16x16x32_bf16 v[64:67], v[176:179], v[212:215], 0
	v_mfma_f32_16x16x32_bf16 v[64:67], v[184:187], v[216:219], v[64:67]
	s_setprio 0
	s_barrier
	ds_read_b128 v[188:191], v151 offset:16384
	ds_read_b128 v[192:195], v151 offset:17408
	ds_read_b128 v[196:199], v151 offset:18432
	ds_read_b128 v[200:203], v151 offset:19456
	ds_read_b128 v[204:207], v151 offset:20480
	ds_read_b128 v[208:211], v151 offset:21504
	ds_read_b128 v[212:215], v151 offset:22528
	ds_read_b128 v[216:219], v151 offset:23552
	s_add_i32 s18, s73, s66
	v_lshl_add_u64 v[144:145], s[60:61], 0, v[130:131]
	s_mov_b32 m0, s18
	s_nop 0
	global_load_lds_dwordx4 v[144:145], off
	s_add_i32 m0, s18, 0x2000
	s_add_u32 s18, s60, 0x40000
	v_lshl_add_u64 v[220:221], s[60:61], 0, v[134:135]
	s_addc_u32 s19, s61, 0
	s_add_i32 s79, s74, s66
	global_load_lds_dwordx4 v[220:221], off
	v_lshl_add_u64 v[222:223], s[18:19], 0, v[130:131]
	s_mov_b32 m0, s79
	v_lshl_add_u64 v[224:225], s[62:63], 0, v[132:133]
	global_load_lds_dwordx4 v[222:223], off
	v_lshl_add_u64 v[222:223], s[18:19], 0, v[134:135]
	s_add_i32 m0, s79, 0x2000
	s_nop 0
	global_load_lds_dwordx4 v[222:223], off
	v_lshl_add_u64 v[222:223], s[62:63], 0, v[128:129]
	s_mov_b32 m0, s57
	s_nop 0
	global_load_lds_dwordx4 v[222:223], off
	s_mov_b32 m0, s67
	s_nop 0
	global_load_lds_dwordx4 v[224:225], off
	s_waitcnt vmcnt(8)
	s_waitcnt lgkmcnt(0)
	s_barrier
	s_setprio 1
	s_waitcnt lgkmcnt(0)
	v_mfma_f32_16x16x32_bf16 v[60:63], v[152:155], v[188:191], 0
	v_mfma_f32_16x16x32_bf16 v[60:63], v[156:159], v[192:195], v[60:63]
	v_mfma_f32_16x16x32_bf16 v[56:59], v[160:163], v[188:191], 0
	v_mfma_f32_16x16x32_bf16 v[56:59], v[164:167], v[192:195], v[56:59]
	v_mfma_f32_16x16x32_bf16 v[52:55], v[152:155], v[196:199], 0
	v_mfma_f32_16x16x32_bf16 v[52:55], v[156:159], v[200:203], v[52:55]
	v_mfma_f32_16x16x32_bf16 v[44:47], v[160:163], v[196:199], 0
	v_mfma_f32_16x16x32_bf16 v[44:47], v[164:167], v[200:203], v[44:47]
	v_mfma_f32_16x16x32_bf16 v[36:39], v[152:155], v[204:207], 0
	v_mfma_f32_16x16x32_bf16 v[36:39], v[156:159], v[208:211], v[36:39]
	v_mfma_f32_16x16x32_bf16 v[28:31], v[160:163], v[204:207], 0
	v_mfma_f32_16x16x32_bf16 v[28:31], v[164:167], v[208:211], v[28:31]
	v_mfma_f32_16x16x32_bf16 v[20:23], v[152:155], v[212:215], 0
	v_mfma_f32_16x16x32_bf16 v[20:23], v[156:159], v[216:219], v[20:23]
	v_mfma_f32_16x16x32_bf16 v[12:15], v[160:163], v[212:215], 0
	v_mfma_f32_16x16x32_bf16 v[12:15], v[164:167], v[216:219], v[12:15]
	v_mfma_f32_16x16x32_bf16 v[48:51], v[168:171], v[188:191], 0
	v_mfma_f32_16x16x32_bf16 v[48:51], v[172:175], v[192:195], v[48:51]
	v_mfma_f32_16x16x32_bf16 v[40:43], v[176:179], v[188:191], 0
	v_mfma_f32_16x16x32_bf16 v[40:43], v[184:187], v[192:195], v[40:43]
	v_mfma_f32_16x16x32_bf16 v[32:35], v[168:171], v[196:199], 0
	v_mfma_f32_16x16x32_bf16 v[32:35], v[172:175], v[200:203], v[32:35]
	v_mfma_f32_16x16x32_bf16 v[24:27], v[176:179], v[196:199], 0
	v_mfma_f32_16x16x32_bf16 v[24:27], v[184:187], v[200:203], v[24:27]
	v_mfma_f32_16x16x32_bf16 v[16:19], v[168:171], v[204:207], 0
	v_mfma_f32_16x16x32_bf16 v[16:19], v[172:175], v[208:211], v[16:19]
	v_mfma_f32_16x16x32_bf16 v[8:11], v[176:179], v[204:207], 0
	v_mfma_f32_16x16x32_bf16 v[8:11], v[184:187], v[208:211], v[8:11]
	v_mfma_f32_16x16x32_bf16 v[4:7], v[168:171], v[212:215], 0
	v_mfma_f32_16x16x32_bf16 v[4:7], v[172:175], v[216:219], v[4:7]
	v_mfma_f32_16x16x32_bf16 v[0:3], v[176:179], v[212:215], 0
	v_mfma_f32_16x16x32_bf16 v[0:3], v[184:187], v[216:219], v[0:3]
	s_setprio 0
	s_barrier
	s_branch .Lmid_gemm3
.LBB0_601:
	ds_read_b128 v[152:155], v149
	ds_read_b128 v[156:159], v149 offset:1024
	ds_read_b128 v[160:163], v149 offset:2048
	ds_read_b128 v[164:167], v149 offset:3072
	ds_read_b128 v[168:171], v150
	ds_read_b128 v[172:175], v150 offset:1024
	ds_read_b128 v[176:179], v150 offset:2048
	ds_read_b128 v[184:187], v150 offset:3072
	ds_read_b128 v[188:191], v151
	ds_read_b128 v[192:195], v151 offset:1024
	ds_read_b128 v[196:199], v151 offset:2048
	ds_read_b128 v[200:203], v151 offset:3072
	ds_read_b128 v[204:207], v151 offset:4096
	ds_read_b128 v[208:211], v151 offset:5120
	ds_read_b128 v[212:215], v151 offset:6144
	ds_read_b128 v[216:219], v151 offset:7168
	s_add_u32 s18, s58, 0xfffc0080
	s_addc_u32 s19, s59, -1
	s_cmp_eq_u32 s88, 12
	s_cselect_b32 s63, s49, s19
	s_cselect_b32 s62, s84, s18
	s_cselect_b32 s61, s47, s87
	s_cselect_b32 s60, s85, s86
	v_lshl_add_u64 v[144:145], s[58:59], 0, v[136:137]
	s_add_i32 m0, s57, 0xc000
	s_nop 0
	global_load_lds_dwordx4 v[144:145], off
	v_lshl_add_u64 v[144:145], s[58:59], 0, v[138:139]
	s_add_i32 m0, s57, 0xe000
	s_nop 0
	global_load_lds_dwordx4 v[144:145], off
	s_waitcnt vmcnt(8)
	s_waitcnt lgkmcnt(0)
	s_barrier
	s_setprio 1
	s_waitcnt lgkmcnt(0)
	v_mfma_f32_16x16x32_bf16 v[124:127], v[152:155], v[188:191], v[124:127]
	v_mfma_f32_16x16x32_bf16 v[124:127], v[156:159], v[192:195], v[124:127]
	v_mfma_f32_16x16x32_bf16 v[120:123], v[160:163], v[188:191], v[120:123]
	v_mfma_f32_16x16x32_bf16 v[120:123], v[164:167], v[192:195], v[120:123]
	v_mfma_f32_16x16x32_bf16 v[116:119], v[152:155], v[196:199], v[116:119]
	v_mfma_f32_16x16x32_bf16 v[116:119], v[156:159], v[200:203], v[116:119]
	v_mfma_f32_16x16x32_bf16 v[108:111], v[160:163], v[196:199], v[108:111]
	v_mfma_f32_16x16x32_bf16 v[108:111], v[164:167], v[200:203], v[108:111]
	v_mfma_f32_16x16x32_bf16 v[100:103], v[152:155], v[204:207], v[100:103]
	v_mfma_f32_16x16x32_bf16 v[100:103], v[156:159], v[208:211], v[100:103]
	v_mfma_f32_16x16x32_bf16 v[92:95], v[160:163], v[204:207], v[92:95]
	v_mfma_f32_16x16x32_bf16 v[92:95], v[164:167], v[208:211], v[92:95]
	v_mfma_f32_16x16x32_bf16 v[84:87], v[152:155], v[212:215], v[84:87]
	v_mfma_f32_16x16x32_bf16 v[84:87], v[156:159], v[216:219], v[84:87]
	v_mfma_f32_16x16x32_bf16 v[76:79], v[160:163], v[212:215], v[76:79]
	v_mfma_f32_16x16x32_bf16 v[76:79], v[164:167], v[216:219], v[76:79]
	v_mfma_f32_16x16x32_bf16 v[112:115], v[168:171], v[188:191], v[112:115]
	v_mfma_f32_16x16x32_bf16 v[112:115], v[172:175], v[192:195], v[112:115]
	v_mfma_f32_16x16x32_bf16 v[104:107], v[176:179], v[188:191], v[104:107]
	v_mfma_f32_16x16x32_bf16 v[104:107], v[184:187], v[192:195], v[104:107]
	v_mfma_f32_16x16x32_bf16 v[96:99], v[168:171], v[196:199], v[96:99]
	v_mfma_f32_16x16x32_bf16 v[96:99], v[172:175], v[200:203], v[96:99]
	v_mfma_f32_16x16x32_bf16 v[88:91], v[176:179], v[196:199], v[88:91]
	v_mfma_f32_16x16x32_bf16 v[88:91], v[184:187], v[200:203], v[88:91]
	v_mfma_f32_16x16x32_bf16 v[80:83], v[168:171], v[204:207], v[80:83]
	v_mfma_f32_16x16x32_bf16 v[80:83], v[172:175], v[208:211], v[80:83]
	v_mfma_f32_16x16x32_bf16 v[72:75], v[176:179], v[204:207], v[72:75]
	v_mfma_f32_16x16x32_bf16 v[72:75], v[184:187], v[208:211], v[72:75]
	v_mfma_f32_16x16x32_bf16 v[68:71], v[168:171], v[212:215], v[68:71]
	v_mfma_f32_16x16x32_bf16 v[68:71], v[172:175], v[216:219], v[68:71]
	v_mfma_f32_16x16x32_bf16 v[64:67], v[176:179], v[212:215], v[64:67]
	v_mfma_f32_16x16x32_bf16 v[64:67], v[184:187], v[216:219], v[64:67]
	s_setprio 0
	s_barrier
	ds_read_b128 v[188:191], v151 offset:16384
	ds_read_b128 v[192:195], v151 offset:17408
	ds_read_b128 v[196:199], v151 offset:18432
	ds_read_b128 v[200:203], v151 offset:19456
	ds_read_b128 v[204:207], v151 offset:20480
	ds_read_b128 v[208:211], v151 offset:21504
	ds_read_b128 v[212:215], v151 offset:22528
	ds_read_b128 v[216:219], v151 offset:23552
	s_add_i32 s18, s73, s66
	v_lshl_add_u64 v[144:145], s[60:61], 0, v[130:131]
	s_mov_b32 m0, s18
	s_nop 0
	global_load_lds_dwordx4 v[144:145], off
	s_add_i32 m0, s18, 0x2000
	s_add_u32 s18, s60, 0x40000
	v_lshl_add_u64 v[220:221], s[60:61], 0, v[134:135]
	s_addc_u32 s19, s61, 0
	s_add_i32 s79, s74, s66
	global_load_lds_dwordx4 v[220:221], off
	v_lshl_add_u64 v[222:223], s[18:19], 0, v[130:131]
	s_mov_b32 m0, s79
	v_lshl_add_u64 v[224:225], s[62:63], 0, v[132:133]
	global_load_lds_dwordx4 v[222:223], off
	v_lshl_add_u64 v[222:223], s[18:19], 0, v[134:135]
	s_add_i32 m0, s79, 0x2000
	s_nop 0
	global_load_lds_dwordx4 v[222:223], off
	v_lshl_add_u64 v[222:223], s[62:63], 0, v[128:129]
	s_mov_b32 m0, s57
	s_nop 0
	global_load_lds_dwordx4 v[222:223], off
	s_mov_b32 m0, s67
	s_nop 0
	global_load_lds_dwordx4 v[224:225], off
	s_waitcnt vmcnt(8)
	s_waitcnt lgkmcnt(0)
	s_barrier
	s_setprio 1
	s_waitcnt lgkmcnt(0)
	v_mfma_f32_16x16x32_bf16 v[60:63], v[152:155], v[188:191], v[60:63]
	v_mfma_f32_16x16x32_bf16 v[60:63], v[156:159], v[192:195], v[60:63]
	v_mfma_f32_16x16x32_bf16 v[56:59], v[160:163], v[188:191], v[56:59]
	v_mfma_f32_16x16x32_bf16 v[56:59], v[164:167], v[192:195], v[56:59]
	v_mfma_f32_16x16x32_bf16 v[52:55], v[152:155], v[196:199], v[52:55]
	v_mfma_f32_16x16x32_bf16 v[52:55], v[156:159], v[200:203], v[52:55]
	v_mfma_f32_16x16x32_bf16 v[44:47], v[160:163], v[196:199], v[44:47]
	v_mfma_f32_16x16x32_bf16 v[44:47], v[164:167], v[200:203], v[44:47]
	v_mfma_f32_16x16x32_bf16 v[36:39], v[152:155], v[204:207], v[36:39]
	v_mfma_f32_16x16x32_bf16 v[36:39], v[156:159], v[208:211], v[36:39]
	v_mfma_f32_16x16x32_bf16 v[28:31], v[160:163], v[204:207], v[28:31]
	v_mfma_f32_16x16x32_bf16 v[28:31], v[164:167], v[208:211], v[28:31]
	v_mfma_f32_16x16x32_bf16 v[20:23], v[152:155], v[212:215], v[20:23]
	v_mfma_f32_16x16x32_bf16 v[20:23], v[156:159], v[216:219], v[20:23]
	v_mfma_f32_16x16x32_bf16 v[12:15], v[160:163], v[212:215], v[12:15]
	v_mfma_f32_16x16x32_bf16 v[12:15], v[164:167], v[216:219], v[12:15]
	v_mfma_f32_16x16x32_bf16 v[48:51], v[168:171], v[188:191], v[48:51]
	v_mfma_f32_16x16x32_bf16 v[48:51], v[172:175], v[192:195], v[48:51]
	v_mfma_f32_16x16x32_bf16 v[40:43], v[176:179], v[188:191], v[40:43]
	v_mfma_f32_16x16x32_bf16 v[40:43], v[184:187], v[192:195], v[40:43]
	v_mfma_f32_16x16x32_bf16 v[32:35], v[168:171], v[196:199], v[32:35]
	v_mfma_f32_16x16x32_bf16 v[32:35], v[172:175], v[200:203], v[32:35]
	v_mfma_f32_16x16x32_bf16 v[24:27], v[176:179], v[196:199], v[24:27]
	v_mfma_f32_16x16x32_bf16 v[24:27], v[184:187], v[200:203], v[24:27]
	v_mfma_f32_16x16x32_bf16 v[16:19], v[168:171], v[204:207], v[16:19]
	v_mfma_f32_16x16x32_bf16 v[16:19], v[172:175], v[208:211], v[16:19]
	v_mfma_f32_16x16x32_bf16 v[8:11], v[176:179], v[204:207], v[8:11]
	v_mfma_f32_16x16x32_bf16 v[8:11], v[184:187], v[208:211], v[8:11]
	v_mfma_f32_16x16x32_bf16 v[4:7], v[168:171], v[212:215], v[4:7]
	v_mfma_f32_16x16x32_bf16 v[4:7], v[172:175], v[216:219], v[4:7]
	v_mfma_f32_16x16x32_bf16 v[0:3], v[176:179], v[212:215], v[0:3]
	v_mfma_f32_16x16x32_bf16 v[0:3], v[184:187], v[216:219], v[0:3]
	s_setprio 0
	s_barrier
.Lmid_gemm3:
	s_add_i32 s79, 0, 0x18000
	s_add_i32 s89, 0, 0x1c000
	v_add_u32_e32 v164, s79, v147
	v_add_u32_e32 v181, s89, v147
	ds_read_b128 v[152:155], v164
	ds_read_b128 v[156:159], v164 offset:1024
	ds_read_b128 v[160:163], v164 offset:2048
	ds_read_b128 v[164:167], v164 offset:3072
	ds_read_b128 v[168:171], v181
	ds_read_b128 v[172:175], v181 offset:1024
	ds_read_b128 v[176:179], v181 offset:2048
	ds_read_b128 v[184:187], v181 offset:3072
	ds_read_b128 v[188:191], v151 offset:32768
	ds_read_b128 v[192:195], v151 offset:33792
	ds_read_b128 v[196:199], v151 offset:34816
	ds_read_b128 v[200:203], v151 offset:35840
	ds_read_b128 v[204:207], v151 offset:36864
	ds_read_b128 v[208:211], v151 offset:37888
	ds_read_b128 v[212:215], v151 offset:38912
	ds_read_b128 v[216:219], v151 offset:39936
	s_add_u32 s18, s62, 0x40000
	s_addc_u32 s19, s63, 0
	s_mov_b32 m0, s68
	v_lshl_add_u64 v[226:227], s[18:19], 0, v[128:129]
	global_load_lds_dwordx4 v[226:227], off
	v_lshl_add_u64 v[226:227], s[18:19], 0, v[132:133]
	s_mov_b32 m0, s69
	s_nop 0
	global_load_lds_dwordx4 v[226:227], off
	s_waitcnt vmcnt(8)
	s_waitcnt lgkmcnt(0)
	s_barrier
	s_setprio 1
	s_waitcnt lgkmcnt(0)
	v_mfma_f32_16x16x32_bf16 v[124:127], v[152:155], v[188:191], v[124:127]
	v_mfma_f32_16x16x32_bf16 v[124:127], v[156:159], v[192:195], v[124:127]
	v_mfma_f32_16x16x32_bf16 v[120:123], v[160:163], v[188:191], v[120:123]
	v_mfma_f32_16x16x32_bf16 v[120:123], v[164:167], v[192:195], v[120:123]
	v_mfma_f32_16x16x32_bf16 v[116:119], v[152:155], v[196:199], v[116:119]
	v_mfma_f32_16x16x32_bf16 v[116:119], v[156:159], v[200:203], v[116:119]
	v_mfma_f32_16x16x32_bf16 v[108:111], v[160:163], v[196:199], v[108:111]
	v_mfma_f32_16x16x32_bf16 v[108:111], v[164:167], v[200:203], v[108:111]
	v_mfma_f32_16x16x32_bf16 v[100:103], v[152:155], v[204:207], v[100:103]
	v_mfma_f32_16x16x32_bf16 v[100:103], v[156:159], v[208:211], v[100:103]
	v_mfma_f32_16x16x32_bf16 v[92:95], v[160:163], v[204:207], v[92:95]
	v_mfma_f32_16x16x32_bf16 v[92:95], v[164:167], v[208:211], v[92:95]
	v_mfma_f32_16x16x32_bf16 v[84:87], v[152:155], v[212:215], v[84:87]
	v_mfma_f32_16x16x32_bf16 v[84:87], v[156:159], v[216:219], v[84:87]
	v_mfma_f32_16x16x32_bf16 v[76:79], v[160:163], v[212:215], v[76:79]
	v_mfma_f32_16x16x32_bf16 v[76:79], v[164:167], v[216:219], v[76:79]
	v_mfma_f32_16x16x32_bf16 v[112:115], v[168:171], v[188:191], v[112:115]
	v_mfma_f32_16x16x32_bf16 v[112:115], v[172:175], v[192:195], v[112:115]
	v_mfma_f32_16x16x32_bf16 v[104:107], v[176:179], v[188:191], v[104:107]
	v_mfma_f32_16x16x32_bf16 v[104:107], v[184:187], v[192:195], v[104:107]
	v_mfma_f32_16x16x32_bf16 v[96:99], v[168:171], v[196:199], v[96:99]
	v_mfma_f32_16x16x32_bf16 v[96:99], v[172:175], v[200:203], v[96:99]
	v_mfma_f32_16x16x32_bf16 v[88:91], v[176:179], v[196:199], v[88:91]
	v_mfma_f32_16x16x32_bf16 v[88:91], v[184:187], v[200:203], v[88:91]
	v_mfma_f32_16x16x32_bf16 v[80:83], v[168:171], v[204:207], v[80:83]
	v_mfma_f32_16x16x32_bf16 v[80:83], v[172:175], v[208:211], v[80:83]
	v_mfma_f32_16x16x32_bf16 v[72:75], v[176:179], v[204:207], v[72:75]
	v_mfma_f32_16x16x32_bf16 v[72:75], v[184:187], v[208:211], v[72:75]
	v_mfma_f32_16x16x32_bf16 v[68:71], v[168:171], v[212:215], v[68:71]
	v_mfma_f32_16x16x32_bf16 v[68:71], v[172:175], v[216:219], v[68:71]
	v_mfma_f32_16x16x32_bf16 v[64:67], v[176:179], v[212:215], v[64:67]
	v_mfma_f32_16x16x32_bf16 v[64:67], v[184:187], v[216:219], v[64:67]
	s_setprio 0
	s_barrier
	ds_read_b128 v[188:191], v151 offset:49152
	ds_read_b128 v[192:195], v151 offset:50176
	ds_read_b128 v[196:199], v151 offset:51200
	ds_read_b128 v[200:203], v151 offset:52224
	ds_read_b128 v[204:207], v151 offset:53248
	ds_read_b128 v[208:211], v151 offset:54272
	ds_read_b128 v[212:215], v151 offset:55296
	ds_read_b128 v[216:219], v151 offset:56320
	s_add_i32 s18, s79, s66
	v_lshl_add_u64 v[144:145], v[144:145], 0, s[10:11]
	s_mov_b32 m0, s18
	s_nop 0
	global_load_lds_dwordx4 v[144:145], off
	s_add_i32 m0, s18, 0x2000
	s_add_u32 s18, s60, 0x40080
	v_lshl_add_u64 v[144:145], v[220:221], 0, s[10:11]
	s_addc_u32 s19, s61, 0
	s_add_i32 s60, s89, s66
	global_load_lds_dwordx4 v[144:145], off
	v_lshl_add_u64 v[144:145], s[18:19], 0, v[130:131]
	s_mov_b32 m0, s60
	s_nop 0
	global_load_lds_dwordx4 v[144:145], off
	v_lshl_add_u64 v[144:145], s[18:19], 0, v[134:135]
	s_add_i32 m0, s60, 0x2000
	s_nop 0
	global_load_lds_dwordx4 v[144:145], off
	v_lshl_add_u64 v[144:145], v[222:223], 0, s[10:11]
	s_mov_b32 m0, s71
	s_nop 0
	global_load_lds_dwordx4 v[144:145], off
	v_lshl_add_u64 v[144:145], v[224:225], 0, s[10:11]
	s_mov_b32 m0, s72
	s_nop 0
	global_load_lds_dwordx4 v[144:145], off
	s_waitcnt vmcnt(8)
	s_waitcnt lgkmcnt(0)
	s_barrier
	s_setprio 1
	s_waitcnt lgkmcnt(0)
	v_mfma_f32_16x16x32_bf16 v[60:63], v[152:155], v[188:191], v[60:63]
	v_mfma_f32_16x16x32_bf16 v[60:63], v[156:159], v[192:195], v[60:63]
	v_mfma_f32_16x16x32_bf16 v[56:59], v[160:163], v[188:191], v[56:59]
	v_mfma_f32_16x16x32_bf16 v[56:59], v[164:167], v[192:195], v[56:59]
	v_mfma_f32_16x16x32_bf16 v[52:55], v[152:155], v[196:199], v[52:55]
	v_mfma_f32_16x16x32_bf16 v[52:55], v[156:159], v[200:203], v[52:55]
	v_mfma_f32_16x16x32_bf16 v[44:47], v[160:163], v[196:199], v[44:47]
	v_mfma_f32_16x16x32_bf16 v[44:47], v[164:167], v[200:203], v[44:47]
	v_mfma_f32_16x16x32_bf16 v[36:39], v[152:155], v[204:207], v[36:39]
	v_mfma_f32_16x16x32_bf16 v[36:39], v[156:159], v[208:211], v[36:39]
	v_mfma_f32_16x16x32_bf16 v[28:31], v[160:163], v[204:207], v[28:31]
	v_mfma_f32_16x16x32_bf16 v[28:31], v[164:167], v[208:211], v[28:31]
	v_mfma_f32_16x16x32_bf16 v[20:23], v[152:155], v[212:215], v[20:23]
	v_mfma_f32_16x16x32_bf16 v[20:23], v[156:159], v[216:219], v[20:23]
	v_mfma_f32_16x16x32_bf16 v[12:15], v[160:163], v[212:215], v[12:15]
	v_mfma_f32_16x16x32_bf16 v[12:15], v[164:167], v[216:219], v[12:15]
	v_mfma_f32_16x16x32_bf16 v[48:51], v[168:171], v[188:191], v[48:51]
	v_mfma_f32_16x16x32_bf16 v[48:51], v[172:175], v[192:195], v[48:51]
	v_mfma_f32_16x16x32_bf16 v[40:43], v[176:179], v[188:191], v[40:43]
	v_mfma_f32_16x16x32_bf16 v[40:43], v[184:187], v[192:195], v[40:43]
	v_mfma_f32_16x16x32_bf16 v[32:35], v[168:171], v[196:199], v[32:35]
	v_mfma_f32_16x16x32_bf16 v[32:35], v[172:175], v[200:203], v[32:35]
	v_mfma_f32_16x16x32_bf16 v[24:27], v[176:179], v[196:199], v[24:27]
	v_mfma_f32_16x16x32_bf16 v[24:27], v[184:187], v[200:203], v[24:27]
	v_mfma_f32_16x16x32_bf16 v[16:19], v[168:171], v[204:207], v[16:19]
	v_mfma_f32_16x16x32_bf16 v[16:19], v[172:175], v[208:211], v[16:19]
	v_mfma_f32_16x16x32_bf16 v[8:11], v[176:179], v[204:207], v[8:11]
	v_mfma_f32_16x16x32_bf16 v[8:11], v[184:187], v[208:211], v[8:11]
	v_mfma_f32_16x16x32_bf16 v[4:7], v[168:171], v[212:215], v[4:7]
	v_mfma_f32_16x16x32_bf16 v[4:7], v[172:175], v[216:219], v[4:7]
	v_mfma_f32_16x16x32_bf16 v[0:3], v[176:179], v[212:215], v[0:3]
	v_mfma_f32_16x16x32_bf16 v[0:3], v[184:187], v[216:219], v[0:3]
	s_setprio 0
	s_barrier
	s_add_i32 s88, s88, 2
	s_add_u32 s58, s58, 0x100
	s_addc_u32 s59, s59, 0
	s_add_u32 s86, s86, 0x100
	s_addc_u32 s87, s87, 0
	s_cmp_gt_u32 s88, 13
	s_cbranch_scc0 .LBB0_601
	s_and_b64 vcc, exec, s[12:13]
	s_cbranch_vccz .LBB0_604
	s_barrier

.LBB0_723:
	s_ashr_i32 s31, s30, 31
	s_lshl_b64 s[36:37], s[30:31], 19
	s_add_u32 s36, s80, s36
	s_addc_u32 s37, s81, s37
	s_and_b64 s[44:45], s[10:11], exec
	s_cselect_b32 s31, s37, s49
	s_cselect_b32 s70, s36, s48
	s_ashr_i32 s19, s18, 31
	s_lshl_b64 s[44:45], s[18:19], 19
	s_add_u32 s44, s56, s44
	s_addc_u32 s45, s57, s45
	s_and_b64 s[54:55], s[10:11], exec
	s_cselect_b32 s19, s45, s53
	s_cselect_b32 s71, s44, s52
	s_add_u32 s48, s48, 0x40080
	s_addc_u32 s49, s49, 0
	s_add_u32 s72, s52, 0x100
	s_addc_u32 s73, s53, 0
	s_mov_b32 s74, -2
	ds_read_b128 v[140:143], v147
	ds_read_b128 v[150:153], v147 offset:1024
	ds_read_b128 v[154:157], v147 offset:2048
	ds_read_b128 v[158:161], v147 offset:3072
	ds_read_b128 v[162:165], v148
	ds_read_b128 v[166:169], v148 offset:1024
	ds_read_b128 v[170:173], v148 offset:2048
	ds_read_b128 v[174:177], v148 offset:3072
	s_add_u32 s52, s48, 0xfffc0080
	s_addc_u32 s53, s49, -1
	s_cmp_eq_u32 s74, 12
	s_cselect_b32 s55, s31, s53
	s_cselect_b32 s54, s70, s52
	s_cselect_b32 s53, s19, s73
	s_cselect_b32 s52, s71, s72
	v_lshl_add_u64 v[178:179], s[48:49], 0, v[132:133]
	s_add_i32 m0, s47, 0xc000
	ds_read_b128 v[184:187], v149
	ds_read_b128 v[188:191], v149 offset:1024
	ds_read_b128 v[192:195], v149 offset:2048
	ds_read_b128 v[196:199], v149 offset:3072
	ds_read_b128 v[200:203], v149 offset:4096
	ds_read_b128 v[204:207], v149 offset:5120
	ds_read_b128 v[208:211], v149 offset:6144
	ds_read_b128 v[212:215], v149 offset:7168
	global_load_lds_dwordx4 v[178:179], off
	v_lshl_add_u64 v[178:179], s[48:49], 0, v[134:135]
	s_add_i32 m0, s47, 0xe000
	s_nop 0
	global_load_lds_dwordx4 v[178:179], off
	s_waitcnt vmcnt(8)
	s_waitcnt lgkmcnt(0)
	s_barrier
	s_setprio 1
	s_waitcnt lgkmcnt(0)
	v_mfma_f32_16x16x32_bf16 v[124:127], v[140:143], v[184:187], 0
	v_mfma_f32_16x16x32_bf16 v[124:127], v[150:153], v[188:191], v[124:127]
	v_mfma_f32_16x16x32_bf16 v[120:123], v[154:157], v[184:187], 0
	v_mfma_f32_16x16x32_bf16 v[120:123], v[158:161], v[188:191], v[120:123]
	v_mfma_f32_16x16x32_bf16 v[108:111], v[140:143], v[192:195], 0
	v_mfma_f32_16x16x32_bf16 v[108:111], v[150:153], v[196:199], v[108:111]
	v_mfma_f32_16x16x32_bf16 v[104:107], v[154:157], v[192:195], 0
	v_mfma_f32_16x16x32_bf16 v[104:107], v[158:161], v[196:199], v[104:107]
	v_mfma_f32_16x16x32_bf16 v[92:95], v[140:143], v[200:203], 0
	v_mfma_f32_16x16x32_bf16 v[92:95], v[150:153], v[204:207], v[92:95]
	v_mfma_f32_16x16x32_bf16 v[88:91], v[154:157], v[200:203], 0
	v_mfma_f32_16x16x32_bf16 v[88:91], v[158:161], v[204:207], v[88:91]
	v_mfma_f32_16x16x32_bf16 v[76:79], v[140:143], v[208:211], 0
	v_mfma_f32_16x16x32_bf16 v[76:79], v[150:153], v[212:215], v[76:79]
	v_mfma_f32_16x16x32_bf16 v[72:75], v[154:157], v[208:211], 0
	v_mfma_f32_16x16x32_bf16 v[72:75], v[158:161], v[212:215], v[72:75]
	v_mfma_f32_16x16x32_bf16 v[116:119], v[162:165], v[184:187], 0
	v_mfma_f32_16x16x32_bf16 v[116:119], v[166:169], v[188:191], v[116:119]
	v_mfma_f32_16x16x32_bf16 v[112:115], v[170:173], v[184:187], 0
	v_mfma_f32_16x16x32_bf16 v[112:115], v[174:177], v[188:191], v[112:115]
	v_mfma_f32_16x16x32_bf16 v[100:103], v[162:165], v[192:195], 0
	v_mfma_f32_16x16x32_bf16 v[100:103], v[166:169], v[196:199], v[100:103]
	v_mfma_f32_16x16x32_bf16 v[96:99], v[170:173], v[192:195], 0
	v_mfma_f32_16x16x32_bf16 v[96:99], v[174:177], v[196:199], v[96:99]
	v_mfma_f32_16x16x32_bf16 v[84:87], v[162:165], v[200:203], 0
	v_mfma_f32_16x16x32_bf16 v[84:87], v[166:169], v[204:207], v[84:87]
	v_mfma_f32_16x16x32_bf16 v[80:83], v[170:173], v[200:203], 0
	v_mfma_f32_16x16x32_bf16 v[80:83], v[174:177], v[204:207], v[80:83]
	v_mfma_f32_16x16x32_bf16 v[68:71], v[162:165], v[208:211], 0
	v_mfma_f32_16x16x32_bf16 v[68:71], v[166:169], v[212:215], v[68:71]
	v_mfma_f32_16x16x32_bf16 v[64:67], v[170:173], v[208:211], 0
	v_mfma_f32_16x16x32_bf16 v[64:67], v[174:177], v[212:215], v[64:67]
	s_setprio 0
	s_barrier
	ds_read_b128 v[184:187], v149 offset:16384
	ds_read_b128 v[188:191], v149 offset:17408
	ds_read_b128 v[192:195], v149 offset:18432
	ds_read_b128 v[196:199], v149 offset:19456
	ds_read_b128 v[200:203], v149 offset:20480
	ds_read_b128 v[204:207], v149 offset:21504
	ds_read_b128 v[208:211], v149 offset:22528
	ds_read_b128 v[212:215], v149 offset:23552
	s_add_i32 s75, s66, s58
	v_lshl_add_u64 v[178:179], s[52:53], 0, v[130:131]
	s_mov_b32 m0, s75
	s_nop 0
	global_load_lds_dwordx4 v[178:179], off
	s_add_i32 m0, s75, 0x2000
	s_add_u32 s76, s52, 0x40000
	v_lshl_add_u64 v[216:217], s[52:53], 0, v[128:129]
	s_addc_u32 s77, s53, 0
	s_add_i32 s75, s67, s58
	global_load_lds_dwordx4 v[216:217], off
	v_lshl_add_u64 v[218:219], s[76:77], 0, v[130:131]
	s_mov_b32 m0, s75
	v_lshl_add_u64 v[220:221], s[54:55], 0, v[128:129]
	global_load_lds_dwordx4 v[218:219], off
	v_lshl_add_u64 v[218:219], s[76:77], 0, v[128:129]
	s_add_i32 m0, s75, 0x2000
	s_nop 0
	global_load_lds_dwordx4 v[218:219], off
	v_lshl_add_u64 v[218:219], s[54:55], 0, v[130:131]
	s_mov_b32 m0, s47
	s_nop 0
	global_load_lds_dwordx4 v[218:219], off
	s_mov_b32 m0, s60
	s_nop 0
	global_load_lds_dwordx4 v[220:221], off
	s_waitcnt vmcnt(8)
	s_waitcnt lgkmcnt(0)
	s_barrier
	s_setprio 1
	s_waitcnt lgkmcnt(0)
	v_mfma_f32_16x16x32_bf16 v[60:63], v[140:143], v[184:187], 0
	v_mfma_f32_16x16x32_bf16 v[60:63], v[150:153], v[188:191], v[60:63]
	v_mfma_f32_16x16x32_bf16 v[56:59], v[154:157], v[184:187], 0
	v_mfma_f32_16x16x32_bf16 v[56:59], v[158:161], v[188:191], v[56:59]
	v_mfma_f32_16x16x32_bf16 v[44:47], v[140:143], v[192:195], 0
	v_mfma_f32_16x16x32_bf16 v[44:47], v[150:153], v[196:199], v[44:47]
	v_mfma_f32_16x16x32_bf16 v[40:43], v[154:157], v[192:195], 0
	v_mfma_f32_16x16x32_bf16 v[40:43], v[158:161], v[196:199], v[40:43]
	v_mfma_f32_16x16x32_bf16 v[28:31], v[140:143], v[200:203], 0
	v_mfma_f32_16x16x32_bf16 v[28:31], v[150:153], v[204:207], v[28:31]
	v_mfma_f32_16x16x32_bf16 v[24:27], v[154:157], v[200:203], 0
	v_mfma_f32_16x16x32_bf16 v[24:27], v[158:161], v[204:207], v[24:27]
	v_mfma_f32_16x16x32_bf16 v[12:15], v[140:143], v[208:211], 0
	v_mfma_f32_16x16x32_bf16 v[12:15], v[150:153], v[212:215], v[12:15]
	v_mfma_f32_16x16x32_bf16 v[8:11], v[154:157], v[208:211], 0
	v_mfma_f32_16x16x32_bf16 v[8:11], v[158:161], v[212:215], v[8:11]
	v_mfma_f32_16x16x32_bf16 v[52:55], v[162:165], v[184:187], 0
	v_mfma_f32_16x16x32_bf16 v[52:55], v[166:169], v[188:191], v[52:55]
	v_mfma_f32_16x16x32_bf16 v[48:51], v[170:173], v[184:187], 0
	v_mfma_f32_16x16x32_bf16 v[48:51], v[174:177], v[188:191], v[48:51]
	v_mfma_f32_16x16x32_bf16 v[36:39], v[162:165], v[192:195], 0
	v_mfma_f32_16x16x32_bf16 v[36:39], v[166:169], v[196:199], v[36:39]
	v_mfma_f32_16x16x32_bf16 v[32:35], v[170:173], v[192:195], 0
	v_mfma_f32_16x16x32_bf16 v[32:35], v[174:177], v[196:199], v[32:35]
	v_mfma_f32_16x16x32_bf16 v[20:23], v[162:165], v[200:203], 0
	v_mfma_f32_16x16x32_bf16 v[20:23], v[166:169], v[204:207], v[20:23]
	v_mfma_f32_16x16x32_bf16 v[16:19], v[170:173], v[200:203], 0
	v_mfma_f32_16x16x32_bf16 v[16:19], v[174:177], v[204:207], v[16:19]
	v_mfma_f32_16x16x32_bf16 v[4:7], v[162:165], v[208:211], 0
	v_mfma_f32_16x16x32_bf16 v[4:7], v[166:169], v[212:215], v[4:7]
	v_mfma_f32_16x16x32_bf16 v[0:3], v[170:173], v[208:211], 0
	v_mfma_f32_16x16x32_bf16 v[0:3], v[174:177], v[212:215], v[0:3]
	s_setprio 0
	s_barrier
	s_branch .Lmid_gemm4
.LBB0_724:
	ds_read_b128 v[140:143], v147
	ds_read_b128 v[150:153], v147 offset:1024
	ds_read_b128 v[154:157], v147 offset:2048
	ds_read_b128 v[158:161], v147 offset:3072
	ds_read_b128 v[162:165], v148
	ds_read_b128 v[166:169], v148 offset:1024
	ds_read_b128 v[170:173], v148 offset:2048
	ds_read_b128 v[174:177], v148 offset:3072
	ds_read_b128 v[184:187], v149
	ds_read_b128 v[188:191], v149 offset:1024
	ds_read_b128 v[192:195], v149 offset:2048
	ds_read_b128 v[196:199], v149 offset:3072
	ds_read_b128 v[200:203], v149 offset:4096
	ds_read_b128 v[204:207], v149 offset:5120
	ds_read_b128 v[208:211], v149 offset:6144
	ds_read_b128 v[212:215], v149 offset:7168
	s_add_u32 s52, s48, 0xfffc0080
	s_addc_u32 s53, s49, -1
	s_cmp_eq_u32 s74, 12
	s_cselect_b32 s55, s31, s53
	s_cselect_b32 s54, s70, s52
	s_cselect_b32 s53, s19, s73
	s_cselect_b32 s52, s71, s72
	v_lshl_add_u64 v[178:179], s[48:49], 0, v[132:133]
	s_add_i32 m0, s47, 0xc000
	s_nop 0
	global_load_lds_dwordx4 v[178:179], off
	v_lshl_add_u64 v[178:179], s[48:49], 0, v[134:135]
	s_add_i32 m0, s47, 0xe000
	s_nop 0
	global_load_lds_dwordx4 v[178:179], off
	s_waitcnt vmcnt(8)
	s_waitcnt lgkmcnt(0)
	s_barrier
	s_setprio 1
	s_waitcnt lgkmcnt(0)
	v_mfma_f32_16x16x32_bf16 v[124:127], v[140:143], v[184:187], v[124:127]
	v_mfma_f32_16x16x32_bf16 v[124:127], v[150:153], v[188:191], v[124:127]
	v_mfma_f32_16x16x32_bf16 v[120:123], v[154:157], v[184:187], v[120:123]
	v_mfma_f32_16x16x32_bf16 v[120:123], v[158:161], v[188:191], v[120:123]
	v_mfma_f32_16x16x32_bf16 v[108:111], v[140:143], v[192:195], v[108:111]
	v_mfma_f32_16x16x32_bf16 v[108:111], v[150:153], v[196:199], v[108:111]
	v_mfma_f32_16x16x32_bf16 v[104:107], v[154:157], v[192:195], v[104:107]
	v_mfma_f32_16x16x32_bf16 v[104:107], v[158:161], v[196:199], v[104:107]
	v_mfma_f32_16x16x32_bf16 v[92:95], v[140:143], v[200:203], v[92:95]
	v_mfma_f32_16x16x32_bf16 v[92:95], v[150:153], v[204:207], v[92:95]
	v_mfma_f32_16x16x32_bf16 v[88:91], v[154:157], v[200:203], v[88:91]
	v_mfma_f32_16x16x32_bf16 v[88:91], v[158:161], v[204:207], v[88:91]
	v_mfma_f32_16x16x32_bf16 v[76:79], v[140:143], v[208:211], v[76:79]
	v_mfma_f32_16x16x32_bf16 v[76:79], v[150:153], v[212:215], v[76:79]
	v_mfma_f32_16x16x32_bf16 v[72:75], v[154:157], v[208:211], v[72:75]
	v_mfma_f32_16x16x32_bf16 v[72:75], v[158:161], v[212:215], v[72:75]
	v_mfma_f32_16x16x32_bf16 v[116:119], v[162:165], v[184:187], v[116:119]
	v_mfma_f32_16x16x32_bf16 v[116:119], v[166:169], v[188:191], v[116:119]
	v_mfma_f32_16x16x32_bf16 v[112:115], v[170:173], v[184:187], v[112:115]
	v_mfma_f32_16x16x32_bf16 v[112:115], v[174:177], v[188:191], v[112:115]
	v_mfma_f32_16x16x32_bf16 v[100:103], v[162:165], v[192:195], v[100:103]
	v_mfma_f32_16x16x32_bf16 v[100:103], v[166:169], v[196:199], v[100:103]
	v_mfma_f32_16x16x32_bf16 v[96:99], v[170:173], v[192:195], v[96:99]
	v_mfma_f32_16x16x32_bf16 v[96:99], v[174:177], v[196:199], v[96:99]
	v_mfma_f32_16x16x32_bf16 v[84:87], v[162:165], v[200:203], v[84:87]
	v_mfma_f32_16x16x32_bf16 v[84:87], v[166:169], v[204:207], v[84:87]
	v_mfma_f32_16x16x32_bf16 v[80:83], v[170:173], v[200:203], v[80:83]
	v_mfma_f32_16x16x32_bf16 v[80:83], v[174:177], v[204:207], v[80:83]
	v_mfma_f32_16x16x32_bf16 v[68:71], v[162:165], v[208:211], v[68:71]
	v_mfma_f32_16x16x32_bf16 v[68:71], v[166:169], v[212:215], v[68:71]
	v_mfma_f32_16x16x32_bf16 v[64:67], v[170:173], v[208:211], v[64:67]
	v_mfma_f32_16x16x32_bf16 v[64:67], v[174:177], v[212:215], v[64:67]
	s_setprio 0
	s_barrier
	ds_read_b128 v[184:187], v149 offset:16384
	ds_read_b128 v[188:191], v149 offset:17408
	ds_read_b128 v[192:195], v149 offset:18432
	ds_read_b128 v[196:199], v149 offset:19456
	ds_read_b128 v[200:203], v149 offset:20480
	ds_read_b128 v[204:207], v149 offset:21504
	ds_read_b128 v[208:211], v149 offset:22528
	ds_read_b128 v[212:215], v149 offset:23552
	s_add_i32 s75, s66, s58
	v_lshl_add_u64 v[178:179], s[52:53], 0, v[130:131]
	s_mov_b32 m0, s75
	s_nop 0
	global_load_lds_dwordx4 v[178:179], off
	s_add_i32 m0, s75, 0x2000
	s_add_u32 s76, s52, 0x40000
	v_lshl_add_u64 v[216:217], s[52:53], 0, v[128:129]
	s_addc_u32 s77, s53, 0
	s_add_i32 s75, s67, s58
	global_load_lds_dwordx4 v[216:217], off
	v_lshl_add_u64 v[218:219], s[76:77], 0, v[130:131]
	s_mov_b32 m0, s75
	v_lshl_add_u64 v[220:221], s[54:55], 0, v[128:129]
	global_load_lds_dwordx4 v[218:219], off
	v_lshl_add_u64 v[218:219], s[76:77], 0, v[128:129]
	s_add_i32 m0, s75, 0x2000
	s_nop 0
	global_load_lds_dwordx4 v[218:219], off
	v_lshl_add_u64 v[218:219], s[54:55], 0, v[130:131]
	s_mov_b32 m0, s47
	s_nop 0
	global_load_lds_dwordx4 v[218:219], off
	s_mov_b32 m0, s60
	s_nop 0
	global_load_lds_dwordx4 v[220:221], off
	s_waitcnt vmcnt(8)
	s_waitcnt lgkmcnt(0)
	s_barrier
	s_setprio 1
	s_waitcnt lgkmcnt(0)
	v_mfma_f32_16x16x32_bf16 v[60:63], v[140:143], v[184:187], v[60:63]
	v_mfma_f32_16x16x32_bf16 v[60:63], v[150:153], v[188:191], v[60:63]
	v_mfma_f32_16x16x32_bf16 v[56:59], v[154:157], v[184:187], v[56:59]
	v_mfma_f32_16x16x32_bf16 v[56:59], v[158:161], v[188:191], v[56:59]
	v_mfma_f32_16x16x32_bf16 v[44:47], v[140:143], v[192:195], v[44:47]
	v_mfma_f32_16x16x32_bf16 v[44:47], v[150:153], v[196:199], v[44:47]
	v_mfma_f32_16x16x32_bf16 v[40:43], v[154:157], v[192:195], v[40:43]
	v_mfma_f32_16x16x32_bf16 v[40:43], v[158:161], v[196:199], v[40:43]
	v_mfma_f32_16x16x32_bf16 v[28:31], v[140:143], v[200:203], v[28:31]
	v_mfma_f32_16x16x32_bf16 v[28:31], v[150:153], v[204:207], v[28:31]
	v_mfma_f32_16x16x32_bf16 v[24:27], v[154:157], v[200:203], v[24:27]
	v_mfma_f32_16x16x32_bf16 v[24:27], v[158:161], v[204:207], v[24:27]
	v_mfma_f32_16x16x32_bf16 v[12:15], v[140:143], v[208:211], v[12:15]
	v_mfma_f32_16x16x32_bf16 v[12:15], v[150:153], v[212:215], v[12:15]
	v_mfma_f32_16x16x32_bf16 v[8:11], v[154:157], v[208:211], v[8:11]
	v_mfma_f32_16x16x32_bf16 v[8:11], v[158:161], v[212:215], v[8:11]
	v_mfma_f32_16x16x32_bf16 v[52:55], v[162:165], v[184:187], v[52:55]
	v_mfma_f32_16x16x32_bf16 v[52:55], v[166:169], v[188:191], v[52:55]
	v_mfma_f32_16x16x32_bf16 v[48:51], v[170:173], v[184:187], v[48:51]
	v_mfma_f32_16x16x32_bf16 v[48:51], v[174:177], v[188:191], v[48:51]
	v_mfma_f32_16x16x32_bf16 v[36:39], v[162:165], v[192:195], v[36:39]
	v_mfma_f32_16x16x32_bf16 v[36:39], v[166:169], v[196:199], v[36:39]
	v_mfma_f32_16x16x32_bf16 v[32:35], v[170:173], v[192:195], v[32:35]
	v_mfma_f32_16x16x32_bf16 v[32:35], v[174:177], v[196:199], v[32:35]
	v_mfma_f32_16x16x32_bf16 v[20:23], v[162:165], v[200:203], v[20:23]
	v_mfma_f32_16x16x32_bf16 v[20:23], v[166:169], v[204:207], v[20:23]
	v_mfma_f32_16x16x32_bf16 v[16:19], v[170:173], v[200:203], v[16:19]
	v_mfma_f32_16x16x32_bf16 v[16:19], v[174:177], v[204:207], v[16:19]
	v_mfma_f32_16x16x32_bf16 v[4:7], v[162:165], v[208:211], v[4:7]
	v_mfma_f32_16x16x32_bf16 v[4:7], v[166:169], v[212:215], v[4:7]
	v_mfma_f32_16x16x32_bf16 v[0:3], v[170:173], v[208:211], v[0:3]
	v_mfma_f32_16x16x32_bf16 v[0:3], v[174:177], v[212:215], v[0:3]
	s_setprio 0
	s_barrier
.Lmid_gemm4:
	s_add_i32 s75, 0, 0x18000
	s_add_i32 s76, 0, 0x1c000
	v_add_u32_e32 v158, s75, v145
	v_add_u32_e32 v174, s76, v145
	ds_read_b128 v[140:143], v158
	ds_read_b128 v[150:153], v158 offset:1024
	ds_read_b128 v[154:157], v158 offset:2048
	ds_read_b128 v[158:161], v158 offset:3072
	ds_read_b128 v[162:165], v174
	ds_read_b128 v[166:169], v174 offset:1024
	ds_read_b128 v[170:173], v174 offset:2048
	ds_read_b128 v[174:177], v174 offset:3072
	ds_read_b128 v[184:187], v149 offset:32768
	ds_read_b128 v[188:191], v149 offset:33792
	ds_read_b128 v[192:195], v149 offset:34816
	ds_read_b128 v[196:199], v149 offset:35840
	ds_read_b128 v[200:203], v149 offset:36864
	ds_read_b128 v[204:207], v149 offset:37888
	ds_read_b128 v[208:211], v149 offset:38912
	ds_read_b128 v[212:215], v149 offset:39936
	s_add_u32 s54, s54, 0x40000
	s_addc_u32 s55, s55, 0
	s_mov_b32 m0, s61
	v_lshl_add_u64 v[222:223], s[54:55], 0, v[130:131]
	global_load_lds_dwordx4 v[222:223], off
	v_lshl_add_u64 v[222:223], s[54:55], 0, v[128:129]
	s_mov_b32 m0, s62
	s_nop 0
	global_load_lds_dwordx4 v[222:223], off
	s_waitcnt vmcnt(8)
	s_waitcnt lgkmcnt(0)
	s_barrier
	s_setprio 1
	s_waitcnt lgkmcnt(0)
	v_mfma_f32_16x16x32_bf16 v[124:127], v[140:143], v[184:187], v[124:127]
	v_mfma_f32_16x16x32_bf16 v[124:127], v[150:153], v[188:191], v[124:127]
	v_mfma_f32_16x16x32_bf16 v[120:123], v[154:157], v[184:187], v[120:123]
	v_mfma_f32_16x16x32_bf16 v[120:123], v[158:161], v[188:191], v[120:123]
	v_mfma_f32_16x16x32_bf16 v[108:111], v[140:143], v[192:195], v[108:111]
	v_mfma_f32_16x16x32_bf16 v[108:111], v[150:153], v[196:199], v[108:111]
	v_mfma_f32_16x16x32_bf16 v[104:107], v[154:157], v[192:195], v[104:107]
	v_mfma_f32_16x16x32_bf16 v[104:107], v[158:161], v[196:199], v[104:107]
	v_mfma_f32_16x16x32_bf16 v[92:95], v[140:143], v[200:203], v[92:95]
	v_mfma_f32_16x16x32_bf16 v[92:95], v[150:153], v[204:207], v[92:95]
	v_mfma_f32_16x16x32_bf16 v[88:91], v[154:157], v[200:203], v[88:91]
	v_mfma_f32_16x16x32_bf16 v[88:91], v[158:161], v[204:207], v[88:91]
	v_mfma_f32_16x16x32_bf16 v[76:79], v[140:143], v[208:211], v[76:79]
	v_mfma_f32_16x16x32_bf16 v[76:79], v[150:153], v[212:215], v[76:79]
	v_mfma_f32_16x16x32_bf16 v[72:75], v[154:157], v[208:211], v[72:75]
	v_mfma_f32_16x16x32_bf16 v[72:75], v[158:161], v[212:215], v[72:75]
	v_mfma_f32_16x16x32_bf16 v[116:119], v[162:165], v[184:187], v[116:119]
	v_mfma_f32_16x16x32_bf16 v[116:119], v[166:169], v[188:191], v[116:119]
	v_mfma_f32_16x16x32_bf16 v[112:115], v[170:173], v[184:187], v[112:115]
	v_mfma_f32_16x16x32_bf16 v[112:115], v[174:177], v[188:191], v[112:115]
	v_mfma_f32_16x16x32_bf16 v[100:103], v[162:165], v[192:195], v[100:103]
	v_mfma_f32_16x16x32_bf16 v[100:103], v[166:169], v[196:199], v[100:103]
	v_mfma_f32_16x16x32_bf16 v[96:99], v[170:173], v[192:195], v[96:99]
	v_mfma_f32_16x16x32_bf16 v[96:99], v[174:177], v[196:199], v[96:99]
	v_mfma_f32_16x16x32_bf16 v[84:87], v[162:165], v[200:203], v[84:87]
	v_mfma_f32_16x16x32_bf16 v[84:87], v[166:169], v[204:207], v[84:87]
	v_mfma_f32_16x16x32_bf16 v[80:83], v[170:173], v[200:203], v[80:83]
	v_mfma_f32_16x16x32_bf16 v[80:83], v[174:177], v[204:207], v[80:83]
	v_mfma_f32_16x16x32_bf16 v[68:71], v[162:165], v[208:211], v[68:71]
	v_mfma_f32_16x16x32_bf16 v[68:71], v[166:169], v[212:215], v[68:71]
	v_mfma_f32_16x16x32_bf16 v[64:67], v[170:173], v[208:211], v[64:67]
	v_mfma_f32_16x16x32_bf16 v[64:67], v[174:177], v[212:215], v[64:67]
	s_setprio 0
	s_barrier
	ds_read_b128 v[184:187], v149 offset:49152
	ds_read_b128 v[188:191], v149 offset:50176
	ds_read_b128 v[192:195], v149 offset:51200
	ds_read_b128 v[196:199], v149 offset:52224
	ds_read_b128 v[200:203], v149 offset:53248
	ds_read_b128 v[204:207], v149 offset:54272
	ds_read_b128 v[208:211], v149 offset:55296
	ds_read_b128 v[212:215], v149 offset:56320
	s_add_i32 s54, s75, s58
	v_lshl_add_u64 v[178:179], v[178:179], 0, s[12:13]
	s_mov_b32 m0, s54
	s_nop 0
	global_load_lds_dwordx4 v[178:179], off
	s_add_i32 m0, s54, 0x2000
	s_add_u32 s52, s52, 0x40080
	v_lshl_add_u64 v[178:179], v[216:217], 0, s[12:13]
	s_addc_u32 s53, s53, 0
	s_add_i32 s54, s76, s58
	global_load_lds_dwordx4 v[178:179], off
	v_lshl_add_u64 v[178:179], s[52:53], 0, v[130:131]
	s_mov_b32 m0, s54
	s_nop 0
	global_load_lds_dwordx4 v[178:179], off
	v_lshl_add_u64 v[178:179], s[52:53], 0, v[128:129]
	s_add_i32 m0, s54, 0x2000
	s_nop 0
	global_load_lds_dwordx4 v[178:179], off
	v_lshl_add_u64 v[178:179], v[218:219], 0, s[12:13]
	s_mov_b32 m0, s64
	s_nop 0
	global_load_lds_dwordx4 v[178:179], off
	v_lshl_add_u64 v[178:179], v[220:221], 0, s[12:13]
	s_mov_b32 m0, s65
	s_nop 0
	global_load_lds_dwordx4 v[178:179], off
	s_waitcnt vmcnt(8)
	s_waitcnt lgkmcnt(0)
	s_barrier
	s_setprio 1
	s_waitcnt lgkmcnt(0)
	v_mfma_f32_16x16x32_bf16 v[60:63], v[140:143], v[184:187], v[60:63]
	v_mfma_f32_16x16x32_bf16 v[60:63], v[150:153], v[188:191], v[60:63]
	v_mfma_f32_16x16x32_bf16 v[56:59], v[154:157], v[184:187], v[56:59]
	v_mfma_f32_16x16x32_bf16 v[56:59], v[158:161], v[188:191], v[56:59]
	v_mfma_f32_16x16x32_bf16 v[44:47], v[140:143], v[192:195], v[44:47]
	v_mfma_f32_16x16x32_bf16 v[44:47], v[150:153], v[196:199], v[44:47]
	v_mfma_f32_16x16x32_bf16 v[40:43], v[154:157], v[192:195], v[40:43]
	v_mfma_f32_16x16x32_bf16 v[40:43], v[158:161], v[196:199], v[40:43]
	v_mfma_f32_16x16x32_bf16 v[28:31], v[140:143], v[200:203], v[28:31]
	v_mfma_f32_16x16x32_bf16 v[28:31], v[150:153], v[204:207], v[28:31]
	v_mfma_f32_16x16x32_bf16 v[24:27], v[154:157], v[200:203], v[24:27]
	v_mfma_f32_16x16x32_bf16 v[24:27], v[158:161], v[204:207], v[24:27]
	v_mfma_f32_16x16x32_bf16 v[12:15], v[140:143], v[208:211], v[12:15]
	v_mfma_f32_16x16x32_bf16 v[12:15], v[150:153], v[212:215], v[12:15]
	v_mfma_f32_16x16x32_bf16 v[8:11], v[154:157], v[208:211], v[8:11]
	v_mfma_f32_16x16x32_bf16 v[8:11], v[158:161], v[212:215], v[8:11]
	v_mfma_f32_16x16x32_bf16 v[52:55], v[162:165], v[184:187], v[52:55]
	v_mfma_f32_16x16x32_bf16 v[52:55], v[166:169], v[188:191], v[52:55]
	v_mfma_f32_16x16x32_bf16 v[48:51], v[170:173], v[184:187], v[48:51]
	v_mfma_f32_16x16x32_bf16 v[48:51], v[174:177], v[188:191], v[48:51]
	v_mfma_f32_16x16x32_bf16 v[36:39], v[162:165], v[192:195], v[36:39]
	v_mfma_f32_16x16x32_bf16 v[36:39], v[166:169], v[196:199], v[36:39]
	v_mfma_f32_16x16x32_bf16 v[32:35], v[170:173], v[192:195], v[32:35]
	v_mfma_f32_16x16x32_bf16 v[32:35], v[174:177], v[196:199], v[32:35]
	v_mfma_f32_16x16x32_bf16 v[20:23], v[162:165], v[200:203], v[20:23]
	v_mfma_f32_16x16x32_bf16 v[20:23], v[166:169], v[204:207], v[20:23]
	v_mfma_f32_16x16x32_bf16 v[16:19], v[170:173], v[200:203], v[16:19]
	v_mfma_f32_16x16x32_bf16 v[16:19], v[174:177], v[204:207], v[16:19]
	v_mfma_f32_16x16x32_bf16 v[4:7], v[162:165], v[208:211], v[4:7]
	v_mfma_f32_16x16x32_bf16 v[4:7], v[166:169], v[212:215], v[4:7]
	v_mfma_f32_16x16x32_bf16 v[0:3], v[170:173], v[208:211], v[0:3]
	v_mfma_f32_16x16x32_bf16 v[0:3], v[174:177], v[212:215], v[0:3]
	s_setprio 0
	s_barrier
	s_add_i32 s74, s74, 2
	s_add_u32 s48, s48, 0x100
	s_addc_u32 s49, s49, 0
	s_add_u32 s72, s72, 0x100
	s_addc_u32 s73, s73, 0
	s_cmp_gt_u32 s74, 13
	s_cbranch_scc0 .LBB0_724
	s_and_b64 vcc, exec, s[16:17]
	s_cbranch_vccz .LBB0_727
	s_barrier

.LBB0_803:
	s_add_u32 s84, s54, 0x100
	s_addc_u32 s85, s55, 0
	s_mov_b32 s86, -2
	ds_read_b128 v[152:155], v149
	ds_read_b128 v[156:159], v149 offset:1024
	ds_read_b128 v[160:163], v149 offset:2048
	ds_read_b128 v[164:167], v149 offset:3072
	ds_read_b128 v[168:171], v150
	ds_read_b128 v[172:175], v150 offset:1024
	ds_read_b128 v[176:179], v150 offset:2048
	ds_read_b128 v[184:187], v150 offset:3072
	s_add_u32 s54, s52, 0x100
	s_addc_u32 s55, s53, 0
	s_cmp_eq_u32 s86, 40
	s_cselect_b32 s59, s13, s55
	s_cselect_b32 s58, s12, s54
	s_cselect_b32 s57, s49, s85
	s_cselect_b32 s56, s48, s84
	v_lshl_add_u64 v[144:145], s[52:53], 0, v[136:137]
	s_add_i32 m0, s63, 0xc000
	ds_read_b128 v[188:191], v151
	ds_read_b128 v[192:195], v151 offset:1024
	ds_read_b128 v[196:199], v151 offset:2048
	ds_read_b128 v[200:203], v151 offset:3072
	ds_read_b128 v[204:207], v151 offset:4096
	ds_read_b128 v[208:211], v151 offset:5120
	ds_read_b128 v[212:215], v151 offset:6144
	ds_read_b128 v[216:219], v151 offset:7168
	global_load_lds_dwordx4 v[144:145], off
	v_lshl_add_u64 v[144:145], s[52:53], 0, v[138:139]
	s_add_i32 m0, s63, 0xe000
	s_nop 0
	global_load_lds_dwordx4 v[144:145], off
	s_waitcnt vmcnt(8)
	s_waitcnt lgkmcnt(0)
	s_barrier
	s_setprio 1
	s_waitcnt lgkmcnt(0)
	v_mfma_f32_16x16x32_bf16 v[124:127], v[152:155], v[188:191], 0
	v_mfma_f32_16x16x32_bf16 v[124:127], v[156:159], v[192:195], v[124:127]
	v_mfma_f32_16x16x32_bf16 v[120:123], v[160:163], v[188:191], 0
	v_mfma_f32_16x16x32_bf16 v[120:123], v[164:167], v[192:195], v[120:123]
	v_mfma_f32_16x16x32_bf16 v[116:119], v[152:155], v[196:199], 0
	v_mfma_f32_16x16x32_bf16 v[116:119], v[156:159], v[200:203], v[116:119]
	v_mfma_f32_16x16x32_bf16 v[108:111], v[160:163], v[196:199], 0
	v_mfma_f32_16x16x32_bf16 v[108:111], v[164:167], v[200:203], v[108:111]
	v_mfma_f32_16x16x32_bf16 v[100:103], v[152:155], v[204:207], 0
	v_mfma_f32_16x16x32_bf16 v[100:103], v[156:159], v[208:211], v[100:103]
	v_mfma_f32_16x16x32_bf16 v[92:95], v[160:163], v[204:207], 0
	v_mfma_f32_16x16x32_bf16 v[92:95], v[164:167], v[208:211], v[92:95]
	v_mfma_f32_16x16x32_bf16 v[84:87], v[152:155], v[212:215], 0
	v_mfma_f32_16x16x32_bf16 v[84:87], v[156:159], v[216:219], v[84:87]
	v_mfma_f32_16x16x32_bf16 v[76:79], v[160:163], v[212:215], 0
	v_mfma_f32_16x16x32_bf16 v[76:79], v[164:167], v[216:219], v[76:79]
	v_mfma_f32_16x16x32_bf16 v[112:115], v[168:171], v[188:191], 0
	v_mfma_f32_16x16x32_bf16 v[112:115], v[172:175], v[192:195], v[112:115]
	v_mfma_f32_16x16x32_bf16 v[104:107], v[176:179], v[188:191], 0
	v_mfma_f32_16x16x32_bf16 v[104:107], v[184:187], v[192:195], v[104:107]
	v_mfma_f32_16x16x32_bf16 v[96:99], v[168:171], v[196:199], 0
	v_mfma_f32_16x16x32_bf16 v[96:99], v[172:175], v[200:203], v[96:99]
	v_mfma_f32_16x16x32_bf16 v[88:91], v[176:179], v[196:199], 0
	v_mfma_f32_16x16x32_bf16 v[88:91], v[184:187], v[200:203], v[88:91]
	v_mfma_f32_16x16x32_bf16 v[80:83], v[168:171], v[204:207], 0
	v_mfma_f32_16x16x32_bf16 v[80:83], v[172:175], v[208:211], v[80:83]
	v_mfma_f32_16x16x32_bf16 v[72:75], v[176:179], v[204:207], 0
	v_mfma_f32_16x16x32_bf16 v[72:75], v[184:187], v[208:211], v[72:75]
	v_mfma_f32_16x16x32_bf16 v[68:71], v[168:171], v[212:215], 0
	v_mfma_f32_16x16x32_bf16 v[68:71], v[172:175], v[216:219], v[68:71]
	v_mfma_f32_16x16x32_bf16 v[64:67], v[176:179], v[212:215], 0
	v_mfma_f32_16x16x32_bf16 v[64:67], v[184:187], v[216:219], v[64:67]
	s_setprio 0
	s_barrier
	ds_read_b128 v[188:191], v151 offset:16384
	ds_read_b128 v[192:195], v151 offset:17408
	ds_read_b128 v[196:199], v151 offset:18432
	ds_read_b128 v[200:203], v151 offset:19456
	ds_read_b128 v[204:207], v151 offset:20480
	ds_read_b128 v[208:211], v151 offset:21504
	ds_read_b128 v[212:215], v151 offset:22528
	ds_read_b128 v[216:219], v151 offset:23552
	s_add_i32 s52, s70, s62
	v_lshl_add_u64 v[144:145], s[56:57], 0, v[130:131]
	s_mov_b32 m0, s52
	s_nop 0
	global_load_lds_dwordx4 v[144:145], off
	s_add_i32 m0, s52, 0x2000
	s_add_u32 s52, s56, 0xb0000
	v_lshl_add_u64 v[220:221], s[56:57], 0, v[134:135]
	s_addc_u32 s53, s57, 0
	s_add_i32 s79, s71, s62
	global_load_lds_dwordx4 v[220:221], off
	v_lshl_add_u64 v[222:223], s[52:53], 0, v[130:131]
	s_mov_b32 m0, s79
	v_lshl_add_u64 v[224:225], s[58:59], 0, v[132:133]
	global_load_lds_dwordx4 v[222:223], off
	v_lshl_add_u64 v[222:223], s[52:53], 0, v[134:135]
	s_add_i32 m0, s79, 0x2000
	s_nop 0
	global_load_lds_dwordx4 v[222:223], off
	v_lshl_add_u64 v[222:223], s[58:59], 0, v[128:129]
	s_mov_b32 m0, s63
	s_nop 0
	global_load_lds_dwordx4 v[222:223], off
	s_mov_b32 m0, s64
	s_nop 0
	global_load_lds_dwordx4 v[224:225], off
	s_waitcnt vmcnt(8)
	s_waitcnt lgkmcnt(0)
	s_barrier
	s_setprio 1
	s_waitcnt lgkmcnt(0)
	v_mfma_f32_16x16x32_bf16 v[60:63], v[152:155], v[188:191], 0
	v_mfma_f32_16x16x32_bf16 v[60:63], v[156:159], v[192:195], v[60:63]
	v_mfma_f32_16x16x32_bf16 v[56:59], v[160:163], v[188:191], 0
	v_mfma_f32_16x16x32_bf16 v[56:59], v[164:167], v[192:195], v[56:59]
	v_mfma_f32_16x16x32_bf16 v[52:55], v[152:155], v[196:199], 0
	v_mfma_f32_16x16x32_bf16 v[52:55], v[156:159], v[200:203], v[52:55]
	v_mfma_f32_16x16x32_bf16 v[44:47], v[160:163], v[196:199], 0
	v_mfma_f32_16x16x32_bf16 v[44:47], v[164:167], v[200:203], v[44:47]
	v_mfma_f32_16x16x32_bf16 v[36:39], v[152:155], v[204:207], 0
	v_mfma_f32_16x16x32_bf16 v[36:39], v[156:159], v[208:211], v[36:39]
	v_mfma_f32_16x16x32_bf16 v[28:31], v[160:163], v[204:207], 0
	v_mfma_f32_16x16x32_bf16 v[28:31], v[164:167], v[208:211], v[28:31]
	v_mfma_f32_16x16x32_bf16 v[20:23], v[152:155], v[212:215], 0
	v_mfma_f32_16x16x32_bf16 v[20:23], v[156:159], v[216:219], v[20:23]
	v_mfma_f32_16x16x32_bf16 v[12:15], v[160:163], v[212:215], 0
	v_mfma_f32_16x16x32_bf16 v[12:15], v[164:167], v[216:219], v[12:15]
	v_mfma_f32_16x16x32_bf16 v[48:51], v[168:171], v[188:191], 0
	v_mfma_f32_16x16x32_bf16 v[48:51], v[172:175], v[192:195], v[48:51]
	v_mfma_f32_16x16x32_bf16 v[40:43], v[176:179], v[188:191], 0
	v_mfma_f32_16x16x32_bf16 v[40:43], v[184:187], v[192:195], v[40:43]
	v_mfma_f32_16x16x32_bf16 v[32:35], v[168:171], v[196:199], 0
	v_mfma_f32_16x16x32_bf16 v[32:35], v[172:175], v[200:203], v[32:35]
	v_mfma_f32_16x16x32_bf16 v[24:27], v[176:179], v[196:199], 0
	v_mfma_f32_16x16x32_bf16 v[24:27], v[184:187], v[200:203], v[24:27]
	v_mfma_f32_16x16x32_bf16 v[16:19], v[168:171], v[204:207], 0
	v_mfma_f32_16x16x32_bf16 v[16:19], v[172:175], v[208:211], v[16:19]
	v_mfma_f32_16x16x32_bf16 v[8:11], v[176:179], v[204:207], 0
	v_mfma_f32_16x16x32_bf16 v[8:11], v[184:187], v[208:211], v[8:11]
	v_mfma_f32_16x16x32_bf16 v[4:7], v[168:171], v[212:215], 0
	v_mfma_f32_16x16x32_bf16 v[4:7], v[172:175], v[216:219], v[4:7]
	v_mfma_f32_16x16x32_bf16 v[0:3], v[176:179], v[212:215], 0
	v_mfma_f32_16x16x32_bf16 v[0:3], v[184:187], v[216:219], v[0:3]
	s_setprio 0
	s_barrier
	s_branch .Lmid_gemm5
.LBB0_804:
	ds_read_b128 v[152:155], v149
	ds_read_b128 v[156:159], v149 offset:1024
	ds_read_b128 v[160:163], v149 offset:2048
	ds_read_b128 v[164:167], v149 offset:3072
	ds_read_b128 v[168:171], v150
	ds_read_b128 v[172:175], v150 offset:1024
	ds_read_b128 v[176:179], v150 offset:2048
	ds_read_b128 v[184:187], v150 offset:3072
	ds_read_b128 v[188:191], v151
	ds_read_b128 v[192:195], v151 offset:1024
	ds_read_b128 v[196:199], v151 offset:2048
	ds_read_b128 v[200:203], v151 offset:3072
	ds_read_b128 v[204:207], v151 offset:4096
	ds_read_b128 v[208:211], v151 offset:5120
	ds_read_b128 v[212:215], v151 offset:6144
	ds_read_b128 v[216:219], v151 offset:7168
	s_add_u32 s54, s52, 0x100
	s_addc_u32 s55, s53, 0
	s_cmp_eq_u32 s86, 40
	s_cselect_b32 s59, s13, s55
	s_cselect_b32 s58, s12, s54
	s_cselect_b32 s57, s49, s85
	s_cselect_b32 s56, s48, s84
	v_lshl_add_u64 v[144:145], s[52:53], 0, v[136:137]
	s_add_i32 m0, s63, 0xc000
	s_nop 0
	global_load_lds_dwordx4 v[144:145], off
	v_lshl_add_u64 v[144:145], s[52:53], 0, v[138:139]
	s_add_i32 m0, s63, 0xe000
	s_nop 0
	global_load_lds_dwordx4 v[144:145], off
	s_waitcnt vmcnt(8)
	s_waitcnt lgkmcnt(0)
	s_barrier
	s_setprio 1
	s_waitcnt lgkmcnt(0)
	v_mfma_f32_16x16x32_bf16 v[124:127], v[152:155], v[188:191], v[124:127]
	v_mfma_f32_16x16x32_bf16 v[124:127], v[156:159], v[192:195], v[124:127]
	v_mfma_f32_16x16x32_bf16 v[120:123], v[160:163], v[188:191], v[120:123]
	v_mfma_f32_16x16x32_bf16 v[120:123], v[164:167], v[192:195], v[120:123]
	v_mfma_f32_16x16x32_bf16 v[116:119], v[152:155], v[196:199], v[116:119]
	v_mfma_f32_16x16x32_bf16 v[116:119], v[156:159], v[200:203], v[116:119]
	v_mfma_f32_16x16x32_bf16 v[108:111], v[160:163], v[196:199], v[108:111]
	v_mfma_f32_16x16x32_bf16 v[108:111], v[164:167], v[200:203], v[108:111]
	v_mfma_f32_16x16x32_bf16 v[100:103], v[152:155], v[204:207], v[100:103]
	v_mfma_f32_16x16x32_bf16 v[100:103], v[156:159], v[208:211], v[100:103]
	v_mfma_f32_16x16x32_bf16 v[92:95], v[160:163], v[204:207], v[92:95]
	v_mfma_f32_16x16x32_bf16 v[92:95], v[164:167], v[208:211], v[92:95]
	v_mfma_f32_16x16x32_bf16 v[84:87], v[152:155], v[212:215], v[84:87]
	v_mfma_f32_16x16x32_bf16 v[84:87], v[156:159], v[216:219], v[84:87]
	v_mfma_f32_16x16x32_bf16 v[76:79], v[160:163], v[212:215], v[76:79]
	v_mfma_f32_16x16x32_bf16 v[76:79], v[164:167], v[216:219], v[76:79]
	v_mfma_f32_16x16x32_bf16 v[112:115], v[168:171], v[188:191], v[112:115]
	v_mfma_f32_16x16x32_bf16 v[112:115], v[172:175], v[192:195], v[112:115]
	v_mfma_f32_16x16x32_bf16 v[104:107], v[176:179], v[188:191], v[104:107]
	v_mfma_f32_16x16x32_bf16 v[104:107], v[184:187], v[192:195], v[104:107]
	v_mfma_f32_16x16x32_bf16 v[96:99], v[168:171], v[196:199], v[96:99]
	v_mfma_f32_16x16x32_bf16 v[96:99], v[172:175], v[200:203], v[96:99]
	v_mfma_f32_16x16x32_bf16 v[88:91], v[176:179], v[196:199], v[88:91]
	v_mfma_f32_16x16x32_bf16 v[88:91], v[184:187], v[200:203], v[88:91]
	v_mfma_f32_16x16x32_bf16 v[80:83], v[168:171], v[204:207], v[80:83]
	v_mfma_f32_16x16x32_bf16 v[80:83], v[172:175], v[208:211], v[80:83]
	v_mfma_f32_16x16x32_bf16 v[72:75], v[176:179], v[204:207], v[72:75]
	v_mfma_f32_16x16x32_bf16 v[72:75], v[184:187], v[208:211], v[72:75]
	v_mfma_f32_16x16x32_bf16 v[68:71], v[168:171], v[212:215], v[68:71]
	v_mfma_f32_16x16x32_bf16 v[68:71], v[172:175], v[216:219], v[68:71]
	v_mfma_f32_16x16x32_bf16 v[64:67], v[176:179], v[212:215], v[64:67]
	v_mfma_f32_16x16x32_bf16 v[64:67], v[184:187], v[216:219], v[64:67]
	s_setprio 0
	s_barrier
	ds_read_b128 v[188:191], v151 offset:16384
	ds_read_b128 v[192:195], v151 offset:17408
	ds_read_b128 v[196:199], v151 offset:18432
	ds_read_b128 v[200:203], v151 offset:19456
	ds_read_b128 v[204:207], v151 offset:20480
	ds_read_b128 v[208:211], v151 offset:21504
	ds_read_b128 v[212:215], v151 offset:22528
	ds_read_b128 v[216:219], v151 offset:23552
	s_add_i32 s52, s70, s62
	v_lshl_add_u64 v[144:145], s[56:57], 0, v[130:131]
	s_mov_b32 m0, s52
	s_nop 0
	global_load_lds_dwordx4 v[144:145], off
	s_add_i32 m0, s52, 0x2000
	s_add_u32 s52, s56, 0xb0000
	v_lshl_add_u64 v[220:221], s[56:57], 0, v[134:135]
	s_addc_u32 s53, s57, 0
	s_add_i32 s79, s71, s62
	global_load_lds_dwordx4 v[220:221], off
	v_lshl_add_u64 v[222:223], s[52:53], 0, v[130:131]
	s_mov_b32 m0, s79
	v_lshl_add_u64 v[224:225], s[58:59], 0, v[132:133]
	global_load_lds_dwordx4 v[222:223], off
	v_lshl_add_u64 v[222:223], s[52:53], 0, v[134:135]
	s_add_i32 m0, s79, 0x2000
	s_nop 0
	global_load_lds_dwordx4 v[222:223], off
	v_lshl_add_u64 v[222:223], s[58:59], 0, v[128:129]
	s_mov_b32 m0, s63
	s_nop 0
	global_load_lds_dwordx4 v[222:223], off
	s_mov_b32 m0, s64
	s_nop 0
	global_load_lds_dwordx4 v[224:225], off
	s_waitcnt vmcnt(8)
	s_waitcnt lgkmcnt(0)
	s_barrier
	s_setprio 1
	s_waitcnt lgkmcnt(0)
	v_mfma_f32_16x16x32_bf16 v[60:63], v[152:155], v[188:191], v[60:63]
	v_mfma_f32_16x16x32_bf16 v[60:63], v[156:159], v[192:195], v[60:63]
	v_mfma_f32_16x16x32_bf16 v[56:59], v[160:163], v[188:191], v[56:59]
	v_mfma_f32_16x16x32_bf16 v[56:59], v[164:167], v[192:195], v[56:59]
	v_mfma_f32_16x16x32_bf16 v[52:55], v[152:155], v[196:199], v[52:55]
	v_mfma_f32_16x16x32_bf16 v[52:55], v[156:159], v[200:203], v[52:55]
	v_mfma_f32_16x16x32_bf16 v[44:47], v[160:163], v[196:199], v[44:47]
	v_mfma_f32_16x16x32_bf16 v[44:47], v[164:167], v[200:203], v[44:47]
	v_mfma_f32_16x16x32_bf16 v[36:39], v[152:155], v[204:207], v[36:39]
	v_mfma_f32_16x16x32_bf16 v[36:39], v[156:159], v[208:211], v[36:39]
	v_mfma_f32_16x16x32_bf16 v[28:31], v[160:163], v[204:207], v[28:31]
	v_mfma_f32_16x16x32_bf16 v[28:31], v[164:167], v[208:211], v[28:31]
	v_mfma_f32_16x16x32_bf16 v[20:23], v[152:155], v[212:215], v[20:23]
	v_mfma_f32_16x16x32_bf16 v[20:23], v[156:159], v[216:219], v[20:23]
	v_mfma_f32_16x16x32_bf16 v[12:15], v[160:163], v[212:215], v[12:15]
	v_mfma_f32_16x16x32_bf16 v[12:15], v[164:167], v[216:219], v[12:15]
	v_mfma_f32_16x16x32_bf16 v[48:51], v[168:171], v[188:191], v[48:51]
	v_mfma_f32_16x16x32_bf16 v[48:51], v[172:175], v[192:195], v[48:51]
	v_mfma_f32_16x16x32_bf16 v[40:43], v[176:179], v[188:191], v[40:43]
	v_mfma_f32_16x16x32_bf16 v[40:43], v[184:187], v[192:195], v[40:43]
	v_mfma_f32_16x16x32_bf16 v[32:35], v[168:171], v[196:199], v[32:35]
	v_mfma_f32_16x16x32_bf16 v[32:35], v[172:175], v[200:203], v[32:35]
	v_mfma_f32_16x16x32_bf16 v[24:27], v[176:179], v[196:199], v[24:27]
	v_mfma_f32_16x16x32_bf16 v[24:27], v[184:187], v[200:203], v[24:27]
	v_mfma_f32_16x16x32_bf16 v[16:19], v[168:171], v[204:207], v[16:19]
	v_mfma_f32_16x16x32_bf16 v[16:19], v[172:175], v[208:211], v[16:19]
	v_mfma_f32_16x16x32_bf16 v[8:11], v[176:179], v[204:207], v[8:11]
	v_mfma_f32_16x16x32_bf16 v[8:11], v[184:187], v[208:211], v[8:11]
	v_mfma_f32_16x16x32_bf16 v[4:7], v[168:171], v[212:215], v[4:7]
	v_mfma_f32_16x16x32_bf16 v[4:7], v[172:175], v[216:219], v[4:7]
	v_mfma_f32_16x16x32_bf16 v[0:3], v[176:179], v[212:215], v[0:3]
	v_mfma_f32_16x16x32_bf16 v[0:3], v[184:187], v[216:219], v[0:3]
	s_setprio 0
	s_barrier
.Lmid_gemm5:
	s_add_i32 s79, 0, 0x18000
	s_add_i32 s87, 0, 0x1c000
	v_add_u32_e32 v164, s79, v147
	v_add_u32_e32 v181, s87, v147
	ds_read_b128 v[152:155], v164
	ds_read_b128 v[156:159], v164 offset:1024
	ds_read_b128 v[160:163], v164 offset:2048
	ds_read_b128 v[164:167], v164 offset:3072
	ds_read_b128 v[168:171], v181
	ds_read_b128 v[172:175], v181 offset:1024
	ds_read_b128 v[176:179], v181 offset:2048
	ds_read_b128 v[184:187], v181 offset:3072
	ds_read_b128 v[188:191], v151 offset:32768
	ds_read_b128 v[192:195], v151 offset:33792
	ds_read_b128 v[196:199], v151 offset:34816
	ds_read_b128 v[200:203], v151 offset:35840
	ds_read_b128 v[204:207], v151 offset:36864
	ds_read_b128 v[208:211], v151 offset:37888
	ds_read_b128 v[212:215], v151 offset:38912
	ds_read_b128 v[216:219], v151 offset:39936
	s_add_u32 s52, s58, 0xb0000
	s_addc_u32 s53, s59, 0
	s_mov_b32 m0, s65
	v_lshl_add_u64 v[226:227], s[52:53], 0, v[128:129]
	global_load_lds_dwordx4 v[226:227], off
	v_lshl_add_u64 v[226:227], s[52:53], 0, v[132:133]
	s_mov_b32 m0, s66
	s_nop 0
	global_load_lds_dwordx4 v[226:227], off
	s_waitcnt vmcnt(8)
	s_waitcnt lgkmcnt(0)
	s_barrier
	s_setprio 1
	s_waitcnt lgkmcnt(0)
	v_mfma_f32_16x16x32_bf16 v[124:127], v[152:155], v[188:191], v[124:127]
	v_mfma_f32_16x16x32_bf16 v[124:127], v[156:159], v[192:195], v[124:127]
	v_mfma_f32_16x16x32_bf16 v[120:123], v[160:163], v[188:191], v[120:123]
	v_mfma_f32_16x16x32_bf16 v[120:123], v[164:167], v[192:195], v[120:123]
	v_mfma_f32_16x16x32_bf16 v[116:119], v[152:155], v[196:199], v[116:119]
	v_mfma_f32_16x16x32_bf16 v[116:119], v[156:159], v[200:203], v[116:119]
	v_mfma_f32_16x16x32_bf16 v[108:111], v[160:163], v[196:199], v[108:111]
	v_mfma_f32_16x16x32_bf16 v[108:111], v[164:167], v[200:203], v[108:111]
	v_mfma_f32_16x16x32_bf16 v[100:103], v[152:155], v[204:207], v[100:103]
	v_mfma_f32_16x16x32_bf16 v[100:103], v[156:159], v[208:211], v[100:103]
	v_mfma_f32_16x16x32_bf16 v[92:95], v[160:163], v[204:207], v[92:95]
	v_mfma_f32_16x16x32_bf16 v[92:95], v[164:167], v[208:211], v[92:95]
	v_mfma_f32_16x16x32_bf16 v[84:87], v[152:155], v[212:215], v[84:87]
	v_mfma_f32_16x16x32_bf16 v[84:87], v[156:159], v[216:219], v[84:87]
	v_mfma_f32_16x16x32_bf16 v[76:79], v[160:163], v[212:215], v[76:79]
	v_mfma_f32_16x16x32_bf16 v[76:79], v[164:167], v[216:219], v[76:79]
	v_mfma_f32_16x16x32_bf16 v[112:115], v[168:171], v[188:191], v[112:115]
	v_mfma_f32_16x16x32_bf16 v[112:115], v[172:175], v[192:195], v[112:115]
	v_mfma_f32_16x16x32_bf16 v[104:107], v[176:179], v[188:191], v[104:107]
	v_mfma_f32_16x16x32_bf16 v[104:107], v[184:187], v[192:195], v[104:107]
	v_mfma_f32_16x16x32_bf16 v[96:99], v[168:171], v[196:199], v[96:99]
	v_mfma_f32_16x16x32_bf16 v[96:99], v[172:175], v[200:203], v[96:99]
	v_mfma_f32_16x16x32_bf16 v[88:91], v[176:179], v[196:199], v[88:91]
	v_mfma_f32_16x16x32_bf16 v[88:91], v[184:187], v[200:203], v[88:91]
	v_mfma_f32_16x16x32_bf16 v[80:83], v[168:171], v[204:207], v[80:83]
	v_mfma_f32_16x16x32_bf16 v[80:83], v[172:175], v[208:211], v[80:83]
	v_mfma_f32_16x16x32_bf16 v[72:75], v[176:179], v[204:207], v[72:75]
	v_mfma_f32_16x16x32_bf16 v[72:75], v[184:187], v[208:211], v[72:75]
	v_mfma_f32_16x16x32_bf16 v[68:71], v[168:171], v[212:215], v[68:71]
	v_mfma_f32_16x16x32_bf16 v[68:71], v[172:175], v[216:219], v[68:71]
	v_mfma_f32_16x16x32_bf16 v[64:67], v[176:179], v[212:215], v[64:67]
	v_mfma_f32_16x16x32_bf16 v[64:67], v[184:187], v[216:219], v[64:67]
	s_setprio 0
	s_barrier
	ds_read_b128 v[188:191], v151 offset:49152
	ds_read_b128 v[192:195], v151 offset:50176
	ds_read_b128 v[196:199], v151 offset:51200
	ds_read_b128 v[200:203], v151 offset:52224
	ds_read_b128 v[204:207], v151 offset:53248
	ds_read_b128 v[208:211], v151 offset:54272
	ds_read_b128 v[212:215], v151 offset:55296
	ds_read_b128 v[216:219], v151 offset:56320
	s_add_i32 s52, s79, s62
	v_lshl_add_u64 v[144:145], v[144:145], 0, s[16:17]
	s_mov_b32 m0, s52
	s_nop 0
	global_load_lds_dwordx4 v[144:145], off
	s_add_i32 m0, s52, 0x2000
	s_add_u32 s52, s56, 0xb0080
	v_lshl_add_u64 v[144:145], v[220:221], 0, s[16:17]
	s_addc_u32 s53, s57, 0
	s_add_i32 s56, s87, s62
	global_load_lds_dwordx4 v[144:145], off
	v_lshl_add_u64 v[144:145], s[52:53], 0, v[130:131]
	s_mov_b32 m0, s56
	s_nop 0
	global_load_lds_dwordx4 v[144:145], off
	v_lshl_add_u64 v[144:145], s[52:53], 0, v[134:135]
	s_add_i32 m0, s56, 0x2000
	s_nop 0
	global_load_lds_dwordx4 v[144:145], off
	v_lshl_add_u64 v[144:145], v[222:223], 0, s[16:17]
	s_mov_b32 m0, s68
	s_nop 0
	global_load_lds_dwordx4 v[144:145], off
	v_lshl_add_u64 v[144:145], v[224:225], 0, s[16:17]
	s_mov_b32 m0, s69
	s_nop 0
	global_load_lds_dwordx4 v[144:145], off
	s_waitcnt vmcnt(8)
	s_waitcnt lgkmcnt(0)
	s_barrier
	s_setprio 1
	s_waitcnt lgkmcnt(0)
	v_mfma_f32_16x16x32_bf16 v[60:63], v[152:155], v[188:191], v[60:63]
	v_mfma_f32_16x16x32_bf16 v[60:63], v[156:159], v[192:195], v[60:63]
	v_mfma_f32_16x16x32_bf16 v[56:59], v[160:163], v[188:191], v[56:59]
	v_mfma_f32_16x16x32_bf16 v[56:59], v[164:167], v[192:195], v[56:59]
	v_mfma_f32_16x16x32_bf16 v[52:55], v[152:155], v[196:199], v[52:55]
	v_mfma_f32_16x16x32_bf16 v[52:55], v[156:159], v[200:203], v[52:55]
	v_mfma_f32_16x16x32_bf16 v[44:47], v[160:163], v[196:199], v[44:47]
	v_mfma_f32_16x16x32_bf16 v[44:47], v[164:167], v[200:203], v[44:47]
	v_mfma_f32_16x16x32_bf16 v[36:39], v[152:155], v[204:207], v[36:39]
	v_mfma_f32_16x16x32_bf16 v[36:39], v[156:159], v[208:211], v[36:39]
	v_mfma_f32_16x16x32_bf16 v[28:31], v[160:163], v[204:207], v[28:31]
	v_mfma_f32_16x16x32_bf16 v[28:31], v[164:167], v[208:211], v[28:31]
	v_mfma_f32_16x16x32_bf16 v[20:23], v[152:155], v[212:215], v[20:23]
	v_mfma_f32_16x16x32_bf16 v[20:23], v[156:159], v[216:219], v[20:23]
	v_mfma_f32_16x16x32_bf16 v[12:15], v[160:163], v[212:215], v[12:15]
	v_mfma_f32_16x16x32_bf16 v[12:15], v[164:167], v[216:219], v[12:15]
	v_mfma_f32_16x16x32_bf16 v[48:51], v[168:171], v[188:191], v[48:51]
	v_mfma_f32_16x16x32_bf16 v[48:51], v[172:175], v[192:195], v[48:51]
	v_mfma_f32_16x16x32_bf16 v[40:43], v[176:179], v[188:191], v[40:43]
	v_mfma_f32_16x16x32_bf16 v[40:43], v[184:187], v[192:195], v[40:43]
	v_mfma_f32_16x16x32_bf16 v[32:35], v[168:171], v[196:199], v[32:35]
	v_mfma_f32_16x16x32_bf16 v[32:35], v[172:175], v[200:203], v[32:35]
	v_mfma_f32_16x16x32_bf16 v[24:27], v[176:179], v[196:199], v[24:27]
	v_mfma_f32_16x16x32_bf16 v[24:27], v[184:187], v[200:203], v[24:27]
	v_mfma_f32_16x16x32_bf16 v[16:19], v[168:171], v[204:207], v[16:19]
	v_mfma_f32_16x16x32_bf16 v[16:19], v[172:175], v[208:211], v[16:19]
	v_mfma_f32_16x16x32_bf16 v[8:11], v[176:179], v[204:207], v[8:11]
	v_mfma_f32_16x16x32_bf16 v[8:11], v[184:187], v[208:211], v[8:11]
	v_mfma_f32_16x16x32_bf16 v[4:7], v[168:171], v[212:215], v[4:7]
	v_mfma_f32_16x16x32_bf16 v[4:7], v[172:175], v[216:219], v[4:7]
	v_mfma_f32_16x16x32_bf16 v[0:3], v[176:179], v[212:215], v[0:3]
	v_mfma_f32_16x16x32_bf16 v[0:3], v[184:187], v[216:219], v[0:3]
	s_setprio 0
	s_barrier
	s_add_i32 s86, s86, 2
	s_add_u32 s84, s84, 0x100
	s_addc_u32 s85, s85, 0
	s_cmp_gt_u32 s86, 41
	s_mov_b64 s[52:53], s[54:55]
	s_cbranch_scc0 .LBB0_804
	s_and_b64 vcc, exec, s[18:19]
	s_cbranch_vccz .LBB0_807
	s_barrier

.LBB0_934:
	s_ashr_i32 s53, s52, 31
	s_lshl_b64 s[54:55], s[52:53], 19
	s_add_u32 s54, s80, s54
	s_addc_u32 s55, s81, s55
	s_and_b64 s[56:57], s[10:11], exec
	s_cselect_b32 s53, s55, s61
	s_cselect_b32 s83, s54, s60
	s_ashr_i32 s49, s48, 31
	s_lshl_b64 s[56:57], s[48:49], 19
	s_add_u32 s56, s66, s56
	s_addc_u32 s57, s67, s57
	s_and_b64 s[64:65], s[10:11], exec
	s_cselect_b32 s49, s57, s63
	s_cselect_b32 s84, s56, s62
	s_add_u32 s60, s60, 0x40080
	s_addc_u32 s61, s61, 0
	s_add_u32 s85, s62, 0x100
	s_addc_u32 s86, s63, 0
	s_mov_b32 s87, -2
	ds_read_b128 v[152:155], v148
	ds_read_b128 v[156:159], v148 offset:1024
	ds_read_b128 v[160:163], v148 offset:2048
	ds_read_b128 v[164:167], v148 offset:3072
	ds_read_b128 v[168:171], v149
	ds_read_b128 v[172:175], v149 offset:1024
	ds_read_b128 v[176:179], v149 offset:2048
	ds_read_b128 v[184:187], v149 offset:3072
	s_add_u32 s62, s60, 0xfffc0080
	s_addc_u32 s63, s61, -1
	s_cmp_eq_u32 s87, 12
	s_cselect_b32 s65, s53, s63
	s_cselect_b32 s64, s83, s62
	s_cselect_b32 s63, s49, s86
	s_cselect_b32 s62, s84, s85
	v_lshl_add_u64 v[220:221], s[60:61], 0, v[138:139]
	s_add_i32 m0, s69, 0xc000
	ds_read_b128 v[188:191], v150
	ds_read_b128 v[192:195], v150 offset:1024
	ds_read_b128 v[196:199], v150 offset:2048
	ds_read_b128 v[200:203], v150 offset:3072
	ds_read_b128 v[204:207], v150 offset:4096
	ds_read_b128 v[208:211], v150 offset:5120
	ds_read_b128 v[212:215], v150 offset:6144
	ds_read_b128 v[216:219], v150 offset:7168
	global_load_lds_dwordx4 v[220:221], off
	v_lshl_add_u64 v[220:221], s[60:61], 0, v[140:141]
	s_add_i32 m0, s69, 0xe000
	s_nop 0
	global_load_lds_dwordx4 v[220:221], off
	s_waitcnt vmcnt(8)
	s_waitcnt lgkmcnt(0)
	s_barrier
	s_setprio 1
	s_waitcnt lgkmcnt(0)
	v_mfma_f32_16x16x32_bf16 v[124:127], v[152:155], v[188:191], 0
	v_mfma_f32_16x16x32_bf16 v[124:127], v[156:159], v[192:195], v[124:127]
	v_mfma_f32_16x16x32_bf16 v[120:123], v[160:163], v[188:191], 0
	v_mfma_f32_16x16x32_bf16 v[120:123], v[164:167], v[192:195], v[120:123]
	v_mfma_f32_16x16x32_bf16 v[116:119], v[152:155], v[196:199], 0
	v_mfma_f32_16x16x32_bf16 v[116:119], v[156:159], v[200:203], v[116:119]
	v_mfma_f32_16x16x32_bf16 v[112:115], v[160:163], v[196:199], 0
	v_mfma_f32_16x16x32_bf16 v[112:115], v[164:167], v[200:203], v[112:115]
	v_mfma_f32_16x16x32_bf16 v[108:111], v[152:155], v[204:207], 0
	v_mfma_f32_16x16x32_bf16 v[108:111], v[156:159], v[208:211], v[108:111]
	v_mfma_f32_16x16x32_bf16 v[104:107], v[160:163], v[204:207], 0
	v_mfma_f32_16x16x32_bf16 v[104:107], v[164:167], v[208:211], v[104:107]
	v_mfma_f32_16x16x32_bf16 v[100:103], v[152:155], v[212:215], 0
	v_mfma_f32_16x16x32_bf16 v[100:103], v[156:159], v[216:219], v[100:103]
	v_mfma_f32_16x16x32_bf16 v[96:99], v[160:163], v[212:215], 0
	v_mfma_f32_16x16x32_bf16 v[96:99], v[164:167], v[216:219], v[96:99]
	v_mfma_f32_16x16x32_bf16 v[76:79], v[168:171], v[188:191], 0
	v_mfma_f32_16x16x32_bf16 v[76:79], v[172:175], v[192:195], v[76:79]
	v_mfma_f32_16x16x32_bf16 v[68:71], v[176:179], v[188:191], 0
	v_mfma_f32_16x16x32_bf16 v[68:71], v[184:187], v[192:195], v[68:71]
	v_mfma_f32_16x16x32_bf16 v[60:63], v[168:171], v[196:199], 0
	v_mfma_f32_16x16x32_bf16 v[60:63], v[172:175], v[200:203], v[60:63]
	v_mfma_f32_16x16x32_bf16 v[52:55], v[176:179], v[196:199], 0
	v_mfma_f32_16x16x32_bf16 v[52:55], v[184:187], v[200:203], v[52:55]
	v_mfma_f32_16x16x32_bf16 v[44:47], v[168:171], v[204:207], 0
	v_mfma_f32_16x16x32_bf16 v[44:47], v[172:175], v[208:211], v[44:47]
	v_mfma_f32_16x16x32_bf16 v[40:43], v[176:179], v[204:207], 0
	v_mfma_f32_16x16x32_bf16 v[40:43], v[184:187], v[208:211], v[40:43]
	v_mfma_f32_16x16x32_bf16 v[36:39], v[168:171], v[212:215], 0
	v_mfma_f32_16x16x32_bf16 v[36:39], v[172:175], v[216:219], v[36:39]
	v_mfma_f32_16x16x32_bf16 v[32:35], v[176:179], v[212:215], 0
	v_mfma_f32_16x16x32_bf16 v[32:35], v[184:187], v[216:219], v[32:35]
	s_setprio 0
	s_barrier
	ds_read_b128 v[188:191], v150 offset:16384
	ds_read_b128 v[192:195], v150 offset:17408
	ds_read_b128 v[196:199], v150 offset:18432
	ds_read_b128 v[200:203], v150 offset:19456
	ds_read_b128 v[204:207], v150 offset:20480
	ds_read_b128 v[208:211], v150 offset:21504
	ds_read_b128 v[212:215], v150 offset:22528
	ds_read_b128 v[216:219], v150 offset:23552
	s_add_i32 s79, s77, s68
	v_lshl_add_u64 v[220:221], s[62:63], 0, v[130:131]
	s_mov_b32 m0, s79
	s_nop 0
	global_load_lds_dwordx4 v[220:221], off
	s_add_i32 m0, s79, 0x2000
	s_add_u32 s88, s62, 0x40000
	v_lshl_add_u64 v[222:223], s[62:63], 0, v[134:135]
	s_addc_u32 s89, s63, 0
	s_add_i32 s79, s82, s68
	global_load_lds_dwordx4 v[222:223], off
	v_lshl_add_u64 v[224:225], s[88:89], 0, v[130:131]
	s_mov_b32 m0, s79
	v_lshl_add_u64 v[226:227], s[64:65], 0, v[132:133]
	global_load_lds_dwordx4 v[224:225], off
	v_lshl_add_u64 v[224:225], s[88:89], 0, v[134:135]
	s_add_i32 m0, s79, 0x2000
	s_nop 0
	global_load_lds_dwordx4 v[224:225], off
	v_lshl_add_u64 v[224:225], s[64:65], 0, v[128:129]
	s_mov_b32 m0, s69
	s_nop 0
	global_load_lds_dwordx4 v[224:225], off
	s_mov_b32 m0, s70
	s_nop 0
	global_load_lds_dwordx4 v[226:227], off
	s_waitcnt vmcnt(8)
	s_waitcnt lgkmcnt(0)
	s_barrier
	s_setprio 1
	s_waitcnt lgkmcnt(0)
	v_mfma_f32_16x16x32_bf16 v[92:95], v[152:155], v[188:191], 0
	v_mfma_f32_16x16x32_bf16 v[92:95], v[156:159], v[192:195], v[92:95]
	v_mfma_f32_16x16x32_bf16 v[88:91], v[160:163], v[188:191], 0
	v_mfma_f32_16x16x32_bf16 v[88:91], v[164:167], v[192:195], v[88:91]
	v_mfma_f32_16x16x32_bf16 v[84:87], v[152:155], v[196:199], 0
	v_mfma_f32_16x16x32_bf16 v[84:87], v[156:159], v[200:203], v[84:87]
	v_mfma_f32_16x16x32_bf16 v[80:83], v[160:163], v[196:199], 0
	v_mfma_f32_16x16x32_bf16 v[80:83], v[164:167], v[200:203], v[80:83]
	v_mfma_f32_16x16x32_bf16 v[72:75], v[152:155], v[204:207], 0
	v_mfma_f32_16x16x32_bf16 v[72:75], v[156:159], v[208:211], v[72:75]
	v_mfma_f32_16x16x32_bf16 v[64:67], v[160:163], v[204:207], 0
	v_mfma_f32_16x16x32_bf16 v[64:67], v[164:167], v[208:211], v[64:67]
	v_mfma_f32_16x16x32_bf16 v[56:59], v[152:155], v[212:215], 0
	v_mfma_f32_16x16x32_bf16 v[56:59], v[156:159], v[216:219], v[56:59]
	v_mfma_f32_16x16x32_bf16 v[48:51], v[160:163], v[212:215], 0
	v_mfma_f32_16x16x32_bf16 v[48:51], v[164:167], v[216:219], v[48:51]
	v_mfma_f32_16x16x32_bf16 v[28:31], v[168:171], v[188:191], 0
	v_mfma_f32_16x16x32_bf16 v[28:31], v[172:175], v[192:195], v[28:31]
	v_mfma_f32_16x16x32_bf16 v[24:27], v[176:179], v[188:191], 0
	v_mfma_f32_16x16x32_bf16 v[24:27], v[184:187], v[192:195], v[24:27]
	v_mfma_f32_16x16x32_bf16 v[20:23], v[168:171], v[196:199], 0
	v_mfma_f32_16x16x32_bf16 v[20:23], v[172:175], v[200:203], v[20:23]
	v_mfma_f32_16x16x32_bf16 v[16:19], v[176:179], v[196:199], 0
	v_mfma_f32_16x16x32_bf16 v[16:19], v[184:187], v[200:203], v[16:19]
	v_mfma_f32_16x16x32_bf16 v[12:15], v[168:171], v[204:207], 0
	v_mfma_f32_16x16x32_bf16 v[12:15], v[172:175], v[208:211], v[12:15]
	v_mfma_f32_16x16x32_bf16 v[8:11], v[176:179], v[204:207], 0
	v_mfma_f32_16x16x32_bf16 v[8:11], v[184:187], v[208:211], v[8:11]
	v_mfma_f32_16x16x32_bf16 v[4:7], v[168:171], v[212:215], 0
	v_mfma_f32_16x16x32_bf16 v[4:7], v[172:175], v[216:219], v[4:7]
	v_mfma_f32_16x16x32_bf16 v[0:3], v[176:179], v[212:215], 0
	v_mfma_f32_16x16x32_bf16 v[0:3], v[184:187], v[216:219], v[0:3]
	s_setprio 0
	s_barrier
	s_branch .Lmid_gemm6
.LBB0_935:
	ds_read_b128 v[152:155], v148
	ds_read_b128 v[156:159], v148 offset:1024
	ds_read_b128 v[160:163], v148 offset:2048
	ds_read_b128 v[164:167], v148 offset:3072
	ds_read_b128 v[168:171], v149
	ds_read_b128 v[172:175], v149 offset:1024
	ds_read_b128 v[176:179], v149 offset:2048
	ds_read_b128 v[184:187], v149 offset:3072
	ds_read_b128 v[188:191], v150
	ds_read_b128 v[192:195], v150 offset:1024
	ds_read_b128 v[196:199], v150 offset:2048
	ds_read_b128 v[200:203], v150 offset:3072
	ds_read_b128 v[204:207], v150 offset:4096
	ds_read_b128 v[208:211], v150 offset:5120
	ds_read_b128 v[212:215], v150 offset:6144
	ds_read_b128 v[216:219], v150 offset:7168
	s_add_u32 s62, s60, 0xfffc0080
	s_addc_u32 s63, s61, -1
	s_cmp_eq_u32 s87, 12
	s_cselect_b32 s65, s53, s63
	s_cselect_b32 s64, s83, s62
	s_cselect_b32 s63, s49, s86
	s_cselect_b32 s62, s84, s85
	v_lshl_add_u64 v[220:221], s[60:61], 0, v[138:139]
	s_add_i32 m0, s69, 0xc000
	s_nop 0
	global_load_lds_dwordx4 v[220:221], off
	v_lshl_add_u64 v[220:221], s[60:61], 0, v[140:141]
	s_add_i32 m0, s69, 0xe000
	s_nop 0
	global_load_lds_dwordx4 v[220:221], off
	s_waitcnt vmcnt(8)
	s_waitcnt lgkmcnt(0)
	s_barrier
	s_setprio 1
	s_waitcnt lgkmcnt(0)
	v_mfma_f32_16x16x32_bf16 v[124:127], v[152:155], v[188:191], v[124:127]
	v_mfma_f32_16x16x32_bf16 v[124:127], v[156:159], v[192:195], v[124:127]
	v_mfma_f32_16x16x32_bf16 v[120:123], v[160:163], v[188:191], v[120:123]
	v_mfma_f32_16x16x32_bf16 v[120:123], v[164:167], v[192:195], v[120:123]
	v_mfma_f32_16x16x32_bf16 v[116:119], v[152:155], v[196:199], v[116:119]
	v_mfma_f32_16x16x32_bf16 v[116:119], v[156:159], v[200:203], v[116:119]
	v_mfma_f32_16x16x32_bf16 v[112:115], v[160:163], v[196:199], v[112:115]
	v_mfma_f32_16x16x32_bf16 v[112:115], v[164:167], v[200:203], v[112:115]
	v_mfma_f32_16x16x32_bf16 v[108:111], v[152:155], v[204:207], v[108:111]
	v_mfma_f32_16x16x32_bf16 v[108:111], v[156:159], v[208:211], v[108:111]
	v_mfma_f32_16x16x32_bf16 v[104:107], v[160:163], v[204:207], v[104:107]
	v_mfma_f32_16x16x32_bf16 v[104:107], v[164:167], v[208:211], v[104:107]
	v_mfma_f32_16x16x32_bf16 v[100:103], v[152:155], v[212:215], v[100:103]
	v_mfma_f32_16x16x32_bf16 v[100:103], v[156:159], v[216:219], v[100:103]
	v_mfma_f32_16x16x32_bf16 v[96:99], v[160:163], v[212:215], v[96:99]
	v_mfma_f32_16x16x32_bf16 v[96:99], v[164:167], v[216:219], v[96:99]
	v_mfma_f32_16x16x32_bf16 v[76:79], v[168:171], v[188:191], v[76:79]
	v_mfma_f32_16x16x32_bf16 v[76:79], v[172:175], v[192:195], v[76:79]
	v_mfma_f32_16x16x32_bf16 v[68:71], v[176:179], v[188:191], v[68:71]
	v_mfma_f32_16x16x32_bf16 v[68:71], v[184:187], v[192:195], v[68:71]
	v_mfma_f32_16x16x32_bf16 v[60:63], v[168:171], v[196:199], v[60:63]
	v_mfma_f32_16x16x32_bf16 v[60:63], v[172:175], v[200:203], v[60:63]
	v_mfma_f32_16x16x32_bf16 v[52:55], v[176:179], v[196:199], v[52:55]
	v_mfma_f32_16x16x32_bf16 v[52:55], v[184:187], v[200:203], v[52:55]
	v_mfma_f32_16x16x32_bf16 v[44:47], v[168:171], v[204:207], v[44:47]
	v_mfma_f32_16x16x32_bf16 v[44:47], v[172:175], v[208:211], v[44:47]
	v_mfma_f32_16x16x32_bf16 v[40:43], v[176:179], v[204:207], v[40:43]
	v_mfma_f32_16x16x32_bf16 v[40:43], v[184:187], v[208:211], v[40:43]
	v_mfma_f32_16x16x32_bf16 v[36:39], v[168:171], v[212:215], v[36:39]
	v_mfma_f32_16x16x32_bf16 v[36:39], v[172:175], v[216:219], v[36:39]
	v_mfma_f32_16x16x32_bf16 v[32:35], v[176:179], v[212:215], v[32:35]
	v_mfma_f32_16x16x32_bf16 v[32:35], v[184:187], v[216:219], v[32:35]
	s_setprio 0
	s_barrier
	ds_read_b128 v[188:191], v150 offset:16384
	ds_read_b128 v[192:195], v150 offset:17408
	ds_read_b128 v[196:199], v150 offset:18432
	ds_read_b128 v[200:203], v150 offset:19456
	ds_read_b128 v[204:207], v150 offset:20480
	ds_read_b128 v[208:211], v150 offset:21504
	ds_read_b128 v[212:215], v150 offset:22528
	ds_read_b128 v[216:219], v150 offset:23552
	s_add_i32 s79, s77, s68
	v_lshl_add_u64 v[220:221], s[62:63], 0, v[130:131]
	s_mov_b32 m0, s79
	s_nop 0
	global_load_lds_dwordx4 v[220:221], off
	s_add_i32 m0, s79, 0x2000
	s_add_u32 s88, s62, 0x40000
	v_lshl_add_u64 v[222:223], s[62:63], 0, v[134:135]
	s_addc_u32 s89, s63, 0
	s_add_i32 s79, s82, s68
	global_load_lds_dwordx4 v[222:223], off
	v_lshl_add_u64 v[224:225], s[88:89], 0, v[130:131]
	s_mov_b32 m0, s79
	v_lshl_add_u64 v[226:227], s[64:65], 0, v[132:133]
	global_load_lds_dwordx4 v[224:225], off
	v_lshl_add_u64 v[224:225], s[88:89], 0, v[134:135]
	s_add_i32 m0, s79, 0x2000
	s_nop 0
	global_load_lds_dwordx4 v[224:225], off
	v_lshl_add_u64 v[224:225], s[64:65], 0, v[128:129]
	s_mov_b32 m0, s69
	s_nop 0
	global_load_lds_dwordx4 v[224:225], off
	s_mov_b32 m0, s70
	s_nop 0
	global_load_lds_dwordx4 v[226:227], off
	s_waitcnt vmcnt(8)
	s_waitcnt lgkmcnt(0)
	s_barrier
	s_setprio 1
	s_waitcnt lgkmcnt(0)
	v_mfma_f32_16x16x32_bf16 v[92:95], v[152:155], v[188:191], v[92:95]
	v_mfma_f32_16x16x32_bf16 v[92:95], v[156:159], v[192:195], v[92:95]
	v_mfma_f32_16x16x32_bf16 v[88:91], v[160:163], v[188:191], v[88:91]
	v_mfma_f32_16x16x32_bf16 v[88:91], v[164:167], v[192:195], v[88:91]
	v_mfma_f32_16x16x32_bf16 v[84:87], v[152:155], v[196:199], v[84:87]
	v_mfma_f32_16x16x32_bf16 v[84:87], v[156:159], v[200:203], v[84:87]
	v_mfma_f32_16x16x32_bf16 v[80:83], v[160:163], v[196:199], v[80:83]
	v_mfma_f32_16x16x32_bf16 v[80:83], v[164:167], v[200:203], v[80:83]
	v_mfma_f32_16x16x32_bf16 v[72:75], v[152:155], v[204:207], v[72:75]
	v_mfma_f32_16x16x32_bf16 v[72:75], v[156:159], v[208:211], v[72:75]
	v_mfma_f32_16x16x32_bf16 v[64:67], v[160:163], v[204:207], v[64:67]
	v_mfma_f32_16x16x32_bf16 v[64:67], v[164:167], v[208:211], v[64:67]
	v_mfma_f32_16x16x32_bf16 v[56:59], v[152:155], v[212:215], v[56:59]
	v_mfma_f32_16x16x32_bf16 v[56:59], v[156:159], v[216:219], v[56:59]
	v_mfma_f32_16x16x32_bf16 v[48:51], v[160:163], v[212:215], v[48:51]
	v_mfma_f32_16x16x32_bf16 v[48:51], v[164:167], v[216:219], v[48:51]
	v_mfma_f32_16x16x32_bf16 v[28:31], v[168:171], v[188:191], v[28:31]
	v_mfma_f32_16x16x32_bf16 v[28:31], v[172:175], v[192:195], v[28:31]
	v_mfma_f32_16x16x32_bf16 v[24:27], v[176:179], v[188:191], v[24:27]
	v_mfma_f32_16x16x32_bf16 v[24:27], v[184:187], v[192:195], v[24:27]
	v_mfma_f32_16x16x32_bf16 v[20:23], v[168:171], v[196:199], v[20:23]
	v_mfma_f32_16x16x32_bf16 v[20:23], v[172:175], v[200:203], v[20:23]
	v_mfma_f32_16x16x32_bf16 v[16:19], v[176:179], v[196:199], v[16:19]
	v_mfma_f32_16x16x32_bf16 v[16:19], v[184:187], v[200:203], v[16:19]
	v_mfma_f32_16x16x32_bf16 v[12:15], v[168:171], v[204:207], v[12:15]
	v_mfma_f32_16x16x32_bf16 v[12:15], v[172:175], v[208:211], v[12:15]
	v_mfma_f32_16x16x32_bf16 v[8:11], v[176:179], v[204:207], v[8:11]
	v_mfma_f32_16x16x32_bf16 v[8:11], v[184:187], v[208:211], v[8:11]
	v_mfma_f32_16x16x32_bf16 v[4:7], v[168:171], v[212:215], v[4:7]
	v_mfma_f32_16x16x32_bf16 v[4:7], v[172:175], v[216:219], v[4:7]
	v_mfma_f32_16x16x32_bf16 v[0:3], v[176:179], v[212:215], v[0:3]
	v_mfma_f32_16x16x32_bf16 v[0:3], v[184:187], v[216:219], v[0:3]
	s_setprio 0
	s_barrier
.Lmid_gemm6:
	s_add_i32 s79, 0, 0x18000
	v_add_u32_e32 v151, s79, v147
	s_add_i32 s88, 0, 0x1c000
	ds_read_b128 v[152:155], v151
	ds_read_b128 v[156:159], v151 offset:1024
	ds_read_b128 v[160:163], v151 offset:2048
	ds_read_b128 v[164:167], v151 offset:3072
	v_add_u32_e32 v151, s88, v147
	ds_read_b128 v[168:171], v151
	ds_read_b128 v[172:175], v151 offset:1024
	ds_read_b128 v[176:179], v151 offset:2048
	ds_read_b128 v[184:187], v151 offset:3072
	s_add_u32 s64, s64, 0x40000
	s_addc_u32 s65, s65, 0
	s_mov_b32 m0, s71
	v_lshl_add_u64 v[228:229], s[64:65], 0, v[128:129]
	ds_read_b128 v[188:191], v150 offset:32768
	ds_read_b128 v[192:195], v150 offset:33792
	ds_read_b128 v[196:199], v150 offset:34816
	ds_read_b128 v[200:203], v150 offset:35840
	ds_read_b128 v[204:207], v150 offset:36864
	ds_read_b128 v[208:211], v150 offset:37888
	ds_read_b128 v[212:215], v150 offset:38912
	ds_read_b128 v[216:219], v150 offset:39936
	global_load_lds_dwordx4 v[228:229], off
	v_lshl_add_u64 v[228:229], s[64:65], 0, v[132:133]
	s_mov_b32 m0, s72
	s_nop 0
	global_load_lds_dwordx4 v[228:229], off
	s_waitcnt vmcnt(8)
	s_waitcnt lgkmcnt(0)
	s_barrier
	s_setprio 1
	s_waitcnt lgkmcnt(0)
	v_mfma_f32_16x16x32_bf16 v[124:127], v[152:155], v[188:191], v[124:127]
	v_mfma_f32_16x16x32_bf16 v[124:127], v[156:159], v[192:195], v[124:127]
	v_mfma_f32_16x16x32_bf16 v[120:123], v[160:163], v[188:191], v[120:123]
	v_mfma_f32_16x16x32_bf16 v[120:123], v[164:167], v[192:195], v[120:123]
	v_mfma_f32_16x16x32_bf16 v[116:119], v[152:155], v[196:199], v[116:119]
	v_mfma_f32_16x16x32_bf16 v[116:119], v[156:159], v[200:203], v[116:119]
	v_mfma_f32_16x16x32_bf16 v[112:115], v[160:163], v[196:199], v[112:115]
	v_mfma_f32_16x16x32_bf16 v[112:115], v[164:167], v[200:203], v[112:115]
	v_mfma_f32_16x16x32_bf16 v[108:111], v[152:155], v[204:207], v[108:111]
	v_mfma_f32_16x16x32_bf16 v[108:111], v[156:159], v[208:211], v[108:111]
	v_mfma_f32_16x16x32_bf16 v[104:107], v[160:163], v[204:207], v[104:107]
	v_mfma_f32_16x16x32_bf16 v[104:107], v[164:167], v[208:211], v[104:107]
	v_mfma_f32_16x16x32_bf16 v[100:103], v[152:155], v[212:215], v[100:103]
	v_mfma_f32_16x16x32_bf16 v[100:103], v[156:159], v[216:219], v[100:103]
	v_mfma_f32_16x16x32_bf16 v[96:99], v[160:163], v[212:215], v[96:99]
	v_mfma_f32_16x16x32_bf16 v[96:99], v[164:167], v[216:219], v[96:99]
	v_mfma_f32_16x16x32_bf16 v[76:79], v[168:171], v[188:191], v[76:79]
	v_mfma_f32_16x16x32_bf16 v[76:79], v[172:175], v[192:195], v[76:79]
	v_mfma_f32_16x16x32_bf16 v[68:71], v[176:179], v[188:191], v[68:71]
	v_mfma_f32_16x16x32_bf16 v[68:71], v[184:187], v[192:195], v[68:71]
	v_mfma_f32_16x16x32_bf16 v[60:63], v[168:171], v[196:199], v[60:63]
	v_mfma_f32_16x16x32_bf16 v[60:63], v[172:175], v[200:203], v[60:63]
	v_mfma_f32_16x16x32_bf16 v[52:55], v[176:179], v[196:199], v[52:55]
	v_mfma_f32_16x16x32_bf16 v[52:55], v[184:187], v[200:203], v[52:55]
	v_mfma_f32_16x16x32_bf16 v[44:47], v[168:171], v[204:207], v[44:47]
	v_mfma_f32_16x16x32_bf16 v[44:47], v[172:175], v[208:211], v[44:47]
	v_mfma_f32_16x16x32_bf16 v[40:43], v[176:179], v[204:207], v[40:43]
	v_mfma_f32_16x16x32_bf16 v[40:43], v[184:187], v[208:211], v[40:43]
	v_mfma_f32_16x16x32_bf16 v[36:39], v[168:171], v[212:215], v[36:39]
	v_mfma_f32_16x16x32_bf16 v[36:39], v[172:175], v[216:219], v[36:39]
	v_mfma_f32_16x16x32_bf16 v[32:35], v[176:179], v[212:215], v[32:35]
	v_mfma_f32_16x16x32_bf16 v[32:35], v[184:187], v[216:219], v[32:35]
	s_setprio 0
	s_barrier
	ds_read_b128 v[188:191], v150 offset:49152
	ds_read_b128 v[192:195], v150 offset:50176
	ds_read_b128 v[196:199], v150 offset:51200
	ds_read_b128 v[200:203], v150 offset:52224
	ds_read_b128 v[204:207], v150 offset:53248
	ds_read_b128 v[208:211], v150 offset:54272
	ds_read_b128 v[212:215], v150 offset:55296
	ds_read_b128 v[216:219], v150 offset:56320
	s_add_i32 s64, s79, s68
	v_lshl_add_u64 v[220:221], v[220:221], 0, s[12:13]
	s_mov_b32 m0, s64
	s_nop 0
	global_load_lds_dwordx4 v[220:221], off
	s_add_i32 m0, s64, 0x2000
	s_add_u32 s62, s62, 0x40080
	v_lshl_add_u64 v[220:221], v[222:223], 0, s[12:13]
	s_addc_u32 s63, s63, 0
	s_add_i32 s64, s88, s68
	global_load_lds_dwordx4 v[220:221], off
	v_lshl_add_u64 v[220:221], s[62:63], 0, v[130:131]
	s_mov_b32 m0, s64
	s_nop 0
	global_load_lds_dwordx4 v[220:221], off
	v_lshl_add_u64 v[220:221], s[62:63], 0, v[134:135]
	s_add_i32 m0, s64, 0x2000
	s_nop 0
	global_load_lds_dwordx4 v[220:221], off
	v_lshl_add_u64 v[220:221], v[224:225], 0, s[12:13]
	s_mov_b32 m0, s75
	s_nop 0
	global_load_lds_dwordx4 v[220:221], off
	v_lshl_add_u64 v[220:221], v[226:227], 0, s[12:13]
	s_mov_b32 m0, s76
	s_nop 0
	global_load_lds_dwordx4 v[220:221], off
	s_waitcnt vmcnt(8)
	s_waitcnt lgkmcnt(0)
	s_barrier
	s_setprio 1
	s_waitcnt lgkmcnt(0)
	v_mfma_f32_16x16x32_bf16 v[92:95], v[152:155], v[188:191], v[92:95]
	v_mfma_f32_16x16x32_bf16 v[92:95], v[156:159], v[192:195], v[92:95]
	v_mfma_f32_16x16x32_bf16 v[88:91], v[160:163], v[188:191], v[88:91]
	v_mfma_f32_16x16x32_bf16 v[88:91], v[164:167], v[192:195], v[88:91]
	v_mfma_f32_16x16x32_bf16 v[84:87], v[152:155], v[196:199], v[84:87]
	v_mfma_f32_16x16x32_bf16 v[84:87], v[156:159], v[200:203], v[84:87]
	v_mfma_f32_16x16x32_bf16 v[80:83], v[160:163], v[196:199], v[80:83]
	v_mfma_f32_16x16x32_bf16 v[80:83], v[164:167], v[200:203], v[80:83]
	v_mfma_f32_16x16x32_bf16 v[72:75], v[152:155], v[204:207], v[72:75]
	v_mfma_f32_16x16x32_bf16 v[72:75], v[156:159], v[208:211], v[72:75]
	v_mfma_f32_16x16x32_bf16 v[64:67], v[160:163], v[204:207], v[64:67]
	v_mfma_f32_16x16x32_bf16 v[64:67], v[164:167], v[208:211], v[64:67]
	v_mfma_f32_16x16x32_bf16 v[56:59], v[152:155], v[212:215], v[56:59]
	v_mfma_f32_16x16x32_bf16 v[56:59], v[156:159], v[216:219], v[56:59]
	v_mfma_f32_16x16x32_bf16 v[48:51], v[160:163], v[212:215], v[48:51]
	v_mfma_f32_16x16x32_bf16 v[48:51], v[164:167], v[216:219], v[48:51]
	v_mfma_f32_16x16x32_bf16 v[28:31], v[168:171], v[188:191], v[28:31]
	v_mfma_f32_16x16x32_bf16 v[28:31], v[172:175], v[192:195], v[28:31]
	v_mfma_f32_16x16x32_bf16 v[24:27], v[176:179], v[188:191], v[24:27]
	v_mfma_f32_16x16x32_bf16 v[24:27], v[184:187], v[192:195], v[24:27]
	v_mfma_f32_16x16x32_bf16 v[20:23], v[168:171], v[196:199], v[20:23]
	v_mfma_f32_16x16x32_bf16 v[20:23], v[172:175], v[200:203], v[20:23]
	v_mfma_f32_16x16x32_bf16 v[16:19], v[176:179], v[196:199], v[16:19]
	v_mfma_f32_16x16x32_bf16 v[16:19], v[184:187], v[200:203], v[16:19]
	v_mfma_f32_16x16x32_bf16 v[12:15], v[168:171], v[204:207], v[12:15]
	v_mfma_f32_16x16x32_bf16 v[12:15], v[172:175], v[208:211], v[12:15]
	v_mfma_f32_16x16x32_bf16 v[8:11], v[176:179], v[204:207], v[8:11]
	v_mfma_f32_16x16x32_bf16 v[8:11], v[184:187], v[208:211], v[8:11]
	v_mfma_f32_16x16x32_bf16 v[4:7], v[168:171], v[212:215], v[4:7]
	v_mfma_f32_16x16x32_bf16 v[4:7], v[172:175], v[216:219], v[4:7]
	v_mfma_f32_16x16x32_bf16 v[0:3], v[176:179], v[212:215], v[0:3]
	v_mfma_f32_16x16x32_bf16 v[0:3], v[184:187], v[216:219], v[0:3]
	s_setprio 0
	s_barrier
	s_add_i32 s87, s87, 2
	s_add_u32 s60, s60, 0x100
	s_addc_u32 s61, s61, 0
	s_add_u32 s85, s85, 0x100
	s_addc_u32 s86, s86, 0
	s_cmp_gt_u32 s87, 13
	s_cbranch_scc0 .LBB0_935
	s_and_b64 vcc, exec, s[16:17]
	s_cbranch_vccz .LBB0_938
	s_barrier

.LBB0_950:
	s_ashr_i32 s37, s36, 31
	s_lshl_b64 s[44:45], s[36:37], 19
	s_add_u32 s44, s80, s44
	s_addc_u32 s45, s81, s45
	s_and_b64 s[46:47], s[10:11], exec
	s_cselect_b32 s37, s45, s53
	s_cselect_b32 s72, s44, s52
	s_ashr_i32 s19, s18, 31
	s_lshl_b64 s[46:47], s[18:19], 19
	s_add_u32 s46, s58, s46
	s_addc_u32 s47, s59, s47
	s_and_b64 s[56:57], s[10:11], exec
	s_cselect_b32 s19, s47, s55
	s_cselect_b32 s73, s46, s54
	s_add_u32 s52, s52, 0x40080
	s_addc_u32 s53, s53, 0
	s_add_u32 s74, s54, 0x100
	s_addc_u32 s75, s55, 0
	s_mov_b32 s76, -2
	ds_read_b128 v[140:143], v147
	ds_read_b128 v[150:153], v147 offset:1024
	ds_read_b128 v[154:157], v147 offset:2048
	ds_read_b128 v[158:161], v147 offset:3072
	ds_read_b128 v[162:165], v148
	ds_read_b128 v[166:169], v148 offset:1024
	ds_read_b128 v[170:173], v148 offset:2048
	ds_read_b128 v[174:177], v148 offset:3072
	s_add_u32 s54, s52, 0xfffc0080
	s_addc_u32 s55, s53, -1
	s_cmp_eq_u32 s76, 12
	s_cselect_b32 s57, s37, s55
	s_cselect_b32 s56, s72, s54
	s_cselect_b32 s55, s19, s75
	s_cselect_b32 s54, s73, s74
	v_lshl_add_u64 v[178:179], s[52:53], 0, v[132:133]
	s_add_i32 m0, s49, 0xc000
	ds_read_b128 v[184:187], v149
	ds_read_b128 v[188:191], v149 offset:1024
	ds_read_b128 v[192:195], v149 offset:2048
	ds_read_b128 v[196:199], v149 offset:3072
	ds_read_b128 v[200:203], v149 offset:4096
	ds_read_b128 v[204:207], v149 offset:5120
	ds_read_b128 v[208:211], v149 offset:6144
	ds_read_b128 v[212:215], v149 offset:7168
	global_load_lds_dwordx4 v[178:179], off
	v_lshl_add_u64 v[178:179], s[52:53], 0, v[134:135]
	s_add_i32 m0, s49, 0xe000
	s_nop 0
	global_load_lds_dwordx4 v[178:179], off
	s_waitcnt vmcnt(8)
	s_waitcnt lgkmcnt(0)
	s_barrier
	s_setprio 1
	s_waitcnt lgkmcnt(0)
	v_mfma_f32_16x16x32_bf16 v[124:127], v[140:143], v[184:187], 0
	v_mfma_f32_16x16x32_bf16 v[124:127], v[150:153], v[188:191], v[124:127]
	v_mfma_f32_16x16x32_bf16 v[120:123], v[154:157], v[184:187], 0
	v_mfma_f32_16x16x32_bf16 v[120:123], v[158:161], v[188:191], v[120:123]
	v_mfma_f32_16x16x32_bf16 v[108:111], v[140:143], v[192:195], 0
	v_mfma_f32_16x16x32_bf16 v[108:111], v[150:153], v[196:199], v[108:111]
	v_mfma_f32_16x16x32_bf16 v[104:107], v[154:157], v[192:195], 0
	v_mfma_f32_16x16x32_bf16 v[104:107], v[158:161], v[196:199], v[104:107]
	v_mfma_f32_16x16x32_bf16 v[92:95], v[140:143], v[200:203], 0
	v_mfma_f32_16x16x32_bf16 v[92:95], v[150:153], v[204:207], v[92:95]
	v_mfma_f32_16x16x32_bf16 v[88:91], v[154:157], v[200:203], 0
	v_mfma_f32_16x16x32_bf16 v[88:91], v[158:161], v[204:207], v[88:91]
	v_mfma_f32_16x16x32_bf16 v[76:79], v[140:143], v[208:211], 0
	v_mfma_f32_16x16x32_bf16 v[76:79], v[150:153], v[212:215], v[76:79]
	v_mfma_f32_16x16x32_bf16 v[72:75], v[154:157], v[208:211], 0
	v_mfma_f32_16x16x32_bf16 v[72:75], v[158:161], v[212:215], v[72:75]
	v_mfma_f32_16x16x32_bf16 v[116:119], v[162:165], v[184:187], 0
	v_mfma_f32_16x16x32_bf16 v[116:119], v[166:169], v[188:191], v[116:119]
	v_mfma_f32_16x16x32_bf16 v[112:115], v[170:173], v[184:187], 0
	v_mfma_f32_16x16x32_bf16 v[112:115], v[174:177], v[188:191], v[112:115]
	v_mfma_f32_16x16x32_bf16 v[100:103], v[162:165], v[192:195], 0
	v_mfma_f32_16x16x32_bf16 v[100:103], v[166:169], v[196:199], v[100:103]
	v_mfma_f32_16x16x32_bf16 v[96:99], v[170:173], v[192:195], 0
	v_mfma_f32_16x16x32_bf16 v[96:99], v[174:177], v[196:199], v[96:99]
	v_mfma_f32_16x16x32_bf16 v[84:87], v[162:165], v[200:203], 0
	v_mfma_f32_16x16x32_bf16 v[84:87], v[166:169], v[204:207], v[84:87]
	v_mfma_f32_16x16x32_bf16 v[80:83], v[170:173], v[200:203], 0
	v_mfma_f32_16x16x32_bf16 v[80:83], v[174:177], v[204:207], v[80:83]
	v_mfma_f32_16x16x32_bf16 v[68:71], v[162:165], v[208:211], 0
	v_mfma_f32_16x16x32_bf16 v[68:71], v[166:169], v[212:215], v[68:71]
	v_mfma_f32_16x16x32_bf16 v[64:67], v[170:173], v[208:211], 0
	v_mfma_f32_16x16x32_bf16 v[64:67], v[174:177], v[212:215], v[64:67]
	s_setprio 0
	s_barrier
	ds_read_b128 v[184:187], v149 offset:16384
	ds_read_b128 v[188:191], v149 offset:17408
	ds_read_b128 v[192:195], v149 offset:18432
	ds_read_b128 v[196:199], v149 offset:19456
	ds_read_b128 v[200:203], v149 offset:20480
	ds_read_b128 v[204:207], v149 offset:21504
	ds_read_b128 v[208:211], v149 offset:22528
	ds_read_b128 v[212:215], v149 offset:23552
	s_add_i32 s77, s68, s60
	v_lshl_add_u64 v[178:179], s[54:55], 0, v[130:131]
	s_mov_b32 m0, s77
	s_nop 0
	global_load_lds_dwordx4 v[178:179], off
	s_add_i32 m0, s77, 0x2000
	s_add_u32 s82, s54, 0x40000
	v_lshl_add_u64 v[216:217], s[54:55], 0, v[128:129]
	s_addc_u32 s83, s55, 0
	s_add_i32 s77, s69, s60
	global_load_lds_dwordx4 v[216:217], off
	v_lshl_add_u64 v[218:219], s[82:83], 0, v[130:131]
	s_mov_b32 m0, s77
	v_lshl_add_u64 v[220:221], s[56:57], 0, v[128:129]
	global_load_lds_dwordx4 v[218:219], off
	v_lshl_add_u64 v[218:219], s[82:83], 0, v[128:129]
	s_add_i32 m0, s77, 0x2000
	s_nop 0
	global_load_lds_dwordx4 v[218:219], off
	v_lshl_add_u64 v[218:219], s[56:57], 0, v[130:131]
	s_mov_b32 m0, s49
	s_nop 0
	global_load_lds_dwordx4 v[218:219], off
	s_mov_b32 m0, s62
	s_nop 0
	global_load_lds_dwordx4 v[220:221], off
	s_waitcnt vmcnt(8)
	s_waitcnt lgkmcnt(0)
	s_barrier
	s_setprio 1
	s_waitcnt lgkmcnt(0)
	v_mfma_f32_16x16x32_bf16 v[60:63], v[140:143], v[184:187], 0
	v_mfma_f32_16x16x32_bf16 v[60:63], v[150:153], v[188:191], v[60:63]
	v_mfma_f32_16x16x32_bf16 v[56:59], v[154:157], v[184:187], 0
	v_mfma_f32_16x16x32_bf16 v[56:59], v[158:161], v[188:191], v[56:59]
	v_mfma_f32_16x16x32_bf16 v[44:47], v[140:143], v[192:195], 0
	v_mfma_f32_16x16x32_bf16 v[44:47], v[150:153], v[196:199], v[44:47]
	v_mfma_f32_16x16x32_bf16 v[40:43], v[154:157], v[192:195], 0
	v_mfma_f32_16x16x32_bf16 v[40:43], v[158:161], v[196:199], v[40:43]
	v_mfma_f32_16x16x32_bf16 v[28:31], v[140:143], v[200:203], 0
	v_mfma_f32_16x16x32_bf16 v[28:31], v[150:153], v[204:207], v[28:31]
	v_mfma_f32_16x16x32_bf16 v[24:27], v[154:157], v[200:203], 0
	v_mfma_f32_16x16x32_bf16 v[24:27], v[158:161], v[204:207], v[24:27]
	v_mfma_f32_16x16x32_bf16 v[12:15], v[140:143], v[208:211], 0
	v_mfma_f32_16x16x32_bf16 v[12:15], v[150:153], v[212:215], v[12:15]
	v_mfma_f32_16x16x32_bf16 v[8:11], v[154:157], v[208:211], 0
	v_mfma_f32_16x16x32_bf16 v[8:11], v[158:161], v[212:215], v[8:11]
	v_mfma_f32_16x16x32_bf16 v[52:55], v[162:165], v[184:187], 0
	v_mfma_f32_16x16x32_bf16 v[52:55], v[166:169], v[188:191], v[52:55]
	v_mfma_f32_16x16x32_bf16 v[48:51], v[170:173], v[184:187], 0
	v_mfma_f32_16x16x32_bf16 v[48:51], v[174:177], v[188:191], v[48:51]
	v_mfma_f32_16x16x32_bf16 v[36:39], v[162:165], v[192:195], 0
	v_mfma_f32_16x16x32_bf16 v[36:39], v[166:169], v[196:199], v[36:39]
	v_mfma_f32_16x16x32_bf16 v[32:35], v[170:173], v[192:195], 0
	v_mfma_f32_16x16x32_bf16 v[32:35], v[174:177], v[196:199], v[32:35]
	v_mfma_f32_16x16x32_bf16 v[20:23], v[162:165], v[200:203], 0
	v_mfma_f32_16x16x32_bf16 v[20:23], v[166:169], v[204:207], v[20:23]
	v_mfma_f32_16x16x32_bf16 v[16:19], v[170:173], v[200:203], 0
	v_mfma_f32_16x16x32_bf16 v[16:19], v[174:177], v[204:207], v[16:19]
	v_mfma_f32_16x16x32_bf16 v[4:7], v[162:165], v[208:211], 0
	v_mfma_f32_16x16x32_bf16 v[4:7], v[166:169], v[212:215], v[4:7]
	v_mfma_f32_16x16x32_bf16 v[0:3], v[170:173], v[208:211], 0
	v_mfma_f32_16x16x32_bf16 v[0:3], v[174:177], v[212:215], v[0:3]
	s_setprio 0
	s_barrier
	s_branch .Lmid_gemm7
.LBB0_951:
	ds_read_b128 v[140:143], v147
	ds_read_b128 v[150:153], v147 offset:1024
	ds_read_b128 v[154:157], v147 offset:2048
	ds_read_b128 v[158:161], v147 offset:3072
	ds_read_b128 v[162:165], v148
	ds_read_b128 v[166:169], v148 offset:1024
	ds_read_b128 v[170:173], v148 offset:2048
	ds_read_b128 v[174:177], v148 offset:3072
	ds_read_b128 v[184:187], v149
	ds_read_b128 v[188:191], v149 offset:1024
	ds_read_b128 v[192:195], v149 offset:2048
	ds_read_b128 v[196:199], v149 offset:3072
	ds_read_b128 v[200:203], v149 offset:4096
	ds_read_b128 v[204:207], v149 offset:5120
	ds_read_b128 v[208:211], v149 offset:6144
	ds_read_b128 v[212:215], v149 offset:7168
	s_add_u32 s54, s52, 0xfffc0080
	s_addc_u32 s55, s53, -1
	s_cmp_eq_u32 s76, 12
	s_cselect_b32 s57, s37, s55
	s_cselect_b32 s56, s72, s54
	s_cselect_b32 s55, s19, s75
	s_cselect_b32 s54, s73, s74
	v_lshl_add_u64 v[178:179], s[52:53], 0, v[132:133]
	s_add_i32 m0, s49, 0xc000
	s_nop 0
	global_load_lds_dwordx4 v[178:179], off
	v_lshl_add_u64 v[178:179], s[52:53], 0, v[134:135]
	s_add_i32 m0, s49, 0xe000
	s_nop 0
	global_load_lds_dwordx4 v[178:179], off
	s_waitcnt vmcnt(8)
	s_waitcnt lgkmcnt(0)
	s_barrier
	s_setprio 1
	s_waitcnt lgkmcnt(0)
	v_mfma_f32_16x16x32_bf16 v[124:127], v[140:143], v[184:187], v[124:127]
	v_mfma_f32_16x16x32_bf16 v[124:127], v[150:153], v[188:191], v[124:127]
	v_mfma_f32_16x16x32_bf16 v[120:123], v[154:157], v[184:187], v[120:123]
	v_mfma_f32_16x16x32_bf16 v[120:123], v[158:161], v[188:191], v[120:123]
	v_mfma_f32_16x16x32_bf16 v[108:111], v[140:143], v[192:195], v[108:111]
	v_mfma_f32_16x16x32_bf16 v[108:111], v[150:153], v[196:199], v[108:111]
	v_mfma_f32_16x16x32_bf16 v[104:107], v[154:157], v[192:195], v[104:107]
	v_mfma_f32_16x16x32_bf16 v[104:107], v[158:161], v[196:199], v[104:107]
	v_mfma_f32_16x16x32_bf16 v[92:95], v[140:143], v[200:203], v[92:95]
	v_mfma_f32_16x16x32_bf16 v[92:95], v[150:153], v[204:207], v[92:95]
	v_mfma_f32_16x16x32_bf16 v[88:91], v[154:157], v[200:203], v[88:91]
	v_mfma_f32_16x16x32_bf16 v[88:91], v[158:161], v[204:207], v[88:91]
	v_mfma_f32_16x16x32_bf16 v[76:79], v[140:143], v[208:211], v[76:79]
	v_mfma_f32_16x16x32_bf16 v[76:79], v[150:153], v[212:215], v[76:79]
	v_mfma_f32_16x16x32_bf16 v[72:75], v[154:157], v[208:211], v[72:75]
	v_mfma_f32_16x16x32_bf16 v[72:75], v[158:161], v[212:215], v[72:75]
	v_mfma_f32_16x16x32_bf16 v[116:119], v[162:165], v[184:187], v[116:119]
	v_mfma_f32_16x16x32_bf16 v[116:119], v[166:169], v[188:191], v[116:119]
	v_mfma_f32_16x16x32_bf16 v[112:115], v[170:173], v[184:187], v[112:115]
	v_mfma_f32_16x16x32_bf16 v[112:115], v[174:177], v[188:191], v[112:115]
	v_mfma_f32_16x16x32_bf16 v[100:103], v[162:165], v[192:195], v[100:103]
	v_mfma_f32_16x16x32_bf16 v[100:103], v[166:169], v[196:199], v[100:103]
	v_mfma_f32_16x16x32_bf16 v[96:99], v[170:173], v[192:195], v[96:99]
	v_mfma_f32_16x16x32_bf16 v[96:99], v[174:177], v[196:199], v[96:99]
	v_mfma_f32_16x16x32_bf16 v[84:87], v[162:165], v[200:203], v[84:87]
	v_mfma_f32_16x16x32_bf16 v[84:87], v[166:169], v[204:207], v[84:87]
	v_mfma_f32_16x16x32_bf16 v[80:83], v[170:173], v[200:203], v[80:83]
	v_mfma_f32_16x16x32_bf16 v[80:83], v[174:177], v[204:207], v[80:83]
	v_mfma_f32_16x16x32_bf16 v[68:71], v[162:165], v[208:211], v[68:71]
	v_mfma_f32_16x16x32_bf16 v[68:71], v[166:169], v[212:215], v[68:71]
	v_mfma_f32_16x16x32_bf16 v[64:67], v[170:173], v[208:211], v[64:67]
	v_mfma_f32_16x16x32_bf16 v[64:67], v[174:177], v[212:215], v[64:67]
	s_setprio 0
	s_barrier
	ds_read_b128 v[184:187], v149 offset:16384
	ds_read_b128 v[188:191], v149 offset:17408
	ds_read_b128 v[192:195], v149 offset:18432
	ds_read_b128 v[196:199], v149 offset:19456
	ds_read_b128 v[200:203], v149 offset:20480
	ds_read_b128 v[204:207], v149 offset:21504
	ds_read_b128 v[208:211], v149 offset:22528
	ds_read_b128 v[212:215], v149 offset:23552
	s_add_i32 s77, s68, s60
	v_lshl_add_u64 v[178:179], s[54:55], 0, v[130:131]
	s_mov_b32 m0, s77
	s_nop 0
	global_load_lds_dwordx4 v[178:179], off
	s_add_i32 m0, s77, 0x2000
	s_add_u32 s82, s54, 0x40000
	v_lshl_add_u64 v[216:217], s[54:55], 0, v[128:129]
	s_addc_u32 s83, s55, 0
	s_add_i32 s77, s69, s60
	global_load_lds_dwordx4 v[216:217], off
	v_lshl_add_u64 v[218:219], s[82:83], 0, v[130:131]
	s_mov_b32 m0, s77
	v_lshl_add_u64 v[220:221], s[56:57], 0, v[128:129]
	global_load_lds_dwordx4 v[218:219], off
	v_lshl_add_u64 v[218:219], s[82:83], 0, v[128:129]
	s_add_i32 m0, s77, 0x2000
	s_nop 0
	global_load_lds_dwordx4 v[218:219], off
	v_lshl_add_u64 v[218:219], s[56:57], 0, v[130:131]
	s_mov_b32 m0, s49
	s_nop 0
	global_load_lds_dwordx4 v[218:219], off
	s_mov_b32 m0, s62
	s_nop 0
	global_load_lds_dwordx4 v[220:221], off
	s_waitcnt vmcnt(8)
	s_waitcnt lgkmcnt(0)
	s_barrier
	s_setprio 1
	s_waitcnt lgkmcnt(0)
	v_mfma_f32_16x16x32_bf16 v[60:63], v[140:143], v[184:187], v[60:63]
	v_mfma_f32_16x16x32_bf16 v[60:63], v[150:153], v[188:191], v[60:63]
	v_mfma_f32_16x16x32_bf16 v[56:59], v[154:157], v[184:187], v[56:59]
	v_mfma_f32_16x16x32_bf16 v[56:59], v[158:161], v[188:191], v[56:59]
	v_mfma_f32_16x16x32_bf16 v[44:47], v[140:143], v[192:195], v[44:47]
	v_mfma_f32_16x16x32_bf16 v[44:47], v[150:153], v[196:199], v[44:47]
	v_mfma_f32_16x16x32_bf16 v[40:43], v[154:157], v[192:195], v[40:43]
	v_mfma_f32_16x16x32_bf16 v[40:43], v[158:161], v[196:199], v[40:43]
	v_mfma_f32_16x16x32_bf16 v[28:31], v[140:143], v[200:203], v[28:31]
	v_mfma_f32_16x16x32_bf16 v[28:31], v[150:153], v[204:207], v[28:31]
	v_mfma_f32_16x16x32_bf16 v[24:27], v[154:157], v[200:203], v[24:27]
	v_mfma_f32_16x16x32_bf16 v[24:27], v[158:161], v[204:207], v[24:27]
	v_mfma_f32_16x16x32_bf16 v[12:15], v[140:143], v[208:211], v[12:15]
	v_mfma_f32_16x16x32_bf16 v[12:15], v[150:153], v[212:215], v[12:15]
	v_mfma_f32_16x16x32_bf16 v[8:11], v[154:157], v[208:211], v[8:11]
	v_mfma_f32_16x16x32_bf16 v[8:11], v[158:161], v[212:215], v[8:11]
	v_mfma_f32_16x16x32_bf16 v[52:55], v[162:165], v[184:187], v[52:55]
	v_mfma_f32_16x16x32_bf16 v[52:55], v[166:169], v[188:191], v[52:55]
	v_mfma_f32_16x16x32_bf16 v[48:51], v[170:173], v[184:187], v[48:51]
	v_mfma_f32_16x16x32_bf16 v[48:51], v[174:177], v[188:191], v[48:51]
	v_mfma_f32_16x16x32_bf16 v[36:39], v[162:165], v[192:195], v[36:39]
	v_mfma_f32_16x16x32_bf16 v[36:39], v[166:169], v[196:199], v[36:39]
	v_mfma_f32_16x16x32_bf16 v[32:35], v[170:173], v[192:195], v[32:35]
	v_mfma_f32_16x16x32_bf16 v[32:35], v[174:177], v[196:199], v[32:35]
	v_mfma_f32_16x16x32_bf16 v[20:23], v[162:165], v[200:203], v[20:23]
	v_mfma_f32_16x16x32_bf16 v[20:23], v[166:169], v[204:207], v[20:23]
	v_mfma_f32_16x16x32_bf16 v[16:19], v[170:173], v[200:203], v[16:19]
	v_mfma_f32_16x16x32_bf16 v[16:19], v[174:177], v[204:207], v[16:19]
	v_mfma_f32_16x16x32_bf16 v[4:7], v[162:165], v[208:211], v[4:7]
	v_mfma_f32_16x16x32_bf16 v[4:7], v[166:169], v[212:215], v[4:7]
	v_mfma_f32_16x16x32_bf16 v[0:3], v[170:173], v[208:211], v[0:3]
	v_mfma_f32_16x16x32_bf16 v[0:3], v[174:177], v[212:215], v[0:3]
	s_setprio 0
	s_barrier
.Lmid_gemm7:
	s_add_i32 s77, 0, 0x18000
	s_add_i32 s79, 0, 0x1c000
	v_add_u32_e32 v158, s77, v145
	v_add_u32_e32 v174, s79, v145
	ds_read_b128 v[140:143], v158
	ds_read_b128 v[150:153], v158 offset:1024
	ds_read_b128 v[154:157], v158 offset:2048
	ds_read_b128 v[158:161], v158 offset:3072
	ds_read_b128 v[162:165], v174
	ds_read_b128 v[166:169], v174 offset:1024
	ds_read_b128 v[170:173], v174 offset:2048
	ds_read_b128 v[174:177], v174 offset:3072
	ds_read_b128 v[184:187], v149 offset:32768
	ds_read_b128 v[188:191], v149 offset:33792
	ds_read_b128 v[192:195], v149 offset:34816
	ds_read_b128 v[196:199], v149 offset:35840
	ds_read_b128 v[200:203], v149 offset:36864
	ds_read_b128 v[204:207], v149 offset:37888
	ds_read_b128 v[208:211], v149 offset:38912
	ds_read_b128 v[212:215], v149 offset:39936
	s_add_u32 s56, s56, 0x40000
	s_addc_u32 s57, s57, 0
	s_mov_b32 m0, s63
	v_lshl_add_u64 v[222:223], s[56:57], 0, v[130:131]
	global_load_lds_dwordx4 v[222:223], off
	v_lshl_add_u64 v[222:223], s[56:57], 0, v[128:129]
	s_mov_b32 m0, s64
	s_nop 0
	global_load_lds_dwordx4 v[222:223], off
	s_waitcnt vmcnt(8)
	s_waitcnt lgkmcnt(0)
	s_barrier
	s_setprio 1
	s_waitcnt lgkmcnt(0)
	v_mfma_f32_16x16x32_bf16 v[124:127], v[140:143], v[184:187], v[124:127]
	v_mfma_f32_16x16x32_bf16 v[124:127], v[150:153], v[188:191], v[124:127]
	v_mfma_f32_16x16x32_bf16 v[120:123], v[154:157], v[184:187], v[120:123]
	v_mfma_f32_16x16x32_bf16 v[120:123], v[158:161], v[188:191], v[120:123]
	v_mfma_f32_16x16x32_bf16 v[108:111], v[140:143], v[192:195], v[108:111]
	v_mfma_f32_16x16x32_bf16 v[108:111], v[150:153], v[196:199], v[108:111]
	v_mfma_f32_16x16x32_bf16 v[104:107], v[154:157], v[192:195], v[104:107]
	v_mfma_f32_16x16x32_bf16 v[104:107], v[158:161], v[196:199], v[104:107]
	v_mfma_f32_16x16x32_bf16 v[92:95], v[140:143], v[200:203], v[92:95]
	v_mfma_f32_16x16x32_bf16 v[92:95], v[150:153], v[204:207], v[92:95]
	v_mfma_f32_16x16x32_bf16 v[88:91], v[154:157], v[200:203], v[88:91]
	v_mfma_f32_16x16x32_bf16 v[88:91], v[158:161], v[204:207], v[88:91]
	v_mfma_f32_16x16x32_bf16 v[76:79], v[140:143], v[208:211], v[76:79]
	v_mfma_f32_16x16x32_bf16 v[76:79], v[150:153], v[212:215], v[76:79]
	v_mfma_f32_16x16x32_bf16 v[72:75], v[154:157], v[208:211], v[72:75]
	v_mfma_f32_16x16x32_bf16 v[72:75], v[158:161], v[212:215], v[72:75]
	v_mfma_f32_16x16x32_bf16 v[116:119], v[162:165], v[184:187], v[116:119]
	v_mfma_f32_16x16x32_bf16 v[116:119], v[166:169], v[188:191], v[116:119]
	v_mfma_f32_16x16x32_bf16 v[112:115], v[170:173], v[184:187], v[112:115]
	v_mfma_f32_16x16x32_bf16 v[112:115], v[174:177], v[188:191], v[112:115]
	v_mfma_f32_16x16x32_bf16 v[100:103], v[162:165], v[192:195], v[100:103]
	v_mfma_f32_16x16x32_bf16 v[100:103], v[166:169], v[196:199], v[100:103]
	v_mfma_f32_16x16x32_bf16 v[96:99], v[170:173], v[192:195], v[96:99]
	v_mfma_f32_16x16x32_bf16 v[96:99], v[174:177], v[196:199], v[96:99]
	v_mfma_f32_16x16x32_bf16 v[84:87], v[162:165], v[200:203], v[84:87]
	v_mfma_f32_16x16x32_bf16 v[84:87], v[166:169], v[204:207], v[84:87]
	v_mfma_f32_16x16x32_bf16 v[80:83], v[170:173], v[200:203], v[80:83]
	v_mfma_f32_16x16x32_bf16 v[80:83], v[174:177], v[204:207], v[80:83]
	v_mfma_f32_16x16x32_bf16 v[68:71], v[162:165], v[208:211], v[68:71]
	v_mfma_f32_16x16x32_bf16 v[68:71], v[166:169], v[212:215], v[68:71]
	v_mfma_f32_16x16x32_bf16 v[64:67], v[170:173], v[208:211], v[64:67]
	v_mfma_f32_16x16x32_bf16 v[64:67], v[174:177], v[212:215], v[64:67]
	s_setprio 0
	s_barrier
	ds_read_b128 v[184:187], v149 offset:49152
	ds_read_b128 v[188:191], v149 offset:50176
	ds_read_b128 v[192:195], v149 offset:51200
	ds_read_b128 v[196:199], v149 offset:52224
	ds_read_b128 v[200:203], v149 offset:53248
	ds_read_b128 v[204:207], v149 offset:54272
	ds_read_b128 v[208:211], v149 offset:55296
	ds_read_b128 v[212:215], v149 offset:56320
	s_add_i32 s56, s77, s60
	v_lshl_add_u64 v[178:179], v[178:179], 0, s[12:13]
	s_mov_b32 m0, s56
	s_nop 0
	global_load_lds_dwordx4 v[178:179], off
	s_add_i32 m0, s56, 0x2000
	s_add_u32 s54, s54, 0x40080
	v_lshl_add_u64 v[178:179], v[216:217], 0, s[12:13]
	s_addc_u32 s55, s55, 0
	s_add_i32 s56, s79, s60
	global_load_lds_dwordx4 v[178:179], off
	v_lshl_add_u64 v[178:179], s[54:55], 0, v[130:131]
	s_mov_b32 m0, s56
	s_nop 0
	global_load_lds_dwordx4 v[178:179], off
	v_lshl_add_u64 v[178:179], s[54:55], 0, v[128:129]
	s_add_i32 m0, s56, 0x2000
	s_nop 0
	global_load_lds_dwordx4 v[178:179], off
	v_lshl_add_u64 v[178:179], v[218:219], 0, s[12:13]
	s_mov_b32 m0, s66
	s_nop 0
	global_load_lds_dwordx4 v[178:179], off
	v_lshl_add_u64 v[178:179], v[220:221], 0, s[12:13]
	s_mov_b32 m0, s67
	s_nop 0
	global_load_lds_dwordx4 v[178:179], off
	s_waitcnt vmcnt(8)
	s_waitcnt lgkmcnt(0)
	s_barrier
	s_setprio 1
	s_waitcnt lgkmcnt(0)
	v_mfma_f32_16x16x32_bf16 v[60:63], v[140:143], v[184:187], v[60:63]
	v_mfma_f32_16x16x32_bf16 v[60:63], v[150:153], v[188:191], v[60:63]
	v_mfma_f32_16x16x32_bf16 v[56:59], v[154:157], v[184:187], v[56:59]
	v_mfma_f32_16x16x32_bf16 v[56:59], v[158:161], v[188:191], v[56:59]
	v_mfma_f32_16x16x32_bf16 v[44:47], v[140:143], v[192:195], v[44:47]
	v_mfma_f32_16x16x32_bf16 v[44:47], v[150:153], v[196:199], v[44:47]
	v_mfma_f32_16x16x32_bf16 v[40:43], v[154:157], v[192:195], v[40:43]
	v_mfma_f32_16x16x32_bf16 v[40:43], v[158:161], v[196:199], v[40:43]
	v_mfma_f32_16x16x32_bf16 v[28:31], v[140:143], v[200:203], v[28:31]
	v_mfma_f32_16x16x32_bf16 v[28:31], v[150:153], v[204:207], v[28:31]
	v_mfma_f32_16x16x32_bf16 v[24:27], v[154:157], v[200:203], v[24:27]
	v_mfma_f32_16x16x32_bf16 v[24:27], v[158:161], v[204:207], v[24:27]
	v_mfma_f32_16x16x32_bf16 v[12:15], v[140:143], v[208:211], v[12:15]
	v_mfma_f32_16x16x32_bf16 v[12:15], v[150:153], v[212:215], v[12:15]
	v_mfma_f32_16x16x32_bf16 v[8:11], v[154:157], v[208:211], v[8:11]
	v_mfma_f32_16x16x32_bf16 v[8:11], v[158:161], v[212:215], v[8:11]
	v_mfma_f32_16x16x32_bf16 v[52:55], v[162:165], v[184:187], v[52:55]
	v_mfma_f32_16x16x32_bf16 v[52:55], v[166:169], v[188:191], v[52:55]
	v_mfma_f32_16x16x32_bf16 v[48:51], v[170:173], v[184:187], v[48:51]
	v_mfma_f32_16x16x32_bf16 v[48:51], v[174:177], v[188:191], v[48:51]
	v_mfma_f32_16x16x32_bf16 v[36:39], v[162:165], v[192:195], v[36:39]
	v_mfma_f32_16x16x32_bf16 v[36:39], v[166:169], v[196:199], v[36:39]
	v_mfma_f32_16x16x32_bf16 v[32:35], v[170:173], v[192:195], v[32:35]
	v_mfma_f32_16x16x32_bf16 v[32:35], v[174:177], v[196:199], v[32:35]
	v_mfma_f32_16x16x32_bf16 v[20:23], v[162:165], v[200:203], v[20:23]
	v_mfma_f32_16x16x32_bf16 v[20:23], v[166:169], v[204:207], v[20:23]
	v_mfma_f32_16x16x32_bf16 v[16:19], v[170:173], v[200:203], v[16:19]
	v_mfma_f32_16x16x32_bf16 v[16:19], v[174:177], v[204:207], v[16:19]
	v_mfma_f32_16x16x32_bf16 v[4:7], v[162:165], v[208:211], v[4:7]
	v_mfma_f32_16x16x32_bf16 v[4:7], v[166:169], v[212:215], v[4:7]
	v_mfma_f32_16x16x32_bf16 v[0:3], v[170:173], v[208:211], v[0:3]
	v_mfma_f32_16x16x32_bf16 v[0:3], v[174:177], v[212:215], v[0:3]
	s_setprio 0
	s_barrier
	s_add_i32 s76, s76, 2
	s_add_u32 s52, s52, 0x100
	s_addc_u32 s53, s53, 0
	s_add_u32 s74, s74, 0x100
	s_addc_u32 s75, s75, 0
	s_cmp_gt_u32 s76, 13
	s_cbranch_scc0 .LBB0_951
	s_and_b64 vcc, exec, s[16:17]
	s_cbranch_vccz .LBB0_954
	s_barrier

.LBB0_1030:
	s_add_u32 s86, s56, 0x100
	s_addc_u32 s87, s57, 0
	s_mov_b32 s88, -2
	ds_read_b128 v[152:155], v149
	ds_read_b128 v[156:159], v149 offset:1024
	ds_read_b128 v[160:163], v149 offset:2048
	ds_read_b128 v[164:167], v149 offset:3072
	ds_read_b128 v[168:171], v150
	ds_read_b128 v[172:175], v150 offset:1024
	ds_read_b128 v[176:179], v150 offset:2048
	ds_read_b128 v[184:187], v150 offset:3072
	s_add_u32 s56, s54, 0x100
	s_addc_u32 s57, s55, 0
	s_cmp_eq_u32 s88, 40
	s_cselect_b32 s61, s13, s57
	s_cselect_b32 s60, s12, s56
	s_cselect_b32 s59, s53, s87
	s_cselect_b32 s58, s52, s86
	v_lshl_add_u64 v[144:145], s[54:55], 0, v[136:137]
	s_add_i32 m0, s65, 0xc000
	ds_read_b128 v[188:191], v151
	ds_read_b128 v[192:195], v151 offset:1024
	ds_read_b128 v[196:199], v151 offset:2048
	ds_read_b128 v[200:203], v151 offset:3072
	ds_read_b128 v[204:207], v151 offset:4096
	ds_read_b128 v[208:211], v151 offset:5120
	ds_read_b128 v[212:215], v151 offset:6144
	ds_read_b128 v[216:219], v151 offset:7168
	global_load_lds_dwordx4 v[144:145], off
	v_lshl_add_u64 v[144:145], s[54:55], 0, v[138:139]
	s_add_i32 m0, s65, 0xe000
	s_nop 0
	global_load_lds_dwordx4 v[144:145], off
	s_waitcnt vmcnt(8)
	s_waitcnt lgkmcnt(0)
	s_barrier
	s_setprio 1
	s_waitcnt lgkmcnt(0)
	v_mfma_f32_16x16x32_bf16 v[124:127], v[152:155], v[188:191], 0
	v_mfma_f32_16x16x32_bf16 v[124:127], v[156:159], v[192:195], v[124:127]
	v_mfma_f32_16x16x32_bf16 v[120:123], v[160:163], v[188:191], 0
	v_mfma_f32_16x16x32_bf16 v[120:123], v[164:167], v[192:195], v[120:123]
	v_mfma_f32_16x16x32_bf16 v[116:119], v[152:155], v[196:199], 0
	v_mfma_f32_16x16x32_bf16 v[116:119], v[156:159], v[200:203], v[116:119]
	v_mfma_f32_16x16x32_bf16 v[108:111], v[160:163], v[196:199], 0
	v_mfma_f32_16x16x32_bf16 v[108:111], v[164:167], v[200:203], v[108:111]
	v_mfma_f32_16x16x32_bf16 v[100:103], v[152:155], v[204:207], 0
	v_mfma_f32_16x16x32_bf16 v[100:103], v[156:159], v[208:211], v[100:103]
	v_mfma_f32_16x16x32_bf16 v[92:95], v[160:163], v[204:207], 0
	v_mfma_f32_16x16x32_bf16 v[92:95], v[164:167], v[208:211], v[92:95]
	v_mfma_f32_16x16x32_bf16 v[84:87], v[152:155], v[212:215], 0
	v_mfma_f32_16x16x32_bf16 v[84:87], v[156:159], v[216:219], v[84:87]
	v_mfma_f32_16x16x32_bf16 v[76:79], v[160:163], v[212:215], 0
	v_mfma_f32_16x16x32_bf16 v[76:79], v[164:167], v[216:219], v[76:79]
	v_mfma_f32_16x16x32_bf16 v[112:115], v[168:171], v[188:191], 0
	v_mfma_f32_16x16x32_bf16 v[112:115], v[172:175], v[192:195], v[112:115]
	v_mfma_f32_16x16x32_bf16 v[104:107], v[176:179], v[188:191], 0
	v_mfma_f32_16x16x32_bf16 v[104:107], v[184:187], v[192:195], v[104:107]
	v_mfma_f32_16x16x32_bf16 v[96:99], v[168:171], v[196:199], 0
	v_mfma_f32_16x16x32_bf16 v[96:99], v[172:175], v[200:203], v[96:99]
	v_mfma_f32_16x16x32_bf16 v[88:91], v[176:179], v[196:199], 0
	v_mfma_f32_16x16x32_bf16 v[88:91], v[184:187], v[200:203], v[88:91]
	v_mfma_f32_16x16x32_bf16 v[80:83], v[168:171], v[204:207], 0
	v_mfma_f32_16x16x32_bf16 v[80:83], v[172:175], v[208:211], v[80:83]
	v_mfma_f32_16x16x32_bf16 v[72:75], v[176:179], v[204:207], 0
	v_mfma_f32_16x16x32_bf16 v[72:75], v[184:187], v[208:211], v[72:75]
	v_mfma_f32_16x16x32_bf16 v[68:71], v[168:171], v[212:215], 0
	v_mfma_f32_16x16x32_bf16 v[68:71], v[172:175], v[216:219], v[68:71]
	v_mfma_f32_16x16x32_bf16 v[64:67], v[176:179], v[212:215], 0
	v_mfma_f32_16x16x32_bf16 v[64:67], v[184:187], v[216:219], v[64:67]
	s_setprio 0
	s_barrier
	ds_read_b128 v[188:191], v151 offset:16384
	ds_read_b128 v[192:195], v151 offset:17408
	ds_read_b128 v[196:199], v151 offset:18432
	ds_read_b128 v[200:203], v151 offset:19456
	ds_read_b128 v[204:207], v151 offset:20480
	ds_read_b128 v[208:211], v151 offset:21504
	ds_read_b128 v[212:215], v151 offset:22528
	ds_read_b128 v[216:219], v151 offset:23552
	s_add_i32 s54, s72, s64
	v_lshl_add_u64 v[144:145], s[58:59], 0, v[130:131]
	s_mov_b32 m0, s54
	s_nop 0
	global_load_lds_dwordx4 v[144:145], off
	s_add_i32 m0, s54, 0x2000
	s_add_u32 s54, s58, 0xb0000
	v_lshl_add_u64 v[220:221], s[58:59], 0, v[134:135]
	s_addc_u32 s55, s59, 0
	s_add_i32 s79, s73, s64
	global_load_lds_dwordx4 v[220:221], off
	v_lshl_add_u64 v[222:223], s[54:55], 0, v[130:131]
	s_mov_b32 m0, s79
	v_lshl_add_u64 v[224:225], s[60:61], 0, v[132:133]
	global_load_lds_dwordx4 v[222:223], off
	v_lshl_add_u64 v[222:223], s[54:55], 0, v[134:135]
	s_add_i32 m0, s79, 0x2000
	s_nop 0
	global_load_lds_dwordx4 v[222:223], off
	v_lshl_add_u64 v[222:223], s[60:61], 0, v[128:129]
	s_mov_b32 m0, s65
	s_nop 0
	global_load_lds_dwordx4 v[222:223], off
	s_mov_b32 m0, s66
	s_nop 0
	global_load_lds_dwordx4 v[224:225], off
	s_waitcnt vmcnt(8)
	s_waitcnt lgkmcnt(0)
	s_barrier
	s_setprio 1
	s_waitcnt lgkmcnt(0)
	v_mfma_f32_16x16x32_bf16 v[60:63], v[152:155], v[188:191], 0
	v_mfma_f32_16x16x32_bf16 v[60:63], v[156:159], v[192:195], v[60:63]
	v_mfma_f32_16x16x32_bf16 v[56:59], v[160:163], v[188:191], 0
	v_mfma_f32_16x16x32_bf16 v[56:59], v[164:167], v[192:195], v[56:59]
	v_mfma_f32_16x16x32_bf16 v[52:55], v[152:155], v[196:199], 0
	v_mfma_f32_16x16x32_bf16 v[52:55], v[156:159], v[200:203], v[52:55]
	v_mfma_f32_16x16x32_bf16 v[44:47], v[160:163], v[196:199], 0
	v_mfma_f32_16x16x32_bf16 v[44:47], v[164:167], v[200:203], v[44:47]
	v_mfma_f32_16x16x32_bf16 v[36:39], v[152:155], v[204:207], 0
	v_mfma_f32_16x16x32_bf16 v[36:39], v[156:159], v[208:211], v[36:39]
	v_mfma_f32_16x16x32_bf16 v[28:31], v[160:163], v[204:207], 0
	v_mfma_f32_16x16x32_bf16 v[28:31], v[164:167], v[208:211], v[28:31]
	v_mfma_f32_16x16x32_bf16 v[20:23], v[152:155], v[212:215], 0
	v_mfma_f32_16x16x32_bf16 v[20:23], v[156:159], v[216:219], v[20:23]
	v_mfma_f32_16x16x32_bf16 v[12:15], v[160:163], v[212:215], 0
	v_mfma_f32_16x16x32_bf16 v[12:15], v[164:167], v[216:219], v[12:15]
	v_mfma_f32_16x16x32_bf16 v[48:51], v[168:171], v[188:191], 0
	v_mfma_f32_16x16x32_bf16 v[48:51], v[172:175], v[192:195], v[48:51]
	v_mfma_f32_16x16x32_bf16 v[40:43], v[176:179], v[188:191], 0
	v_mfma_f32_16x16x32_bf16 v[40:43], v[184:187], v[192:195], v[40:43]
	v_mfma_f32_16x16x32_bf16 v[32:35], v[168:171], v[196:199], 0
	v_mfma_f32_16x16x32_bf16 v[32:35], v[172:175], v[200:203], v[32:35]
	v_mfma_f32_16x16x32_bf16 v[24:27], v[176:179], v[196:199], 0
	v_mfma_f32_16x16x32_bf16 v[24:27], v[184:187], v[200:203], v[24:27]
	v_mfma_f32_16x16x32_bf16 v[16:19], v[168:171], v[204:207], 0
	v_mfma_f32_16x16x32_bf16 v[16:19], v[172:175], v[208:211], v[16:19]
	v_mfma_f32_16x16x32_bf16 v[8:11], v[176:179], v[204:207], 0
	v_mfma_f32_16x16x32_bf16 v[8:11], v[184:187], v[208:211], v[8:11]
	v_mfma_f32_16x16x32_bf16 v[4:7], v[168:171], v[212:215], 0
	v_mfma_f32_16x16x32_bf16 v[4:7], v[172:175], v[216:219], v[4:7]
	v_mfma_f32_16x16x32_bf16 v[0:3], v[176:179], v[212:215], 0
	v_mfma_f32_16x16x32_bf16 v[0:3], v[184:187], v[216:219], v[0:3]
	s_setprio 0
	s_barrier
	s_branch .Lmid_gemm8
.LBB0_1031:
	ds_read_b128 v[152:155], v149
	ds_read_b128 v[156:159], v149 offset:1024
	ds_read_b128 v[160:163], v149 offset:2048
	ds_read_b128 v[164:167], v149 offset:3072
	ds_read_b128 v[168:171], v150
	ds_read_b128 v[172:175], v150 offset:1024
	ds_read_b128 v[176:179], v150 offset:2048
	ds_read_b128 v[184:187], v150 offset:3072
	ds_read_b128 v[188:191], v151
	ds_read_b128 v[192:195], v151 offset:1024
	ds_read_b128 v[196:199], v151 offset:2048
	ds_read_b128 v[200:203], v151 offset:3072
	ds_read_b128 v[204:207], v151 offset:4096
	ds_read_b128 v[208:211], v151 offset:5120
	ds_read_b128 v[212:215], v151 offset:6144
	ds_read_b128 v[216:219], v151 offset:7168
	s_add_u32 s56, s54, 0x100
	s_addc_u32 s57, s55, 0
	s_cmp_eq_u32 s88, 40
	s_cselect_b32 s61, s13, s57
	s_cselect_b32 s60, s12, s56
	s_cselect_b32 s59, s53, s87
	s_cselect_b32 s58, s52, s86
	v_lshl_add_u64 v[144:145], s[54:55], 0, v[136:137]
	s_add_i32 m0, s65, 0xc000
	s_nop 0
	global_load_lds_dwordx4 v[144:145], off
	v_lshl_add_u64 v[144:145], s[54:55], 0, v[138:139]
	s_add_i32 m0, s65, 0xe000
	s_nop 0
	global_load_lds_dwordx4 v[144:145], off
	s_waitcnt vmcnt(8)
	s_waitcnt lgkmcnt(0)
	s_barrier
	s_setprio 1
	s_waitcnt lgkmcnt(0)
	v_mfma_f32_16x16x32_bf16 v[124:127], v[152:155], v[188:191], v[124:127]
	v_mfma_f32_16x16x32_bf16 v[124:127], v[156:159], v[192:195], v[124:127]
	v_mfma_f32_16x16x32_bf16 v[120:123], v[160:163], v[188:191], v[120:123]
	v_mfma_f32_16x16x32_bf16 v[120:123], v[164:167], v[192:195], v[120:123]
	v_mfma_f32_16x16x32_bf16 v[116:119], v[152:155], v[196:199], v[116:119]
	v_mfma_f32_16x16x32_bf16 v[116:119], v[156:159], v[200:203], v[116:119]
	v_mfma_f32_16x16x32_bf16 v[108:111], v[160:163], v[196:199], v[108:111]
	v_mfma_f32_16x16x32_bf16 v[108:111], v[164:167], v[200:203], v[108:111]
	v_mfma_f32_16x16x32_bf16 v[100:103], v[152:155], v[204:207], v[100:103]
	v_mfma_f32_16x16x32_bf16 v[100:103], v[156:159], v[208:211], v[100:103]
	v_mfma_f32_16x16x32_bf16 v[92:95], v[160:163], v[204:207], v[92:95]
	v_mfma_f32_16x16x32_bf16 v[92:95], v[164:167], v[208:211], v[92:95]
	v_mfma_f32_16x16x32_bf16 v[84:87], v[152:155], v[212:215], v[84:87]
	v_mfma_f32_16x16x32_bf16 v[84:87], v[156:159], v[216:219], v[84:87]
	v_mfma_f32_16x16x32_bf16 v[76:79], v[160:163], v[212:215], v[76:79]
	v_mfma_f32_16x16x32_bf16 v[76:79], v[164:167], v[216:219], v[76:79]
	v_mfma_f32_16x16x32_bf16 v[112:115], v[168:171], v[188:191], v[112:115]
	v_mfma_f32_16x16x32_bf16 v[112:115], v[172:175], v[192:195], v[112:115]
	v_mfma_f32_16x16x32_bf16 v[104:107], v[176:179], v[188:191], v[104:107]
	v_mfma_f32_16x16x32_bf16 v[104:107], v[184:187], v[192:195], v[104:107]
	v_mfma_f32_16x16x32_bf16 v[96:99], v[168:171], v[196:199], v[96:99]
	v_mfma_f32_16x16x32_bf16 v[96:99], v[172:175], v[200:203], v[96:99]
	v_mfma_f32_16x16x32_bf16 v[88:91], v[176:179], v[196:199], v[88:91]
	v_mfma_f32_16x16x32_bf16 v[88:91], v[184:187], v[200:203], v[88:91]
	v_mfma_f32_16x16x32_bf16 v[80:83], v[168:171], v[204:207], v[80:83]
	v_mfma_f32_16x16x32_bf16 v[80:83], v[172:175], v[208:211], v[80:83]
	v_mfma_f32_16x16x32_bf16 v[72:75], v[176:179], v[204:207], v[72:75]
	v_mfma_f32_16x16x32_bf16 v[72:75], v[184:187], v[208:211], v[72:75]
	v_mfma_f32_16x16x32_bf16 v[68:71], v[168:171], v[212:215], v[68:71]
	v_mfma_f32_16x16x32_bf16 v[68:71], v[172:175], v[216:219], v[68:71]
	v_mfma_f32_16x16x32_bf16 v[64:67], v[176:179], v[212:215], v[64:67]
	v_mfma_f32_16x16x32_bf16 v[64:67], v[184:187], v[216:219], v[64:67]
	s_setprio 0
	s_barrier
	ds_read_b128 v[188:191], v151 offset:16384
	ds_read_b128 v[192:195], v151 offset:17408
	ds_read_b128 v[196:199], v151 offset:18432
	ds_read_b128 v[200:203], v151 offset:19456
	ds_read_b128 v[204:207], v151 offset:20480
	ds_read_b128 v[208:211], v151 offset:21504
	ds_read_b128 v[212:215], v151 offset:22528
	ds_read_b128 v[216:219], v151 offset:23552
	s_add_i32 s54, s72, s64
	v_lshl_add_u64 v[144:145], s[58:59], 0, v[130:131]
	s_mov_b32 m0, s54
	s_nop 0
	global_load_lds_dwordx4 v[144:145], off
	s_add_i32 m0, s54, 0x2000
	s_add_u32 s54, s58, 0xb0000
	v_lshl_add_u64 v[220:221], s[58:59], 0, v[134:135]
	s_addc_u32 s55, s59, 0
	s_add_i32 s79, s73, s64
	global_load_lds_dwordx4 v[220:221], off
	v_lshl_add_u64 v[222:223], s[54:55], 0, v[130:131]
	s_mov_b32 m0, s79
	v_lshl_add_u64 v[224:225], s[60:61], 0, v[132:133]
	global_load_lds_dwordx4 v[222:223], off
	v_lshl_add_u64 v[222:223], s[54:55], 0, v[134:135]
	s_add_i32 m0, s79, 0x2000
	s_nop 0
	global_load_lds_dwordx4 v[222:223], off
	v_lshl_add_u64 v[222:223], s[60:61], 0, v[128:129]
	s_mov_b32 m0, s65
	s_nop 0
	global_load_lds_dwordx4 v[222:223], off
	s_mov_b32 m0, s66
	s_nop 0
	global_load_lds_dwordx4 v[224:225], off
	s_waitcnt vmcnt(8)
	s_waitcnt lgkmcnt(0)
	s_barrier
	s_setprio 1
	s_waitcnt lgkmcnt(0)
	v_mfma_f32_16x16x32_bf16 v[60:63], v[152:155], v[188:191], v[60:63]
	v_mfma_f32_16x16x32_bf16 v[60:63], v[156:159], v[192:195], v[60:63]
	v_mfma_f32_16x16x32_bf16 v[56:59], v[160:163], v[188:191], v[56:59]
	v_mfma_f32_16x16x32_bf16 v[56:59], v[164:167], v[192:195], v[56:59]
	v_mfma_f32_16x16x32_bf16 v[52:55], v[152:155], v[196:199], v[52:55]
	v_mfma_f32_16x16x32_bf16 v[52:55], v[156:159], v[200:203], v[52:55]
	v_mfma_f32_16x16x32_bf16 v[44:47], v[160:163], v[196:199], v[44:47]
	v_mfma_f32_16x16x32_bf16 v[44:47], v[164:167], v[200:203], v[44:47]
	v_mfma_f32_16x16x32_bf16 v[36:39], v[152:155], v[204:207], v[36:39]
	v_mfma_f32_16x16x32_bf16 v[36:39], v[156:159], v[208:211], v[36:39]
	v_mfma_f32_16x16x32_bf16 v[28:31], v[160:163], v[204:207], v[28:31]
	v_mfma_f32_16x16x32_bf16 v[28:31], v[164:167], v[208:211], v[28:31]
	v_mfma_f32_16x16x32_bf16 v[20:23], v[152:155], v[212:215], v[20:23]
	v_mfma_f32_16x16x32_bf16 v[20:23], v[156:159], v[216:219], v[20:23]
	v_mfma_f32_16x16x32_bf16 v[12:15], v[160:163], v[212:215], v[12:15]
	v_mfma_f32_16x16x32_bf16 v[12:15], v[164:167], v[216:219], v[12:15]
	v_mfma_f32_16x16x32_bf16 v[48:51], v[168:171], v[188:191], v[48:51]
	v_mfma_f32_16x16x32_bf16 v[48:51], v[172:175], v[192:195], v[48:51]
	v_mfma_f32_16x16x32_bf16 v[40:43], v[176:179], v[188:191], v[40:43]
	v_mfma_f32_16x16x32_bf16 v[40:43], v[184:187], v[192:195], v[40:43]
	v_mfma_f32_16x16x32_bf16 v[32:35], v[168:171], v[196:199], v[32:35]
	v_mfma_f32_16x16x32_bf16 v[32:35], v[172:175], v[200:203], v[32:35]
	v_mfma_f32_16x16x32_bf16 v[24:27], v[176:179], v[196:199], v[24:27]
	v_mfma_f32_16x16x32_bf16 v[24:27], v[184:187], v[200:203], v[24:27]
	v_mfma_f32_16x16x32_bf16 v[16:19], v[168:171], v[204:207], v[16:19]
	v_mfma_f32_16x16x32_bf16 v[16:19], v[172:175], v[208:211], v[16:19]
	v_mfma_f32_16x16x32_bf16 v[8:11], v[176:179], v[204:207], v[8:11]
	v_mfma_f32_16x16x32_bf16 v[8:11], v[184:187], v[208:211], v[8:11]
	v_mfma_f32_16x16x32_bf16 v[4:7], v[168:171], v[212:215], v[4:7]
	v_mfma_f32_16x16x32_bf16 v[4:7], v[172:175], v[216:219], v[4:7]
	v_mfma_f32_16x16x32_bf16 v[0:3], v[176:179], v[212:215], v[0:3]
	v_mfma_f32_16x16x32_bf16 v[0:3], v[184:187], v[216:219], v[0:3]
	s_setprio 0
	s_barrier
.Lmid_gemm8:
	s_add_i32 s79, 0, 0x18000
	s_add_i32 s89, 0, 0x1c000
	v_add_u32_e32 v164, s79, v147
	v_add_u32_e32 v181, s89, v147
	ds_read_b128 v[152:155], v164
	ds_read_b128 v[156:159], v164 offset:1024
	ds_read_b128 v[160:163], v164 offset:2048
	ds_read_b128 v[164:167], v164 offset:3072
	ds_read_b128 v[168:171], v181
	ds_read_b128 v[172:175], v181 offset:1024
	ds_read_b128 v[176:179], v181 offset:2048
	ds_read_b128 v[184:187], v181 offset:3072
	ds_read_b128 v[188:191], v151 offset:32768
	ds_read_b128 v[192:195], v151 offset:33792
	ds_read_b128 v[196:199], v151 offset:34816
	ds_read_b128 v[200:203], v151 offset:35840
	ds_read_b128 v[204:207], v151 offset:36864
	ds_read_b128 v[208:211], v151 offset:37888
	ds_read_b128 v[212:215], v151 offset:38912
	ds_read_b128 v[216:219], v151 offset:39936
	s_add_u32 s54, s60, 0xb0000
	s_addc_u32 s55, s61, 0
	s_mov_b32 m0, s67
	v_lshl_add_u64 v[226:227], s[54:55], 0, v[128:129]
	global_load_lds_dwordx4 v[226:227], off
	v_lshl_add_u64 v[226:227], s[54:55], 0, v[132:133]
	s_mov_b32 m0, s68
	s_nop 0
	global_load_lds_dwordx4 v[226:227], off
	s_waitcnt vmcnt(8)
	s_waitcnt lgkmcnt(0)
	s_barrier
	s_setprio 1
	s_waitcnt lgkmcnt(0)
	v_mfma_f32_16x16x32_bf16 v[124:127], v[152:155], v[188:191], v[124:127]
	v_mfma_f32_16x16x32_bf16 v[124:127], v[156:159], v[192:195], v[124:127]
	v_mfma_f32_16x16x32_bf16 v[120:123], v[160:163], v[188:191], v[120:123]
	v_mfma_f32_16x16x32_bf16 v[120:123], v[164:167], v[192:195], v[120:123]
	v_mfma_f32_16x16x32_bf16 v[116:119], v[152:155], v[196:199], v[116:119]
	v_mfma_f32_16x16x32_bf16 v[116:119], v[156:159], v[200:203], v[116:119]
	v_mfma_f32_16x16x32_bf16 v[108:111], v[160:163], v[196:199], v[108:111]
	v_mfma_f32_16x16x32_bf16 v[108:111], v[164:167], v[200:203], v[108:111]
	v_mfma_f32_16x16x32_bf16 v[100:103], v[152:155], v[204:207], v[100:103]
	v_mfma_f32_16x16x32_bf16 v[100:103], v[156:159], v[208:211], v[100:103]
	v_mfma_f32_16x16x32_bf16 v[92:95], v[160:163], v[204:207], v[92:95]
	v_mfma_f32_16x16x32_bf16 v[92:95], v[164:167], v[208:211], v[92:95]
	v_mfma_f32_16x16x32_bf16 v[84:87], v[152:155], v[212:215], v[84:87]
	v_mfma_f32_16x16x32_bf16 v[84:87], v[156:159], v[216:219], v[84:87]
	v_mfma_f32_16x16x32_bf16 v[76:79], v[160:163], v[212:215], v[76:79]
	v_mfma_f32_16x16x32_bf16 v[76:79], v[164:167], v[216:219], v[76:79]
	v_mfma_f32_16x16x32_bf16 v[112:115], v[168:171], v[188:191], v[112:115]
	v_mfma_f32_16x16x32_bf16 v[112:115], v[172:175], v[192:195], v[112:115]
	v_mfma_f32_16x16x32_bf16 v[104:107], v[176:179], v[188:191], v[104:107]
	v_mfma_f32_16x16x32_bf16 v[104:107], v[184:187], v[192:195], v[104:107]
	v_mfma_f32_16x16x32_bf16 v[96:99], v[168:171], v[196:199], v[96:99]
	v_mfma_f32_16x16x32_bf16 v[96:99], v[172:175], v[200:203], v[96:99]
	v_mfma_f32_16x16x32_bf16 v[88:91], v[176:179], v[196:199], v[88:91]
	v_mfma_f32_16x16x32_bf16 v[88:91], v[184:187], v[200:203], v[88:91]
	v_mfma_f32_16x16x32_bf16 v[80:83], v[168:171], v[204:207], v[80:83]
	v_mfma_f32_16x16x32_bf16 v[80:83], v[172:175], v[208:211], v[80:83]
	v_mfma_f32_16x16x32_bf16 v[72:75], v[176:179], v[204:207], v[72:75]
	v_mfma_f32_16x16x32_bf16 v[72:75], v[184:187], v[208:211], v[72:75]
	v_mfma_f32_16x16x32_bf16 v[68:71], v[168:171], v[212:215], v[68:71]
	v_mfma_f32_16x16x32_bf16 v[68:71], v[172:175], v[216:219], v[68:71]
	v_mfma_f32_16x16x32_bf16 v[64:67], v[176:179], v[212:215], v[64:67]
	v_mfma_f32_16x16x32_bf16 v[64:67], v[184:187], v[216:219], v[64:67]
	s_setprio 0
	s_barrier
	ds_read_b128 v[188:191], v151 offset:49152
	ds_read_b128 v[192:195], v151 offset:50176
	ds_read_b128 v[196:199], v151 offset:51200
	ds_read_b128 v[200:203], v151 offset:52224
	ds_read_b128 v[204:207], v151 offset:53248
	ds_read_b128 v[208:211], v151 offset:54272
	ds_read_b128 v[212:215], v151 offset:55296
	ds_read_b128 v[216:219], v151 offset:56320
	s_add_i32 s54, s79, s64
	v_lshl_add_u64 v[144:145], v[144:145], 0, s[16:17]
	s_mov_b32 m0, s54
	s_nop 0
	global_load_lds_dwordx4 v[144:145], off
	s_add_i32 m0, s54, 0x2000
	s_add_u32 s54, s58, 0xb0080
	v_lshl_add_u64 v[144:145], v[220:221], 0, s[16:17]
	s_addc_u32 s55, s59, 0
	s_add_i32 s58, s89, s64
	global_load_lds_dwordx4 v[144:145], off
	v_lshl_add_u64 v[144:145], s[54:55], 0, v[130:131]
	s_mov_b32 m0, s58
	s_nop 0
	global_load_lds_dwordx4 v[144:145], off
	v_lshl_add_u64 v[144:145], s[54:55], 0, v[134:135]
	s_add_i32 m0, s58, 0x2000
	s_nop 0
	global_load_lds_dwordx4 v[144:145], off
	v_lshl_add_u64 v[144:145], v[222:223], 0, s[16:17]
	s_mov_b32 m0, s70
	s_nop 0
	global_load_lds_dwordx4 v[144:145], off
	v_lshl_add_u64 v[144:145], v[224:225], 0, s[16:17]
	s_mov_b32 m0, s71
	s_nop 0
	global_load_lds_dwordx4 v[144:145], off
	s_waitcnt vmcnt(8)
	s_waitcnt lgkmcnt(0)
	s_barrier
	s_setprio 1
	s_waitcnt lgkmcnt(0)
	v_mfma_f32_16x16x32_bf16 v[60:63], v[152:155], v[188:191], v[60:63]
	v_mfma_f32_16x16x32_bf16 v[60:63], v[156:159], v[192:195], v[60:63]
	v_mfma_f32_16x16x32_bf16 v[56:59], v[160:163], v[188:191], v[56:59]
	v_mfma_f32_16x16x32_bf16 v[56:59], v[164:167], v[192:195], v[56:59]
	v_mfma_f32_16x16x32_bf16 v[52:55], v[152:155], v[196:199], v[52:55]
	v_mfma_f32_16x16x32_bf16 v[52:55], v[156:159], v[200:203], v[52:55]
	v_mfma_f32_16x16x32_bf16 v[44:47], v[160:163], v[196:199], v[44:47]
	v_mfma_f32_16x16x32_bf16 v[44:47], v[164:167], v[200:203], v[44:47]
	v_mfma_f32_16x16x32_bf16 v[36:39], v[152:155], v[204:207], v[36:39]
	v_mfma_f32_16x16x32_bf16 v[36:39], v[156:159], v[208:211], v[36:39]
	v_mfma_f32_16x16x32_bf16 v[28:31], v[160:163], v[204:207], v[28:31]
	v_mfma_f32_16x16x32_bf16 v[28:31], v[164:167], v[208:211], v[28:31]
	v_mfma_f32_16x16x32_bf16 v[20:23], v[152:155], v[212:215], v[20:23]
	v_mfma_f32_16x16x32_bf16 v[20:23], v[156:159], v[216:219], v[20:23]
	v_mfma_f32_16x16x32_bf16 v[12:15], v[160:163], v[212:215], v[12:15]
	v_mfma_f32_16x16x32_bf16 v[12:15], v[164:167], v[216:219], v[12:15]
	v_mfma_f32_16x16x32_bf16 v[48:51], v[168:171], v[188:191], v[48:51]
	v_mfma_f32_16x16x32_bf16 v[48:51], v[172:175], v[192:195], v[48:51]
	v_mfma_f32_16x16x32_bf16 v[40:43], v[176:179], v[188:191], v[40:43]
	v_mfma_f32_16x16x32_bf16 v[40:43], v[184:187], v[192:195], v[40:43]
	v_mfma_f32_16x16x32_bf16 v[32:35], v[168:171], v[196:199], v[32:35]
	v_mfma_f32_16x16x32_bf16 v[32:35], v[172:175], v[200:203], v[32:35]
	v_mfma_f32_16x16x32_bf16 v[24:27], v[176:179], v[196:199], v[24:27]
	v_mfma_f32_16x16x32_bf16 v[24:27], v[184:187], v[200:203], v[24:27]
	v_mfma_f32_16x16x32_bf16 v[16:19], v[168:171], v[204:207], v[16:19]
	v_mfma_f32_16x16x32_bf16 v[16:19], v[172:175], v[208:211], v[16:19]
	v_mfma_f32_16x16x32_bf16 v[8:11], v[176:179], v[204:207], v[8:11]
	v_mfma_f32_16x16x32_bf16 v[8:11], v[184:187], v[208:211], v[8:11]
	v_mfma_f32_16x16x32_bf16 v[4:7], v[168:171], v[212:215], v[4:7]
	v_mfma_f32_16x16x32_bf16 v[4:7], v[172:175], v[216:219], v[4:7]
	v_mfma_f32_16x16x32_bf16 v[0:3], v[176:179], v[212:215], v[0:3]
	v_mfma_f32_16x16x32_bf16 v[0:3], v[184:187], v[216:219], v[0:3]
	s_setprio 0
	s_barrier
	s_add_i32 s88, s88, 2
	s_add_u32 s86, s86, 0x100
	s_addc_u32 s87, s87, 0
	s_cmp_gt_u32 s88, 41
	s_mov_b64 s[54:55], s[56:57]
	s_cbranch_scc0 .LBB0_1031
	s_and_b64 vcc, exec, s[18:19]
	s_cbranch_vccz .LBB0_1034
	s_barrier

.LBB0_1161:
	s_ashr_i32 s53, s52, 31
	s_lshl_b64 s[54:55], s[52:53], 19
	s_add_u32 s54, s80, s54
	s_addc_u32 s55, s81, s55
	s_and_b64 s[56:57], s[10:11], exec
	s_cselect_b32 s53, s55, s61
	s_cselect_b32 s83, s54, s60
	s_ashr_i32 s49, s48, 31
	s_lshl_b64 s[56:57], s[48:49], 19
	s_add_u32 s56, s66, s56
	s_addc_u32 s57, s67, s57
	s_and_b64 s[64:65], s[10:11], exec
	s_cselect_b32 s49, s57, s63
	s_cselect_b32 s84, s56, s62
	s_add_u32 s60, s60, 0x40080
	s_addc_u32 s61, s61, 0
	s_add_u32 s85, s62, 0x100
	s_addc_u32 s86, s63, 0
	s_mov_b32 s87, -2
	ds_read_b128 v[152:155], v148
	ds_read_b128 v[156:159], v148 offset:1024
	ds_read_b128 v[160:163], v148 offset:2048
	ds_read_b128 v[164:167], v148 offset:3072
	ds_read_b128 v[168:171], v149
	ds_read_b128 v[172:175], v149 offset:1024
	ds_read_b128 v[176:179], v149 offset:2048
	ds_read_b128 v[184:187], v149 offset:3072
	s_add_u32 s62, s60, 0xfffc0080
	s_addc_u32 s63, s61, -1
	s_cmp_eq_u32 s87, 12
	s_cselect_b32 s65, s53, s63
	s_cselect_b32 s64, s83, s62
	s_cselect_b32 s63, s49, s86
	s_cselect_b32 s62, s84, s85
	v_lshl_add_u64 v[220:221], s[60:61], 0, v[138:139]
	s_add_i32 m0, s69, 0xc000
	ds_read_b128 v[188:191], v150
	ds_read_b128 v[192:195], v150 offset:1024
	ds_read_b128 v[196:199], v150 offset:2048
	ds_read_b128 v[200:203], v150 offset:3072
	ds_read_b128 v[204:207], v150 offset:4096
	ds_read_b128 v[208:211], v150 offset:5120
	ds_read_b128 v[212:215], v150 offset:6144
	ds_read_b128 v[216:219], v150 offset:7168
	global_load_lds_dwordx4 v[220:221], off
	v_lshl_add_u64 v[220:221], s[60:61], 0, v[140:141]
	s_add_i32 m0, s69, 0xe000
	s_nop 0
	global_load_lds_dwordx4 v[220:221], off
	s_waitcnt vmcnt(8)
	s_waitcnt lgkmcnt(0)
	s_barrier
	s_setprio 1
	s_waitcnt lgkmcnt(0)
	v_mfma_f32_16x16x32_bf16 v[124:127], v[152:155], v[188:191], 0
	v_mfma_f32_16x16x32_bf16 v[124:127], v[156:159], v[192:195], v[124:127]
	v_mfma_f32_16x16x32_bf16 v[120:123], v[160:163], v[188:191], 0
	v_mfma_f32_16x16x32_bf16 v[120:123], v[164:167], v[192:195], v[120:123]
	v_mfma_f32_16x16x32_bf16 v[116:119], v[152:155], v[196:199], 0
	v_mfma_f32_16x16x32_bf16 v[116:119], v[156:159], v[200:203], v[116:119]
	v_mfma_f32_16x16x32_bf16 v[112:115], v[160:163], v[196:199], 0
	v_mfma_f32_16x16x32_bf16 v[112:115], v[164:167], v[200:203], v[112:115]
	v_mfma_f32_16x16x32_bf16 v[108:111], v[152:155], v[204:207], 0
	v_mfma_f32_16x16x32_bf16 v[108:111], v[156:159], v[208:211], v[108:111]
	v_mfma_f32_16x16x32_bf16 v[104:107], v[160:163], v[204:207], 0
	v_mfma_f32_16x16x32_bf16 v[104:107], v[164:167], v[208:211], v[104:107]
	v_mfma_f32_16x16x32_bf16 v[100:103], v[152:155], v[212:215], 0
	v_mfma_f32_16x16x32_bf16 v[100:103], v[156:159], v[216:219], v[100:103]
	v_mfma_f32_16x16x32_bf16 v[96:99], v[160:163], v[212:215], 0
	v_mfma_f32_16x16x32_bf16 v[96:99], v[164:167], v[216:219], v[96:99]
	v_mfma_f32_16x16x32_bf16 v[68:71], v[168:171], v[188:191], 0
	v_mfma_f32_16x16x32_bf16 v[68:71], v[172:175], v[192:195], v[68:71]
	v_mfma_f32_16x16x32_bf16 v[64:67], v[176:179], v[188:191], 0
	v_mfma_f32_16x16x32_bf16 v[64:67], v[184:187], v[192:195], v[64:67]
	v_mfma_f32_16x16x32_bf16 v[52:55], v[168:171], v[196:199], 0
	v_mfma_f32_16x16x32_bf16 v[52:55], v[172:175], v[200:203], v[52:55]
	v_mfma_f32_16x16x32_bf16 v[48:51], v[176:179], v[196:199], 0
	v_mfma_f32_16x16x32_bf16 v[48:51], v[184:187], v[200:203], v[48:51]
	v_mfma_f32_16x16x32_bf16 v[44:47], v[168:171], v[204:207], 0
	v_mfma_f32_16x16x32_bf16 v[44:47], v[172:175], v[208:211], v[44:47]
	v_mfma_f32_16x16x32_bf16 v[40:43], v[176:179], v[204:207], 0
	v_mfma_f32_16x16x32_bf16 v[40:43], v[184:187], v[208:211], v[40:43]
	v_mfma_f32_16x16x32_bf16 v[36:39], v[168:171], v[212:215], 0
	v_mfma_f32_16x16x32_bf16 v[36:39], v[172:175], v[216:219], v[36:39]
	v_mfma_f32_16x16x32_bf16 v[32:35], v[176:179], v[212:215], 0
	v_mfma_f32_16x16x32_bf16 v[32:35], v[184:187], v[216:219], v[32:35]
	s_setprio 0
	s_barrier
	ds_read_b128 v[188:191], v150 offset:16384
	ds_read_b128 v[192:195], v150 offset:17408
	ds_read_b128 v[196:199], v150 offset:18432
	ds_read_b128 v[200:203], v150 offset:19456
	ds_read_b128 v[204:207], v150 offset:20480
	ds_read_b128 v[208:211], v150 offset:21504
	ds_read_b128 v[212:215], v150 offset:22528
	ds_read_b128 v[216:219], v150 offset:23552
	s_add_i32 s79, s77, s68
	v_lshl_add_u64 v[220:221], s[62:63], 0, v[130:131]
	s_mov_b32 m0, s79
	s_nop 0
	global_load_lds_dwordx4 v[220:221], off
	s_add_i32 m0, s79, 0x2000
	s_add_u32 s88, s62, 0x40000
	v_lshl_add_u64 v[222:223], s[62:63], 0, v[134:135]
	s_addc_u32 s89, s63, 0
	s_add_i32 s79, s82, s68
	global_load_lds_dwordx4 v[222:223], off
	v_lshl_add_u64 v[224:225], s[88:89], 0, v[130:131]
	s_mov_b32 m0, s79
	v_lshl_add_u64 v[226:227], s[64:65], 0, v[132:133]
	global_load_lds_dwordx4 v[224:225], off
	v_lshl_add_u64 v[224:225], s[88:89], 0, v[134:135]
	s_add_i32 m0, s79, 0x2000
	s_nop 0
	global_load_lds_dwordx4 v[224:225], off
	v_lshl_add_u64 v[224:225], s[64:65], 0, v[128:129]
	s_mov_b32 m0, s69
	s_nop 0
	global_load_lds_dwordx4 v[224:225], off
	s_mov_b32 m0, s70
	s_nop 0
	global_load_lds_dwordx4 v[226:227], off
	s_waitcnt vmcnt(8)
	s_waitcnt lgkmcnt(0)
	s_barrier
	s_setprio 1
	s_waitcnt lgkmcnt(0)
	v_mfma_f32_16x16x32_bf16 v[92:95], v[152:155], v[188:191], 0
	v_mfma_f32_16x16x32_bf16 v[92:95], v[156:159], v[192:195], v[92:95]
	v_mfma_f32_16x16x32_bf16 v[88:91], v[160:163], v[188:191], 0
	v_mfma_f32_16x16x32_bf16 v[88:91], v[164:167], v[192:195], v[88:91]
	v_mfma_f32_16x16x32_bf16 v[84:87], v[152:155], v[196:199], 0
	v_mfma_f32_16x16x32_bf16 v[84:87], v[156:159], v[200:203], v[84:87]
	v_mfma_f32_16x16x32_bf16 v[80:83], v[160:163], v[196:199], 0
	v_mfma_f32_16x16x32_bf16 v[80:83], v[164:167], v[200:203], v[80:83]
	v_mfma_f32_16x16x32_bf16 v[76:79], v[152:155], v[204:207], 0
	v_mfma_f32_16x16x32_bf16 v[76:79], v[156:159], v[208:211], v[76:79]
	v_mfma_f32_16x16x32_bf16 v[72:75], v[160:163], v[204:207], 0
	v_mfma_f32_16x16x32_bf16 v[72:75], v[164:167], v[208:211], v[72:75]
	v_mfma_f32_16x16x32_bf16 v[60:63], v[152:155], v[212:215], 0
	v_mfma_f32_16x16x32_bf16 v[60:63], v[156:159], v[216:219], v[60:63]
	v_mfma_f32_16x16x32_bf16 v[56:59], v[160:163], v[212:215], 0
	v_mfma_f32_16x16x32_bf16 v[56:59], v[164:167], v[216:219], v[56:59]
	v_mfma_f32_16x16x32_bf16 v[28:31], v[168:171], v[188:191], 0
	v_mfma_f32_16x16x32_bf16 v[28:31], v[172:175], v[192:195], v[28:31]
	v_mfma_f32_16x16x32_bf16 v[24:27], v[176:179], v[188:191], 0
	v_mfma_f32_16x16x32_bf16 v[24:27], v[184:187], v[192:195], v[24:27]
	v_mfma_f32_16x16x32_bf16 v[20:23], v[168:171], v[196:199], 0
	v_mfma_f32_16x16x32_bf16 v[20:23], v[172:175], v[200:203], v[20:23]
	v_mfma_f32_16x16x32_bf16 v[16:19], v[176:179], v[196:199], 0
	v_mfma_f32_16x16x32_bf16 v[16:19], v[184:187], v[200:203], v[16:19]
	v_mfma_f32_16x16x32_bf16 v[12:15], v[168:171], v[204:207], 0
	v_mfma_f32_16x16x32_bf16 v[12:15], v[172:175], v[208:211], v[12:15]
	v_mfma_f32_16x16x32_bf16 v[8:11], v[176:179], v[204:207], 0
	v_mfma_f32_16x16x32_bf16 v[8:11], v[184:187], v[208:211], v[8:11]
	v_mfma_f32_16x16x32_bf16 v[4:7], v[168:171], v[212:215], 0
	v_mfma_f32_16x16x32_bf16 v[4:7], v[172:175], v[216:219], v[4:7]
	v_mfma_f32_16x16x32_bf16 v[0:3], v[176:179], v[212:215], 0
	v_mfma_f32_16x16x32_bf16 v[0:3], v[184:187], v[216:219], v[0:3]
	s_setprio 0
	s_barrier
	s_branch .Lmid_gemm9
.LBB0_1162:
	ds_read_b128 v[152:155], v148
	ds_read_b128 v[156:159], v148 offset:1024
	ds_read_b128 v[160:163], v148 offset:2048
	ds_read_b128 v[164:167], v148 offset:3072
	ds_read_b128 v[168:171], v149
	ds_read_b128 v[172:175], v149 offset:1024
	ds_read_b128 v[176:179], v149 offset:2048
	ds_read_b128 v[184:187], v149 offset:3072
	ds_read_b128 v[188:191], v150
	ds_read_b128 v[192:195], v150 offset:1024
	ds_read_b128 v[196:199], v150 offset:2048
	ds_read_b128 v[200:203], v150 offset:3072
	ds_read_b128 v[204:207], v150 offset:4096
	ds_read_b128 v[208:211], v150 offset:5120
	ds_read_b128 v[212:215], v150 offset:6144
	ds_read_b128 v[216:219], v150 offset:7168
	s_add_u32 s62, s60, 0xfffc0080
	s_addc_u32 s63, s61, -1
	s_cmp_eq_u32 s87, 12
	s_cselect_b32 s65, s53, s63
	s_cselect_b32 s64, s83, s62
	s_cselect_b32 s63, s49, s86
	s_cselect_b32 s62, s84, s85
	v_lshl_add_u64 v[220:221], s[60:61], 0, v[138:139]
	s_add_i32 m0, s69, 0xc000
	s_nop 0
	global_load_lds_dwordx4 v[220:221], off
	v_lshl_add_u64 v[220:221], s[60:61], 0, v[140:141]
	s_add_i32 m0, s69, 0xe000
	s_nop 0
	global_load_lds_dwordx4 v[220:221], off
	s_waitcnt vmcnt(8)
	s_waitcnt lgkmcnt(0)
	s_barrier
	s_setprio 1
	s_waitcnt lgkmcnt(0)
	v_mfma_f32_16x16x32_bf16 v[124:127], v[152:155], v[188:191], v[124:127]
	v_mfma_f32_16x16x32_bf16 v[124:127], v[156:159], v[192:195], v[124:127]
	v_mfma_f32_16x16x32_bf16 v[120:123], v[160:163], v[188:191], v[120:123]
	v_mfma_f32_16x16x32_bf16 v[120:123], v[164:167], v[192:195], v[120:123]
	v_mfma_f32_16x16x32_bf16 v[116:119], v[152:155], v[196:199], v[116:119]
	v_mfma_f32_16x16x32_bf16 v[116:119], v[156:159], v[200:203], v[116:119]
	v_mfma_f32_16x16x32_bf16 v[112:115], v[160:163], v[196:199], v[112:115]
	v_mfma_f32_16x16x32_bf16 v[112:115], v[164:167], v[200:203], v[112:115]
	v_mfma_f32_16x16x32_bf16 v[108:111], v[152:155], v[204:207], v[108:111]
	v_mfma_f32_16x16x32_bf16 v[108:111], v[156:159], v[208:211], v[108:111]
	v_mfma_f32_16x16x32_bf16 v[104:107], v[160:163], v[204:207], v[104:107]
	v_mfma_f32_16x16x32_bf16 v[104:107], v[164:167], v[208:211], v[104:107]
	v_mfma_f32_16x16x32_bf16 v[100:103], v[152:155], v[212:215], v[100:103]
	v_mfma_f32_16x16x32_bf16 v[100:103], v[156:159], v[216:219], v[100:103]
	v_mfma_f32_16x16x32_bf16 v[96:99], v[160:163], v[212:215], v[96:99]
	v_mfma_f32_16x16x32_bf16 v[96:99], v[164:167], v[216:219], v[96:99]
	v_mfma_f32_16x16x32_bf16 v[68:71], v[168:171], v[188:191], v[68:71]
	v_mfma_f32_16x16x32_bf16 v[68:71], v[172:175], v[192:195], v[68:71]
	v_mfma_f32_16x16x32_bf16 v[64:67], v[176:179], v[188:191], v[64:67]
	v_mfma_f32_16x16x32_bf16 v[64:67], v[184:187], v[192:195], v[64:67]
	v_mfma_f32_16x16x32_bf16 v[52:55], v[168:171], v[196:199], v[52:55]
	v_mfma_f32_16x16x32_bf16 v[52:55], v[172:175], v[200:203], v[52:55]
	v_mfma_f32_16x16x32_bf16 v[48:51], v[176:179], v[196:199], v[48:51]
	v_mfma_f32_16x16x32_bf16 v[48:51], v[184:187], v[200:203], v[48:51]
	v_mfma_f32_16x16x32_bf16 v[44:47], v[168:171], v[204:207], v[44:47]
	v_mfma_f32_16x16x32_bf16 v[44:47], v[172:175], v[208:211], v[44:47]
	v_mfma_f32_16x16x32_bf16 v[40:43], v[176:179], v[204:207], v[40:43]
	v_mfma_f32_16x16x32_bf16 v[40:43], v[184:187], v[208:211], v[40:43]
	v_mfma_f32_16x16x32_bf16 v[36:39], v[168:171], v[212:215], v[36:39]
	v_mfma_f32_16x16x32_bf16 v[36:39], v[172:175], v[216:219], v[36:39]
	v_mfma_f32_16x16x32_bf16 v[32:35], v[176:179], v[212:215], v[32:35]
	v_mfma_f32_16x16x32_bf16 v[32:35], v[184:187], v[216:219], v[32:35]
	s_setprio 0
	s_barrier
	ds_read_b128 v[188:191], v150 offset:16384
	ds_read_b128 v[192:195], v150 offset:17408
	ds_read_b128 v[196:199], v150 offset:18432
	ds_read_b128 v[200:203], v150 offset:19456
	ds_read_b128 v[204:207], v150 offset:20480
	ds_read_b128 v[208:211], v150 offset:21504
	ds_read_b128 v[212:215], v150 offset:22528
	ds_read_b128 v[216:219], v150 offset:23552
	s_add_i32 s79, s77, s68
	v_lshl_add_u64 v[220:221], s[62:63], 0, v[130:131]
	s_mov_b32 m0, s79
	s_nop 0
	global_load_lds_dwordx4 v[220:221], off
	s_add_i32 m0, s79, 0x2000
	s_add_u32 s88, s62, 0x40000
	v_lshl_add_u64 v[222:223], s[62:63], 0, v[134:135]
	s_addc_u32 s89, s63, 0
	s_add_i32 s79, s82, s68
	global_load_lds_dwordx4 v[222:223], off
	v_lshl_add_u64 v[224:225], s[88:89], 0, v[130:131]
	s_mov_b32 m0, s79
	v_lshl_add_u64 v[226:227], s[64:65], 0, v[132:133]
	global_load_lds_dwordx4 v[224:225], off
	v_lshl_add_u64 v[224:225], s[88:89], 0, v[134:135]
	s_add_i32 m0, s79, 0x2000
	s_nop 0
	global_load_lds_dwordx4 v[224:225], off
	v_lshl_add_u64 v[224:225], s[64:65], 0, v[128:129]
	s_mov_b32 m0, s69
	s_nop 0
	global_load_lds_dwordx4 v[224:225], off
	s_mov_b32 m0, s70
	s_nop 0
	global_load_lds_dwordx4 v[226:227], off
	s_waitcnt vmcnt(8)
	s_waitcnt lgkmcnt(0)
	s_barrier
	s_setprio 1
	s_waitcnt lgkmcnt(0)
	v_mfma_f32_16x16x32_bf16 v[92:95], v[152:155], v[188:191], v[92:95]
	v_mfma_f32_16x16x32_bf16 v[92:95], v[156:159], v[192:195], v[92:95]
	v_mfma_f32_16x16x32_bf16 v[88:91], v[160:163], v[188:191], v[88:91]
	v_mfma_f32_16x16x32_bf16 v[88:91], v[164:167], v[192:195], v[88:91]
	v_mfma_f32_16x16x32_bf16 v[84:87], v[152:155], v[196:199], v[84:87]
	v_mfma_f32_16x16x32_bf16 v[84:87], v[156:159], v[200:203], v[84:87]
	v_mfma_f32_16x16x32_bf16 v[80:83], v[160:163], v[196:199], v[80:83]
	v_mfma_f32_16x16x32_bf16 v[80:83], v[164:167], v[200:203], v[80:83]
	v_mfma_f32_16x16x32_bf16 v[76:79], v[152:155], v[204:207], v[76:79]
	v_mfma_f32_16x16x32_bf16 v[76:79], v[156:159], v[208:211], v[76:79]
	v_mfma_f32_16x16x32_bf16 v[72:75], v[160:163], v[204:207], v[72:75]
	v_mfma_f32_16x16x32_bf16 v[72:75], v[164:167], v[208:211], v[72:75]
	v_mfma_f32_16x16x32_bf16 v[60:63], v[152:155], v[212:215], v[60:63]
	v_mfma_f32_16x16x32_bf16 v[60:63], v[156:159], v[216:219], v[60:63]
	v_mfma_f32_16x16x32_bf16 v[56:59], v[160:163], v[212:215], v[56:59]
	v_mfma_f32_16x16x32_bf16 v[56:59], v[164:167], v[216:219], v[56:59]
	v_mfma_f32_16x16x32_bf16 v[28:31], v[168:171], v[188:191], v[28:31]
	v_mfma_f32_16x16x32_bf16 v[28:31], v[172:175], v[192:195], v[28:31]
	v_mfma_f32_16x16x32_bf16 v[24:27], v[176:179], v[188:191], v[24:27]
	v_mfma_f32_16x16x32_bf16 v[24:27], v[184:187], v[192:195], v[24:27]
	v_mfma_f32_16x16x32_bf16 v[20:23], v[168:171], v[196:199], v[20:23]
	v_mfma_f32_16x16x32_bf16 v[20:23], v[172:175], v[200:203], v[20:23]
	v_mfma_f32_16x16x32_bf16 v[16:19], v[176:179], v[196:199], v[16:19]
	v_mfma_f32_16x16x32_bf16 v[16:19], v[184:187], v[200:203], v[16:19]
	v_mfma_f32_16x16x32_bf16 v[12:15], v[168:171], v[204:207], v[12:15]
	v_mfma_f32_16x16x32_bf16 v[12:15], v[172:175], v[208:211], v[12:15]
	v_mfma_f32_16x16x32_bf16 v[8:11], v[176:179], v[204:207], v[8:11]
	v_mfma_f32_16x16x32_bf16 v[8:11], v[184:187], v[208:211], v[8:11]
	v_mfma_f32_16x16x32_bf16 v[4:7], v[168:171], v[212:215], v[4:7]
	v_mfma_f32_16x16x32_bf16 v[4:7], v[172:175], v[216:219], v[4:7]
	v_mfma_f32_16x16x32_bf16 v[0:3], v[176:179], v[212:215], v[0:3]
	v_mfma_f32_16x16x32_bf16 v[0:3], v[184:187], v[216:219], v[0:3]
	s_setprio 0
	s_barrier
.Lmid_gemm9:
	s_add_i32 s79, 0, 0x18000
	s_add_i32 s88, 0, 0x1c000
	v_add_u32_e32 v164, s79, v147
	v_add_u32_e32 v181, s88, v147
	ds_read_b128 v[152:155], v164
	ds_read_b128 v[156:159], v164 offset:1024
	ds_read_b128 v[160:163], v164 offset:2048
	ds_read_b128 v[164:167], v164 offset:3072
	ds_read_b128 v[168:171], v181
	ds_read_b128 v[172:175], v181 offset:1024
	ds_read_b128 v[176:179], v181 offset:2048
	ds_read_b128 v[184:187], v181 offset:3072
	ds_read_b128 v[188:191], v150 offset:32768
	ds_read_b128 v[192:195], v150 offset:33792
	ds_read_b128 v[196:199], v150 offset:34816
	ds_read_b128 v[200:203], v150 offset:35840
	ds_read_b128 v[204:207], v150 offset:36864
	ds_read_b128 v[208:211], v150 offset:37888
	ds_read_b128 v[212:215], v150 offset:38912
	ds_read_b128 v[216:219], v150 offset:39936
	s_add_u32 s64, s64, 0x40000
	s_addc_u32 s65, s65, 0
	s_mov_b32 m0, s71
	v_lshl_add_u64 v[228:229], s[64:65], 0, v[128:129]
	global_load_lds_dwordx4 v[228:229], off
	v_lshl_add_u64 v[228:229], s[64:65], 0, v[132:133]
	s_mov_b32 m0, s72
	s_nop 0
	global_load_lds_dwordx4 v[228:229], off
	s_waitcnt vmcnt(8)
	s_waitcnt lgkmcnt(0)
	s_barrier
	s_setprio 1
	s_waitcnt lgkmcnt(0)
	v_mfma_f32_16x16x32_bf16 v[124:127], v[152:155], v[188:191], v[124:127]
	v_mfma_f32_16x16x32_bf16 v[124:127], v[156:159], v[192:195], v[124:127]
	v_mfma_f32_16x16x32_bf16 v[120:123], v[160:163], v[188:191], v[120:123]
	v_mfma_f32_16x16x32_bf16 v[120:123], v[164:167], v[192:195], v[120:123]
	v_mfma_f32_16x16x32_bf16 v[116:119], v[152:155], v[196:199], v[116:119]
	v_mfma_f32_16x16x32_bf16 v[116:119], v[156:159], v[200:203], v[116:119]
	v_mfma_f32_16x16x32_bf16 v[112:115], v[160:163], v[196:199], v[112:115]
	v_mfma_f32_16x16x32_bf16 v[112:115], v[164:167], v[200:203], v[112:115]
	v_mfma_f32_16x16x32_bf16 v[108:111], v[152:155], v[204:207], v[108:111]
	v_mfma_f32_16x16x32_bf16 v[108:111], v[156:159], v[208:211], v[108:111]
	v_mfma_f32_16x16x32_bf16 v[104:107], v[160:163], v[204:207], v[104:107]
	v_mfma_f32_16x16x32_bf16 v[104:107], v[164:167], v[208:211], v[104:107]
	v_mfma_f32_16x16x32_bf16 v[100:103], v[152:155], v[212:215], v[100:103]
	v_mfma_f32_16x16x32_bf16 v[100:103], v[156:159], v[216:219], v[100:103]
	v_mfma_f32_16x16x32_bf16 v[96:99], v[160:163], v[212:215], v[96:99]
	v_mfma_f32_16x16x32_bf16 v[96:99], v[164:167], v[216:219], v[96:99]
	v_mfma_f32_16x16x32_bf16 v[68:71], v[168:171], v[188:191], v[68:71]
	v_mfma_f32_16x16x32_bf16 v[68:71], v[172:175], v[192:195], v[68:71]
	v_mfma_f32_16x16x32_bf16 v[64:67], v[176:179], v[188:191], v[64:67]
	v_mfma_f32_16x16x32_bf16 v[64:67], v[184:187], v[192:195], v[64:67]
	v_mfma_f32_16x16x32_bf16 v[52:55], v[168:171], v[196:199], v[52:55]
	v_mfma_f32_16x16x32_bf16 v[52:55], v[172:175], v[200:203], v[52:55]
	v_mfma_f32_16x16x32_bf16 v[48:51], v[176:179], v[196:199], v[48:51]
	v_mfma_f32_16x16x32_bf16 v[48:51], v[184:187], v[200:203], v[48:51]
	v_mfma_f32_16x16x32_bf16 v[44:47], v[168:171], v[204:207], v[44:47]
	v_mfma_f32_16x16x32_bf16 v[44:47], v[172:175], v[208:211], v[44:47]
	v_mfma_f32_16x16x32_bf16 v[40:43], v[176:179], v[204:207], v[40:43]
	v_mfma_f32_16x16x32_bf16 v[40:43], v[184:187], v[208:211], v[40:43]
	v_mfma_f32_16x16x32_bf16 v[36:39], v[168:171], v[212:215], v[36:39]
	v_mfma_f32_16x16x32_bf16 v[36:39], v[172:175], v[216:219], v[36:39]
	v_mfma_f32_16x16x32_bf16 v[32:35], v[176:179], v[212:215], v[32:35]
	v_mfma_f32_16x16x32_bf16 v[32:35], v[184:187], v[216:219], v[32:35]
	s_setprio 0
	s_barrier
	ds_read_b128 v[188:191], v150 offset:49152
	ds_read_b128 v[192:195], v150 offset:50176
	ds_read_b128 v[196:199], v150 offset:51200
	ds_read_b128 v[200:203], v150 offset:52224
	ds_read_b128 v[204:207], v150 offset:53248
	ds_read_b128 v[208:211], v150 offset:54272
	ds_read_b128 v[212:215], v150 offset:55296
	ds_read_b128 v[216:219], v150 offset:56320
	s_add_i32 s64, s79, s68
	v_lshl_add_u64 v[220:221], v[220:221], 0, s[12:13]
	s_mov_b32 m0, s64
	s_nop 0
	global_load_lds_dwordx4 v[220:221], off
	s_add_i32 m0, s64, 0x2000
	s_add_u32 s62, s62, 0x40080
	v_lshl_add_u64 v[220:221], v[222:223], 0, s[12:13]
	s_addc_u32 s63, s63, 0
	s_add_i32 s64, s88, s68
	global_load_lds_dwordx4 v[220:221], off
	v_lshl_add_u64 v[220:221], s[62:63], 0, v[130:131]
	s_mov_b32 m0, s64
	s_nop 0
	global_load_lds_dwordx4 v[220:221], off
	v_lshl_add_u64 v[220:221], s[62:63], 0, v[134:135]
	s_add_i32 m0, s64, 0x2000
	s_nop 0
	global_load_lds_dwordx4 v[220:221], off
	v_lshl_add_u64 v[220:221], v[224:225], 0, s[12:13]
	s_mov_b32 m0, s75
	s_nop 0
	global_load_lds_dwordx4 v[220:221], off
	v_lshl_add_u64 v[220:221], v[226:227], 0, s[12:13]
	s_mov_b32 m0, s76
	s_nop 0
	global_load_lds_dwordx4 v[220:221], off
	s_waitcnt vmcnt(8)
	s_waitcnt lgkmcnt(0)
	s_barrier
	s_setprio 1
	s_waitcnt lgkmcnt(0)
	v_mfma_f32_16x16x32_bf16 v[92:95], v[152:155], v[188:191], v[92:95]
	v_mfma_f32_16x16x32_bf16 v[92:95], v[156:159], v[192:195], v[92:95]
	v_mfma_f32_16x16x32_bf16 v[88:91], v[160:163], v[188:191], v[88:91]
	v_mfma_f32_16x16x32_bf16 v[88:91], v[164:167], v[192:195], v[88:91]
	v_mfma_f32_16x16x32_bf16 v[84:87], v[152:155], v[196:199], v[84:87]
	v_mfma_f32_16x16x32_bf16 v[84:87], v[156:159], v[200:203], v[84:87]
	v_mfma_f32_16x16x32_bf16 v[80:83], v[160:163], v[196:199], v[80:83]
	v_mfma_f32_16x16x32_bf16 v[80:83], v[164:167], v[200:203], v[80:83]
	v_mfma_f32_16x16x32_bf16 v[76:79], v[152:155], v[204:207], v[76:79]
	v_mfma_f32_16x16x32_bf16 v[76:79], v[156:159], v[208:211], v[76:79]
	v_mfma_f32_16x16x32_bf16 v[72:75], v[160:163], v[204:207], v[72:75]
	v_mfma_f32_16x16x32_bf16 v[72:75], v[164:167], v[208:211], v[72:75]
	v_mfma_f32_16x16x32_bf16 v[60:63], v[152:155], v[212:215], v[60:63]
	v_mfma_f32_16x16x32_bf16 v[60:63], v[156:159], v[216:219], v[60:63]
	v_mfma_f32_16x16x32_bf16 v[56:59], v[160:163], v[212:215], v[56:59]
	v_mfma_f32_16x16x32_bf16 v[56:59], v[164:167], v[216:219], v[56:59]
	v_mfma_f32_16x16x32_bf16 v[28:31], v[168:171], v[188:191], v[28:31]
	v_mfma_f32_16x16x32_bf16 v[28:31], v[172:175], v[192:195], v[28:31]
	v_mfma_f32_16x16x32_bf16 v[24:27], v[176:179], v[188:191], v[24:27]
	v_mfma_f32_16x16x32_bf16 v[24:27], v[184:187], v[192:195], v[24:27]
	v_mfma_f32_16x16x32_bf16 v[20:23], v[168:171], v[196:199], v[20:23]
	v_mfma_f32_16x16x32_bf16 v[20:23], v[172:175], v[200:203], v[20:23]
	v_mfma_f32_16x16x32_bf16 v[16:19], v[176:179], v[196:199], v[16:19]
	v_mfma_f32_16x16x32_bf16 v[16:19], v[184:187], v[200:203], v[16:19]
	v_mfma_f32_16x16x32_bf16 v[12:15], v[168:171], v[204:207], v[12:15]
	v_mfma_f32_16x16x32_bf16 v[12:15], v[172:175], v[208:211], v[12:15]
	v_mfma_f32_16x16x32_bf16 v[8:11], v[176:179], v[204:207], v[8:11]
	v_mfma_f32_16x16x32_bf16 v[8:11], v[184:187], v[208:211], v[8:11]
	v_mfma_f32_16x16x32_bf16 v[4:7], v[168:171], v[212:215], v[4:7]
	v_mfma_f32_16x16x32_bf16 v[4:7], v[172:175], v[216:219], v[4:7]
	v_mfma_f32_16x16x32_bf16 v[0:3], v[176:179], v[212:215], v[0:3]
	v_mfma_f32_16x16x32_bf16 v[0:3], v[184:187], v[216:219], v[0:3]
	s_setprio 0
	s_barrier
	s_add_i32 s87, s87, 2
	s_add_u32 s60, s60, 0x100
	s_addc_u32 s61, s61, 0
	s_add_u32 s85, s85, 0x100
	s_addc_u32 s86, s86, 0
	s_cmp_gt_u32 s87, 13
	s_cbranch_scc0 .LBB0_1162
	s_and_b64 vcc, exec, s[16:17]
	s_cbranch_vccz .LBB0_1165
	s_barrier

.LBB0_1310:
	s_ashr_i32 s49, s48, 31
	s_lshl_b64 s[50:51], s[48:49], 19
	s_add_u32 s50, s38, s50
	s_addc_u32 s51, s39, s51
	s_and_b64 s[52:53], s[10:11], exec
	s_cselect_b32 s49, s51, s57
	s_cselect_b32 s82, s50, s56
	s_ashr_i32 s47, s46, 31
	s_lshl_b64 s[52:53], s[46:47], 19
	s_add_u32 s52, s62, s52
	s_addc_u32 s53, s63, s53
	s_and_b64 s[60:61], s[10:11], exec
	s_cselect_b32 s47, s53, s59
	s_cselect_b32 s83, s52, s58
	s_add_u32 s56, s56, 0x40080
	s_addc_u32 s57, s57, 0
	s_add_u32 s84, s58, 0x100
	s_addc_u32 s85, s59, 0
	s_mov_b32 s86, -2
	ds_read_b128 v[152:155], v149
	ds_read_b128 v[156:159], v149 offset:1024
	ds_read_b128 v[160:163], v149 offset:2048
	ds_read_b128 v[164:167], v149 offset:3072
	ds_read_b128 v[168:171], v150
	ds_read_b128 v[172:175], v150 offset:1024
	ds_read_b128 v[176:179], v150 offset:2048
	ds_read_b128 v[184:187], v150 offset:3072
	s_add_u32 s58, s56, 0xfffc0080
	s_addc_u32 s59, s57, -1
	s_cmp_eq_u32 s86, 12
	s_cselect_b32 s61, s49, s59
	s_cselect_b32 s60, s82, s58
	s_cselect_b32 s59, s47, s85
	s_cselect_b32 s58, s83, s84
	v_lshl_add_u64 v[144:145], s[56:57], 0, v[136:137]
	s_add_i32 m0, s55, 0xc000
	ds_read_b128 v[188:191], v151
	ds_read_b128 v[192:195], v151 offset:1024
	ds_read_b128 v[196:199], v151 offset:2048
	ds_read_b128 v[200:203], v151 offset:3072
	ds_read_b128 v[204:207], v151 offset:4096
	ds_read_b128 v[208:211], v151 offset:5120
	ds_read_b128 v[212:215], v151 offset:6144
	ds_read_b128 v[216:219], v151 offset:7168
	global_load_lds_dwordx4 v[144:145], off
	v_lshl_add_u64 v[144:145], s[56:57], 0, v[138:139]
	s_add_i32 m0, s55, 0xe000
	s_nop 0
	global_load_lds_dwordx4 v[144:145], off
	s_waitcnt vmcnt(8)
	s_waitcnt lgkmcnt(0)
	s_barrier
	s_setprio 1
	s_waitcnt lgkmcnt(0)
	v_mfma_f32_16x16x32_bf16 v[124:127], v[152:155], v[188:191], 0
	v_mfma_f32_16x16x32_bf16 v[124:127], v[156:159], v[192:195], v[124:127]
	v_mfma_f32_16x16x32_bf16 v[120:123], v[160:163], v[188:191], 0
	v_mfma_f32_16x16x32_bf16 v[120:123], v[164:167], v[192:195], v[120:123]
	v_mfma_f32_16x16x32_bf16 v[116:119], v[152:155], v[196:199], 0
	v_mfma_f32_16x16x32_bf16 v[116:119], v[156:159], v[200:203], v[116:119]
	v_mfma_f32_16x16x32_bf16 v[108:111], v[160:163], v[196:199], 0
	v_mfma_f32_16x16x32_bf16 v[108:111], v[164:167], v[200:203], v[108:111]
	v_mfma_f32_16x16x32_bf16 v[100:103], v[152:155], v[204:207], 0
	v_mfma_f32_16x16x32_bf16 v[100:103], v[156:159], v[208:211], v[100:103]
	v_mfma_f32_16x16x32_bf16 v[92:95], v[160:163], v[204:207], 0
	v_mfma_f32_16x16x32_bf16 v[92:95], v[164:167], v[208:211], v[92:95]
	v_mfma_f32_16x16x32_bf16 v[84:87], v[152:155], v[212:215], 0
	v_mfma_f32_16x16x32_bf16 v[84:87], v[156:159], v[216:219], v[84:87]
	v_mfma_f32_16x16x32_bf16 v[76:79], v[160:163], v[212:215], 0
	v_mfma_f32_16x16x32_bf16 v[76:79], v[164:167], v[216:219], v[76:79]
	v_mfma_f32_16x16x32_bf16 v[112:115], v[168:171], v[188:191], 0
	v_mfma_f32_16x16x32_bf16 v[112:115], v[172:175], v[192:195], v[112:115]
	v_mfma_f32_16x16x32_bf16 v[104:107], v[176:179], v[188:191], 0
	v_mfma_f32_16x16x32_bf16 v[104:107], v[184:187], v[192:195], v[104:107]
	v_mfma_f32_16x16x32_bf16 v[96:99], v[168:171], v[196:199], 0
	v_mfma_f32_16x16x32_bf16 v[96:99], v[172:175], v[200:203], v[96:99]
	v_mfma_f32_16x16x32_bf16 v[88:91], v[176:179], v[196:199], 0
	v_mfma_f32_16x16x32_bf16 v[88:91], v[184:187], v[200:203], v[88:91]
	v_mfma_f32_16x16x32_bf16 v[80:83], v[168:171], v[204:207], 0
	v_mfma_f32_16x16x32_bf16 v[80:83], v[172:175], v[208:211], v[80:83]
	v_mfma_f32_16x16x32_bf16 v[72:75], v[176:179], v[204:207], 0
	v_mfma_f32_16x16x32_bf16 v[72:75], v[184:187], v[208:211], v[72:75]
	v_mfma_f32_16x16x32_bf16 v[68:71], v[168:171], v[212:215], 0
	v_mfma_f32_16x16x32_bf16 v[68:71], v[172:175], v[216:219], v[68:71]
	v_mfma_f32_16x16x32_bf16 v[64:67], v[176:179], v[212:215], 0
	v_mfma_f32_16x16x32_bf16 v[64:67], v[184:187], v[216:219], v[64:67]
	s_setprio 0
	s_barrier
	ds_read_b128 v[188:191], v151 offset:16384
	ds_read_b128 v[192:195], v151 offset:17408
	ds_read_b128 v[196:199], v151 offset:18432
	ds_read_b128 v[200:203], v151 offset:19456
	ds_read_b128 v[204:207], v151 offset:20480
	ds_read_b128 v[208:211], v151 offset:21504
	ds_read_b128 v[212:215], v151 offset:22528
	ds_read_b128 v[216:219], v151 offset:23552
	s_add_i32 s79, s71, s64
	v_lshl_add_u64 v[144:145], s[58:59], 0, v[130:131]
	s_mov_b32 m0, s79
	s_nop 0
	global_load_lds_dwordx4 v[144:145], off
	s_add_i32 m0, s79, 0x2000
	s_add_u32 s88, s58, 0x40000
	v_lshl_add_u64 v[220:221], s[58:59], 0, v[134:135]
	s_addc_u32 s89, s59, 0
	s_add_i32 s79, s72, s64
	global_load_lds_dwordx4 v[220:221], off
	v_lshl_add_u64 v[222:223], s[88:89], 0, v[130:131]
	s_mov_b32 m0, s79
	v_lshl_add_u64 v[224:225], s[60:61], 0, v[132:133]
	global_load_lds_dwordx4 v[222:223], off
	v_lshl_add_u64 v[222:223], s[88:89], 0, v[134:135]
	s_add_i32 m0, s79, 0x2000
	s_nop 0
	global_load_lds_dwordx4 v[222:223], off
	v_lshl_add_u64 v[222:223], s[60:61], 0, v[128:129]
	s_mov_b32 m0, s55
	s_nop 0
	global_load_lds_dwordx4 v[222:223], off
	s_mov_b32 m0, s65
	s_nop 0
	global_load_lds_dwordx4 v[224:225], off
	s_waitcnt vmcnt(8)
	s_waitcnt lgkmcnt(0)
	s_barrier
	s_setprio 1
	s_waitcnt lgkmcnt(0)
	v_mfma_f32_16x16x32_bf16 v[60:63], v[152:155], v[188:191], 0
	v_mfma_f32_16x16x32_bf16 v[60:63], v[156:159], v[192:195], v[60:63]
	v_mfma_f32_16x16x32_bf16 v[56:59], v[160:163], v[188:191], 0
	v_mfma_f32_16x16x32_bf16 v[56:59], v[164:167], v[192:195], v[56:59]
	v_mfma_f32_16x16x32_bf16 v[52:55], v[152:155], v[196:199], 0
	v_mfma_f32_16x16x32_bf16 v[52:55], v[156:159], v[200:203], v[52:55]
	v_mfma_f32_16x16x32_bf16 v[44:47], v[160:163], v[196:199], 0
	v_mfma_f32_16x16x32_bf16 v[44:47], v[164:167], v[200:203], v[44:47]
	v_mfma_f32_16x16x32_bf16 v[36:39], v[152:155], v[204:207], 0
	v_mfma_f32_16x16x32_bf16 v[36:39], v[156:159], v[208:211], v[36:39]
	v_mfma_f32_16x16x32_bf16 v[28:31], v[160:163], v[204:207], 0
	v_mfma_f32_16x16x32_bf16 v[28:31], v[164:167], v[208:211], v[28:31]
	v_mfma_f32_16x16x32_bf16 v[20:23], v[152:155], v[212:215], 0
	v_mfma_f32_16x16x32_bf16 v[20:23], v[156:159], v[216:219], v[20:23]
	v_mfma_f32_16x16x32_bf16 v[12:15], v[160:163], v[212:215], 0
	v_mfma_f32_16x16x32_bf16 v[12:15], v[164:167], v[216:219], v[12:15]
	v_mfma_f32_16x16x32_bf16 v[48:51], v[168:171], v[188:191], 0
	v_mfma_f32_16x16x32_bf16 v[48:51], v[172:175], v[192:195], v[48:51]
	v_mfma_f32_16x16x32_bf16 v[40:43], v[176:179], v[188:191], 0
	v_mfma_f32_16x16x32_bf16 v[40:43], v[184:187], v[192:195], v[40:43]
	v_mfma_f32_16x16x32_bf16 v[32:35], v[168:171], v[196:199], 0
	v_mfma_f32_16x16x32_bf16 v[32:35], v[172:175], v[200:203], v[32:35]
	v_mfma_f32_16x16x32_bf16 v[24:27], v[176:179], v[196:199], 0
	v_mfma_f32_16x16x32_bf16 v[24:27], v[184:187], v[200:203], v[24:27]
	v_mfma_f32_16x16x32_bf16 v[16:19], v[168:171], v[204:207], 0
	v_mfma_f32_16x16x32_bf16 v[16:19], v[172:175], v[208:211], v[16:19]
	v_mfma_f32_16x16x32_bf16 v[8:11], v[176:179], v[204:207], 0
	v_mfma_f32_16x16x32_bf16 v[8:11], v[184:187], v[208:211], v[8:11]
	v_mfma_f32_16x16x32_bf16 v[4:7], v[168:171], v[212:215], 0
	v_mfma_f32_16x16x32_bf16 v[4:7], v[172:175], v[216:219], v[4:7]
	v_mfma_f32_16x16x32_bf16 v[0:3], v[176:179], v[212:215], 0
	v_mfma_f32_16x16x32_bf16 v[0:3], v[184:187], v[216:219], v[0:3]
	s_setprio 0
	s_barrier
	s_branch .Lmid_gemm10
.LBB0_1311:
	ds_read_b128 v[152:155], v149
	ds_read_b128 v[156:159], v149 offset:1024
	ds_read_b128 v[160:163], v149 offset:2048
	ds_read_b128 v[164:167], v149 offset:3072
	ds_read_b128 v[168:171], v150
	ds_read_b128 v[172:175], v150 offset:1024
	ds_read_b128 v[176:179], v150 offset:2048
	ds_read_b128 v[184:187], v150 offset:3072
	ds_read_b128 v[188:191], v151
	ds_read_b128 v[192:195], v151 offset:1024
	ds_read_b128 v[196:199], v151 offset:2048
	ds_read_b128 v[200:203], v151 offset:3072
	ds_read_b128 v[204:207], v151 offset:4096
	ds_read_b128 v[208:211], v151 offset:5120
	ds_read_b128 v[212:215], v151 offset:6144
	ds_read_b128 v[216:219], v151 offset:7168
	s_add_u32 s58, s56, 0xfffc0080
	s_addc_u32 s59, s57, -1
	s_cmp_eq_u32 s86, 12
	s_cselect_b32 s61, s49, s59
	s_cselect_b32 s60, s82, s58
	s_cselect_b32 s59, s47, s85
	s_cselect_b32 s58, s83, s84
	v_lshl_add_u64 v[144:145], s[56:57], 0, v[136:137]
	s_add_i32 m0, s55, 0xc000
	s_nop 0
	global_load_lds_dwordx4 v[144:145], off
	v_lshl_add_u64 v[144:145], s[56:57], 0, v[138:139]
	s_add_i32 m0, s55, 0xe000
	s_nop 0
	global_load_lds_dwordx4 v[144:145], off
	s_waitcnt vmcnt(8)
	s_waitcnt lgkmcnt(0)
	s_barrier
	s_setprio 1
	s_waitcnt lgkmcnt(0)
	v_mfma_f32_16x16x32_bf16 v[124:127], v[152:155], v[188:191], v[124:127]
	v_mfma_f32_16x16x32_bf16 v[124:127], v[156:159], v[192:195], v[124:127]
	v_mfma_f32_16x16x32_bf16 v[120:123], v[160:163], v[188:191], v[120:123]
	v_mfma_f32_16x16x32_bf16 v[120:123], v[164:167], v[192:195], v[120:123]
	v_mfma_f32_16x16x32_bf16 v[116:119], v[152:155], v[196:199], v[116:119]
	v_mfma_f32_16x16x32_bf16 v[116:119], v[156:159], v[200:203], v[116:119]
	v_mfma_f32_16x16x32_bf16 v[108:111], v[160:163], v[196:199], v[108:111]
	v_mfma_f32_16x16x32_bf16 v[108:111], v[164:167], v[200:203], v[108:111]
	v_mfma_f32_16x16x32_bf16 v[100:103], v[152:155], v[204:207], v[100:103]
	v_mfma_f32_16x16x32_bf16 v[100:103], v[156:159], v[208:211], v[100:103]
	v_mfma_f32_16x16x32_bf16 v[92:95], v[160:163], v[204:207], v[92:95]
	v_mfma_f32_16x16x32_bf16 v[92:95], v[164:167], v[208:211], v[92:95]
	v_mfma_f32_16x16x32_bf16 v[84:87], v[152:155], v[212:215], v[84:87]
	v_mfma_f32_16x16x32_bf16 v[84:87], v[156:159], v[216:219], v[84:87]
	v_mfma_f32_16x16x32_bf16 v[76:79], v[160:163], v[212:215], v[76:79]
	v_mfma_f32_16x16x32_bf16 v[76:79], v[164:167], v[216:219], v[76:79]
	v_mfma_f32_16x16x32_bf16 v[112:115], v[168:171], v[188:191], v[112:115]
	v_mfma_f32_16x16x32_bf16 v[112:115], v[172:175], v[192:195], v[112:115]
	v_mfma_f32_16x16x32_bf16 v[104:107], v[176:179], v[188:191], v[104:107]
	v_mfma_f32_16x16x32_bf16 v[104:107], v[184:187], v[192:195], v[104:107]
	v_mfma_f32_16x16x32_bf16 v[96:99], v[168:171], v[196:199], v[96:99]
	v_mfma_f32_16x16x32_bf16 v[96:99], v[172:175], v[200:203], v[96:99]
	v_mfma_f32_16x16x32_bf16 v[88:91], v[176:179], v[196:199], v[88:91]
	v_mfma_f32_16x16x32_bf16 v[88:91], v[184:187], v[200:203], v[88:91]
	v_mfma_f32_16x16x32_bf16 v[80:83], v[168:171], v[204:207], v[80:83]
	v_mfma_f32_16x16x32_bf16 v[80:83], v[172:175], v[208:211], v[80:83]
	v_mfma_f32_16x16x32_bf16 v[72:75], v[176:179], v[204:207], v[72:75]
	v_mfma_f32_16x16x32_bf16 v[72:75], v[184:187], v[208:211], v[72:75]
	v_mfma_f32_16x16x32_bf16 v[68:71], v[168:171], v[212:215], v[68:71]
	v_mfma_f32_16x16x32_bf16 v[68:71], v[172:175], v[216:219], v[68:71]
	v_mfma_f32_16x16x32_bf16 v[64:67], v[176:179], v[212:215], v[64:67]
	v_mfma_f32_16x16x32_bf16 v[64:67], v[184:187], v[216:219], v[64:67]
	s_setprio 0
	s_barrier
	ds_read_b128 v[188:191], v151 offset:16384
	ds_read_b128 v[192:195], v151 offset:17408
	ds_read_b128 v[196:199], v151 offset:18432
	ds_read_b128 v[200:203], v151 offset:19456
	ds_read_b128 v[204:207], v151 offset:20480
	ds_read_b128 v[208:211], v151 offset:21504
	ds_read_b128 v[212:215], v151 offset:22528
	ds_read_b128 v[216:219], v151 offset:23552
	s_add_i32 s79, s71, s64
	v_lshl_add_u64 v[144:145], s[58:59], 0, v[130:131]
	s_mov_b32 m0, s79
	s_nop 0
	global_load_lds_dwordx4 v[144:145], off
	s_add_i32 m0, s79, 0x2000
	s_add_u32 s88, s58, 0x40000
	v_lshl_add_u64 v[220:221], s[58:59], 0, v[134:135]
	s_addc_u32 s89, s59, 0
	s_add_i32 s79, s72, s64
	global_load_lds_dwordx4 v[220:221], off
	v_lshl_add_u64 v[222:223], s[88:89], 0, v[130:131]
	s_mov_b32 m0, s79
	v_lshl_add_u64 v[224:225], s[60:61], 0, v[132:133]
	global_load_lds_dwordx4 v[222:223], off
	v_lshl_add_u64 v[222:223], s[88:89], 0, v[134:135]
	s_add_i32 m0, s79, 0x2000
	s_nop 0
	global_load_lds_dwordx4 v[222:223], off
	v_lshl_add_u64 v[222:223], s[60:61], 0, v[128:129]
	s_mov_b32 m0, s55
	s_nop 0
	global_load_lds_dwordx4 v[222:223], off
	s_mov_b32 m0, s65
	s_nop 0
	global_load_lds_dwordx4 v[224:225], off
	s_waitcnt vmcnt(8)
	s_waitcnt lgkmcnt(0)
	s_barrier
	s_setprio 1
	s_waitcnt lgkmcnt(0)
	v_mfma_f32_16x16x32_bf16 v[60:63], v[152:155], v[188:191], v[60:63]
	v_mfma_f32_16x16x32_bf16 v[60:63], v[156:159], v[192:195], v[60:63]
	v_mfma_f32_16x16x32_bf16 v[56:59], v[160:163], v[188:191], v[56:59]
	v_mfma_f32_16x16x32_bf16 v[56:59], v[164:167], v[192:195], v[56:59]
	v_mfma_f32_16x16x32_bf16 v[52:55], v[152:155], v[196:199], v[52:55]
	v_mfma_f32_16x16x32_bf16 v[52:55], v[156:159], v[200:203], v[52:55]
	v_mfma_f32_16x16x32_bf16 v[44:47], v[160:163], v[196:199], v[44:47]
	v_mfma_f32_16x16x32_bf16 v[44:47], v[164:167], v[200:203], v[44:47]
	v_mfma_f32_16x16x32_bf16 v[36:39], v[152:155], v[204:207], v[36:39]
	v_mfma_f32_16x16x32_bf16 v[36:39], v[156:159], v[208:211], v[36:39]
	v_mfma_f32_16x16x32_bf16 v[28:31], v[160:163], v[204:207], v[28:31]
	v_mfma_f32_16x16x32_bf16 v[28:31], v[164:167], v[208:211], v[28:31]
	v_mfma_f32_16x16x32_bf16 v[20:23], v[152:155], v[212:215], v[20:23]
	v_mfma_f32_16x16x32_bf16 v[20:23], v[156:159], v[216:219], v[20:23]
	v_mfma_f32_16x16x32_bf16 v[12:15], v[160:163], v[212:215], v[12:15]
	v_mfma_f32_16x16x32_bf16 v[12:15], v[164:167], v[216:219], v[12:15]
	v_mfma_f32_16x16x32_bf16 v[48:51], v[168:171], v[188:191], v[48:51]
	v_mfma_f32_16x16x32_bf16 v[48:51], v[172:175], v[192:195], v[48:51]
	v_mfma_f32_16x16x32_bf16 v[40:43], v[176:179], v[188:191], v[40:43]
	v_mfma_f32_16x16x32_bf16 v[40:43], v[184:187], v[192:195], v[40:43]
	v_mfma_f32_16x16x32_bf16 v[32:35], v[168:171], v[196:199], v[32:35]
	v_mfma_f32_16x16x32_bf16 v[32:35], v[172:175], v[200:203], v[32:35]
	v_mfma_f32_16x16x32_bf16 v[24:27], v[176:179], v[196:199], v[24:27]
	v_mfma_f32_16x16x32_bf16 v[24:27], v[184:187], v[200:203], v[24:27]
	v_mfma_f32_16x16x32_bf16 v[16:19], v[168:171], v[204:207], v[16:19]
	v_mfma_f32_16x16x32_bf16 v[16:19], v[172:175], v[208:211], v[16:19]
	v_mfma_f32_16x16x32_bf16 v[8:11], v[176:179], v[204:207], v[8:11]
	v_mfma_f32_16x16x32_bf16 v[8:11], v[184:187], v[208:211], v[8:11]
	v_mfma_f32_16x16x32_bf16 v[4:7], v[168:171], v[212:215], v[4:7]
	v_mfma_f32_16x16x32_bf16 v[4:7], v[172:175], v[216:219], v[4:7]
	v_mfma_f32_16x16x32_bf16 v[0:3], v[176:179], v[212:215], v[0:3]
	v_mfma_f32_16x16x32_bf16 v[0:3], v[184:187], v[216:219], v[0:3]
	s_setprio 0
	s_barrier
.Lmid_gemm10:
	s_add_i32 s79, 0, 0x18000
	s_add_i32 s87, 0, 0x1c000
	v_add_u32_e32 v164, s79, v147
	v_add_u32_e32 v181, s87, v147
	ds_read_b128 v[152:155], v164
	ds_read_b128 v[156:159], v164 offset:1024
	ds_read_b128 v[160:163], v164 offset:2048
	ds_read_b128 v[164:167], v164 offset:3072
	ds_read_b128 v[168:171], v181
	ds_read_b128 v[172:175], v181 offset:1024
	ds_read_b128 v[176:179], v181 offset:2048
	ds_read_b128 v[184:187], v181 offset:3072
	ds_read_b128 v[188:191], v151 offset:32768
	ds_read_b128 v[192:195], v151 offset:33792
	ds_read_b128 v[196:199], v151 offset:34816
	ds_read_b128 v[200:203], v151 offset:35840
	ds_read_b128 v[204:207], v151 offset:36864
	ds_read_b128 v[208:211], v151 offset:37888
	ds_read_b128 v[212:215], v151 offset:38912
	ds_read_b128 v[216:219], v151 offset:39936
	s_add_u32 s60, s60, 0x40000
	s_addc_u32 s61, s61, 0
	s_mov_b32 m0, s66
	v_lshl_add_u64 v[226:227], s[60:61], 0, v[128:129]
	global_load_lds_dwordx4 v[226:227], off
	v_lshl_add_u64 v[226:227], s[60:61], 0, v[132:133]
	s_mov_b32 m0, s67
	s_nop 0
	global_load_lds_dwordx4 v[226:227], off
	s_waitcnt vmcnt(8)
	s_waitcnt lgkmcnt(0)
	s_barrier
	s_setprio 1
	s_waitcnt lgkmcnt(0)
	v_mfma_f32_16x16x32_bf16 v[124:127], v[152:155], v[188:191], v[124:127]
	v_mfma_f32_16x16x32_bf16 v[124:127], v[156:159], v[192:195], v[124:127]
	v_mfma_f32_16x16x32_bf16 v[120:123], v[160:163], v[188:191], v[120:123]
	v_mfma_f32_16x16x32_bf16 v[120:123], v[164:167], v[192:195], v[120:123]
	v_mfma_f32_16x16x32_bf16 v[116:119], v[152:155], v[196:199], v[116:119]
	v_mfma_f32_16x16x32_bf16 v[116:119], v[156:159], v[200:203], v[116:119]
	v_mfma_f32_16x16x32_bf16 v[108:111], v[160:163], v[196:199], v[108:111]
	v_mfma_f32_16x16x32_bf16 v[108:111], v[164:167], v[200:203], v[108:111]
	v_mfma_f32_16x16x32_bf16 v[100:103], v[152:155], v[204:207], v[100:103]
	v_mfma_f32_16x16x32_bf16 v[100:103], v[156:159], v[208:211], v[100:103]
	v_mfma_f32_16x16x32_bf16 v[92:95], v[160:163], v[204:207], v[92:95]
	v_mfma_f32_16x16x32_bf16 v[92:95], v[164:167], v[208:211], v[92:95]
	v_mfma_f32_16x16x32_bf16 v[84:87], v[152:155], v[212:215], v[84:87]
	v_mfma_f32_16x16x32_bf16 v[84:87], v[156:159], v[216:219], v[84:87]
	v_mfma_f32_16x16x32_bf16 v[76:79], v[160:163], v[212:215], v[76:79]
	v_mfma_f32_16x16x32_bf16 v[76:79], v[164:167], v[216:219], v[76:79]
	v_mfma_f32_16x16x32_bf16 v[112:115], v[168:171], v[188:191], v[112:115]
	v_mfma_f32_16x16x32_bf16 v[112:115], v[172:175], v[192:195], v[112:115]
	v_mfma_f32_16x16x32_bf16 v[104:107], v[176:179], v[188:191], v[104:107]
	v_mfma_f32_16x16x32_bf16 v[104:107], v[184:187], v[192:195], v[104:107]
	v_mfma_f32_16x16x32_bf16 v[96:99], v[168:171], v[196:199], v[96:99]
	v_mfma_f32_16x16x32_bf16 v[96:99], v[172:175], v[200:203], v[96:99]
	v_mfma_f32_16x16x32_bf16 v[88:91], v[176:179], v[196:199], v[88:91]
	v_mfma_f32_16x16x32_bf16 v[88:91], v[184:187], v[200:203], v[88:91]
	v_mfma_f32_16x16x32_bf16 v[80:83], v[168:171], v[204:207], v[80:83]
	v_mfma_f32_16x16x32_bf16 v[80:83], v[172:175], v[208:211], v[80:83]
	v_mfma_f32_16x16x32_bf16 v[72:75], v[176:179], v[204:207], v[72:75]
	v_mfma_f32_16x16x32_bf16 v[72:75], v[184:187], v[208:211], v[72:75]
	v_mfma_f32_16x16x32_bf16 v[68:71], v[168:171], v[212:215], v[68:71]
	v_mfma_f32_16x16x32_bf16 v[68:71], v[172:175], v[216:219], v[68:71]
	v_mfma_f32_16x16x32_bf16 v[64:67], v[176:179], v[212:215], v[64:67]
	v_mfma_f32_16x16x32_bf16 v[64:67], v[184:187], v[216:219], v[64:67]
	s_setprio 0
	s_barrier
	ds_read_b128 v[188:191], v151 offset:49152
	ds_read_b128 v[192:195], v151 offset:50176
	ds_read_b128 v[196:199], v151 offset:51200
	ds_read_b128 v[200:203], v151 offset:52224
	ds_read_b128 v[204:207], v151 offset:53248
	ds_read_b128 v[208:211], v151 offset:54272
	ds_read_b128 v[212:215], v151 offset:55296
	ds_read_b128 v[216:219], v151 offset:56320
	s_add_i32 s60, s79, s64
	v_lshl_add_u64 v[144:145], v[144:145], 0, s[16:17]
	s_mov_b32 m0, s60
	s_nop 0
	global_load_lds_dwordx4 v[144:145], off
	s_add_i32 m0, s60, 0x2000
	s_add_u32 s58, s58, 0x40080
	v_lshl_add_u64 v[144:145], v[220:221], 0, s[16:17]
	s_addc_u32 s59, s59, 0
	s_add_i32 s60, s87, s64
	global_load_lds_dwordx4 v[144:145], off
	v_lshl_add_u64 v[144:145], s[58:59], 0, v[130:131]
	s_mov_b32 m0, s60
	s_nop 0
	global_load_lds_dwordx4 v[144:145], off
	v_lshl_add_u64 v[144:145], s[58:59], 0, v[134:135]
	s_add_i32 m0, s60, 0x2000
	s_nop 0
	global_load_lds_dwordx4 v[144:145], off
	v_lshl_add_u64 v[144:145], v[222:223], 0, s[16:17]
	s_mov_b32 m0, s69
	s_nop 0
	global_load_lds_dwordx4 v[144:145], off
	v_lshl_add_u64 v[144:145], v[224:225], 0, s[16:17]
	s_mov_b32 m0, s70
	s_nop 0
	global_load_lds_dwordx4 v[144:145], off
	s_waitcnt vmcnt(8)
	s_waitcnt lgkmcnt(0)
	s_barrier
	s_setprio 1
	s_waitcnt lgkmcnt(0)
	v_mfma_f32_16x16x32_bf16 v[60:63], v[152:155], v[188:191], v[60:63]
	v_mfma_f32_16x16x32_bf16 v[60:63], v[156:159], v[192:195], v[60:63]
	v_mfma_f32_16x16x32_bf16 v[56:59], v[160:163], v[188:191], v[56:59]
	v_mfma_f32_16x16x32_bf16 v[56:59], v[164:167], v[192:195], v[56:59]
	v_mfma_f32_16x16x32_bf16 v[52:55], v[152:155], v[196:199], v[52:55]
	v_mfma_f32_16x16x32_bf16 v[52:55], v[156:159], v[200:203], v[52:55]
	v_mfma_f32_16x16x32_bf16 v[44:47], v[160:163], v[196:199], v[44:47]
	v_mfma_f32_16x16x32_bf16 v[44:47], v[164:167], v[200:203], v[44:47]
	v_mfma_f32_16x16x32_bf16 v[36:39], v[152:155], v[204:207], v[36:39]
	v_mfma_f32_16x16x32_bf16 v[36:39], v[156:159], v[208:211], v[36:39]
	v_mfma_f32_16x16x32_bf16 v[28:31], v[160:163], v[204:207], v[28:31]
	v_mfma_f32_16x16x32_bf16 v[28:31], v[164:167], v[208:211], v[28:31]
	v_mfma_f32_16x16x32_bf16 v[20:23], v[152:155], v[212:215], v[20:23]
	v_mfma_f32_16x16x32_bf16 v[20:23], v[156:159], v[216:219], v[20:23]
	v_mfma_f32_16x16x32_bf16 v[12:15], v[160:163], v[212:215], v[12:15]
	v_mfma_f32_16x16x32_bf16 v[12:15], v[164:167], v[216:219], v[12:15]
	v_mfma_f32_16x16x32_bf16 v[48:51], v[168:171], v[188:191], v[48:51]
	v_mfma_f32_16x16x32_bf16 v[48:51], v[172:175], v[192:195], v[48:51]
	v_mfma_f32_16x16x32_bf16 v[40:43], v[176:179], v[188:191], v[40:43]
	v_mfma_f32_16x16x32_bf16 v[40:43], v[184:187], v[192:195], v[40:43]
	v_mfma_f32_16x16x32_bf16 v[32:35], v[168:171], v[196:199], v[32:35]
	v_mfma_f32_16x16x32_bf16 v[32:35], v[172:175], v[200:203], v[32:35]
	v_mfma_f32_16x16x32_bf16 v[24:27], v[176:179], v[196:199], v[24:27]
	v_mfma_f32_16x16x32_bf16 v[24:27], v[184:187], v[200:203], v[24:27]
	v_mfma_f32_16x16x32_bf16 v[16:19], v[168:171], v[204:207], v[16:19]
	v_mfma_f32_16x16x32_bf16 v[16:19], v[172:175], v[208:211], v[16:19]
	v_mfma_f32_16x16x32_bf16 v[8:11], v[176:179], v[204:207], v[8:11]
	v_mfma_f32_16x16x32_bf16 v[8:11], v[184:187], v[208:211], v[8:11]
	v_mfma_f32_16x16x32_bf16 v[4:7], v[168:171], v[212:215], v[4:7]
	v_mfma_f32_16x16x32_bf16 v[4:7], v[172:175], v[216:219], v[4:7]
	v_mfma_f32_16x16x32_bf16 v[0:3], v[176:179], v[212:215], v[0:3]
	v_mfma_f32_16x16x32_bf16 v[0:3], v[184:187], v[216:219], v[0:3]
	s_setprio 0
	s_barrier
	s_add_i32 s86, s86, 2
	s_add_u32 s56, s56, 0x100
	s_addc_u32 s57, s57, 0
	s_add_u32 s84, s84, 0x100
	s_addc_u32 s85, s85, 0
	s_cmp_gt_u32 s86, 13
	s_cbranch_scc0 .LBB0_1311
	s_and_b64 vcc, exec, s[18:19]
	s_cbranch_vccz .LBB0_1314
	s_barrier

.LBB0_1433:
	s_ashr_i32 s19, s18, 31
	s_lshl_b64 s[30:31], s[18:19], 19
	s_add_u32 s30, s80, s30
	s_addc_u32 s31, s81, s31
	s_and_b64 s[36:37], s[8:9], exec
	s_cselect_b32 s19, s31, s47
	s_cselect_b32 s66, s30, s46
	s_ashr_i32 s17, s16, 31
	s_lshl_b64 s[36:37], s[16:17], 19
	s_add_u32 s36, s52, s36
	s_addc_u32 s37, s53, s37
	s_and_b64 s[50:51], s[8:9], exec
	s_cselect_b32 s17, s37, s49
	s_cselect_b32 s67, s36, s48
	s_add_u32 s46, s46, 0x40080
	s_addc_u32 s47, s47, 0
	s_add_u32 s68, s48, 0x100
	s_addc_u32 s69, s49, 0
	s_mov_b32 s70, -2
	ds_read_b128 v[140:143], v147
	ds_read_b128 v[150:153], v147 offset:1024
	ds_read_b128 v[154:157], v147 offset:2048
	ds_read_b128 v[158:161], v147 offset:3072
	ds_read_b128 v[162:165], v148
	ds_read_b128 v[166:169], v148 offset:1024
	ds_read_b128 v[170:173], v148 offset:2048
	ds_read_b128 v[174:177], v148 offset:3072
	s_add_u32 s48, s46, 0xfffc0080
	s_addc_u32 s49, s47, -1
	s_cmp_eq_u32 s70, 12
	s_cselect_b32 s51, s19, s49
	s_cselect_b32 s50, s66, s48
	s_cselect_b32 s49, s17, s69
	s_cselect_b32 s48, s67, s68
	v_lshl_add_u64 v[178:179], s[46:47], 0, v[132:133]
	s_add_i32 m0, s45, 0xc000
	ds_read_b128 v[184:187], v149
	ds_read_b128 v[188:191], v149 offset:1024
	ds_read_b128 v[192:195], v149 offset:2048
	ds_read_b128 v[196:199], v149 offset:3072
	ds_read_b128 v[200:203], v149 offset:4096
	ds_read_b128 v[204:207], v149 offset:5120
	ds_read_b128 v[208:211], v149 offset:6144
	ds_read_b128 v[212:215], v149 offset:7168
	global_load_lds_dwordx4 v[178:179], off
	v_lshl_add_u64 v[178:179], s[46:47], 0, v[134:135]
	s_add_i32 m0, s45, 0xe000
	s_nop 0
	global_load_lds_dwordx4 v[178:179], off
	s_waitcnt vmcnt(8)
	s_waitcnt lgkmcnt(0)
	s_barrier
	s_setprio 1
	s_waitcnt lgkmcnt(0)
	v_mfma_f32_16x16x32_bf16 v[124:127], v[140:143], v[184:187], 0
	v_mfma_f32_16x16x32_bf16 v[124:127], v[150:153], v[188:191], v[124:127]
	v_mfma_f32_16x16x32_bf16 v[120:123], v[154:157], v[184:187], 0
	v_mfma_f32_16x16x32_bf16 v[120:123], v[158:161], v[188:191], v[120:123]
	v_mfma_f32_16x16x32_bf16 v[108:111], v[140:143], v[192:195], 0
	v_mfma_f32_16x16x32_bf16 v[108:111], v[150:153], v[196:199], v[108:111]
	v_mfma_f32_16x16x32_bf16 v[104:107], v[154:157], v[192:195], 0
	v_mfma_f32_16x16x32_bf16 v[104:107], v[158:161], v[196:199], v[104:107]
	v_mfma_f32_16x16x32_bf16 v[92:95], v[140:143], v[200:203], 0
	v_mfma_f32_16x16x32_bf16 v[92:95], v[150:153], v[204:207], v[92:95]
	v_mfma_f32_16x16x32_bf16 v[88:91], v[154:157], v[200:203], 0
	v_mfma_f32_16x16x32_bf16 v[88:91], v[158:161], v[204:207], v[88:91]
	v_mfma_f32_16x16x32_bf16 v[76:79], v[140:143], v[208:211], 0
	v_mfma_f32_16x16x32_bf16 v[76:79], v[150:153], v[212:215], v[76:79]
	v_mfma_f32_16x16x32_bf16 v[72:75], v[154:157], v[208:211], 0
	v_mfma_f32_16x16x32_bf16 v[72:75], v[158:161], v[212:215], v[72:75]
	v_mfma_f32_16x16x32_bf16 v[116:119], v[162:165], v[184:187], 0
	v_mfma_f32_16x16x32_bf16 v[116:119], v[166:169], v[188:191], v[116:119]
	v_mfma_f32_16x16x32_bf16 v[112:115], v[170:173], v[184:187], 0
	v_mfma_f32_16x16x32_bf16 v[112:115], v[174:177], v[188:191], v[112:115]
	v_mfma_f32_16x16x32_bf16 v[100:103], v[162:165], v[192:195], 0
	v_mfma_f32_16x16x32_bf16 v[100:103], v[166:169], v[196:199], v[100:103]
	v_mfma_f32_16x16x32_bf16 v[96:99], v[170:173], v[192:195], 0
	v_mfma_f32_16x16x32_bf16 v[96:99], v[174:177], v[196:199], v[96:99]
	v_mfma_f32_16x16x32_bf16 v[84:87], v[162:165], v[200:203], 0
	v_mfma_f32_16x16x32_bf16 v[84:87], v[166:169], v[204:207], v[84:87]
	v_mfma_f32_16x16x32_bf16 v[80:83], v[170:173], v[200:203], 0
	v_mfma_f32_16x16x32_bf16 v[80:83], v[174:177], v[204:207], v[80:83]
	v_mfma_f32_16x16x32_bf16 v[68:71], v[162:165], v[208:211], 0
	v_mfma_f32_16x16x32_bf16 v[68:71], v[166:169], v[212:215], v[68:71]
	v_mfma_f32_16x16x32_bf16 v[64:67], v[170:173], v[208:211], 0
	v_mfma_f32_16x16x32_bf16 v[64:67], v[174:177], v[212:215], v[64:67]
	s_setprio 0
	s_barrier
	ds_read_b128 v[184:187], v149 offset:16384
	ds_read_b128 v[188:191], v149 offset:17408
	ds_read_b128 v[192:195], v149 offset:18432
	ds_read_b128 v[196:199], v149 offset:19456
	ds_read_b128 v[200:203], v149 offset:20480
	ds_read_b128 v[204:207], v149 offset:21504
	ds_read_b128 v[208:211], v149 offset:22528
	ds_read_b128 v[212:215], v149 offset:23552
	s_add_i32 s71, s62, s54
	v_lshl_add_u64 v[178:179], s[48:49], 0, v[130:131]
	s_mov_b32 m0, s71
	s_nop 0
	global_load_lds_dwordx4 v[178:179], off
	s_add_i32 m0, s71, 0x2000
	s_add_u32 s72, s48, 0x40000
	v_lshl_add_u64 v[216:217], s[48:49], 0, v[128:129]
	s_addc_u32 s73, s49, 0
	s_add_i32 s71, s63, s54
	global_load_lds_dwordx4 v[216:217], off
	v_lshl_add_u64 v[218:219], s[72:73], 0, v[130:131]
	s_mov_b32 m0, s71
	v_lshl_add_u64 v[220:221], s[50:51], 0, v[128:129]
	global_load_lds_dwordx4 v[218:219], off
	v_lshl_add_u64 v[218:219], s[72:73], 0, v[128:129]
	s_add_i32 m0, s71, 0x2000
	s_nop 0
	global_load_lds_dwordx4 v[218:219], off
	v_lshl_add_u64 v[218:219], s[50:51], 0, v[130:131]
	s_mov_b32 m0, s45
	s_nop 0
	global_load_lds_dwordx4 v[218:219], off
	s_mov_b32 m0, s56
	s_nop 0
	global_load_lds_dwordx4 v[220:221], off
	s_waitcnt vmcnt(8)
	s_waitcnt lgkmcnt(0)
	s_barrier
	s_setprio 1
	s_waitcnt lgkmcnt(0)
	v_mfma_f32_16x16x32_bf16 v[60:63], v[140:143], v[184:187], 0
	v_mfma_f32_16x16x32_bf16 v[60:63], v[150:153], v[188:191], v[60:63]
	v_mfma_f32_16x16x32_bf16 v[56:59], v[154:157], v[184:187], 0
	v_mfma_f32_16x16x32_bf16 v[56:59], v[158:161], v[188:191], v[56:59]
	v_mfma_f32_16x16x32_bf16 v[44:47], v[140:143], v[192:195], 0
	v_mfma_f32_16x16x32_bf16 v[44:47], v[150:153], v[196:199], v[44:47]
	v_mfma_f32_16x16x32_bf16 v[40:43], v[154:157], v[192:195], 0
	v_mfma_f32_16x16x32_bf16 v[40:43], v[158:161], v[196:199], v[40:43]
	v_mfma_f32_16x16x32_bf16 v[28:31], v[140:143], v[200:203], 0
	v_mfma_f32_16x16x32_bf16 v[28:31], v[150:153], v[204:207], v[28:31]
	v_mfma_f32_16x16x32_bf16 v[24:27], v[154:157], v[200:203], 0
	v_mfma_f32_16x16x32_bf16 v[24:27], v[158:161], v[204:207], v[24:27]
	v_mfma_f32_16x16x32_bf16 v[12:15], v[140:143], v[208:211], 0
	v_mfma_f32_16x16x32_bf16 v[12:15], v[150:153], v[212:215], v[12:15]
	v_mfma_f32_16x16x32_bf16 v[8:11], v[154:157], v[208:211], 0
	v_mfma_f32_16x16x32_bf16 v[8:11], v[158:161], v[212:215], v[8:11]
	v_mfma_f32_16x16x32_bf16 v[52:55], v[162:165], v[184:187], 0
	v_mfma_f32_16x16x32_bf16 v[52:55], v[166:169], v[188:191], v[52:55]
	v_mfma_f32_16x16x32_bf16 v[48:51], v[170:173], v[184:187], 0
	v_mfma_f32_16x16x32_bf16 v[48:51], v[174:177], v[188:191], v[48:51]
	v_mfma_f32_16x16x32_bf16 v[36:39], v[162:165], v[192:195], 0
	v_mfma_f32_16x16x32_bf16 v[36:39], v[166:169], v[196:199], v[36:39]
	v_mfma_f32_16x16x32_bf16 v[32:35], v[170:173], v[192:195], 0
	v_mfma_f32_16x16x32_bf16 v[32:35], v[174:177], v[196:199], v[32:35]
	v_mfma_f32_16x16x32_bf16 v[20:23], v[162:165], v[200:203], 0
	v_mfma_f32_16x16x32_bf16 v[20:23], v[166:169], v[204:207], v[20:23]
	v_mfma_f32_16x16x32_bf16 v[16:19], v[170:173], v[200:203], 0
	v_mfma_f32_16x16x32_bf16 v[16:19], v[174:177], v[204:207], v[16:19]
	v_mfma_f32_16x16x32_bf16 v[4:7], v[162:165], v[208:211], 0
	v_mfma_f32_16x16x32_bf16 v[4:7], v[166:169], v[212:215], v[4:7]
	v_mfma_f32_16x16x32_bf16 v[0:3], v[170:173], v[208:211], 0
	v_mfma_f32_16x16x32_bf16 v[0:3], v[174:177], v[212:215], v[0:3]
	s_setprio 0
	s_barrier
	s_branch .Lmid_gemm11
.LBB0_1434:
	ds_read_b128 v[140:143], v147
	ds_read_b128 v[150:153], v147 offset:1024
	ds_read_b128 v[154:157], v147 offset:2048
	ds_read_b128 v[158:161], v147 offset:3072
	ds_read_b128 v[162:165], v148
	ds_read_b128 v[166:169], v148 offset:1024
	ds_read_b128 v[170:173], v148 offset:2048
	ds_read_b128 v[174:177], v148 offset:3072
	ds_read_b128 v[184:187], v149
	ds_read_b128 v[188:191], v149 offset:1024
	ds_read_b128 v[192:195], v149 offset:2048
	ds_read_b128 v[196:199], v149 offset:3072
	ds_read_b128 v[200:203], v149 offset:4096
	ds_read_b128 v[204:207], v149 offset:5120
	ds_read_b128 v[208:211], v149 offset:6144
	ds_read_b128 v[212:215], v149 offset:7168
	s_add_u32 s48, s46, 0xfffc0080
	s_addc_u32 s49, s47, -1
	s_cmp_eq_u32 s70, 12
	s_cselect_b32 s51, s19, s49
	s_cselect_b32 s50, s66, s48
	s_cselect_b32 s49, s17, s69
	s_cselect_b32 s48, s67, s68
	v_lshl_add_u64 v[178:179], s[46:47], 0, v[132:133]
	s_add_i32 m0, s45, 0xc000
	s_nop 0
	global_load_lds_dwordx4 v[178:179], off
	v_lshl_add_u64 v[178:179], s[46:47], 0, v[134:135]
	s_add_i32 m0, s45, 0xe000
	s_nop 0
	global_load_lds_dwordx4 v[178:179], off
	s_waitcnt vmcnt(8)
	s_waitcnt lgkmcnt(0)
	s_barrier
	s_setprio 1
	s_waitcnt lgkmcnt(0)
	v_mfma_f32_16x16x32_bf16 v[124:127], v[140:143], v[184:187], v[124:127]
	v_mfma_f32_16x16x32_bf16 v[124:127], v[150:153], v[188:191], v[124:127]
	v_mfma_f32_16x16x32_bf16 v[120:123], v[154:157], v[184:187], v[120:123]
	v_mfma_f32_16x16x32_bf16 v[120:123], v[158:161], v[188:191], v[120:123]
	v_mfma_f32_16x16x32_bf16 v[108:111], v[140:143], v[192:195], v[108:111]
	v_mfma_f32_16x16x32_bf16 v[108:111], v[150:153], v[196:199], v[108:111]
	v_mfma_f32_16x16x32_bf16 v[104:107], v[154:157], v[192:195], v[104:107]
	v_mfma_f32_16x16x32_bf16 v[104:107], v[158:161], v[196:199], v[104:107]
	v_mfma_f32_16x16x32_bf16 v[92:95], v[140:143], v[200:203], v[92:95]
	v_mfma_f32_16x16x32_bf16 v[92:95], v[150:153], v[204:207], v[92:95]
	v_mfma_f32_16x16x32_bf16 v[88:91], v[154:157], v[200:203], v[88:91]
	v_mfma_f32_16x16x32_bf16 v[88:91], v[158:161], v[204:207], v[88:91]
	v_mfma_f32_16x16x32_bf16 v[76:79], v[140:143], v[208:211], v[76:79]
	v_mfma_f32_16x16x32_bf16 v[76:79], v[150:153], v[212:215], v[76:79]
	v_mfma_f32_16x16x32_bf16 v[72:75], v[154:157], v[208:211], v[72:75]
	v_mfma_f32_16x16x32_bf16 v[72:75], v[158:161], v[212:215], v[72:75]
	v_mfma_f32_16x16x32_bf16 v[116:119], v[162:165], v[184:187], v[116:119]
	v_mfma_f32_16x16x32_bf16 v[116:119], v[166:169], v[188:191], v[116:119]
	v_mfma_f32_16x16x32_bf16 v[112:115], v[170:173], v[184:187], v[112:115]
	v_mfma_f32_16x16x32_bf16 v[112:115], v[174:177], v[188:191], v[112:115]
	v_mfma_f32_16x16x32_bf16 v[100:103], v[162:165], v[192:195], v[100:103]
	v_mfma_f32_16x16x32_bf16 v[100:103], v[166:169], v[196:199], v[100:103]
	v_mfma_f32_16x16x32_bf16 v[96:99], v[170:173], v[192:195], v[96:99]
	v_mfma_f32_16x16x32_bf16 v[96:99], v[174:177], v[196:199], v[96:99]
	v_mfma_f32_16x16x32_bf16 v[84:87], v[162:165], v[200:203], v[84:87]
	v_mfma_f32_16x16x32_bf16 v[84:87], v[166:169], v[204:207], v[84:87]
	v_mfma_f32_16x16x32_bf16 v[80:83], v[170:173], v[200:203], v[80:83]
	v_mfma_f32_16x16x32_bf16 v[80:83], v[174:177], v[204:207], v[80:83]
	v_mfma_f32_16x16x32_bf16 v[68:71], v[162:165], v[208:211], v[68:71]
	v_mfma_f32_16x16x32_bf16 v[68:71], v[166:169], v[212:215], v[68:71]
	v_mfma_f32_16x16x32_bf16 v[64:67], v[170:173], v[208:211], v[64:67]
	v_mfma_f32_16x16x32_bf16 v[64:67], v[174:177], v[212:215], v[64:67]
	s_setprio 0
	s_barrier
	ds_read_b128 v[184:187], v149 offset:16384
	ds_read_b128 v[188:191], v149 offset:17408
	ds_read_b128 v[192:195], v149 offset:18432
	ds_read_b128 v[196:199], v149 offset:19456
	ds_read_b128 v[200:203], v149 offset:20480
	ds_read_b128 v[204:207], v149 offset:21504
	ds_read_b128 v[208:211], v149 offset:22528
	ds_read_b128 v[212:215], v149 offset:23552
	s_add_i32 s71, s62, s54
	v_lshl_add_u64 v[178:179], s[48:49], 0, v[130:131]
	s_mov_b32 m0, s71
	s_nop 0
	global_load_lds_dwordx4 v[178:179], off
	s_add_i32 m0, s71, 0x2000
	s_add_u32 s72, s48, 0x40000
	v_lshl_add_u64 v[216:217], s[48:49], 0, v[128:129]
	s_addc_u32 s73, s49, 0
	s_add_i32 s71, s63, s54
	global_load_lds_dwordx4 v[216:217], off
	v_lshl_add_u64 v[218:219], s[72:73], 0, v[130:131]
	s_mov_b32 m0, s71
	v_lshl_add_u64 v[220:221], s[50:51], 0, v[128:129]
	global_load_lds_dwordx4 v[218:219], off
	v_lshl_add_u64 v[218:219], s[72:73], 0, v[128:129]
	s_add_i32 m0, s71, 0x2000
	s_nop 0
	global_load_lds_dwordx4 v[218:219], off
	v_lshl_add_u64 v[218:219], s[50:51], 0, v[130:131]
	s_mov_b32 m0, s45
	s_nop 0
	global_load_lds_dwordx4 v[218:219], off
	s_mov_b32 m0, s56
	s_nop 0
	global_load_lds_dwordx4 v[220:221], off
	s_waitcnt vmcnt(8)
	s_waitcnt lgkmcnt(0)
	s_barrier
	s_setprio 1
	s_waitcnt lgkmcnt(0)
	v_mfma_f32_16x16x32_bf16 v[60:63], v[140:143], v[184:187], v[60:63]
	v_mfma_f32_16x16x32_bf16 v[60:63], v[150:153], v[188:191], v[60:63]
	v_mfma_f32_16x16x32_bf16 v[56:59], v[154:157], v[184:187], v[56:59]
	v_mfma_f32_16x16x32_bf16 v[56:59], v[158:161], v[188:191], v[56:59]
	v_mfma_f32_16x16x32_bf16 v[44:47], v[140:143], v[192:195], v[44:47]
	v_mfma_f32_16x16x32_bf16 v[44:47], v[150:153], v[196:199], v[44:47]
	v_mfma_f32_16x16x32_bf16 v[40:43], v[154:157], v[192:195], v[40:43]
	v_mfma_f32_16x16x32_bf16 v[40:43], v[158:161], v[196:199], v[40:43]
	v_mfma_f32_16x16x32_bf16 v[28:31], v[140:143], v[200:203], v[28:31]
	v_mfma_f32_16x16x32_bf16 v[28:31], v[150:153], v[204:207], v[28:31]
	v_mfma_f32_16x16x32_bf16 v[24:27], v[154:157], v[200:203], v[24:27]
	v_mfma_f32_16x16x32_bf16 v[24:27], v[158:161], v[204:207], v[24:27]
	v_mfma_f32_16x16x32_bf16 v[12:15], v[140:143], v[208:211], v[12:15]
	v_mfma_f32_16x16x32_bf16 v[12:15], v[150:153], v[212:215], v[12:15]
	v_mfma_f32_16x16x32_bf16 v[8:11], v[154:157], v[208:211], v[8:11]
	v_mfma_f32_16x16x32_bf16 v[8:11], v[158:161], v[212:215], v[8:11]
	v_mfma_f32_16x16x32_bf16 v[52:55], v[162:165], v[184:187], v[52:55]
	v_mfma_f32_16x16x32_bf16 v[52:55], v[166:169], v[188:191], v[52:55]
	v_mfma_f32_16x16x32_bf16 v[48:51], v[170:173], v[184:187], v[48:51]
	v_mfma_f32_16x16x32_bf16 v[48:51], v[174:177], v[188:191], v[48:51]
	v_mfma_f32_16x16x32_bf16 v[36:39], v[162:165], v[192:195], v[36:39]
	v_mfma_f32_16x16x32_bf16 v[36:39], v[166:169], v[196:199], v[36:39]
	v_mfma_f32_16x16x32_bf16 v[32:35], v[170:173], v[192:195], v[32:35]
	v_mfma_f32_16x16x32_bf16 v[32:35], v[174:177], v[196:199], v[32:35]
	v_mfma_f32_16x16x32_bf16 v[20:23], v[162:165], v[200:203], v[20:23]
	v_mfma_f32_16x16x32_bf16 v[20:23], v[166:169], v[204:207], v[20:23]
	v_mfma_f32_16x16x32_bf16 v[16:19], v[170:173], v[200:203], v[16:19]
	v_mfma_f32_16x16x32_bf16 v[16:19], v[174:177], v[204:207], v[16:19]
	v_mfma_f32_16x16x32_bf16 v[4:7], v[162:165], v[208:211], v[4:7]
	v_mfma_f32_16x16x32_bf16 v[4:7], v[166:169], v[212:215], v[4:7]
	v_mfma_f32_16x16x32_bf16 v[0:3], v[170:173], v[208:211], v[0:3]
	v_mfma_f32_16x16x32_bf16 v[0:3], v[174:177], v[212:215], v[0:3]
	s_setprio 0
	s_barrier
.Lmid_gemm11:
	s_add_i32 s71, 0, 0x18000
	s_add_i32 s72, 0, 0x1c000
	v_add_u32_e32 v158, s71, v145
	v_add_u32_e32 v174, s72, v145
	ds_read_b128 v[140:143], v158
	ds_read_b128 v[150:153], v158 offset:1024
	ds_read_b128 v[154:157], v158 offset:2048
	ds_read_b128 v[158:161], v158 offset:3072
	ds_read_b128 v[162:165], v174
	ds_read_b128 v[166:169], v174 offset:1024
	ds_read_b128 v[170:173], v174 offset:2048
	ds_read_b128 v[174:177], v174 offset:3072
	ds_read_b128 v[184:187], v149 offset:32768
	ds_read_b128 v[188:191], v149 offset:33792
	ds_read_b128 v[192:195], v149 offset:34816
	ds_read_b128 v[196:199], v149 offset:35840
	ds_read_b128 v[200:203], v149 offset:36864
	ds_read_b128 v[204:207], v149 offset:37888
	ds_read_b128 v[208:211], v149 offset:38912
	ds_read_b128 v[212:215], v149 offset:39936
	s_add_u32 s50, s50, 0x40000
	s_addc_u32 s51, s51, 0
	s_mov_b32 m0, s57
	v_lshl_add_u64 v[222:223], s[50:51], 0, v[130:131]
	global_load_lds_dwordx4 v[222:223], off
	v_lshl_add_u64 v[222:223], s[50:51], 0, v[128:129]
	s_mov_b32 m0, s58
	s_nop 0
	global_load_lds_dwordx4 v[222:223], off
	s_waitcnt vmcnt(8)
	s_waitcnt lgkmcnt(0)
	s_barrier
	s_setprio 1
	s_waitcnt lgkmcnt(0)
	v_mfma_f32_16x16x32_bf16 v[124:127], v[140:143], v[184:187], v[124:127]
	v_mfma_f32_16x16x32_bf16 v[124:127], v[150:153], v[188:191], v[124:127]
	v_mfma_f32_16x16x32_bf16 v[120:123], v[154:157], v[184:187], v[120:123]
	v_mfma_f32_16x16x32_bf16 v[120:123], v[158:161], v[188:191], v[120:123]
	v_mfma_f32_16x16x32_bf16 v[108:111], v[140:143], v[192:195], v[108:111]
	v_mfma_f32_16x16x32_bf16 v[108:111], v[150:153], v[196:199], v[108:111]
	v_mfma_f32_16x16x32_bf16 v[104:107], v[154:157], v[192:195], v[104:107]
	v_mfma_f32_16x16x32_bf16 v[104:107], v[158:161], v[196:199], v[104:107]
	v_mfma_f32_16x16x32_bf16 v[92:95], v[140:143], v[200:203], v[92:95]
	v_mfma_f32_16x16x32_bf16 v[92:95], v[150:153], v[204:207], v[92:95]
	v_mfma_f32_16x16x32_bf16 v[88:91], v[154:157], v[200:203], v[88:91]
	v_mfma_f32_16x16x32_bf16 v[88:91], v[158:161], v[204:207], v[88:91]
	v_mfma_f32_16x16x32_bf16 v[76:79], v[140:143], v[208:211], v[76:79]
	v_mfma_f32_16x16x32_bf16 v[76:79], v[150:153], v[212:215], v[76:79]
	v_mfma_f32_16x16x32_bf16 v[72:75], v[154:157], v[208:211], v[72:75]
	v_mfma_f32_16x16x32_bf16 v[72:75], v[158:161], v[212:215], v[72:75]
	v_mfma_f32_16x16x32_bf16 v[116:119], v[162:165], v[184:187], v[116:119]
	v_mfma_f32_16x16x32_bf16 v[116:119], v[166:169], v[188:191], v[116:119]
	v_mfma_f32_16x16x32_bf16 v[112:115], v[170:173], v[184:187], v[112:115]
	v_mfma_f32_16x16x32_bf16 v[112:115], v[174:177], v[188:191], v[112:115]
	v_mfma_f32_16x16x32_bf16 v[100:103], v[162:165], v[192:195], v[100:103]
	v_mfma_f32_16x16x32_bf16 v[100:103], v[166:169], v[196:199], v[100:103]
	v_mfma_f32_16x16x32_bf16 v[96:99], v[170:173], v[192:195], v[96:99]
	v_mfma_f32_16x16x32_bf16 v[96:99], v[174:177], v[196:199], v[96:99]
	v_mfma_f32_16x16x32_bf16 v[84:87], v[162:165], v[200:203], v[84:87]
	v_mfma_f32_16x16x32_bf16 v[84:87], v[166:169], v[204:207], v[84:87]
	v_mfma_f32_16x16x32_bf16 v[80:83], v[170:173], v[200:203], v[80:83]
	v_mfma_f32_16x16x32_bf16 v[80:83], v[174:177], v[204:207], v[80:83]
	v_mfma_f32_16x16x32_bf16 v[68:71], v[162:165], v[208:211], v[68:71]
	v_mfma_f32_16x16x32_bf16 v[68:71], v[166:169], v[212:215], v[68:71]
	v_mfma_f32_16x16x32_bf16 v[64:67], v[170:173], v[208:211], v[64:67]
	v_mfma_f32_16x16x32_bf16 v[64:67], v[174:177], v[212:215], v[64:67]
	s_setprio 0
	s_barrier
	ds_read_b128 v[184:187], v149 offset:49152
	ds_read_b128 v[188:191], v149 offset:50176
	ds_read_b128 v[192:195], v149 offset:51200
	ds_read_b128 v[196:199], v149 offset:52224
	ds_read_b128 v[200:203], v149 offset:53248
	ds_read_b128 v[204:207], v149 offset:54272
	ds_read_b128 v[208:211], v149 offset:55296
	ds_read_b128 v[212:215], v149 offset:56320
	s_add_i32 s50, s71, s54
	v_lshl_add_u64 v[178:179], v[178:179], 0, s[10:11]
	s_mov_b32 m0, s50
	s_nop 0
	global_load_lds_dwordx4 v[178:179], off
	s_add_i32 m0, s50, 0x2000
	s_add_u32 s48, s48, 0x40080
	v_lshl_add_u64 v[178:179], v[216:217], 0, s[10:11]
	s_addc_u32 s49, s49, 0
	s_add_i32 s50, s72, s54
	global_load_lds_dwordx4 v[178:179], off
	v_lshl_add_u64 v[178:179], s[48:49], 0, v[130:131]
	s_mov_b32 m0, s50
	s_nop 0
	global_load_lds_dwordx4 v[178:179], off
	v_lshl_add_u64 v[178:179], s[48:49], 0, v[128:129]
	s_add_i32 m0, s50, 0x2000
	s_nop 0
	global_load_lds_dwordx4 v[178:179], off
	v_lshl_add_u64 v[178:179], v[218:219], 0, s[10:11]
	s_mov_b32 m0, s60
	s_nop 0
	global_load_lds_dwordx4 v[178:179], off
	v_lshl_add_u64 v[178:179], v[220:221], 0, s[10:11]
	s_mov_b32 m0, s61
	s_nop 0
	global_load_lds_dwordx4 v[178:179], off
	s_waitcnt vmcnt(8)
	s_waitcnt lgkmcnt(0)
	s_barrier
	s_setprio 1
	s_waitcnt lgkmcnt(0)
	v_mfma_f32_16x16x32_bf16 v[60:63], v[140:143], v[184:187], v[60:63]
	v_mfma_f32_16x16x32_bf16 v[60:63], v[150:153], v[188:191], v[60:63]
	v_mfma_f32_16x16x32_bf16 v[56:59], v[154:157], v[184:187], v[56:59]
	v_mfma_f32_16x16x32_bf16 v[56:59], v[158:161], v[188:191], v[56:59]
	v_mfma_f32_16x16x32_bf16 v[44:47], v[140:143], v[192:195], v[44:47]
	v_mfma_f32_16x16x32_bf16 v[44:47], v[150:153], v[196:199], v[44:47]
	v_mfma_f32_16x16x32_bf16 v[40:43], v[154:157], v[192:195], v[40:43]
	v_mfma_f32_16x16x32_bf16 v[40:43], v[158:161], v[196:199], v[40:43]
	v_mfma_f32_16x16x32_bf16 v[28:31], v[140:143], v[200:203], v[28:31]
	v_mfma_f32_16x16x32_bf16 v[28:31], v[150:153], v[204:207], v[28:31]
	v_mfma_f32_16x16x32_bf16 v[24:27], v[154:157], v[200:203], v[24:27]
	v_mfma_f32_16x16x32_bf16 v[24:27], v[158:161], v[204:207], v[24:27]
	v_mfma_f32_16x16x32_bf16 v[12:15], v[140:143], v[208:211], v[12:15]
	v_mfma_f32_16x16x32_bf16 v[12:15], v[150:153], v[212:215], v[12:15]
	v_mfma_f32_16x16x32_bf16 v[8:11], v[154:157], v[208:211], v[8:11]
	v_mfma_f32_16x16x32_bf16 v[8:11], v[158:161], v[212:215], v[8:11]
	v_mfma_f32_16x16x32_bf16 v[52:55], v[162:165], v[184:187], v[52:55]
	v_mfma_f32_16x16x32_bf16 v[52:55], v[166:169], v[188:191], v[52:55]
	v_mfma_f32_16x16x32_bf16 v[48:51], v[170:173], v[184:187], v[48:51]
	v_mfma_f32_16x16x32_bf16 v[48:51], v[174:177], v[188:191], v[48:51]
	v_mfma_f32_16x16x32_bf16 v[36:39], v[162:165], v[192:195], v[36:39]
	v_mfma_f32_16x16x32_bf16 v[36:39], v[166:169], v[196:199], v[36:39]
	v_mfma_f32_16x16x32_bf16 v[32:35], v[170:173], v[192:195], v[32:35]
	v_mfma_f32_16x16x32_bf16 v[32:35], v[174:177], v[196:199], v[32:35]
	v_mfma_f32_16x16x32_bf16 v[20:23], v[162:165], v[200:203], v[20:23]
	v_mfma_f32_16x16x32_bf16 v[20:23], v[166:169], v[204:207], v[20:23]
	v_mfma_f32_16x16x32_bf16 v[16:19], v[170:173], v[200:203], v[16:19]
	v_mfma_f32_16x16x32_bf16 v[16:19], v[174:177], v[204:207], v[16:19]
	v_mfma_f32_16x16x32_bf16 v[4:7], v[162:165], v[208:211], v[4:7]
	v_mfma_f32_16x16x32_bf16 v[4:7], v[166:169], v[212:215], v[4:7]
	v_mfma_f32_16x16x32_bf16 v[0:3], v[170:173], v[208:211], v[0:3]
	v_mfma_f32_16x16x32_bf16 v[0:3], v[174:177], v[212:215], v[0:3]
	s_setprio 0
	s_barrier
	s_add_i32 s70, s70, 2
	s_add_u32 s46, s46, 0x100
	s_addc_u32 s47, s47, 0
	s_add_u32 s68, s68, 0x100
	s_addc_u32 s69, s69, 0
	s_cmp_gt_u32 s70, 13
	s_cbranch_scc0 .LBB0_1434
	s_and_b64 vcc, exec, s[12:13]
	s_cbranch_vccz .LBB0_1437
	s_barrier

.LBB0_1513:
	s_add_u32 s74, s48, 0x100
	s_addc_u32 s75, s49, 0
	s_mov_b32 s76, -2
	ds_read_b128 v[152:155], v149
	ds_read_b128 v[156:159], v149 offset:1024
	ds_read_b128 v[160:163], v149 offset:2048
	ds_read_b128 v[164:167], v149 offset:3072
	ds_read_b128 v[168:171], v150
	ds_read_b128 v[172:175], v150 offset:1024
	ds_read_b128 v[176:179], v150 offset:2048
	ds_read_b128 v[184:187], v150 offset:3072
	s_add_u32 s48, s46, 0x100
	s_addc_u32 s49, s47, 0
	s_cmp_eq_u32 s76, 40
	s_cselect_b32 s53, s9, s49
	s_cselect_b32 s52, s8, s48
	s_cselect_b32 s51, s45, s75
	s_cselect_b32 s50, s44, s74
	v_lshl_add_u64 v[144:145], s[46:47], 0, v[136:137]
	s_add_i32 m0, s57, 0xc000
	ds_read_b128 v[188:191], v151
	ds_read_b128 v[192:195], v151 offset:1024
	ds_read_b128 v[196:199], v151 offset:2048
	ds_read_b128 v[200:203], v151 offset:3072
	ds_read_b128 v[204:207], v151 offset:4096
	ds_read_b128 v[208:211], v151 offset:5120
	ds_read_b128 v[212:215], v151 offset:6144
	ds_read_b128 v[216:219], v151 offset:7168
	global_load_lds_dwordx4 v[144:145], off
	v_lshl_add_u64 v[144:145], s[46:47], 0, v[138:139]
	s_add_i32 m0, s57, 0xe000
	s_nop 0
	global_load_lds_dwordx4 v[144:145], off
	s_waitcnt vmcnt(8)
	s_waitcnt lgkmcnt(0)
	s_barrier
	s_setprio 1
	s_waitcnt lgkmcnt(0)
	v_mfma_f32_16x16x32_bf16 v[124:127], v[152:155], v[188:191], 0
	v_mfma_f32_16x16x32_bf16 v[124:127], v[156:159], v[192:195], v[124:127]
	v_mfma_f32_16x16x32_bf16 v[120:123], v[160:163], v[188:191], 0
	v_mfma_f32_16x16x32_bf16 v[120:123], v[164:167], v[192:195], v[120:123]
	v_mfma_f32_16x16x32_bf16 v[116:119], v[152:155], v[196:199], 0
	v_mfma_f32_16x16x32_bf16 v[116:119], v[156:159], v[200:203], v[116:119]
	v_mfma_f32_16x16x32_bf16 v[108:111], v[160:163], v[196:199], 0
	v_mfma_f32_16x16x32_bf16 v[108:111], v[164:167], v[200:203], v[108:111]
	v_mfma_f32_16x16x32_bf16 v[100:103], v[152:155], v[204:207], 0
	v_mfma_f32_16x16x32_bf16 v[100:103], v[156:159], v[208:211], v[100:103]
	v_mfma_f32_16x16x32_bf16 v[92:95], v[160:163], v[204:207], 0
	v_mfma_f32_16x16x32_bf16 v[92:95], v[164:167], v[208:211], v[92:95]
	v_mfma_f32_16x16x32_bf16 v[84:87], v[152:155], v[212:215], 0
	v_mfma_f32_16x16x32_bf16 v[84:87], v[156:159], v[216:219], v[84:87]
	v_mfma_f32_16x16x32_bf16 v[76:79], v[160:163], v[212:215], 0
	v_mfma_f32_16x16x32_bf16 v[76:79], v[164:167], v[216:219], v[76:79]
	v_mfma_f32_16x16x32_bf16 v[112:115], v[168:171], v[188:191], 0
	v_mfma_f32_16x16x32_bf16 v[112:115], v[172:175], v[192:195], v[112:115]
	v_mfma_f32_16x16x32_bf16 v[104:107], v[176:179], v[188:191], 0
	v_mfma_f32_16x16x32_bf16 v[104:107], v[184:187], v[192:195], v[104:107]
	v_mfma_f32_16x16x32_bf16 v[96:99], v[168:171], v[196:199], 0
	v_mfma_f32_16x16x32_bf16 v[96:99], v[172:175], v[200:203], v[96:99]
	v_mfma_f32_16x16x32_bf16 v[88:91], v[176:179], v[196:199], 0
	v_mfma_f32_16x16x32_bf16 v[88:91], v[184:187], v[200:203], v[88:91]
	v_mfma_f32_16x16x32_bf16 v[80:83], v[168:171], v[204:207], 0
	v_mfma_f32_16x16x32_bf16 v[80:83], v[172:175], v[208:211], v[80:83]
	v_mfma_f32_16x16x32_bf16 v[72:75], v[176:179], v[204:207], 0
	v_mfma_f32_16x16x32_bf16 v[72:75], v[184:187], v[208:211], v[72:75]
	v_mfma_f32_16x16x32_bf16 v[68:71], v[168:171], v[212:215], 0
	v_mfma_f32_16x16x32_bf16 v[68:71], v[172:175], v[216:219], v[68:71]
	v_mfma_f32_16x16x32_bf16 v[64:67], v[176:179], v[212:215], 0
	v_mfma_f32_16x16x32_bf16 v[64:67], v[184:187], v[216:219], v[64:67]
	s_setprio 0
	s_barrier
	ds_read_b128 v[188:191], v151 offset:16384
	ds_read_b128 v[192:195], v151 offset:17408
	ds_read_b128 v[196:199], v151 offset:18432
	ds_read_b128 v[200:203], v151 offset:19456
	ds_read_b128 v[204:207], v151 offset:20480
	ds_read_b128 v[208:211], v151 offset:21504
	ds_read_b128 v[212:215], v151 offset:22528
	ds_read_b128 v[216:219], v151 offset:23552
	s_add_i32 s46, s64, s56
	v_lshl_add_u64 v[144:145], s[50:51], 0, v[130:131]
	s_mov_b32 m0, s46
	s_nop 0
	global_load_lds_dwordx4 v[144:145], off
	s_add_i32 m0, s46, 0x2000
	s_add_u32 s46, s50, 0xb0000
	v_lshl_add_u64 v[220:221], s[50:51], 0, v[134:135]
	s_addc_u32 s47, s51, 0
	s_add_i32 s77, s65, s56
	global_load_lds_dwordx4 v[220:221], off
	v_lshl_add_u64 v[222:223], s[46:47], 0, v[130:131]
	s_mov_b32 m0, s77
	v_lshl_add_u64 v[224:225], s[52:53], 0, v[132:133]
	global_load_lds_dwordx4 v[222:223], off
	v_lshl_add_u64 v[222:223], s[46:47], 0, v[134:135]
	s_add_i32 m0, s77, 0x2000
	s_nop 0
	global_load_lds_dwordx4 v[222:223], off
	v_lshl_add_u64 v[222:223], s[52:53], 0, v[128:129]
	s_mov_b32 m0, s57
	s_nop 0
	global_load_lds_dwordx4 v[222:223], off
	s_mov_b32 m0, s58
	s_nop 0
	global_load_lds_dwordx4 v[224:225], off
	s_waitcnt vmcnt(8)
	s_waitcnt lgkmcnt(0)
	s_barrier
	s_setprio 1
	s_waitcnt lgkmcnt(0)
	v_mfma_f32_16x16x32_bf16 v[60:63], v[152:155], v[188:191], 0
	v_mfma_f32_16x16x32_bf16 v[60:63], v[156:159], v[192:195], v[60:63]
	v_mfma_f32_16x16x32_bf16 v[56:59], v[160:163], v[188:191], 0
	v_mfma_f32_16x16x32_bf16 v[56:59], v[164:167], v[192:195], v[56:59]
	v_mfma_f32_16x16x32_bf16 v[52:55], v[152:155], v[196:199], 0
	v_mfma_f32_16x16x32_bf16 v[52:55], v[156:159], v[200:203], v[52:55]
	v_mfma_f32_16x16x32_bf16 v[44:47], v[160:163], v[196:199], 0
	v_mfma_f32_16x16x32_bf16 v[44:47], v[164:167], v[200:203], v[44:47]
	v_mfma_f32_16x16x32_bf16 v[36:39], v[152:155], v[204:207], 0
	v_mfma_f32_16x16x32_bf16 v[36:39], v[156:159], v[208:211], v[36:39]
	v_mfma_f32_16x16x32_bf16 v[28:31], v[160:163], v[204:207], 0
	v_mfma_f32_16x16x32_bf16 v[28:31], v[164:167], v[208:211], v[28:31]
	v_mfma_f32_16x16x32_bf16 v[20:23], v[152:155], v[212:215], 0
	v_mfma_f32_16x16x32_bf16 v[20:23], v[156:159], v[216:219], v[20:23]
	v_mfma_f32_16x16x32_bf16 v[12:15], v[160:163], v[212:215], 0
	v_mfma_f32_16x16x32_bf16 v[12:15], v[164:167], v[216:219], v[12:15]
	v_mfma_f32_16x16x32_bf16 v[48:51], v[168:171], v[188:191], 0
	v_mfma_f32_16x16x32_bf16 v[48:51], v[172:175], v[192:195], v[48:51]
	v_mfma_f32_16x16x32_bf16 v[40:43], v[176:179], v[188:191], 0
	v_mfma_f32_16x16x32_bf16 v[40:43], v[184:187], v[192:195], v[40:43]
	v_mfma_f32_16x16x32_bf16 v[32:35], v[168:171], v[196:199], 0
	v_mfma_f32_16x16x32_bf16 v[32:35], v[172:175], v[200:203], v[32:35]
	v_mfma_f32_16x16x32_bf16 v[24:27], v[176:179], v[196:199], 0
	v_mfma_f32_16x16x32_bf16 v[24:27], v[184:187], v[200:203], v[24:27]
	v_mfma_f32_16x16x32_bf16 v[16:19], v[168:171], v[204:207], 0
	v_mfma_f32_16x16x32_bf16 v[16:19], v[172:175], v[208:211], v[16:19]
	v_mfma_f32_16x16x32_bf16 v[8:11], v[176:179], v[204:207], 0
	v_mfma_f32_16x16x32_bf16 v[8:11], v[184:187], v[208:211], v[8:11]
	v_mfma_f32_16x16x32_bf16 v[4:7], v[168:171], v[212:215], 0
	v_mfma_f32_16x16x32_bf16 v[4:7], v[172:175], v[216:219], v[4:7]
	v_mfma_f32_16x16x32_bf16 v[0:3], v[176:179], v[212:215], 0
	v_mfma_f32_16x16x32_bf16 v[0:3], v[184:187], v[216:219], v[0:3]
	s_setprio 0
	s_barrier
	s_branch .Lmid_gemm12
.LBB0_1514:
	ds_read_b128 v[152:155], v149
	ds_read_b128 v[156:159], v149 offset:1024
	ds_read_b128 v[160:163], v149 offset:2048
	ds_read_b128 v[164:167], v149 offset:3072
	ds_read_b128 v[168:171], v150
	ds_read_b128 v[172:175], v150 offset:1024
	ds_read_b128 v[176:179], v150 offset:2048
	ds_read_b128 v[184:187], v150 offset:3072
	ds_read_b128 v[188:191], v151
	ds_read_b128 v[192:195], v151 offset:1024
	ds_read_b128 v[196:199], v151 offset:2048
	ds_read_b128 v[200:203], v151 offset:3072
	ds_read_b128 v[204:207], v151 offset:4096
	ds_read_b128 v[208:211], v151 offset:5120
	ds_read_b128 v[212:215], v151 offset:6144
	ds_read_b128 v[216:219], v151 offset:7168
	s_add_u32 s48, s46, 0x100
	s_addc_u32 s49, s47, 0
	s_cmp_eq_u32 s76, 40
	s_cselect_b32 s53, s9, s49
	s_cselect_b32 s52, s8, s48
	s_cselect_b32 s51, s45, s75
	s_cselect_b32 s50, s44, s74
	v_lshl_add_u64 v[144:145], s[46:47], 0, v[136:137]
	s_add_i32 m0, s57, 0xc000
	s_nop 0
	global_load_lds_dwordx4 v[144:145], off
	v_lshl_add_u64 v[144:145], s[46:47], 0, v[138:139]
	s_add_i32 m0, s57, 0xe000
	s_nop 0
	global_load_lds_dwordx4 v[144:145], off
	s_waitcnt vmcnt(8)
	s_waitcnt lgkmcnt(0)
	s_barrier
	s_setprio 1
	s_waitcnt lgkmcnt(0)
	v_mfma_f32_16x16x32_bf16 v[124:127], v[152:155], v[188:191], v[124:127]
	v_mfma_f32_16x16x32_bf16 v[124:127], v[156:159], v[192:195], v[124:127]
	v_mfma_f32_16x16x32_bf16 v[120:123], v[160:163], v[188:191], v[120:123]
	v_mfma_f32_16x16x32_bf16 v[120:123], v[164:167], v[192:195], v[120:123]
	v_mfma_f32_16x16x32_bf16 v[116:119], v[152:155], v[196:199], v[116:119]
	v_mfma_f32_16x16x32_bf16 v[116:119], v[156:159], v[200:203], v[116:119]
	v_mfma_f32_16x16x32_bf16 v[108:111], v[160:163], v[196:199], v[108:111]
	v_mfma_f32_16x16x32_bf16 v[108:111], v[164:167], v[200:203], v[108:111]
	v_mfma_f32_16x16x32_bf16 v[100:103], v[152:155], v[204:207], v[100:103]
	v_mfma_f32_16x16x32_bf16 v[100:103], v[156:159], v[208:211], v[100:103]
	v_mfma_f32_16x16x32_bf16 v[92:95], v[160:163], v[204:207], v[92:95]
	v_mfma_f32_16x16x32_bf16 v[92:95], v[164:167], v[208:211], v[92:95]
	v_mfma_f32_16x16x32_bf16 v[84:87], v[152:155], v[212:215], v[84:87]
	v_mfma_f32_16x16x32_bf16 v[84:87], v[156:159], v[216:219], v[84:87]
	v_mfma_f32_16x16x32_bf16 v[76:79], v[160:163], v[212:215], v[76:79]
	v_mfma_f32_16x16x32_bf16 v[76:79], v[164:167], v[216:219], v[76:79]
	v_mfma_f32_16x16x32_bf16 v[112:115], v[168:171], v[188:191], v[112:115]
	v_mfma_f32_16x16x32_bf16 v[112:115], v[172:175], v[192:195], v[112:115]
	v_mfma_f32_16x16x32_bf16 v[104:107], v[176:179], v[188:191], v[104:107]
	v_mfma_f32_16x16x32_bf16 v[104:107], v[184:187], v[192:195], v[104:107]
	v_mfma_f32_16x16x32_bf16 v[96:99], v[168:171], v[196:199], v[96:99]
	v_mfma_f32_16x16x32_bf16 v[96:99], v[172:175], v[200:203], v[96:99]
	v_mfma_f32_16x16x32_bf16 v[88:91], v[176:179], v[196:199], v[88:91]
	v_mfma_f32_16x16x32_bf16 v[88:91], v[184:187], v[200:203], v[88:91]
	v_mfma_f32_16x16x32_bf16 v[80:83], v[168:171], v[204:207], v[80:83]
	v_mfma_f32_16x16x32_bf16 v[80:83], v[172:175], v[208:211], v[80:83]
	v_mfma_f32_16x16x32_bf16 v[72:75], v[176:179], v[204:207], v[72:75]
	v_mfma_f32_16x16x32_bf16 v[72:75], v[184:187], v[208:211], v[72:75]
	v_mfma_f32_16x16x32_bf16 v[68:71], v[168:171], v[212:215], v[68:71]
	v_mfma_f32_16x16x32_bf16 v[68:71], v[172:175], v[216:219], v[68:71]
	v_mfma_f32_16x16x32_bf16 v[64:67], v[176:179], v[212:215], v[64:67]
	v_mfma_f32_16x16x32_bf16 v[64:67], v[184:187], v[216:219], v[64:67]
	s_setprio 0
	s_barrier
	ds_read_b128 v[188:191], v151 offset:16384
	ds_read_b128 v[192:195], v151 offset:17408
	ds_read_b128 v[196:199], v151 offset:18432
	ds_read_b128 v[200:203], v151 offset:19456
	ds_read_b128 v[204:207], v151 offset:20480
	ds_read_b128 v[208:211], v151 offset:21504
	ds_read_b128 v[212:215], v151 offset:22528
	ds_read_b128 v[216:219], v151 offset:23552
	s_add_i32 s46, s64, s56
	v_lshl_add_u64 v[144:145], s[50:51], 0, v[130:131]
	s_mov_b32 m0, s46
	s_nop 0
	global_load_lds_dwordx4 v[144:145], off
	s_add_i32 m0, s46, 0x2000
	s_add_u32 s46, s50, 0xb0000
	v_lshl_add_u64 v[220:221], s[50:51], 0, v[134:135]
	s_addc_u32 s47, s51, 0
	s_add_i32 s77, s65, s56
	global_load_lds_dwordx4 v[220:221], off
	v_lshl_add_u64 v[222:223], s[46:47], 0, v[130:131]
	s_mov_b32 m0, s77
	v_lshl_add_u64 v[224:225], s[52:53], 0, v[132:133]
	global_load_lds_dwordx4 v[222:223], off
	v_lshl_add_u64 v[222:223], s[46:47], 0, v[134:135]
	s_add_i32 m0, s77, 0x2000
	s_nop 0
	global_load_lds_dwordx4 v[222:223], off
	v_lshl_add_u64 v[222:223], s[52:53], 0, v[128:129]
	s_mov_b32 m0, s57
	s_nop 0
	global_load_lds_dwordx4 v[222:223], off
	s_mov_b32 m0, s58
	s_nop 0
	global_load_lds_dwordx4 v[224:225], off
	s_waitcnt vmcnt(8)
	s_waitcnt lgkmcnt(0)
	s_barrier
	s_setprio 1
	s_waitcnt lgkmcnt(0)
	v_mfma_f32_16x16x32_bf16 v[60:63], v[152:155], v[188:191], v[60:63]
	v_mfma_f32_16x16x32_bf16 v[60:63], v[156:159], v[192:195], v[60:63]
	v_mfma_f32_16x16x32_bf16 v[56:59], v[160:163], v[188:191], v[56:59]
	v_mfma_f32_16x16x32_bf16 v[56:59], v[164:167], v[192:195], v[56:59]
	v_mfma_f32_16x16x32_bf16 v[52:55], v[152:155], v[196:199], v[52:55]
	v_mfma_f32_16x16x32_bf16 v[52:55], v[156:159], v[200:203], v[52:55]
	v_mfma_f32_16x16x32_bf16 v[44:47], v[160:163], v[196:199], v[44:47]
	v_mfma_f32_16x16x32_bf16 v[44:47], v[164:167], v[200:203], v[44:47]
	v_mfma_f32_16x16x32_bf16 v[36:39], v[152:155], v[204:207], v[36:39]
	v_mfma_f32_16x16x32_bf16 v[36:39], v[156:159], v[208:211], v[36:39]
	v_mfma_f32_16x16x32_bf16 v[28:31], v[160:163], v[204:207], v[28:31]
	v_mfma_f32_16x16x32_bf16 v[28:31], v[164:167], v[208:211], v[28:31]
	v_mfma_f32_16x16x32_bf16 v[20:23], v[152:155], v[212:215], v[20:23]
	v_mfma_f32_16x16x32_bf16 v[20:23], v[156:159], v[216:219], v[20:23]
	v_mfma_f32_16x16x32_bf16 v[12:15], v[160:163], v[212:215], v[12:15]
	v_mfma_f32_16x16x32_bf16 v[12:15], v[164:167], v[216:219], v[12:15]
	v_mfma_f32_16x16x32_bf16 v[48:51], v[168:171], v[188:191], v[48:51]
	v_mfma_f32_16x16x32_bf16 v[48:51], v[172:175], v[192:195], v[48:51]
	v_mfma_f32_16x16x32_bf16 v[40:43], v[176:179], v[188:191], v[40:43]
	v_mfma_f32_16x16x32_bf16 v[40:43], v[184:187], v[192:195], v[40:43]
	v_mfma_f32_16x16x32_bf16 v[32:35], v[168:171], v[196:199], v[32:35]
	v_mfma_f32_16x16x32_bf16 v[32:35], v[172:175], v[200:203], v[32:35]
	v_mfma_f32_16x16x32_bf16 v[24:27], v[176:179], v[196:199], v[24:27]
	v_mfma_f32_16x16x32_bf16 v[24:27], v[184:187], v[200:203], v[24:27]
	v_mfma_f32_16x16x32_bf16 v[16:19], v[168:171], v[204:207], v[16:19]
	v_mfma_f32_16x16x32_bf16 v[16:19], v[172:175], v[208:211], v[16:19]
	v_mfma_f32_16x16x32_bf16 v[8:11], v[176:179], v[204:207], v[8:11]
	v_mfma_f32_16x16x32_bf16 v[8:11], v[184:187], v[208:211], v[8:11]
	v_mfma_f32_16x16x32_bf16 v[4:7], v[168:171], v[212:215], v[4:7]
	v_mfma_f32_16x16x32_bf16 v[4:7], v[172:175], v[216:219], v[4:7]
	v_mfma_f32_16x16x32_bf16 v[0:3], v[176:179], v[212:215], v[0:3]
	v_mfma_f32_16x16x32_bf16 v[0:3], v[184:187], v[216:219], v[0:3]
	s_setprio 0
	s_barrier
.Lmid_gemm12:
	s_add_i32 s77, 0, 0x18000
	s_add_i32 s79, 0, 0x1c000
	v_add_u32_e32 v164, s77, v147
	v_add_u32_e32 v181, s79, v147
	ds_read_b128 v[152:155], v164
	ds_read_b128 v[156:159], v164 offset:1024
	ds_read_b128 v[160:163], v164 offset:2048
	ds_read_b128 v[164:167], v164 offset:3072
	ds_read_b128 v[168:171], v181
	ds_read_b128 v[172:175], v181 offset:1024
	ds_read_b128 v[176:179], v181 offset:2048
	ds_read_b128 v[184:187], v181 offset:3072
	ds_read_b128 v[188:191], v151 offset:32768
	ds_read_b128 v[192:195], v151 offset:33792
	ds_read_b128 v[196:199], v151 offset:34816
	ds_read_b128 v[200:203], v151 offset:35840
	ds_read_b128 v[204:207], v151 offset:36864
	ds_read_b128 v[208:211], v151 offset:37888
	ds_read_b128 v[212:215], v151 offset:38912
	ds_read_b128 v[216:219], v151 offset:39936
	s_add_u32 s46, s52, 0xb0000
	s_addc_u32 s47, s53, 0
	s_mov_b32 m0, s59
	v_lshl_add_u64 v[226:227], s[46:47], 0, v[128:129]
	global_load_lds_dwordx4 v[226:227], off
	v_lshl_add_u64 v[226:227], s[46:47], 0, v[132:133]
	s_mov_b32 m0, s60
	s_nop 0
	global_load_lds_dwordx4 v[226:227], off
	s_waitcnt vmcnt(8)
	s_waitcnt lgkmcnt(0)
	s_barrier
	s_setprio 1
	s_waitcnt lgkmcnt(0)
	v_mfma_f32_16x16x32_bf16 v[124:127], v[152:155], v[188:191], v[124:127]
	v_mfma_f32_16x16x32_bf16 v[124:127], v[156:159], v[192:195], v[124:127]
	v_mfma_f32_16x16x32_bf16 v[120:123], v[160:163], v[188:191], v[120:123]
	v_mfma_f32_16x16x32_bf16 v[120:123], v[164:167], v[192:195], v[120:123]
	v_mfma_f32_16x16x32_bf16 v[116:119], v[152:155], v[196:199], v[116:119]
	v_mfma_f32_16x16x32_bf16 v[116:119], v[156:159], v[200:203], v[116:119]
	v_mfma_f32_16x16x32_bf16 v[108:111], v[160:163], v[196:199], v[108:111]
	v_mfma_f32_16x16x32_bf16 v[108:111], v[164:167], v[200:203], v[108:111]
	v_mfma_f32_16x16x32_bf16 v[100:103], v[152:155], v[204:207], v[100:103]
	v_mfma_f32_16x16x32_bf16 v[100:103], v[156:159], v[208:211], v[100:103]
	v_mfma_f32_16x16x32_bf16 v[92:95], v[160:163], v[204:207], v[92:95]
	v_mfma_f32_16x16x32_bf16 v[92:95], v[164:167], v[208:211], v[92:95]
	v_mfma_f32_16x16x32_bf16 v[84:87], v[152:155], v[212:215], v[84:87]
	v_mfma_f32_16x16x32_bf16 v[84:87], v[156:159], v[216:219], v[84:87]
	v_mfma_f32_16x16x32_bf16 v[76:79], v[160:163], v[212:215], v[76:79]
	v_mfma_f32_16x16x32_bf16 v[76:79], v[164:167], v[216:219], v[76:79]
	v_mfma_f32_16x16x32_bf16 v[112:115], v[168:171], v[188:191], v[112:115]
	v_mfma_f32_16x16x32_bf16 v[112:115], v[172:175], v[192:195], v[112:115]
	v_mfma_f32_16x16x32_bf16 v[104:107], v[176:179], v[188:191], v[104:107]
	v_mfma_f32_16x16x32_bf16 v[104:107], v[184:187], v[192:195], v[104:107]
	v_mfma_f32_16x16x32_bf16 v[96:99], v[168:171], v[196:199], v[96:99]
	v_mfma_f32_16x16x32_bf16 v[96:99], v[172:175], v[200:203], v[96:99]
	v_mfma_f32_16x16x32_bf16 v[88:91], v[176:179], v[196:199], v[88:91]
	v_mfma_f32_16x16x32_bf16 v[88:91], v[184:187], v[200:203], v[88:91]
	v_mfma_f32_16x16x32_bf16 v[80:83], v[168:171], v[204:207], v[80:83]
	v_mfma_f32_16x16x32_bf16 v[80:83], v[172:175], v[208:211], v[80:83]
	v_mfma_f32_16x16x32_bf16 v[72:75], v[176:179], v[204:207], v[72:75]
	v_mfma_f32_16x16x32_bf16 v[72:75], v[184:187], v[208:211], v[72:75]
	v_mfma_f32_16x16x32_bf16 v[68:71], v[168:171], v[212:215], v[68:71]
	v_mfma_f32_16x16x32_bf16 v[68:71], v[172:175], v[216:219], v[68:71]
	v_mfma_f32_16x16x32_bf16 v[64:67], v[176:179], v[212:215], v[64:67]
	v_mfma_f32_16x16x32_bf16 v[64:67], v[184:187], v[216:219], v[64:67]
	s_setprio 0
	s_barrier
	ds_read_b128 v[188:191], v151 offset:49152
	ds_read_b128 v[192:195], v151 offset:50176
	ds_read_b128 v[196:199], v151 offset:51200
	ds_read_b128 v[200:203], v151 offset:52224
	ds_read_b128 v[204:207], v151 offset:53248
	ds_read_b128 v[208:211], v151 offset:54272
	ds_read_b128 v[212:215], v151 offset:55296
	ds_read_b128 v[216:219], v151 offset:56320
	s_add_i32 s46, s77, s56
	v_lshl_add_u64 v[144:145], v[144:145], 0, s[10:11]
	s_mov_b32 m0, s46
	s_nop 0
	global_load_lds_dwordx4 v[144:145], off
	s_add_i32 m0, s46, 0x2000
	s_add_u32 s46, s50, 0xb0080
	v_lshl_add_u64 v[144:145], v[220:221], 0, s[10:11]
	s_addc_u32 s47, s51, 0
	s_add_i32 s50, s79, s56
	global_load_lds_dwordx4 v[144:145], off
	v_lshl_add_u64 v[144:145], s[46:47], 0, v[130:131]
	s_mov_b32 m0, s50
	s_nop 0
	global_load_lds_dwordx4 v[144:145], off
	v_lshl_add_u64 v[144:145], s[46:47], 0, v[134:135]
	s_add_i32 m0, s50, 0x2000
	s_nop 0
	global_load_lds_dwordx4 v[144:145], off
	v_lshl_add_u64 v[144:145], v[222:223], 0, s[10:11]
	s_mov_b32 m0, s62
	s_nop 0
	global_load_lds_dwordx4 v[144:145], off
	v_lshl_add_u64 v[144:145], v[224:225], 0, s[10:11]
	s_mov_b32 m0, s63
	s_nop 0
	global_load_lds_dwordx4 v[144:145], off
	s_waitcnt vmcnt(8)
	s_waitcnt lgkmcnt(0)
	s_barrier
	s_setprio 1
	s_waitcnt lgkmcnt(0)
	v_mfma_f32_16x16x32_bf16 v[60:63], v[152:155], v[188:191], v[60:63]
	v_mfma_f32_16x16x32_bf16 v[60:63], v[156:159], v[192:195], v[60:63]
	v_mfma_f32_16x16x32_bf16 v[56:59], v[160:163], v[188:191], v[56:59]
	v_mfma_f32_16x16x32_bf16 v[56:59], v[164:167], v[192:195], v[56:59]
	v_mfma_f32_16x16x32_bf16 v[52:55], v[152:155], v[196:199], v[52:55]
	v_mfma_f32_16x16x32_bf16 v[52:55], v[156:159], v[200:203], v[52:55]
	v_mfma_f32_16x16x32_bf16 v[44:47], v[160:163], v[196:199], v[44:47]
	v_mfma_f32_16x16x32_bf16 v[44:47], v[164:167], v[200:203], v[44:47]
	v_mfma_f32_16x16x32_bf16 v[36:39], v[152:155], v[204:207], v[36:39]
	v_mfma_f32_16x16x32_bf16 v[36:39], v[156:159], v[208:211], v[36:39]
	v_mfma_f32_16x16x32_bf16 v[28:31], v[160:163], v[204:207], v[28:31]
	v_mfma_f32_16x16x32_bf16 v[28:31], v[164:167], v[208:211], v[28:31]
	v_mfma_f32_16x16x32_bf16 v[20:23], v[152:155], v[212:215], v[20:23]
	v_mfma_f32_16x16x32_bf16 v[20:23], v[156:159], v[216:219], v[20:23]
	v_mfma_f32_16x16x32_bf16 v[12:15], v[160:163], v[212:215], v[12:15]
	v_mfma_f32_16x16x32_bf16 v[12:15], v[164:167], v[216:219], v[12:15]
	v_mfma_f32_16x16x32_bf16 v[48:51], v[168:171], v[188:191], v[48:51]
	v_mfma_f32_16x16x32_bf16 v[48:51], v[172:175], v[192:195], v[48:51]
	v_mfma_f32_16x16x32_bf16 v[40:43], v[176:179], v[188:191], v[40:43]
	v_mfma_f32_16x16x32_bf16 v[40:43], v[184:187], v[192:195], v[40:43]
	v_mfma_f32_16x16x32_bf16 v[32:35], v[168:171], v[196:199], v[32:35]
	v_mfma_f32_16x16x32_bf16 v[32:35], v[172:175], v[200:203], v[32:35]
	v_mfma_f32_16x16x32_bf16 v[24:27], v[176:179], v[196:199], v[24:27]
	v_mfma_f32_16x16x32_bf16 v[24:27], v[184:187], v[200:203], v[24:27]
	v_mfma_f32_16x16x32_bf16 v[16:19], v[168:171], v[204:207], v[16:19]
	v_mfma_f32_16x16x32_bf16 v[16:19], v[172:175], v[208:211], v[16:19]
	v_mfma_f32_16x16x32_bf16 v[8:11], v[176:179], v[204:207], v[8:11]
	v_mfma_f32_16x16x32_bf16 v[8:11], v[184:187], v[208:211], v[8:11]
	v_mfma_f32_16x16x32_bf16 v[4:7], v[168:171], v[212:215], v[4:7]
	v_mfma_f32_16x16x32_bf16 v[4:7], v[172:175], v[216:219], v[4:7]
	v_mfma_f32_16x16x32_bf16 v[0:3], v[176:179], v[212:215], v[0:3]
	v_mfma_f32_16x16x32_bf16 v[0:3], v[184:187], v[216:219], v[0:3]
	s_setprio 0
	s_barrier
	s_add_i32 s76, s76, 2
	s_add_u32 s74, s74, 0x100
	s_addc_u32 s75, s75, 0
	s_cmp_gt_u32 s76, 41
	s_mov_b64 s[46:47], s[48:49]
	s_cbranch_scc0 .LBB0_1514
	s_and_b64 vcc, exec, s[12:13]
	s_cbranch_vccz .LBB0_1517
	s_barrier
